# GEMM epilogue 16-byte stores made write-through (sc1) so the grid barrier's L2 write-back is cheap; attention K swizzle widened to 4 bits (conflict-free fragment reads)
# speedup vs baseline: 1.0192x; 1.0140x over previous
;     __device__ __forceinline__ void operator()(const f32x4 (&acc)[2][2][4][2], const Unit& u, int wr, int wc, int fr, int fq) const {
;         const int rowt = u.pm * BM, b = rowt >= MLAT ? 2 : (rowt >> 13);
;         const int row0 = rowt + wr * 64 + fr, col0 = u.pn * BM + wc * 32 + 8 * fq;
;         f32x4 bv[2][2];
; #pragma unroll
;         for (int bj = 0; bj < 2; ++bj)
; #pragma unroll
;             for (int n = 0; n < 2; ++n) bv[bj][n] = *(const f32x4*)(bias + (size_t)b * nbias + col0 + bj * HALF + 4 * n);
;         float rsv[2][4];
;         { f32x4 pq[2][4];
; #pragma unroll
;           for (int ai = 0; ai < 2; ++ai)
; #pragma unroll
;               for (int m = 0; m < 4; ++m) pq[ai][m] = *(const f32x4*)(ssq + (size_t)(row0 + ai * HALF + m * 16) * 16 + 4 * fq);
; #pragma unroll
;           for (int ai = 0; ai < 2; ++ai)
; #pragma unroll
;               for (int m = 0; m < 4; ++m) { float t = (pq[ai][m][0] + pq[ai][m][1]) + (pq[ai][m][2] + pq[ai][m][3]); t += __shfl_xor(t, 16); t += __shfl_xor(t, 32);
;                   rsv[ai][m] = rsqrtf(t * (1.f / DM) + EPS); } }
; #pragma unroll
;         for (int ai = 0; ai < 2; ++ai)
; #pragma unroll
;             for (int m = 0; m < 4; ++m) { const int row = row0 + ai * HALF + m * 16; bf16_t* rowp = O + (size_t)row * ldc + col0; float s = 0.f, q = 0.f;
;                 const float rstd = rsv[ai][m];
; #pragma unroll
;                 for (int bj = 0; bj < 2; ++bj) { f32x4 v0 = acc[ai][bj][m][0] * rstd + bv[bj][0], v1 = acc[ai][bj][m][1] * rstd + bv[bj][1];
;                     if (ACT == 1) {
; #pragma unroll
;                         for (int e = 0; e < 4; ++e) { const float a = fmaxf(v0[e], 0.f), b2 = fmaxf(v1[e], 0.f); v0[e] = a * a; v1[e] = b2 * b2; } }
;                     if (ACT == 2) {
; #pragma unroll
;                         for (int e = 0; e < 4; ++e) { v0[e] = gelu_tanh(v0[e]); v1[e] = gelu_tanh(v1[e]); s += v0[e] + v1[e]; q += v0[e] * v0[e] + v1[e] * v1[e]; } }
.LBB0_186:
	s_min_i32 s15, s36, 64
	s_ashr_i32 s16, s15, 5
	s_ashr_i32 s17, s16, 31
	s_lshl_b64 s[16:17], s[16:17], 14
	v_lshl_add_u32 v196, s36, 8, v201
	v_lshl_or_b32 v182, s44, 8, v203
	s_add_u32 s16, s62, s16
	v_ashrrev_i32_e32 v197, 31, v196
	s_addc_u32 s17, s63, s17
	v_ashrrev_i32_e32 v183, 31, v182
	v_lshlrev_b64 v[144:145], 6, v[196:197]
	v_or_b32_e32 v194, 16, v196
	v_lshl_add_u64 v[36:37], v[182:183], 2, s[16:17]
	v_lshl_add_u64 v[144:145], v[174:175], 0, v[144:145]
	v_ashrrev_i32_e32 v195, 31, v194
	global_load_dwordx4 v[40:43], v[36:37], off offset:16
	global_load_dwordx4 v[44:47], v[36:37], off
	global_load_dwordx4 v[32:35], v[36:37], off offset:528
	s_nop 0
	global_load_dwordx4 v[36:39], v[36:37], off offset:512
	v_or_b32_e32 v192, 32, v196
	global_load_dwordx4 v[208:211], v[144:145], off
	v_lshlrev_b64 v[144:145], 6, v[194:195]
	v_lshl_add_u64 v[144:145], v[174:175], 0, v[144:145]
	global_load_dwordx4 v[220:223], v[144:145], off
	v_ashrrev_i32_e32 v193, 31, v192
	v_lshlrev_b64 v[144:145], 6, v[192:193]
	v_or_b32_e32 v190, 48, v196
	v_lshl_add_u64 v[144:145], v[174:175], 0, v[144:145]
	v_ashrrev_i32_e32 v191, 31, v190
	global_load_dwordx4 v[160:163], v[144:145], off
	v_lshlrev_b64 v[144:145], 6, v[190:191]
	v_add_u32_e32 v188, 0x80, v196
	v_lshl_add_u64 v[144:145], v[174:175], 0, v[144:145]
	v_ashrrev_i32_e32 v189, 31, v188
	global_load_dwordx4 v[164:167], v[144:145], off
	v_lshlrev_b64 v[144:145], 6, v[188:189]
	v_add_u32_e32 v186, 0x90, v196
	v_lshl_add_u64 v[144:145], v[174:175], 0, v[144:145]
	v_ashrrev_i32_e32 v187, 31, v186
	global_load_dwordx4 v[156:159], v[144:145], off
	v_lshlrev_b64 v[144:145], 6, v[186:187]
	v_add_u32_e32 v184, 0xa0, v196
	v_lshl_add_u64 v[144:145], v[174:175], 0, v[144:145]
	v_ashrrev_i32_e32 v185, 31, v184
	global_load_dwordx4 v[152:155], v[144:145], off
	v_lshlrev_b64 v[144:145], 6, v[184:185]
	v_add_u32_e32 v180, 0xb0, v196
	v_lshl_add_u64 v[144:145], v[174:175], 0, v[144:145]
	v_ashrrev_i32_e32 v181, 31, v180
	global_load_dwordx4 v[148:151], v[144:145], off
	v_lshlrev_b64 v[144:145], 6, v[180:181]
	v_lshl_add_u64 v[144:145], v[174:175], 0, v[144:145]
	global_load_dwordx4 v[144:147], v[144:145], off
	v_and_b32_e32 v199, 64, v246
	v_xor_b32_e32 v198, 16, v246
	v_add_u32_e32 v199, 64, v199
	v_cmp_lt_i32_e32 vcc, v198, v199
	s_mov_b32 s16, 0x3a800000
	s_cmp_gt_i32 s44, 7
	v_cndmask_b32_e32 v198, v246, v198, vcc
	v_lshlrev_b32_e32 v205, 2, v198
	v_xor_b32_e32 v198, 32, v246
	v_cmp_lt_i32_e32 vcc, v198, v199
	s_cselect_b64 s[46:47], -1, 0
	s_lshl_b32 s15, s44, 2
	v_cndmask_b32_e32 v198, v246, v198, vcc
	v_lshlrev_b32_e32 v206, 2, v198
	s_waitcnt vmcnt(0)
	v_mov_b32_e32 v198, v209
	v_mov_b32_e32 v199, v210
	v_mov_b32_e32 v209, v211
	v_pk_add_f32 v[198:199], v[198:199], v[208:209]
	v_mov_b32_e32 v208, v221
	v_mov_b32_e32 v209, v222
	v_mov_b32_e32 v221, v223
	v_pk_add_f32 v[208:209], v[208:209], v[220:221]
	v_mov_b32_e32 v211, v198
	v_mov_b32_e32 v210, v208
	v_mov_b32_e32 v198, v209
	v_pk_add_f32 v[198:199], v[210:211], v[198:199]
	ds_bpermute_b32 v209, v205, v199
	ds_bpermute_b32 v208, v205, v198
	s_waitcnt lgkmcnt(0)
	v_pk_add_f32 v[198:199], v[198:199], v[208:209]
	ds_bpermute_b32 v209, v206, v199
	ds_bpermute_b32 v208, v206, v198
	s_waitcnt lgkmcnt(0)
	v_pk_add_f32 v[198:199], v[198:199], v[208:209]
	s_nop 0
	v_pk_fma_f32 v[198:199], v[198:199], s[16:17], v[214:215] op_sel_hi:[1,0,0]
	v_mov_b32_e32 v208, v161
	v_mul_f32_e32 v200, 0x4b800000, v199
	v_cmp_gt_f32_e64 s[42:43], s27, v199
	v_mov_b32_e32 v209, v162
	v_mov_b32_e32 v161, v163
	v_cndmask_b32_e64 v199, v199, v200, s[42:43]
	v_mov_b32_e32 v162, v165
	v_mov_b32_e32 v163, v166
	v_mov_b32_e32 v165, v167
	v_rsq_f32_e32 v199, v199
	v_pk_add_f32 v[160:161], v[208:209], v[160:161]
	v_pk_add_f32 v[162:163], v[162:163], v[164:165]
	v_mov_b32_e32 v165, v160
	v_mov_b32_e32 v164, v162
	v_mov_b32_e32 v160, v163
	v_pk_add_f32 v[160:161], v[164:165], v[160:161]
	v_mov_b32_e32 v164, v157
	v_mov_b32_e32 v165, v158
	v_mov_b32_e32 v157, v159
	v_mov_b32_e32 v158, v153
	v_mov_b32_e32 v159, v154
	v_mov_b32_e32 v153, v155
	v_pk_add_f32 v[156:157], v[164:165], v[156:157]
	v_pk_add_f32 v[152:153], v[158:159], v[152:153]
	v_mul_f32_e32 v200, 0x45800000, v199
	v_mov_b32_e32 v154, v152
	v_mov_b32_e32 v155, v156
	v_mov_b32_e32 v156, v153
	v_cndmask_b32_e64 v200, v199, v200, s[42:43]
	v_pk_add_f32 v[152:153], v[154:155], v[156:157]
	v_mov_b32_e32 v156, v149
	v_mov_b32_e32 v157, v150
	v_mov_b32_e32 v149, v151
	v_mov_b32_e32 v150, v145
	v_mov_b32_e32 v151, v146
	v_mov_b32_e32 v145, v147
	v_pk_add_f32 v[144:145], v[150:151], v[144:145]
	v_pk_fma_f32 v[150:151], v[138:139], v[200:201], v[42:43] op_sel_hi:[1,0,1]
	v_pk_fma_f32 v[138:139], v[136:137], v[200:201], v[40:41] op_sel_hi:[1,0,1]
	v_pk_fma_f32 v[140:141], v[140:141], v[200:201], v[44:45] op_sel_hi:[1,0,1]
	v_mul_f32_e32 v137, 0x3d122279, v138
	v_fmaak_f32 v137, v138, v137, 0x3f4c422a
	v_mul_f32_e32 v137, v138, v137
	v_mul_f32_e32 v137, 0x4038aa3b, v137
	v_exp_f32_e32 v137, v137
	v_pk_add_f32 v[148:149], v[156:157], v[148:149]
	v_mul_f32_e32 v136, 0x3d122279, v140
	v_fmaak_f32 v136, v140, v136, 0x3f4c422a
	v_add_f32_e32 v137, 1.0, v137
	v_rcp_f32_e32 v156, v137
	v_mul_f32_e32 v137, 0x3d122279, v141
	v_fmaak_f32 v137, v141, v137, 0x3f4c422a
	v_mul_f32_e32 v136, v140, v136
	v_mul_f32_e32 v137, v141, v137
	v_mul_f32_e32 v136, 0x4038aa3b, v136
	v_mul_f32_e32 v137, 0x4038aa3b, v137
	v_exp_f32_e32 v136, v136
	v_exp_f32_e32 v137, v137
	v_mul_f32_e32 v157, 0x3d122279, v139
	v_fmaak_f32 v157, v139, v157, 0x3f4c422a
	v_add_f32_e32 v136, 1.0, v136
	v_add_f32_e32 v137, 1.0, v137
	v_rcp_f32_e32 v136, v136
	v_rcp_f32_e32 v137, v137
; __device__ __forceinline__ unsigned cvt_pk_bf16(float lo, float hi) { unsigned r; asm volatile("v_cvt_pk_bf16_f32 %0, %1, %2" : "=v"(r) : "v"(lo), "v"(hi)); return r; }
;     __device__ __forceinline__ void operator()(const f32x4 (&acc)[2][2][4][2], const Unit& u, int wr, int wc, int fr, int fq) const {
;     ...
;             for (int m = 0; m < 4; ++m) { const int row = row0 + ai * HALF + m * 16; bf16_t* rowp = O + (size_t)row * ldc + col0; float s = 0.f, q = 0.f;
;                 const float rstd = rsv[ai][m];
; #pragma unroll
;                 for (int bj = 0; bj < 2; ++bj) { f32x4 v0 = acc[ai][bj][m][0] * rstd + bv[bj][0], v1 = acc[ai][bj][m][1] * rstd + bv[bj][1];
;                     if (ACT == 1) {
; #pragma unroll
;                         for (int e = 0; e < 4; ++e) { const float a = fmaxf(v0[e], 0.f), b2 = fmaxf(v1[e], 0.f); v0[e] = a * a; v1[e] = b2 * b2; } }
;                     if (ACT == 2) {
; #pragma unroll
;                         for (int e = 0; e < 4; ++e) { v0[e] = gelu_tanh(v0[e]); v1[e] = gelu_tanh(v1[e]); s += v0[e] + v1[e]; q += v0[e] * v0[e] + v1[e] * v1[e]; } }
;                     u32x4 w; w.x = cvt_pk_bf16(v0[0], v0[1]); w.y = cvt_pk_bf16(v0[2], v0[3]); w.z = cvt_pk_bf16(v1[0], v1[1]); w.w = cvt_pk_bf16(v1[2], v1[3]);
;                     *(u32x4*)(rowp + bj * HALF) = w; }
	v_mul_f32_e32 v157, v139, v157
	v_mul_f32_e32 v157, 0x4038aa3b, v157
	v_exp_f32_e32 v157, v157
	v_pk_fma_f32 v[136:137], v[140:141], v[136:137], v[140:141] neg_lo:[1,0,0] neg_hi:[1,0,0]
	v_mul_f32_e32 v141, 0x3d122279, v150
	v_fmaak_f32 v141, v150, v141, 0x3f4c422a
	v_mul_f32_e32 v141, v150, v141
	v_mul_f32_e32 v141, 0x4038aa3b, v141
	v_add_f32_e32 v157, 1.0, v157
	v_exp_f32_e32 v141, v141
	v_rcp_f32_e32 v157, v157
	v_pk_fma_f32 v[142:143], v[142:143], v[200:201], v[46:47] op_sel_hi:[1,0,1]
	v_mov_b32_e32 v146, v144
	v_add_f32_e32 v141, 1.0, v141
	v_pk_fma_f32 v[138:139], v[138:139], v[156:157], v[138:139] neg_lo:[1,0,0] neg_hi:[1,0,0]
	v_mul_f32_e32 v140, 0x3d122279, v142
	v_rcp_f32_e32 v156, v141
	v_mul_f32_e32 v141, 0x3d122279, v143
	v_mul_f32_e32 v157, 0x3d122279, v151
	v_fmaak_f32 v140, v142, v140, 0x3f4c422a
	v_fmaak_f32 v141, v143, v141, 0x3f4c422a
	v_fmaak_f32 v157, v151, v157, 0x3f4c422a
	v_mul_f32_e32 v140, v142, v140
	v_mul_f32_e32 v141, v143, v141
	v_mul_f32_e32 v157, v151, v157
	v_mul_f32_e32 v140, 0x4038aa3b, v140
	v_mul_f32_e32 v141, 0x4038aa3b, v141
	v_mul_f32_e32 v157, 0x4038aa3b, v157
	v_exp_f32_e32 v140, v140
	v_exp_f32_e32 v141, v141
	v_exp_f32_e32 v157, v157
	v_mov_b32_e32 v147, v148
	v_add_f32_e32 v140, 1.0, v140
	v_add_f32_e32 v141, 1.0, v141
	v_add_f32_e32 v157, 1.0, v157
	v_rcp_f32_e32 v140, v140
	v_rcp_f32_e32 v141, v141
	v_rcp_f32_e32 v157, v157
	v_mov_b32_e32 v148, v145
	v_pk_add_f32 v[144:145], v[146:147], v[148:149]
	v_pk_fma_f32 v[140:141], v[142:143], v[140:141], v[142:143] neg_lo:[1,0,0] neg_hi:[1,0,0]
	v_pk_fma_f32 v[142:143], v[150:151], v[156:157], v[150:151] neg_lo:[1,0,0] neg_hi:[1,0,0]
	v_pk_fma_f32 v[150:151], v[130:131], v[200:201], v[34:35] op_sel_hi:[1,0,1]
	v_pk_fma_f32 v[130:131], v[128:129], v[200:201], v[32:33] op_sel_hi:[1,0,1]
	v_lshlrev_b64 v[148:149], 13, v[196:197]
	v_mul_f32_e32 v129, 0x3d122279, v130
	v_fmaak_f32 v129, v130, v129, 0x3f4c422a
	v_mul_f32_e32 v129, v130, v129
	v_mul_f32_e32 v129, 0x4038aa3b, v129
	v_exp_f32_e32 v129, v129
	v_lshl_add_u64 v[148:149], s[2:3], 0, v[148:149]
	v_lshl_add_u64 v[148:149], v[182:183], 1, v[148:149]
	v_cvt_pk_bf16_f32 v156, v136, v137
	v_pk_fma_f32 v[132:133], v[132:133], v[200:201], v[36:37] op_sel_hi:[1,0,1]
	v_add_f32_e32 v129, 1.0, v129
	v_cvt_pk_bf16_f32 v157, v140, v141
	v_cvt_pk_bf16_f32 v158, v138, v139
	v_cvt_pk_bf16_f32 v159, v142, v143
	global_store_dwordx4 v[148:149], v[156:159], off sc1
	v_mul_f32_e32 v128, 0x3d122279, v132
	v_fmaak_f32 v128, v132, v128, 0x3f4c422a
	v_rcp_f32_e32 v156, v129
	v_mul_f32_e32 v129, 0x3d122279, v133
	v_fmaak_f32 v129, v133, v129, 0x3f4c422a
	v_mul_f32_e32 v128, v132, v128
	v_mul_f32_e32 v129, v133, v129
	v_mul_f32_e32 v128, 0x4038aa3b, v128
	v_mul_f32_e32 v129, 0x4038aa3b, v129
	v_exp_f32_e32 v128, v128
	v_exp_f32_e32 v129, v129
	v_mul_f32_e32 v157, 0x3d122279, v131
	v_fmaak_f32 v157, v131, v157, 0x3f4c422a
	v_add_f32_e32 v128, 1.0, v128
	v_add_f32_e32 v129, 1.0, v129
	v_rcp_f32_e32 v128, v128
	v_rcp_f32_e32 v129, v129
	v_mul_f32_e32 v157, v131, v157
	v_mul_f32_e32 v157, 0x4038aa3b, v157
	v_exp_f32_e32 v157, v157
	v_pk_fma_f32 v[128:129], v[132:133], v[128:129], v[132:133] neg_lo:[1,0,0] neg_hi:[1,0,0]
	v_mul_f32_e32 v133, 0x3d122279, v150
	v_fmaak_f32 v133, v150, v133, 0x3f4c422a
	v_mul_f32_e32 v133, v150, v133
	v_mul_f32_e32 v133, 0x4038aa3b, v133
	v_add_f32_e32 v157, 1.0, v157
	v_exp_f32_e32 v133, v133
	v_rcp_f32_e32 v157, v157
	v_pk_fma_f32 v[134:135], v[134:135], v[200:201], v[38:39] op_sel_hi:[1,0,1]
	v_mov_b32_e32 v158, v150
	v_add_f32_e32 v133, 1.0, v133
	v_pk_fma_f32 v[130:131], v[130:131], v[156:157], v[130:131] neg_lo:[1,0,0] neg_hi:[1,0,0]
	v_rcp_f32_e32 v156, v133
	v_mul_f32_e32 v133, 0x3d122279, v135
	v_mul_f32_e32 v132, 0x3d122279, v134
	v_fmaak_f32 v133, v135, v133, 0x3f4c422a
	v_mul_f32_e32 v150, 0x3d122279, v151
	v_fmaak_f32 v132, v134, v132, 0x3f4c422a
	v_mul_f32_e32 v133, v135, v133
	v_fmaak_f32 v150, v151, v150, 0x3f4c422a
	v_mul_f32_e32 v132, v134, v132
	v_mul_f32_e32 v133, 0x4038aa3b, v133
	v_mul_f32_e32 v150, v151, v150
	ds_bpermute_b32 v163, v205, v161
	ds_bpermute_b32 v162, v205, v160
	ds_bpermute_b32 v155, v205, v153
	ds_bpermute_b32 v154, v205, v152
	ds_bpermute_b32 v147, v205, v145
	ds_bpermute_b32 v146, v205, v144
	v_mul_f32_e32 v132, 0x4038aa3b, v132
	v_exp_f32_e32 v133, v133
	v_mul_f32_e32 v150, 0x4038aa3b, v150
	v_exp_f32_e32 v132, v132
	v_exp_f32_e32 v150, v150
	v_add_f32_e32 v133, 1.0, v133
	s_waitcnt lgkmcnt(4)
	v_pk_add_f32 v[160:161], v[160:161], v[162:163]
	s_waitcnt lgkmcnt(2)
	v_pk_add_f32 v[152:153], v[152:153], v[154:155]
	s_waitcnt lgkmcnt(0)
	v_pk_add_f32 v[144:145], v[144:145], v[146:147]
	v_add_f32_e32 v132, 1.0, v132
	v_rcp_f32_e32 v133, v133
	v_add_f32_e32 v150, 1.0, v150
	ds_bpermute_b32 v163, v206, v161
	ds_bpermute_b32 v162, v206, v160
	ds_bpermute_b32 v155, v206, v153
	ds_bpermute_b32 v154, v206, v152
	ds_bpermute_b32 v147, v206, v145
	ds_bpermute_b32 v146, v206, v144
	v_rcp_f32_e32 v132, v132
	v_rcp_f32_e32 v150, v150
	s_sub_i32 s16, s15, 32
	s_ashr_i32 s17, s16, 31
	s_or_b64 s[36:37], s[16:17], s[8:9]
	v_mov_b32_e32 v159, v135
	v_mov_b32_e32 v157, v133
	v_cmp_gt_f32_e32 vcc, s27, v198
	s_cmp_lt_i32 s44, 8
	v_pk_fma_f32 v[132:133], v[134:135], v[132:133], v[134:135] neg_lo:[1,0,0] neg_hi:[1,0,0]
	v_pk_fma_f32 v[134:135], v[158:159], v[156:157], v[158:159] neg_lo:[1,0,0] neg_hi:[1,0,0]
	v_fma_f32 v150, -v151, v150, v151
	v_cvt_pk_bf16_f32 v156, v128, v129
	v_cvt_pk_bf16_f32 v157, v132, v133
	v_cvt_pk_bf16_f32 v158, v130, v131
	v_cvt_pk_bf16_f32 v159, v134, v150
	global_store_dwordx4 v[148:149], v[156:159], off offset:256 sc1
	s_cbranch_scc1 .LBB0_190
; __device__ __forceinline__ unsigned cvt_pk_bf16(float lo, float hi) { unsigned r; asm volatile("v_cvt_pk_bf16_f32 %0, %1, %2" : "=v"(r) : "v"(lo), "v"(hi)); return r; }
;     __device__ __forceinline__ void operator()(const f32x4 (&acc)[2][2][4][2], const Unit& u, int wr, int wc, int fr, int fq) const {
;     ...
;                         for (int e = 0; e < 4; ++e) { v0[e] = gelu_tanh(v0[e]); v1[e] = gelu_tanh(v1[e]); s += v0[e] + v1[e]; q += v0[e] * v0[e] + v1[e] * v1[e]; } }
;                     u32x4 w; w.x = cvt_pk_bf16(v0[0], v0[1]); w.y = cvt_pk_bf16(v0[2], v0[3]); w.z = cvt_pk_bf16(v1[0], v1[1]); w.w = cvt_pk_bf16(v1[2], v1[3]);
;                     *(u32x4*)(rowp + bj * HALF) = w; }
;                 if (ACT == 2) { if (u.pn >= 8) { s += __shfl_xor(s, 16); s += __shfl_xor(s, 32); q += __shfl_xor(q, 16); q += __shfl_xor(q, 32);
;                     if (fq == 0) *(f32x2*)(stats + ((size_t)row * 32 + (u.pn - 8) * 4 + wc) * 2) = (f32x2){s, q}; } }
	v_pk_mul_f32 v[148:149], v[138:139], v[138:139]
	v_pk_mul_f32 v[156:157], v[142:143], v[142:143]
	v_pk_fma_f32 v[148:149], v[136:137], v[136:137], v[148:149]
	v_pk_fma_f32 v[156:157], v[140:141], v[140:141], v[156:157]
	v_add_f32_e32 v148, v148, v149
	v_pk_mul_f32 v[158:159], v[130:131], v[130:131]
	v_add_f32_e32 v148, v156, v148
	v_pk_fma_f32 v[158:159], v[128:129], v[128:129], v[158:159]
	v_add_f32_e32 v148, v157, v148
	v_add_f32_e32 v148, v158, v148
	v_pk_add_f32 v[148:149], v[158:159], v[148:149] op_sel_hi:[1,0]
	v_pk_add_f32 v[136:137], v[136:137], v[138:139]
	v_mov_b32_e32 v156, v132
	v_mov_b32_e32 v157, v134
	v_mul_f32_e32 v148, v132, v132
	v_pk_add_f32 v[158:159], v[132:133], v[134:135]
	v_pk_mul_f32 v[134:135], v[132:133], v[134:135]
	v_add_f32_e32 v132, 0, v136
	v_add_f32_e32 v132, v137, v132
	v_pk_add_f32 v[136:137], v[140:141], v[142:143]
	v_pk_add_f32 v[128:129], v[128:129], v[130:131]
	v_add_f32_e32 v132, v136, v132
	v_add_f32_e32 v132, v137, v132
	v_pk_fma_f32 v[156:157], v[156:157], v[156:157], v[148:149] op_sel_hi:[1,1,0]
	v_add_f32_e32 v128, v128, v132
	v_mov_b32_e32 v159, v135
	v_mul_f32_e32 v135, v150, v150
	v_add_f32_e32 v134, v129, v128
	v_mov_b32_e32 v156, v133
	v_mov_b32_e32 v151, v149
	v_pk_add_f32 v[128:129], v[158:159], v[134:135]
	v_pk_add_f32 v[130:131], v[156:157], v[150:151]
	s_nop 0
	v_pk_add_f32 v[128:129], v[128:129], v[130:131]
	ds_bpermute_b32 v130, v205, v128
	ds_bpermute_b32 v131, v205, v129
	s_waitcnt lgkmcnt(0)
	v_pk_add_f32 v[128:129], v[128:129], v[130:131]
	ds_bpermute_b32 v130, v206, v128
	ds_bpermute_b32 v131, v206, v129
	s_and_saveexec_b64 s[42:43], s[38:39]
	s_cbranch_execz .LBB0_189
	v_lshlrev_b64 v[132:133], 8, v[196:197]
	s_waitcnt lgkmcnt(0)
	v_pk_add_f32 v[128:129], v[128:129], v[130:131]
	v_lshl_add_u64 v[130:131], s[6:7], 0, v[132:133]
	v_lshl_add_u64 v[130:131], s[36:37], 3, v[130:131]
	global_store_dwordx2 v[130:131], v[128:129], off

; __device__ __forceinline__ unsigned cvt_pk_bf16(float lo, float hi) { unsigned r; asm volatile("v_cvt_pk_bf16_f32 %0, %1, %2" : "=v"(r) : "v"(lo), "v"(hi)); return r; }
;     __device__ __forceinline__ void operator()(const f32x4 (&acc)[2][2][4][2], const Unit& u, int wr, int wc, int fr, int fq) const {
;     ...
;             for (int m = 0; m < 4; ++m) { const int row = row0 + ai * HALF + m * 16; bf16_t* rowp = O + (size_t)row * ldc + col0; float s = 0.f, q = 0.f;
;                 const float rstd = rsv[ai][m];
; #pragma unroll
;                 for (int bj = 0; bj < 2; ++bj) { f32x4 v0 = acc[ai][bj][m][0] * rstd + bv[bj][0], v1 = acc[ai][bj][m][1] * rstd + bv[bj][1];
;                     if (ACT == 1) {
; #pragma unroll
;                         for (int e = 0; e < 4; ++e) { const float a = fmaxf(v0[e], 0.f), b2 = fmaxf(v1[e], 0.f); v0[e] = a * a; v1[e] = b2 * b2; } }
;                     if (ACT == 2) {
; #pragma unroll
;                         for (int e = 0; e < 4; ++e) { v0[e] = gelu_tanh(v0[e]); v1[e] = gelu_tanh(v1[e]); s += v0[e] + v1[e]; q += v0[e] * v0[e] + v1[e] * v1[e]; } }
;                     u32x4 w; w.x = cvt_pk_bf16(v0[0], v0[1]); w.y = cvt_pk_bf16(v0[2], v0[3]); w.z = cvt_pk_bf16(v1[0], v1[1]); w.w = cvt_pk_bf16(v1[2], v1[3]);
;                     *(u32x4*)(rowp + bj * HALF) = w; }
.LBB0_190:
	v_mul_f32_e32 v128, 0x4b800000, v198
	v_cndmask_b32_e32 v128, v198, v128, vcc
	v_rsq_f32_e32 v128, v128
	s_nop 0
	v_mul_f32_e32 v129, 0x45800000, v128
	v_cndmask_b32_e32 v134, v128, v129, vcc
	s_waitcnt lgkmcnt(0)
	v_pk_fma_f32 v[130:131], v[122:123], v[134:135], v[42:43] op_sel_hi:[1,0,1]
	v_pk_fma_f32 v[122:123], v[120:121], v[134:135], v[40:41] op_sel_hi:[1,0,1]
	v_pk_fma_f32 v[124:125], v[124:125], v[134:135], v[44:45] op_sel_hi:[1,0,1]
	v_mul_f32_e32 v121, 0x3d122279, v122
	v_fmaak_f32 v121, v122, v121, 0x3f4c422a
	v_mul_f32_e32 v121, v122, v121
	v_mul_f32_e32 v121, 0x4038aa3b, v121
	v_exp_f32_e32 v121, v121
	v_mul_f32_e32 v120, 0x3d122279, v124
	v_fmaak_f32 v120, v124, v120, 0x3f4c422a
	v_mul_f32_e32 v120, v124, v120
	v_add_f32_e32 v121, 1.0, v121
	v_rcp_f32_e32 v132, v121
	v_mul_f32_e32 v121, 0x3d122279, v125
	v_fmaak_f32 v121, v125, v121, 0x3f4c422a
	v_mul_f32_e32 v121, v125, v121
	v_mul_f32_e32 v120, 0x4038aa3b, v120
	v_mul_f32_e32 v121, 0x4038aa3b, v121
	v_exp_f32_e32 v120, v120
	v_exp_f32_e32 v121, v121
	v_mul_f32_e32 v133, 0x3d122279, v123
	v_fmaak_f32 v133, v123, v133, 0x3f4c422a
	v_add_f32_e32 v120, 1.0, v120
	v_add_f32_e32 v121, 1.0, v121
	v_rcp_f32_e32 v120, v120
	v_rcp_f32_e32 v121, v121
	v_mul_f32_e32 v133, v123, v133
	v_mul_f32_e32 v133, 0x4038aa3b, v133
	v_exp_f32_e32 v133, v133
	v_pk_fma_f32 v[120:121], v[124:125], v[120:121], v[124:125] neg_lo:[1,0,0] neg_hi:[1,0,0]
	v_mul_f32_e32 v125, 0x3d122279, v130
	v_fmaak_f32 v125, v130, v125, 0x3f4c422a
	v_mul_f32_e32 v125, v130, v125
	v_mul_f32_e32 v125, 0x4038aa3b, v125
	v_add_f32_e32 v133, 1.0, v133
	v_exp_f32_e32 v125, v125
	v_rcp_f32_e32 v133, v133
	v_pk_fma_f32 v[126:127], v[126:127], v[134:135], v[46:47] op_sel_hi:[1,0,1]
	v_lshlrev_b64 v[128:129], 13, v[194:195]
	v_add_f32_e32 v125, 1.0, v125
	v_pk_fma_f32 v[122:123], v[122:123], v[132:133], v[122:123] neg_lo:[1,0,0] neg_hi:[1,0,0]
	v_mul_f32_e32 v124, 0x3d122279, v126
	v_rcp_f32_e32 v132, v125
	v_mul_f32_e32 v125, 0x3d122279, v127
	v_mul_f32_e32 v133, 0x3d122279, v131
	v_fmaak_f32 v124, v126, v124, 0x3f4c422a
	v_fmaak_f32 v125, v127, v125, 0x3f4c422a
	v_fmaak_f32 v133, v131, v133, 0x3f4c422a
	v_mul_f32_e32 v124, v126, v124
	v_mul_f32_e32 v125, v127, v125
	v_mul_f32_e32 v133, v131, v133
	v_mul_f32_e32 v124, 0x4038aa3b, v124
	v_mul_f32_e32 v125, 0x4038aa3b, v125
	v_mul_f32_e32 v133, 0x4038aa3b, v133
	v_exp_f32_e32 v124, v124
	v_exp_f32_e32 v125, v125
	v_exp_f32_e32 v133, v133
	v_lshl_add_u64 v[128:129], s[2:3], 0, v[128:129]
	v_add_f32_e32 v124, 1.0, v124
	v_add_f32_e32 v125, 1.0, v125
	v_add_f32_e32 v133, 1.0, v133
	v_rcp_f32_e32 v124, v124
	v_rcp_f32_e32 v125, v125
	v_rcp_f32_e32 v133, v133
	v_lshl_add_u64 v[128:129], v[182:183], 1, v[128:129]
	v_pk_fma_f32 v[116:117], v[116:117], v[134:135], v[36:37] op_sel_hi:[1,0,1]
	v_pk_fma_f32 v[124:125], v[126:127], v[124:125], v[126:127] neg_lo:[1,0,0] neg_hi:[1,0,0]
	v_pk_fma_f32 v[126:127], v[130:131], v[132:133], v[130:131] neg_lo:[1,0,0] neg_hi:[1,0,0]
	v_cvt_pk_bf16_f32 v130, v120, v121
	v_cvt_pk_bf16_f32 v131, v124, v125
	v_cvt_pk_bf16_f32 v132, v122, v123
	v_pk_fma_f32 v[118:119], v[118:119], v[134:135], v[38:39] op_sel_hi:[1,0,1]
	v_cvt_pk_bf16_f32 v133, v126, v127
	global_store_dwordx4 v[128:129], v[130:133], off sc1
	s_andn2_b64 vcc, exec, s[46:47]
	s_nop 0
	v_pk_fma_f32 v[130:131], v[114:115], v[134:135], v[34:35] op_sel_hi:[1,0,1]
	v_pk_fma_f32 v[114:115], v[112:113], v[134:135], v[32:33] op_sel_hi:[1,0,1]
	v_mul_f32_e32 v112, 0x3d122279, v116
	v_mul_f32_e32 v113, 0x3d122279, v114
	v_fmaak_f32 v113, v114, v113, 0x3f4c422a
	v_mul_f32_e32 v113, v114, v113
	v_mul_f32_e32 v113, 0x4038aa3b, v113
	v_exp_f32_e32 v113, v113
	v_fmaak_f32 v112, v116, v112, 0x3f4c422a
	v_mul_f32_e32 v112, v116, v112
	v_mul_f32_e32 v112, 0x4038aa3b, v112
	v_add_f32_e32 v113, 1.0, v113
	v_rcp_f32_e32 v132, v113
	v_mul_f32_e32 v113, 0x3d122279, v117
	v_fmaak_f32 v113, v117, v113, 0x3f4c422a
	v_mul_f32_e32 v113, v117, v113
	v_mul_f32_e32 v113, 0x4038aa3b, v113
	v_exp_f32_e32 v112, v112
	v_exp_f32_e32 v113, v113
	v_mul_f32_e32 v133, 0x3d122279, v115
	v_fmaak_f32 v133, v115, v133, 0x3f4c422a
	v_add_f32_e32 v112, 1.0, v112
	v_add_f32_e32 v113, 1.0, v113
	v_rcp_f32_e32 v112, v112
	v_rcp_f32_e32 v113, v113
	v_mul_f32_e32 v133, v115, v133
	v_mul_f32_e32 v133, 0x4038aa3b, v133
	v_exp_f32_e32 v133, v133
	v_pk_fma_f32 v[112:113], v[116:117], v[112:113], v[116:117] neg_lo:[1,0,0] neg_hi:[1,0,0]
	v_mul_f32_e32 v117, 0x3d122279, v130
	v_fmaak_f32 v117, v130, v117, 0x3f4c422a
	v_mul_f32_e32 v117, v130, v117
	v_mul_f32_e32 v117, 0x4038aa3b, v117
	v_add_f32_e32 v133, 1.0, v133
	v_exp_f32_e32 v117, v117
	v_rcp_f32_e32 v133, v133
	v_mul_f32_e32 v116, 0x3d122279, v118
	v_mov_b32_e32 v134, v130
	v_add_f32_e32 v117, 1.0, v117
	v_pk_fma_f32 v[114:115], v[114:115], v[132:133], v[114:115] neg_lo:[1,0,0] neg_hi:[1,0,0]
	v_rcp_f32_e32 v132, v117
	v_mul_f32_e32 v117, 0x3d122279, v119
	v_fmaak_f32 v117, v119, v117, 0x3f4c422a
	v_mul_f32_e32 v130, 0x3d122279, v131
	v_fmaak_f32 v116, v118, v116, 0x3f4c422a
	v_mul_f32_e32 v117, v119, v117
	v_fmaak_f32 v130, v131, v130, 0x3f4c422a
	v_mul_f32_e32 v116, v118, v116
	v_mul_f32_e32 v117, 0x4038aa3b, v117
	v_mul_f32_e32 v130, v131, v130
	v_mul_f32_e32 v116, 0x4038aa3b, v116
	v_exp_f32_e32 v117, v117
	v_mul_f32_e32 v130, 0x4038aa3b, v130
	v_exp_f32_e32 v116, v116
	v_exp_f32_e32 v130, v130
	v_add_f32_e32 v117, 1.0, v117
	v_rcp_f32_e32 v117, v117
	v_add_f32_e32 v116, 1.0, v116
	v_add_f32_e32 v130, 1.0, v130
	v_rcp_f32_e32 v116, v116
	v_rcp_f32_e32 v130, v130
	v_mov_b32_e32 v135, v119
	v_mov_b32_e32 v133, v117
	v_pk_fma_f32 v[116:117], v[118:119], v[116:117], v[118:119] neg_lo:[1,0,0] neg_hi:[1,0,0]
	v_pk_fma_f32 v[118:119], v[134:135], v[132:133], v[134:135] neg_lo:[1,0,0] neg_hi:[1,0,0]
	v_fma_f32 v130, -v131, v130, v131
	v_cvt_pk_bf16_f32 v132, v112, v113
	v_cvt_pk_bf16_f32 v133, v116, v117
	v_cvt_pk_bf16_f32 v134, v114, v115
	v_cvt_pk_bf16_f32 v135, v118, v130
	global_store_dwordx4 v[128:129], v[132:135], off offset:256 sc1
	v_cndmask_b32_e64 v128, 0, 1, s[46:47]
	v_cmp_ne_u32_e64 s[42:43], 1, v128
	s_cbranch_vccnz .LBB0_194
; __device__ __forceinline__ unsigned cvt_pk_bf16(float lo, float hi) { unsigned r; asm volatile("v_cvt_pk_bf16_f32 %0, %1, %2" : "=v"(r) : "v"(lo), "v"(hi)); return r; }
;     __device__ __forceinline__ void operator()(const f32x4 (&acc)[2][2][4][2], const Unit& u, int wr, int wc, int fr, int fq) const {
;     ...
;                         for (int e = 0; e < 4; ++e) { v0[e] = gelu_tanh(v0[e]); v1[e] = gelu_tanh(v1[e]); s += v0[e] + v1[e]; q += v0[e] * v0[e] + v1[e] * v1[e]; } }
;                     u32x4 w; w.x = cvt_pk_bf16(v0[0], v0[1]); w.y = cvt_pk_bf16(v0[2], v0[3]); w.z = cvt_pk_bf16(v1[0], v1[1]); w.w = cvt_pk_bf16(v1[2], v1[3]);
;                     *(u32x4*)(rowp + bj * HALF) = w; }
;                 if (ACT == 2) { if (u.pn >= 8) { s += __shfl_xor(s, 16); s += __shfl_xor(s, 32); q += __shfl_xor(q, 16); q += __shfl_xor(q, 32);
;                     if (fq == 0) *(f32x2*)(stats + ((size_t)row * 32 + (u.pn - 8) * 4 + wc) * 2) = (f32x2){s, q}; } }
	v_pk_mul_f32 v[128:129], v[122:123], v[122:123]
	v_pk_mul_f32 v[132:133], v[126:127], v[126:127]
	v_pk_fma_f32 v[128:129], v[120:121], v[120:121], v[128:129]
	v_pk_fma_f32 v[132:133], v[124:125], v[124:125], v[132:133]
	v_add_f32_e32 v128, v128, v129
	v_pk_mul_f32 v[134:135], v[114:115], v[114:115]
	v_add_f32_e32 v128, v132, v128
	v_pk_fma_f32 v[134:135], v[112:113], v[112:113], v[134:135]
	v_add_f32_e32 v128, v133, v128
	v_add_f32_e32 v128, v134, v128
	v_pk_add_f32 v[128:129], v[134:135], v[128:129] op_sel_hi:[1,0]
	v_pk_add_f32 v[120:121], v[120:121], v[122:123]
	v_mov_b32_e32 v132, v116
	v_mov_b32_e32 v133, v118
	v_mul_f32_e32 v128, v116, v116
	v_pk_add_f32 v[134:135], v[116:117], v[118:119]
	v_pk_mul_f32 v[118:119], v[116:117], v[118:119]
	v_add_f32_e32 v116, 0, v120
	v_add_f32_e32 v116, v121, v116
	v_pk_add_f32 v[120:121], v[124:125], v[126:127]
	v_pk_add_f32 v[112:113], v[112:113], v[114:115]
	v_add_f32_e32 v116, v120, v116
	v_add_f32_e32 v116, v121, v116
	v_pk_fma_f32 v[132:133], v[132:133], v[132:133], v[128:129] op_sel_hi:[1,1,0]
	v_add_f32_e32 v112, v112, v116
	v_mov_b32_e32 v135, v119
	v_mul_f32_e32 v119, v130, v130
	v_add_f32_e32 v118, v113, v112
	v_mov_b32_e32 v132, v117
	v_mov_b32_e32 v131, v129
	v_pk_add_f32 v[112:113], v[134:135], v[118:119]
	v_pk_add_f32 v[114:115], v[132:133], v[130:131]
	s_nop 0
	v_pk_add_f32 v[112:113], v[112:113], v[114:115]
	ds_bpermute_b32 v114, v205, v112
	ds_bpermute_b32 v115, v205, v113
	s_waitcnt lgkmcnt(0)
	v_pk_add_f32 v[112:113], v[112:113], v[114:115]
	ds_bpermute_b32 v114, v206, v112
	ds_bpermute_b32 v115, v206, v113
	s_and_saveexec_b64 s[44:45], s[38:39]
	s_cbranch_execz .LBB0_193
	v_lshlrev_b64 v[116:117], 8, v[194:195]
	s_waitcnt lgkmcnt(0)
	v_pk_add_f32 v[112:113], v[112:113], v[114:115]
	v_lshl_add_u64 v[114:115], s[6:7], 0, v[116:117]
	v_lshl_add_u64 v[114:115], s[36:37], 3, v[114:115]
	global_store_dwordx2 v[114:115], v[112:113], off

; __device__ __forceinline__ unsigned cvt_pk_bf16(float lo, float hi) { unsigned r; asm volatile("v_cvt_pk_bf16_f32 %0, %1, %2" : "=v"(r) : "v"(lo), "v"(hi)); return r; }
;     __device__ __forceinline__ void operator()(const f32x4 (&acc)[2][2][4][2], const Unit& u, int wr, int wc, int fr, int fq) const {
;     ...
;             for (int m = 0; m < 4; ++m) { const int row = row0 + ai * HALF + m * 16; bf16_t* rowp = O + (size_t)row * ldc + col0; float s = 0.f, q = 0.f;
;                 const float rstd = rsv[ai][m];
; #pragma unroll
;                 for (int bj = 0; bj < 2; ++bj) { f32x4 v0 = acc[ai][bj][m][0] * rstd + bv[bj][0], v1 = acc[ai][bj][m][1] * rstd + bv[bj][1];
;                     if (ACT == 1) {
; #pragma unroll
;                         for (int e = 0; e < 4; ++e) { const float a = fmaxf(v0[e], 0.f), b2 = fmaxf(v1[e], 0.f); v0[e] = a * a; v1[e] = b2 * b2; } }
;                     if (ACT == 2) {
; #pragma unroll
;                         for (int e = 0; e < 4; ++e) { v0[e] = gelu_tanh(v0[e]); v1[e] = gelu_tanh(v1[e]); s += v0[e] + v1[e]; q += v0[e] * v0[e] + v1[e] * v1[e]; } }
;                     u32x4 w; w.x = cvt_pk_bf16(v0[0], v0[1]); w.y = cvt_pk_bf16(v0[2], v0[3]); w.z = cvt_pk_bf16(v1[0], v1[1]); w.w = cvt_pk_bf16(v1[2], v1[3]);
;                     *(u32x4*)(rowp + bj * HALF) = w; }
.LBB0_194:
	v_pk_add_f32 v[112:113], v[160:161], v[162:163]
	s_mov_b32 s16, 0x3a800000
	v_pk_fma_f32 v[112:113], v[112:113], s[16:17], v[214:215] op_sel_hi:[1,0,0]
	s_waitcnt lgkmcnt(1)
	v_mul_f32_e32 v114, 0x4b800000, v113
	v_cmp_gt_f32_e32 vcc, s27, v113
	v_cmp_gt_f32_e64 s[44:45], s27, v112
	s_nop 0
	v_cndmask_b32_e32 v113, v113, v114, vcc
	v_rsq_f32_e32 v113, v113
	s_nop 0
	v_mul_f32_e32 v114, 0x45800000, v113
	v_cndmask_b32_e32 v120, v113, v114, vcc
	v_pk_fma_f32 v[116:117], v[106:107], v[120:121], v[42:43] op_sel_hi:[1,0,1]
	v_pk_fma_f32 v[106:107], v[104:105], v[120:121], v[40:41] op_sel_hi:[1,0,1]
	v_pk_fma_f32 v[108:109], v[108:109], v[120:121], v[44:45] op_sel_hi:[1,0,1]
	v_mul_f32_e32 v105, 0x3d122279, v106
	v_fmaak_f32 v105, v106, v105, 0x3f4c422a
	v_mul_f32_e32 v105, v106, v105
	v_mul_f32_e32 v105, 0x4038aa3b, v105
	v_exp_f32_e32 v105, v105
	v_mul_f32_e32 v104, 0x3d122279, v108
	v_fmaak_f32 v104, v108, v104, 0x3f4c422a
	v_mul_f32_e32 v104, v108, v104
	v_add_f32_e32 v105, 1.0, v105
	v_rcp_f32_e32 v118, v105
	v_mul_f32_e32 v105, 0x3d122279, v109
	v_fmaak_f32 v105, v109, v105, 0x3f4c422a
	v_mul_f32_e32 v105, v109, v105
	v_mul_f32_e32 v104, 0x4038aa3b, v104
	v_mul_f32_e32 v105, 0x4038aa3b, v105
	v_exp_f32_e32 v104, v104
	v_exp_f32_e32 v105, v105
	v_mul_f32_e32 v113, 0x3d122279, v107
	v_fmaak_f32 v113, v107, v113, 0x3f4c422a
	v_add_f32_e32 v104, 1.0, v104
	v_add_f32_e32 v105, 1.0, v105
	v_rcp_f32_e32 v104, v104
	v_rcp_f32_e32 v105, v105
	v_mul_f32_e32 v113, v107, v113
	v_mul_f32_e32 v113, 0x4038aa3b, v113
	v_exp_f32_e32 v113, v113
	v_pk_fma_f32 v[104:105], v[108:109], v[104:105], v[108:109] neg_lo:[1,0,0] neg_hi:[1,0,0]
	v_mul_f32_e32 v109, 0x3d122279, v116
	v_fmaak_f32 v109, v116, v109, 0x3f4c422a
	v_mul_f32_e32 v109, v116, v109
	v_mul_f32_e32 v109, 0x4038aa3b, v109
	v_add_f32_e32 v113, 1.0, v113
	v_exp_f32_e32 v109, v109
	v_rcp_f32_e32 v119, v113
	v_pk_fma_f32 v[110:111], v[110:111], v[120:121], v[46:47] op_sel_hi:[1,0,1]
	v_mul_f32_e32 v113, 0x3d122279, v117
	v_add_f32_e32 v109, 1.0, v109
	v_pk_fma_f32 v[106:107], v[106:107], v[118:119], v[106:107] neg_lo:[1,0,0] neg_hi:[1,0,0]
	v_mul_f32_e32 v108, 0x3d122279, v110
	v_rcp_f32_e32 v118, v109
	v_mul_f32_e32 v109, 0x3d122279, v111
	v_fmaak_f32 v108, v110, v108, 0x3f4c422a
	v_fmaak_f32 v109, v111, v109, 0x3f4c422a
	v_fmaak_f32 v113, v117, v113, 0x3f4c422a
	v_mul_f32_e32 v108, v110, v108
	v_mul_f32_e32 v109, v111, v109
	v_mul_f32_e32 v113, v117, v113
	v_mul_f32_e32 v108, 0x4038aa3b, v108
	v_mul_f32_e32 v109, 0x4038aa3b, v109
	v_mul_f32_e32 v113, 0x4038aa3b, v113
	v_exp_f32_e32 v108, v108
	v_exp_f32_e32 v109, v109
	v_exp_f32_e32 v113, v113
	s_waitcnt lgkmcnt(0)
	v_lshlrev_b64 v[114:115], 13, v[192:193]
	v_add_f32_e32 v108, 1.0, v108
	v_add_f32_e32 v109, 1.0, v109
	v_add_f32_e32 v113, 1.0, v113
	v_rcp_f32_e32 v108, v108
	v_rcp_f32_e32 v109, v109
	v_rcp_f32_e32 v119, v113
	v_lshl_add_u64 v[114:115], s[2:3], 0, v[114:115]
	v_lshl_add_u64 v[114:115], v[182:183], 1, v[114:115]
	v_pk_fma_f32 v[108:109], v[110:111], v[108:109], v[110:111] neg_lo:[1,0,0] neg_hi:[1,0,0]
	v_pk_fma_f32 v[110:111], v[116:117], v[118:119], v[116:117] neg_lo:[1,0,0] neg_hi:[1,0,0]
	v_cvt_pk_bf16_f32 v116, v104, v105
	v_cvt_pk_bf16_f32 v117, v108, v109
	v_cvt_pk_bf16_f32 v118, v106, v107
	v_pk_fma_f32 v[100:101], v[100:101], v[120:121], v[36:37] op_sel_hi:[1,0,1]
	v_cvt_pk_bf16_f32 v119, v110, v111
	global_store_dwordx4 v[114:115], v[116:119], off sc1
	v_pk_fma_f32 v[102:103], v[102:103], v[120:121], v[38:39] op_sel_hi:[1,0,1]
	s_and_b64 vcc, exec, s[42:43]
	v_pk_fma_f32 v[116:117], v[98:99], v[120:121], v[34:35] op_sel_hi:[1,0,1]
	v_pk_fma_f32 v[98:99], v[96:97], v[120:121], v[32:33] op_sel_hi:[1,0,1]
	v_mul_f32_e32 v96, 0x3d122279, v100
	v_mul_f32_e32 v97, 0x3d122279, v98
	v_fmaak_f32 v97, v98, v97, 0x3f4c422a
	v_mul_f32_e32 v97, v98, v97
	v_mul_f32_e32 v97, 0x4038aa3b, v97
	v_exp_f32_e32 v97, v97
	v_fmaak_f32 v96, v100, v96, 0x3f4c422a
	v_mul_f32_e32 v96, v100, v96
	v_mul_f32_e32 v96, 0x4038aa3b, v96
	v_add_f32_e32 v97, 1.0, v97
	v_rcp_f32_e32 v118, v97
	v_mul_f32_e32 v97, 0x3d122279, v101
	v_fmaak_f32 v97, v101, v97, 0x3f4c422a
	v_mul_f32_e32 v97, v101, v97
	v_mul_f32_e32 v97, 0x4038aa3b, v97
	v_exp_f32_e32 v96, v96
	v_exp_f32_e32 v97, v97
	v_mul_f32_e32 v113, 0x3d122279, v99
	v_fmaak_f32 v113, v99, v113, 0x3f4c422a
	v_add_f32_e32 v96, 1.0, v96
	v_add_f32_e32 v97, 1.0, v97
	v_rcp_f32_e32 v96, v96
	v_rcp_f32_e32 v97, v97
	v_mul_f32_e32 v113, v99, v113
	v_mul_f32_e32 v113, 0x4038aa3b, v113
	v_exp_f32_e32 v113, v113
	v_pk_fma_f32 v[96:97], v[100:101], v[96:97], v[100:101] neg_lo:[1,0,0] neg_hi:[1,0,0]
	v_mul_f32_e32 v101, 0x3d122279, v116
	v_fmaak_f32 v101, v116, v101, 0x3f4c422a
	v_mul_f32_e32 v101, v116, v101
	v_mul_f32_e32 v101, 0x4038aa3b, v101
	v_add_f32_e32 v113, 1.0, v113
	v_exp_f32_e32 v101, v101
	v_rcp_f32_e32 v119, v113
	v_mul_f32_e32 v100, 0x3d122279, v102
	v_mul_f32_e32 v113, 0x3d122279, v117
	v_add_f32_e32 v101, 1.0, v101
	v_pk_fma_f32 v[98:99], v[98:99], v[118:119], v[98:99] neg_lo:[1,0,0] neg_hi:[1,0,0]
	v_rcp_f32_e32 v118, v101
	v_mul_f32_e32 v101, 0x3d122279, v103
	v_fmaak_f32 v101, v103, v101, 0x3f4c422a
	v_fmaak_f32 v100, v102, v100, 0x3f4c422a
	v_mul_f32_e32 v101, v103, v101
	v_fmaak_f32 v113, v117, v113, 0x3f4c422a
	v_mul_f32_e32 v100, v102, v100
	v_mul_f32_e32 v101, 0x4038aa3b, v101
	v_mul_f32_e32 v113, v117, v113
	v_mul_f32_e32 v100, 0x4038aa3b, v100
	v_exp_f32_e32 v101, v101
	v_mul_f32_e32 v113, 0x4038aa3b, v113
	v_exp_f32_e32 v100, v100
	v_exp_f32_e32 v113, v113
	v_add_f32_e32 v101, 1.0, v101
	v_rcp_f32_e32 v101, v101
	v_add_f32_e32 v100, 1.0, v100
	v_add_f32_e32 v113, 1.0, v113
	v_rcp_f32_e32 v100, v100
	v_rcp_f32_e32 v113, v113
	v_mov_b32_e32 v120, v116
	v_mov_b32_e32 v121, v103
	v_mov_b32_e32 v119, v101
	v_pk_fma_f32 v[100:101], v[102:103], v[100:101], v[102:103] neg_lo:[1,0,0] neg_hi:[1,0,0]
	v_pk_fma_f32 v[102:103], v[120:121], v[118:119], v[120:121] neg_lo:[1,0,0] neg_hi:[1,0,0]
	v_fma_f32 v116, -v117, v113, v117
	v_cvt_pk_bf16_f32 v118, v96, v97
	v_cvt_pk_bf16_f32 v119, v100, v101
	v_cvt_pk_bf16_f32 v120, v98, v99
	v_cvt_pk_bf16_f32 v121, v102, v116
	global_store_dwordx4 v[114:115], v[118:121], off offset:256 sc1
	s_cbranch_vccnz .LBB0_198
; __device__ __forceinline__ unsigned cvt_pk_bf16(float lo, float hi) { unsigned r; asm volatile("v_cvt_pk_bf16_f32 %0, %1, %2" : "=v"(r) : "v"(lo), "v"(hi)); return r; }
;     __device__ __forceinline__ void operator()(const f32x4 (&acc)[2][2][4][2], const Unit& u, int wr, int wc, int fr, int fq) const {
;     ...
;                         for (int e = 0; e < 4; ++e) { v0[e] = gelu_tanh(v0[e]); v1[e] = gelu_tanh(v1[e]); s += v0[e] + v1[e]; q += v0[e] * v0[e] + v1[e] * v1[e]; } }
;                     u32x4 w; w.x = cvt_pk_bf16(v0[0], v0[1]); w.y = cvt_pk_bf16(v0[2], v0[3]); w.z = cvt_pk_bf16(v1[0], v1[1]); w.w = cvt_pk_bf16(v1[2], v1[3]);
;                     *(u32x4*)(rowp + bj * HALF) = w; }
;                 if (ACT == 2) { if (u.pn >= 8) { s += __shfl_xor(s, 16); s += __shfl_xor(s, 32); q += __shfl_xor(q, 16); q += __shfl_xor(q, 32);
;                     if (fq == 0) *(f32x2*)(stats + ((size_t)row * 32 + (u.pn - 8) * 4 + wc) * 2) = (f32x2){s, q}; } }
	v_pk_mul_f32 v[114:115], v[106:107], v[106:107]
	v_pk_mul_f32 v[118:119], v[110:111], v[110:111]
	v_pk_fma_f32 v[114:115], v[104:105], v[104:105], v[114:115]
	v_pk_fma_f32 v[118:119], v[108:109], v[108:109], v[118:119]
	v_add_f32_e32 v113, v114, v115
	v_pk_mul_f32 v[120:121], v[98:99], v[98:99]
	v_add_f32_e32 v113, v118, v113
	v_pk_fma_f32 v[120:121], v[96:97], v[96:97], v[120:121]
	v_add_f32_e32 v113, v119, v113
	v_add_f32_e32 v114, v120, v113
	v_pk_add_f32 v[114:115], v[120:121], v[114:115] op_sel_hi:[1,0]
	v_pk_add_f32 v[104:105], v[104:105], v[106:107]
	v_mov_b32_e32 v118, v100
	v_mov_b32_e32 v119, v102
	v_mul_f32_e32 v114, v100, v100
	v_pk_add_f32 v[120:121], v[100:101], v[102:103]
	v_pk_mul_f32 v[102:103], v[100:101], v[102:103]
	v_add_f32_e32 v100, 0, v104
	v_add_f32_e32 v100, v105, v100
	v_pk_add_f32 v[104:105], v[108:109], v[110:111]
	v_pk_add_f32 v[96:97], v[96:97], v[98:99]
	v_add_f32_e32 v100, v104, v100
	v_add_f32_e32 v100, v105, v100
	v_pk_fma_f32 v[118:119], v[118:119], v[118:119], v[114:115] op_sel_hi:[1,1,0]
	v_add_f32_e32 v96, v96, v100
	v_mov_b32_e32 v121, v103
	v_mul_f32_e32 v103, v116, v116
	v_add_f32_e32 v102, v97, v96
	v_mov_b32_e32 v118, v101
	v_mov_b32_e32 v117, v115
	v_pk_add_f32 v[96:97], v[120:121], v[102:103]
	v_pk_add_f32 v[98:99], v[118:119], v[116:117]
	s_nop 0
	v_pk_add_f32 v[96:97], v[96:97], v[98:99]
	ds_bpermute_b32 v98, v205, v96
	ds_bpermute_b32 v99, v205, v97
	s_waitcnt lgkmcnt(0)
	v_pk_add_f32 v[96:97], v[96:97], v[98:99]
	ds_bpermute_b32 v98, v206, v96
	ds_bpermute_b32 v99, v206, v97
	s_and_saveexec_b64 s[46:47], s[38:39]
	s_cbranch_execz .LBB0_197
	v_lshlrev_b64 v[100:101], 8, v[192:193]
	s_waitcnt lgkmcnt(0)
	v_pk_add_f32 v[96:97], v[96:97], v[98:99]
	v_lshl_add_u64 v[98:99], s[6:7], 0, v[100:101]
	v_lshl_add_u64 v[98:99], s[36:37], 3, v[98:99]
	global_store_dwordx2 v[98:99], v[96:97], off

; __device__ __forceinline__ unsigned cvt_pk_bf16(float lo, float hi) { unsigned r; asm volatile("v_cvt_pk_bf16_f32 %0, %1, %2" : "=v"(r) : "v"(lo), "v"(hi)); return r; }
;     __device__ __forceinline__ void operator()(const f32x4 (&acc)[2][2][4][2], const Unit& u, int wr, int wc, int fr, int fq) const {
;     ...
;             for (int m = 0; m < 4; ++m) { const int row = row0 + ai * HALF + m * 16; bf16_t* rowp = O + (size_t)row * ldc + col0; float s = 0.f, q = 0.f;
;                 const float rstd = rsv[ai][m];
; #pragma unroll
;                 for (int bj = 0; bj < 2; ++bj) { f32x4 v0 = acc[ai][bj][m][0] * rstd + bv[bj][0], v1 = acc[ai][bj][m][1] * rstd + bv[bj][1];
;                     if (ACT == 1) {
; #pragma unroll
;                         for (int e = 0; e < 4; ++e) { const float a = fmaxf(v0[e], 0.f), b2 = fmaxf(v1[e], 0.f); v0[e] = a * a; v1[e] = b2 * b2; } }
;                     if (ACT == 2) {
; #pragma unroll
;                         for (int e = 0; e < 4; ++e) { v0[e] = gelu_tanh(v0[e]); v1[e] = gelu_tanh(v1[e]); s += v0[e] + v1[e]; q += v0[e] * v0[e] + v1[e] * v1[e]; } }
;                     u32x4 w; w.x = cvt_pk_bf16(v0[0], v0[1]); w.y = cvt_pk_bf16(v0[2], v0[3]); w.z = cvt_pk_bf16(v1[0], v1[1]); w.w = cvt_pk_bf16(v1[2], v1[3]);
;                     *(u32x4*)(rowp + bj * HALF) = w; }
.LBB0_198:
	v_mul_f32_e32 v96, 0x4b800000, v112
	v_cndmask_b32_e64 v96, v112, v96, s[44:45]
	v_rsq_f32_e32 v96, v96
	s_and_b64 vcc, exec, s[42:43]
	v_mul_f32_e32 v97, 0x45800000, v96
	v_cndmask_b32_e64 v102, v96, v97, s[44:45]
	s_waitcnt lgkmcnt(0)
	v_pk_fma_f32 v[98:99], v[90:91], v[102:103], v[42:43] op_sel_hi:[1,0,1]
	v_pk_fma_f32 v[90:91], v[88:89], v[102:103], v[40:41] op_sel_hi:[1,0,1]
	v_pk_fma_f32 v[92:93], v[92:93], v[102:103], v[44:45] op_sel_hi:[1,0,1]
	v_mul_f32_e32 v89, 0x3d122279, v90
	v_fmaak_f32 v89, v90, v89, 0x3f4c422a
	v_mul_f32_e32 v89, v90, v89
	v_mul_f32_e32 v89, 0x4038aa3b, v89
	v_exp_f32_e32 v89, v89
	v_mul_f32_e32 v88, 0x3d122279, v92
	v_fmaak_f32 v88, v92, v88, 0x3f4c422a
	v_mul_f32_e32 v88, v92, v88
	v_add_f32_e32 v89, 1.0, v89
	v_rcp_f32_e32 v100, v89
	v_mul_f32_e32 v89, 0x3d122279, v93
	v_fmaak_f32 v89, v93, v89, 0x3f4c422a
	v_mul_f32_e32 v89, v93, v89
	v_mul_f32_e32 v88, 0x4038aa3b, v88
	v_mul_f32_e32 v89, 0x4038aa3b, v89
	v_exp_f32_e32 v88, v88
	v_exp_f32_e32 v89, v89
	v_mul_f32_e32 v101, 0x3d122279, v91
	v_fmaak_f32 v101, v91, v101, 0x3f4c422a
	v_add_f32_e32 v88, 1.0, v88
	v_add_f32_e32 v89, 1.0, v89
	v_rcp_f32_e32 v88, v88
	v_rcp_f32_e32 v89, v89
	v_mul_f32_e32 v101, v91, v101
	v_mul_f32_e32 v101, 0x4038aa3b, v101
	v_exp_f32_e32 v101, v101
	v_pk_fma_f32 v[88:89], v[92:93], v[88:89], v[92:93] neg_lo:[1,0,0] neg_hi:[1,0,0]
	v_mul_f32_e32 v93, 0x3d122279, v98
	v_fmaak_f32 v93, v98, v93, 0x3f4c422a
	v_mul_f32_e32 v93, v98, v93
	v_mul_f32_e32 v93, 0x4038aa3b, v93
	v_add_f32_e32 v101, 1.0, v101
	v_exp_f32_e32 v93, v93
	v_rcp_f32_e32 v101, v101
	v_pk_fma_f32 v[94:95], v[94:95], v[102:103], v[46:47] op_sel_hi:[1,0,1]
	v_lshlrev_b64 v[96:97], 13, v[190:191]
	v_add_f32_e32 v93, 1.0, v93
	v_pk_fma_f32 v[90:91], v[90:91], v[100:101], v[90:91] neg_lo:[1,0,0] neg_hi:[1,0,0]
	v_mul_f32_e32 v92, 0x3d122279, v94
	v_rcp_f32_e32 v100, v93
	v_mul_f32_e32 v93, 0x3d122279, v95
	v_mul_f32_e32 v101, 0x3d122279, v99
	v_fmaak_f32 v92, v94, v92, 0x3f4c422a
	v_fmaak_f32 v93, v95, v93, 0x3f4c422a
	v_fmaak_f32 v101, v99, v101, 0x3f4c422a
	v_mul_f32_e32 v92, v94, v92
	v_mul_f32_e32 v93, v95, v93
	v_mul_f32_e32 v101, v99, v101
	v_mul_f32_e32 v92, 0x4038aa3b, v92
	v_mul_f32_e32 v93, 0x4038aa3b, v93
	v_mul_f32_e32 v101, 0x4038aa3b, v101
	v_exp_f32_e32 v92, v92
	v_exp_f32_e32 v93, v93
	v_exp_f32_e32 v101, v101
	v_lshl_add_u64 v[96:97], s[2:3], 0, v[96:97]
	v_add_f32_e32 v92, 1.0, v92
	v_add_f32_e32 v93, 1.0, v93
	v_add_f32_e32 v101, 1.0, v101
	v_rcp_f32_e32 v92, v92
	v_rcp_f32_e32 v93, v93
	v_rcp_f32_e32 v101, v101
	v_lshl_add_u64 v[96:97], v[182:183], 1, v[96:97]
	v_pk_fma_f32 v[84:85], v[84:85], v[102:103], v[36:37] op_sel_hi:[1,0,1]
	v_pk_fma_f32 v[92:93], v[94:95], v[92:93], v[94:95] neg_lo:[1,0,0] neg_hi:[1,0,0]
	v_pk_fma_f32 v[94:95], v[98:99], v[100:101], v[98:99] neg_lo:[1,0,0] neg_hi:[1,0,0]
	v_cvt_pk_bf16_f32 v98, v88, v89
	v_cvt_pk_bf16_f32 v99, v92, v93
	v_cvt_pk_bf16_f32 v100, v90, v91
	v_pk_fma_f32 v[86:87], v[86:87], v[102:103], v[38:39] op_sel_hi:[1,0,1]
	v_cvt_pk_bf16_f32 v101, v94, v95
	global_store_dwordx4 v[96:97], v[98:101], off sc1
	s_nop 1
	v_pk_fma_f32 v[98:99], v[82:83], v[102:103], v[34:35] op_sel_hi:[1,0,1]
	v_pk_fma_f32 v[82:83], v[80:81], v[102:103], v[32:33] op_sel_hi:[1,0,1]
	v_mul_f32_e32 v80, 0x3d122279, v84
	v_mul_f32_e32 v81, 0x3d122279, v82
	v_fmaak_f32 v81, v82, v81, 0x3f4c422a
	v_mul_f32_e32 v81, v82, v81
	v_mul_f32_e32 v81, 0x4038aa3b, v81
	v_exp_f32_e32 v81, v81
	v_fmaak_f32 v80, v84, v80, 0x3f4c422a
	v_mul_f32_e32 v80, v84, v80
	v_mul_f32_e32 v80, 0x4038aa3b, v80
	v_add_f32_e32 v81, 1.0, v81
	v_rcp_f32_e32 v100, v81
	v_mul_f32_e32 v81, 0x3d122279, v85
	v_fmaak_f32 v81, v85, v81, 0x3f4c422a
	v_mul_f32_e32 v81, v85, v81
	v_mul_f32_e32 v81, 0x4038aa3b, v81
	v_exp_f32_e32 v80, v80
	v_exp_f32_e32 v81, v81
	v_mul_f32_e32 v101, 0x3d122279, v83
	v_fmaak_f32 v101, v83, v101, 0x3f4c422a
	v_add_f32_e32 v80, 1.0, v80
	v_add_f32_e32 v81, 1.0, v81
	v_rcp_f32_e32 v80, v80
	v_rcp_f32_e32 v81, v81
	v_mul_f32_e32 v101, v83, v101
	v_mul_f32_e32 v101, 0x4038aa3b, v101
	v_exp_f32_e32 v101, v101
	v_pk_fma_f32 v[80:81], v[84:85], v[80:81], v[84:85] neg_lo:[1,0,0] neg_hi:[1,0,0]
	v_mul_f32_e32 v85, 0x3d122279, v98
	v_fmaak_f32 v85, v98, v85, 0x3f4c422a
	v_mul_f32_e32 v85, v98, v85
	v_mul_f32_e32 v85, 0x4038aa3b, v85
	v_add_f32_e32 v101, 1.0, v101
	v_exp_f32_e32 v85, v85
	v_rcp_f32_e32 v101, v101
	v_mul_f32_e32 v84, 0x3d122279, v86
	v_mov_b32_e32 v102, v98
	v_add_f32_e32 v85, 1.0, v85
	v_pk_fma_f32 v[82:83], v[82:83], v[100:101], v[82:83] neg_lo:[1,0,0] neg_hi:[1,0,0]
	v_rcp_f32_e32 v100, v85
	v_mul_f32_e32 v85, 0x3d122279, v87
	v_fmaak_f32 v85, v87, v85, 0x3f4c422a
	v_mul_f32_e32 v98, 0x3d122279, v99
	v_fmaak_f32 v84, v86, v84, 0x3f4c422a
	v_mul_f32_e32 v85, v87, v85
	v_fmaak_f32 v98, v99, v98, 0x3f4c422a
	v_mul_f32_e32 v84, v86, v84
	v_mul_f32_e32 v85, 0x4038aa3b, v85
	v_mul_f32_e32 v98, v99, v98
	v_mul_f32_e32 v84, 0x4038aa3b, v84
	v_exp_f32_e32 v85, v85
	v_mul_f32_e32 v98, 0x4038aa3b, v98
	v_exp_f32_e32 v84, v84
	v_exp_f32_e32 v98, v98
	v_add_f32_e32 v85, 1.0, v85
	v_rcp_f32_e32 v85, v85
	v_add_f32_e32 v84, 1.0, v84
	v_add_f32_e32 v98, 1.0, v98
	v_rcp_f32_e32 v84, v84
	v_rcp_f32_e32 v98, v98
	v_mov_b32_e32 v103, v87
	v_mov_b32_e32 v101, v85
	v_pk_fma_f32 v[84:85], v[86:87], v[84:85], v[86:87] neg_lo:[1,0,0] neg_hi:[1,0,0]
	v_pk_fma_f32 v[86:87], v[102:103], v[100:101], v[102:103] neg_lo:[1,0,0] neg_hi:[1,0,0]
	v_fma_f32 v98, -v99, v98, v99
	v_cvt_pk_bf16_f32 v100, v80, v81
	v_cvt_pk_bf16_f32 v101, v84, v85
	v_cvt_pk_bf16_f32 v102, v82, v83
	v_cvt_pk_bf16_f32 v103, v86, v98
	global_store_dwordx4 v[96:97], v[100:103], off offset:256 sc1
	s_cbranch_vccnz .LBB0_202
; __device__ __forceinline__ unsigned cvt_pk_bf16(float lo, float hi) { unsigned r; asm volatile("v_cvt_pk_bf16_f32 %0, %1, %2" : "=v"(r) : "v"(lo), "v"(hi)); return r; }
;     __device__ __forceinline__ void operator()(const f32x4 (&acc)[2][2][4][2], const Unit& u, int wr, int wc, int fr, int fq) const {
;     ...
;                         for (int e = 0; e < 4; ++e) { v0[e] = gelu_tanh(v0[e]); v1[e] = gelu_tanh(v1[e]); s += v0[e] + v1[e]; q += v0[e] * v0[e] + v1[e] * v1[e]; } }
;                     u32x4 w; w.x = cvt_pk_bf16(v0[0], v0[1]); w.y = cvt_pk_bf16(v0[2], v0[3]); w.z = cvt_pk_bf16(v1[0], v1[1]); w.w = cvt_pk_bf16(v1[2], v1[3]);
;                     *(u32x4*)(rowp + bj * HALF) = w; }
;                 if (ACT == 2) { if (u.pn >= 8) { s += __shfl_xor(s, 16); s += __shfl_xor(s, 32); q += __shfl_xor(q, 16); q += __shfl_xor(q, 32);
;                     if (fq == 0) *(f32x2*)(stats + ((size_t)row * 32 + (u.pn - 8) * 4 + wc) * 2) = (f32x2){s, q}; } }
	v_pk_mul_f32 v[96:97], v[90:91], v[90:91]
	v_pk_mul_f32 v[100:101], v[94:95], v[94:95]
	v_pk_fma_f32 v[96:97], v[88:89], v[88:89], v[96:97]
	v_pk_fma_f32 v[100:101], v[92:93], v[92:93], v[100:101]
	v_add_f32_e32 v96, v96, v97
	v_pk_mul_f32 v[102:103], v[82:83], v[82:83]
	v_add_f32_e32 v96, v100, v96
	v_pk_fma_f32 v[102:103], v[80:81], v[80:81], v[102:103]
	v_add_f32_e32 v96, v101, v96
	v_add_f32_e32 v96, v102, v96
	v_pk_add_f32 v[96:97], v[102:103], v[96:97] op_sel_hi:[1,0]
	v_pk_add_f32 v[88:89], v[88:89], v[90:91]
	v_mov_b32_e32 v100, v84
	v_mov_b32_e32 v101, v86
	v_mul_f32_e32 v96, v84, v84
	v_pk_add_f32 v[102:103], v[84:85], v[86:87]
	v_pk_mul_f32 v[86:87], v[84:85], v[86:87]
	v_add_f32_e32 v84, 0, v88
	v_add_f32_e32 v84, v89, v84
	v_pk_add_f32 v[88:89], v[92:93], v[94:95]
	v_pk_add_f32 v[80:81], v[80:81], v[82:83]
	v_add_f32_e32 v84, v88, v84
	v_add_f32_e32 v84, v89, v84
	v_pk_fma_f32 v[100:101], v[100:101], v[100:101], v[96:97] op_sel_hi:[1,1,0]
	v_add_f32_e32 v80, v80, v84
	v_mov_b32_e32 v103, v87
	v_mul_f32_e32 v87, v98, v98
	v_add_f32_e32 v86, v81, v80
	v_mov_b32_e32 v100, v85
	v_mov_b32_e32 v99, v97
	v_pk_add_f32 v[80:81], v[102:103], v[86:87]
	v_pk_add_f32 v[82:83], v[100:101], v[98:99]
	s_nop 0
	v_pk_add_f32 v[80:81], v[80:81], v[82:83]
	ds_bpermute_b32 v82, v205, v80
	ds_bpermute_b32 v83, v205, v81
	s_waitcnt lgkmcnt(0)
	v_pk_add_f32 v[80:81], v[80:81], v[82:83]
	ds_bpermute_b32 v82, v206, v80
	ds_bpermute_b32 v83, v206, v81
	s_and_saveexec_b64 s[44:45], s[38:39]
	s_cbranch_execz .LBB0_201
	v_lshlrev_b64 v[84:85], 8, v[190:191]
	s_waitcnt lgkmcnt(0)
	v_pk_add_f32 v[80:81], v[80:81], v[82:83]
	v_lshl_add_u64 v[82:83], s[6:7], 0, v[84:85]
	v_lshl_add_u64 v[82:83], s[36:37], 3, v[82:83]
	global_store_dwordx2 v[82:83], v[80:81], off

; __device__ __forceinline__ unsigned cvt_pk_bf16(float lo, float hi) { unsigned r; asm volatile("v_cvt_pk_bf16_f32 %0, %1, %2" : "=v"(r) : "v"(lo), "v"(hi)); return r; }
;     __device__ __forceinline__ void operator()(const f32x4 (&acc)[2][2][4][2], const Unit& u, int wr, int wc, int fr, int fq) const {
;     ...
;             for (int m = 0; m < 4; ++m) { const int row = row0 + ai * HALF + m * 16; bf16_t* rowp = O + (size_t)row * ldc + col0; float s = 0.f, q = 0.f;
;                 const float rstd = rsv[ai][m];
; #pragma unroll
;                 for (int bj = 0; bj < 2; ++bj) { f32x4 v0 = acc[ai][bj][m][0] * rstd + bv[bj][0], v1 = acc[ai][bj][m][1] * rstd + bv[bj][1];
;                     if (ACT == 1) {
; #pragma unroll
;                         for (int e = 0; e < 4; ++e) { const float a = fmaxf(v0[e], 0.f), b2 = fmaxf(v1[e], 0.f); v0[e] = a * a; v1[e] = b2 * b2; } }
;                     if (ACT == 2) {
; #pragma unroll
;                         for (int e = 0; e < 4; ++e) { v0[e] = gelu_tanh(v0[e]); v1[e] = gelu_tanh(v1[e]); s += v0[e] + v1[e]; q += v0[e] * v0[e] + v1[e] * v1[e]; } }
;                     u32x4 w; w.x = cvt_pk_bf16(v0[0], v0[1]); w.y = cvt_pk_bf16(v0[2], v0[3]); w.z = cvt_pk_bf16(v1[0], v1[1]); w.w = cvt_pk_bf16(v1[2], v1[3]);
;                     *(u32x4*)(rowp + bj * HALF) = w; }
.LBB0_202:
	v_pk_add_f32 v[80:81], v[152:153], v[154:155]
	s_nop 0
	v_pk_fma_f32 v[80:81], v[80:81], s[16:17], v[214:215] op_sel_hi:[1,0,0]
	s_waitcnt lgkmcnt(1)
	v_mul_f32_e32 v82, 0x4b800000, v81
	v_cmp_gt_f32_e32 vcc, s27, v81
	v_cmp_gt_f32_e64 s[44:45], s27, v80
	s_nop 0
	v_cndmask_b32_e32 v81, v81, v82, vcc
	v_rsq_f32_e32 v81, v81
	s_nop 0
	v_mul_f32_e32 v82, 0x45800000, v81
	v_cndmask_b32_e32 v88, v81, v82, vcc
	v_pk_fma_f32 v[84:85], v[74:75], v[88:89], v[42:43] op_sel_hi:[1,0,1]
	v_pk_fma_f32 v[74:75], v[72:73], v[88:89], v[40:41] op_sel_hi:[1,0,1]
	v_pk_fma_f32 v[76:77], v[76:77], v[88:89], v[44:45] op_sel_hi:[1,0,1]
	v_mul_f32_e32 v73, 0x3d122279, v74
	v_fmaak_f32 v73, v74, v73, 0x3f4c422a
	v_mul_f32_e32 v73, v74, v73
	v_mul_f32_e32 v73, 0x4038aa3b, v73
	v_exp_f32_e32 v73, v73
	v_mul_f32_e32 v72, 0x3d122279, v76
	v_fmaak_f32 v72, v76, v72, 0x3f4c422a
	v_mul_f32_e32 v72, v76, v72
	v_add_f32_e32 v73, 1.0, v73
	v_rcp_f32_e32 v86, v73
	v_mul_f32_e32 v73, 0x3d122279, v77
	v_fmaak_f32 v73, v77, v73, 0x3f4c422a
	v_mul_f32_e32 v73, v77, v73
	v_mul_f32_e32 v72, 0x4038aa3b, v72
	v_mul_f32_e32 v73, 0x4038aa3b, v73
	v_exp_f32_e32 v72, v72
	v_exp_f32_e32 v73, v73
	v_mul_f32_e32 v81, 0x3d122279, v75
	v_fmaak_f32 v81, v75, v81, 0x3f4c422a
	v_add_f32_e32 v72, 1.0, v72
	v_add_f32_e32 v73, 1.0, v73
	v_rcp_f32_e32 v72, v72
	v_rcp_f32_e32 v73, v73
	v_mul_f32_e32 v81, v75, v81
	v_mul_f32_e32 v81, 0x4038aa3b, v81
	v_exp_f32_e32 v81, v81
	v_pk_fma_f32 v[72:73], v[76:77], v[72:73], v[76:77] neg_lo:[1,0,0] neg_hi:[1,0,0]
	v_mul_f32_e32 v77, 0x3d122279, v84
	v_fmaak_f32 v77, v84, v77, 0x3f4c422a
	v_mul_f32_e32 v77, v84, v77
	v_mul_f32_e32 v77, 0x4038aa3b, v77
	v_add_f32_e32 v81, 1.0, v81
	v_exp_f32_e32 v77, v77
	v_rcp_f32_e32 v87, v81
	v_pk_fma_f32 v[78:79], v[78:79], v[88:89], v[46:47] op_sel_hi:[1,0,1]
	v_mul_f32_e32 v81, 0x3d122279, v85
	v_add_f32_e32 v77, 1.0, v77
	v_pk_fma_f32 v[74:75], v[74:75], v[86:87], v[74:75] neg_lo:[1,0,0] neg_hi:[1,0,0]
	v_mul_f32_e32 v76, 0x3d122279, v78
	v_rcp_f32_e32 v86, v77
	v_mul_f32_e32 v77, 0x3d122279, v79
	v_fmaak_f32 v76, v78, v76, 0x3f4c422a
	v_fmaak_f32 v77, v79, v77, 0x3f4c422a
	v_fmaak_f32 v81, v85, v81, 0x3f4c422a
	v_mul_f32_e32 v76, v78, v76
	v_mul_f32_e32 v77, v79, v77
	v_mul_f32_e32 v81, v85, v81
	v_mul_f32_e32 v76, 0x4038aa3b, v76
	v_mul_f32_e32 v77, 0x4038aa3b, v77
	v_mul_f32_e32 v81, 0x4038aa3b, v81
	v_exp_f32_e32 v76, v76
	v_exp_f32_e32 v77, v77
	v_exp_f32_e32 v81, v81
	s_waitcnt lgkmcnt(0)
	v_lshlrev_b64 v[82:83], 13, v[188:189]
	v_add_f32_e32 v76, 1.0, v76
	v_add_f32_e32 v77, 1.0, v77
	v_add_f32_e32 v81, 1.0, v81
	v_rcp_f32_e32 v76, v76
	v_rcp_f32_e32 v77, v77
	v_rcp_f32_e32 v87, v81
	v_lshl_add_u64 v[82:83], s[2:3], 0, v[82:83]
	v_lshl_add_u64 v[82:83], v[182:183], 1, v[82:83]
	v_pk_fma_f32 v[76:77], v[78:79], v[76:77], v[78:79] neg_lo:[1,0,0] neg_hi:[1,0,0]
	v_pk_fma_f32 v[78:79], v[84:85], v[86:87], v[84:85] neg_lo:[1,0,0] neg_hi:[1,0,0]
	v_cvt_pk_bf16_f32 v84, v72, v73
	v_cvt_pk_bf16_f32 v85, v76, v77
	v_cvt_pk_bf16_f32 v86, v74, v75
	v_pk_fma_f32 v[68:69], v[68:69], v[88:89], v[36:37] op_sel_hi:[1,0,1]
	v_cvt_pk_bf16_f32 v87, v78, v79
	global_store_dwordx4 v[82:83], v[84:87], off sc1
	v_pk_fma_f32 v[70:71], v[70:71], v[88:89], v[38:39] op_sel_hi:[1,0,1]
	s_and_b64 vcc, exec, s[42:43]
	v_pk_fma_f32 v[84:85], v[66:67], v[88:89], v[34:35] op_sel_hi:[1,0,1]
	v_pk_fma_f32 v[66:67], v[64:65], v[88:89], v[32:33] op_sel_hi:[1,0,1]
	v_mul_f32_e32 v64, 0x3d122279, v68
	v_mul_f32_e32 v65, 0x3d122279, v66
	v_fmaak_f32 v65, v66, v65, 0x3f4c422a
	v_mul_f32_e32 v65, v66, v65
	v_mul_f32_e32 v65, 0x4038aa3b, v65
	v_exp_f32_e32 v65, v65
	v_fmaak_f32 v64, v68, v64, 0x3f4c422a
	v_mul_f32_e32 v64, v68, v64
	v_mul_f32_e32 v64, 0x4038aa3b, v64
	v_add_f32_e32 v65, 1.0, v65
	v_rcp_f32_e32 v86, v65
	v_mul_f32_e32 v65, 0x3d122279, v69
	v_fmaak_f32 v65, v69, v65, 0x3f4c422a
	v_mul_f32_e32 v65, v69, v65
	v_mul_f32_e32 v65, 0x4038aa3b, v65
	v_exp_f32_e32 v64, v64
	v_exp_f32_e32 v65, v65
	v_mul_f32_e32 v81, 0x3d122279, v67
	v_fmaak_f32 v81, v67, v81, 0x3f4c422a
	v_add_f32_e32 v64, 1.0, v64
	v_add_f32_e32 v65, 1.0, v65
	v_rcp_f32_e32 v64, v64
	v_rcp_f32_e32 v65, v65
	v_mul_f32_e32 v81, v67, v81
	v_mul_f32_e32 v81, 0x4038aa3b, v81
	v_exp_f32_e32 v81, v81
	v_pk_fma_f32 v[64:65], v[68:69], v[64:65], v[68:69] neg_lo:[1,0,0] neg_hi:[1,0,0]
	v_mul_f32_e32 v69, 0x3d122279, v84
	v_fmaak_f32 v69, v84, v69, 0x3f4c422a
	v_mul_f32_e32 v69, v84, v69
	v_mul_f32_e32 v69, 0x4038aa3b, v69
	v_add_f32_e32 v81, 1.0, v81
	v_exp_f32_e32 v69, v69
	v_rcp_f32_e32 v87, v81
	v_mul_f32_e32 v68, 0x3d122279, v70
	v_mul_f32_e32 v81, 0x3d122279, v85
	v_add_f32_e32 v69, 1.0, v69
	v_pk_fma_f32 v[66:67], v[66:67], v[86:87], v[66:67] neg_lo:[1,0,0] neg_hi:[1,0,0]
	v_rcp_f32_e32 v86, v69
	v_mul_f32_e32 v69, 0x3d122279, v71
	v_fmaak_f32 v69, v71, v69, 0x3f4c422a
	v_fmaak_f32 v68, v70, v68, 0x3f4c422a
	v_mul_f32_e32 v69, v71, v69
	v_fmaak_f32 v81, v85, v81, 0x3f4c422a
	v_mul_f32_e32 v68, v70, v68
	v_mul_f32_e32 v69, 0x4038aa3b, v69
	v_mul_f32_e32 v81, v85, v81
	v_mul_f32_e32 v68, 0x4038aa3b, v68
	v_exp_f32_e32 v69, v69
	v_mul_f32_e32 v81, 0x4038aa3b, v81
	v_exp_f32_e32 v68, v68
	v_exp_f32_e32 v81, v81
	v_add_f32_e32 v69, 1.0, v69
	v_rcp_f32_e32 v69, v69
	v_add_f32_e32 v68, 1.0, v68
	v_add_f32_e32 v81, 1.0, v81
	v_rcp_f32_e32 v68, v68
	v_rcp_f32_e32 v81, v81
	v_mov_b32_e32 v88, v84
	v_mov_b32_e32 v89, v71
	v_mov_b32_e32 v87, v69
	v_pk_fma_f32 v[68:69], v[70:71], v[68:69], v[70:71] neg_lo:[1,0,0] neg_hi:[1,0,0]
	v_pk_fma_f32 v[70:71], v[88:89], v[86:87], v[88:89] neg_lo:[1,0,0] neg_hi:[1,0,0]
	v_fma_f32 v84, -v85, v81, v85
	v_cvt_pk_bf16_f32 v86, v64, v65
	v_cvt_pk_bf16_f32 v87, v68, v69
	v_cvt_pk_bf16_f32 v88, v66, v67
	v_cvt_pk_bf16_f32 v89, v70, v84
	global_store_dwordx4 v[82:83], v[86:89], off offset:256 sc1
	s_cbranch_vccnz .LBB0_206
; __device__ __forceinline__ unsigned cvt_pk_bf16(float lo, float hi) { unsigned r; asm volatile("v_cvt_pk_bf16_f32 %0, %1, %2" : "=v"(r) : "v"(lo), "v"(hi)); return r; }
;     __device__ __forceinline__ void operator()(const f32x4 (&acc)[2][2][4][2], const Unit& u, int wr, int wc, int fr, int fq) const {
;     ...
;                         for (int e = 0; e < 4; ++e) { v0[e] = gelu_tanh(v0[e]); v1[e] = gelu_tanh(v1[e]); s += v0[e] + v1[e]; q += v0[e] * v0[e] + v1[e] * v1[e]; } }
;                     u32x4 w; w.x = cvt_pk_bf16(v0[0], v0[1]); w.y = cvt_pk_bf16(v0[2], v0[3]); w.z = cvt_pk_bf16(v1[0], v1[1]); w.w = cvt_pk_bf16(v1[2], v1[3]);
;                     *(u32x4*)(rowp + bj * HALF) = w; }
;                 if (ACT == 2) { if (u.pn >= 8) { s += __shfl_xor(s, 16); s += __shfl_xor(s, 32); q += __shfl_xor(q, 16); q += __shfl_xor(q, 32);
;                     if (fq == 0) *(f32x2*)(stats + ((size_t)row * 32 + (u.pn - 8) * 4 + wc) * 2) = (f32x2){s, q}; } }
	v_pk_mul_f32 v[82:83], v[74:75], v[74:75]
	v_pk_mul_f32 v[86:87], v[78:79], v[78:79]
	v_pk_fma_f32 v[82:83], v[72:73], v[72:73], v[82:83]
	v_pk_fma_f32 v[86:87], v[76:77], v[76:77], v[86:87]
	v_add_f32_e32 v81, v82, v83
	v_pk_mul_f32 v[88:89], v[66:67], v[66:67]
	v_add_f32_e32 v81, v86, v81
	v_pk_fma_f32 v[88:89], v[64:65], v[64:65], v[88:89]
	v_add_f32_e32 v81, v87, v81
	v_add_f32_e32 v82, v88, v81
	v_pk_add_f32 v[82:83], v[88:89], v[82:83] op_sel_hi:[1,0]
	v_pk_add_f32 v[72:73], v[72:73], v[74:75]
	v_mov_b32_e32 v86, v68
	v_mov_b32_e32 v87, v70
	v_mul_f32_e32 v82, v68, v68
	v_pk_add_f32 v[88:89], v[68:69], v[70:71]
	v_pk_mul_f32 v[70:71], v[68:69], v[70:71]
	v_add_f32_e32 v68, 0, v72
	v_add_f32_e32 v68, v73, v68
	v_pk_add_f32 v[72:73], v[76:77], v[78:79]
	v_pk_add_f32 v[64:65], v[64:65], v[66:67]
	v_add_f32_e32 v68, v72, v68
	v_add_f32_e32 v68, v73, v68
	v_pk_fma_f32 v[86:87], v[86:87], v[86:87], v[82:83] op_sel_hi:[1,1,0]
	v_add_f32_e32 v64, v64, v68
	v_mov_b32_e32 v89, v71
	v_mul_f32_e32 v71, v84, v84
	v_add_f32_e32 v70, v65, v64
	v_mov_b32_e32 v86, v69
	v_mov_b32_e32 v85, v83
	v_pk_add_f32 v[64:65], v[88:89], v[70:71]
	v_pk_add_f32 v[66:67], v[86:87], v[84:85]
	s_nop 0
	v_pk_add_f32 v[64:65], v[64:65], v[66:67]
	ds_bpermute_b32 v66, v205, v64
	ds_bpermute_b32 v67, v205, v65
	s_waitcnt lgkmcnt(0)
	v_pk_add_f32 v[64:65], v[64:65], v[66:67]
	ds_bpermute_b32 v66, v206, v64
	ds_bpermute_b32 v67, v206, v65
	s_and_saveexec_b64 s[46:47], s[38:39]
	s_cbranch_execz .LBB0_205
	v_lshlrev_b64 v[68:69], 8, v[188:189]
	s_waitcnt lgkmcnt(0)
	v_pk_add_f32 v[64:65], v[64:65], v[66:67]
	v_lshl_add_u64 v[66:67], s[6:7], 0, v[68:69]
	v_lshl_add_u64 v[66:67], s[36:37], 3, v[66:67]
	global_store_dwordx2 v[66:67], v[64:65], off

; __device__ __forceinline__ unsigned cvt_pk_bf16(float lo, float hi) { unsigned r; asm volatile("v_cvt_pk_bf16_f32 %0, %1, %2" : "=v"(r) : "v"(lo), "v"(hi)); return r; }
;     __device__ __forceinline__ void operator()(const f32x4 (&acc)[2][2][4][2], const Unit& u, int wr, int wc, int fr, int fq) const {
;     ...
;             for (int m = 0; m < 4; ++m) { const int row = row0 + ai * HALF + m * 16; bf16_t* rowp = O + (size_t)row * ldc + col0; float s = 0.f, q = 0.f;
;                 const float rstd = rsv[ai][m];
; #pragma unroll
;                 for (int bj = 0; bj < 2; ++bj) { f32x4 v0 = acc[ai][bj][m][0] * rstd + bv[bj][0], v1 = acc[ai][bj][m][1] * rstd + bv[bj][1];
;                     if (ACT == 1) {
; #pragma unroll
;                         for (int e = 0; e < 4; ++e) { const float a = fmaxf(v0[e], 0.f), b2 = fmaxf(v1[e], 0.f); v0[e] = a * a; v1[e] = b2 * b2; } }
;                     if (ACT == 2) {
; #pragma unroll
;                         for (int e = 0; e < 4; ++e) { v0[e] = gelu_tanh(v0[e]); v1[e] = gelu_tanh(v1[e]); s += v0[e] + v1[e]; q += v0[e] * v0[e] + v1[e] * v1[e]; } }
;                     u32x4 w; w.x = cvt_pk_bf16(v0[0], v0[1]); w.y = cvt_pk_bf16(v0[2], v0[3]); w.z = cvt_pk_bf16(v1[0], v1[1]); w.w = cvt_pk_bf16(v1[2], v1[3]);
;                     *(u32x4*)(rowp + bj * HALF) = w; }
.LBB0_206:
	v_mul_f32_e32 v64, 0x4b800000, v80
	v_cndmask_b32_e64 v64, v80, v64, s[44:45]
	v_rsq_f32_e32 v64, v64
	s_and_b64 vcc, exec, s[42:43]
	v_mul_f32_e32 v65, 0x45800000, v64
	v_cndmask_b32_e64 v70, v64, v65, s[44:45]
	s_waitcnt lgkmcnt(0)
	v_pk_fma_f32 v[66:67], v[58:59], v[70:71], v[42:43] op_sel_hi:[1,0,1]
	v_pk_fma_f32 v[58:59], v[56:57], v[70:71], v[40:41] op_sel_hi:[1,0,1]
	v_pk_fma_f32 v[60:61], v[60:61], v[70:71], v[44:45] op_sel_hi:[1,0,1]
	v_mul_f32_e32 v57, 0x3d122279, v58
	v_fmaak_f32 v57, v58, v57, 0x3f4c422a
	v_mul_f32_e32 v57, v58, v57
	v_mul_f32_e32 v57, 0x4038aa3b, v57
	v_exp_f32_e32 v57, v57
	v_mul_f32_e32 v56, 0x3d122279, v60
	v_fmaak_f32 v56, v60, v56, 0x3f4c422a
	v_mul_f32_e32 v56, v60, v56
	v_add_f32_e32 v57, 1.0, v57
	v_rcp_f32_e32 v68, v57
	v_mul_f32_e32 v57, 0x3d122279, v61
	v_fmaak_f32 v57, v61, v57, 0x3f4c422a
	v_mul_f32_e32 v57, v61, v57
	v_mul_f32_e32 v56, 0x4038aa3b, v56
	v_mul_f32_e32 v57, 0x4038aa3b, v57
	v_exp_f32_e32 v56, v56
	v_exp_f32_e32 v57, v57
	v_mul_f32_e32 v69, 0x3d122279, v59
	v_fmaak_f32 v69, v59, v69, 0x3f4c422a
	v_add_f32_e32 v56, 1.0, v56
	v_add_f32_e32 v57, 1.0, v57
	v_rcp_f32_e32 v56, v56
	v_rcp_f32_e32 v57, v57
	v_mul_f32_e32 v69, v59, v69
	v_mul_f32_e32 v69, 0x4038aa3b, v69
	v_exp_f32_e32 v69, v69
	v_pk_fma_f32 v[56:57], v[60:61], v[56:57], v[60:61] neg_lo:[1,0,0] neg_hi:[1,0,0]
	v_mul_f32_e32 v61, 0x3d122279, v66
	v_fmaak_f32 v61, v66, v61, 0x3f4c422a
	v_mul_f32_e32 v61, v66, v61
	v_mul_f32_e32 v61, 0x4038aa3b, v61
	v_add_f32_e32 v69, 1.0, v69
	v_exp_f32_e32 v61, v61
	v_rcp_f32_e32 v69, v69
	v_pk_fma_f32 v[62:63], v[62:63], v[70:71], v[46:47] op_sel_hi:[1,0,1]
	v_lshlrev_b64 v[64:65], 13, v[186:187]
	v_add_f32_e32 v61, 1.0, v61
	v_pk_fma_f32 v[58:59], v[58:59], v[68:69], v[58:59] neg_lo:[1,0,0] neg_hi:[1,0,0]
	v_mul_f32_e32 v60, 0x3d122279, v62
	v_rcp_f32_e32 v68, v61
	v_mul_f32_e32 v61, 0x3d122279, v63
	v_mul_f32_e32 v69, 0x3d122279, v67
	v_fmaak_f32 v60, v62, v60, 0x3f4c422a
	v_fmaak_f32 v61, v63, v61, 0x3f4c422a
	v_fmaak_f32 v69, v67, v69, 0x3f4c422a
	v_mul_f32_e32 v60, v62, v60
	v_mul_f32_e32 v61, v63, v61
	v_mul_f32_e32 v69, v67, v69
	v_mul_f32_e32 v60, 0x4038aa3b, v60
	v_mul_f32_e32 v61, 0x4038aa3b, v61
	v_mul_f32_e32 v69, 0x4038aa3b, v69
	v_exp_f32_e32 v60, v60
	v_exp_f32_e32 v61, v61
	v_exp_f32_e32 v69, v69
	v_lshl_add_u64 v[64:65], s[2:3], 0, v[64:65]
	v_add_f32_e32 v60, 1.0, v60
	v_add_f32_e32 v61, 1.0, v61
	v_add_f32_e32 v69, 1.0, v69
	v_rcp_f32_e32 v60, v60
	v_rcp_f32_e32 v61, v61
	v_rcp_f32_e32 v69, v69
	v_lshl_add_u64 v[64:65], v[182:183], 1, v[64:65]
	v_pk_fma_f32 v[52:53], v[52:53], v[70:71], v[36:37] op_sel_hi:[1,0,1]
	v_pk_fma_f32 v[60:61], v[62:63], v[60:61], v[62:63] neg_lo:[1,0,0] neg_hi:[1,0,0]
	v_pk_fma_f32 v[62:63], v[66:67], v[68:69], v[66:67] neg_lo:[1,0,0] neg_hi:[1,0,0]
	v_cvt_pk_bf16_f32 v66, v56, v57
	v_cvt_pk_bf16_f32 v67, v60, v61
	v_cvt_pk_bf16_f32 v68, v58, v59
	v_pk_fma_f32 v[54:55], v[54:55], v[70:71], v[38:39] op_sel_hi:[1,0,1]
	v_cvt_pk_bf16_f32 v69, v62, v63
	global_store_dwordx4 v[64:65], v[66:69], off sc1
	s_nop 1
	v_pk_fma_f32 v[66:67], v[50:51], v[70:71], v[34:35] op_sel_hi:[1,0,1]
	v_pk_fma_f32 v[50:51], v[48:49], v[70:71], v[32:33] op_sel_hi:[1,0,1]
	v_mul_f32_e32 v48, 0x3d122279, v52
	v_mul_f32_e32 v49, 0x3d122279, v50
	v_fmaak_f32 v49, v50, v49, 0x3f4c422a
	v_mul_f32_e32 v49, v50, v49
	v_mul_f32_e32 v49, 0x4038aa3b, v49
	v_exp_f32_e32 v49, v49
	v_fmaak_f32 v48, v52, v48, 0x3f4c422a
	v_mul_f32_e32 v48, v52, v48
	v_mul_f32_e32 v48, 0x4038aa3b, v48
	v_add_f32_e32 v49, 1.0, v49
	v_rcp_f32_e32 v68, v49
	v_mul_f32_e32 v49, 0x3d122279, v53
	v_fmaak_f32 v49, v53, v49, 0x3f4c422a
	v_mul_f32_e32 v49, v53, v49
	v_mul_f32_e32 v49, 0x4038aa3b, v49
	v_exp_f32_e32 v48, v48
	v_exp_f32_e32 v49, v49
	v_mul_f32_e32 v69, 0x3d122279, v51
	v_fmaak_f32 v69, v51, v69, 0x3f4c422a
	v_add_f32_e32 v48, 1.0, v48
	v_add_f32_e32 v49, 1.0, v49
	v_rcp_f32_e32 v48, v48
	v_rcp_f32_e32 v49, v49
	v_mul_f32_e32 v69, v51, v69
	v_mul_f32_e32 v69, 0x4038aa3b, v69
	v_exp_f32_e32 v69, v69
	v_pk_fma_f32 v[48:49], v[52:53], v[48:49], v[52:53] neg_lo:[1,0,0] neg_hi:[1,0,0]
	v_mul_f32_e32 v53, 0x3d122279, v66
	v_fmaak_f32 v53, v66, v53, 0x3f4c422a
	v_mul_f32_e32 v53, v66, v53
	v_mul_f32_e32 v53, 0x4038aa3b, v53
	v_add_f32_e32 v69, 1.0, v69
	v_exp_f32_e32 v53, v53
	v_rcp_f32_e32 v69, v69
	v_mul_f32_e32 v52, 0x3d122279, v54
	v_mov_b32_e32 v70, v66
	v_add_f32_e32 v53, 1.0, v53
	v_pk_fma_f32 v[50:51], v[50:51], v[68:69], v[50:51] neg_lo:[1,0,0] neg_hi:[1,0,0]
	v_rcp_f32_e32 v68, v53
	v_mul_f32_e32 v53, 0x3d122279, v55
	v_fmaak_f32 v53, v55, v53, 0x3f4c422a
	v_mul_f32_e32 v66, 0x3d122279, v67
	v_fmaak_f32 v52, v54, v52, 0x3f4c422a
	v_mul_f32_e32 v53, v55, v53
	v_fmaak_f32 v66, v67, v66, 0x3f4c422a
	v_mul_f32_e32 v52, v54, v52
	v_mul_f32_e32 v53, 0x4038aa3b, v53
	v_mul_f32_e32 v66, v67, v66
	v_mul_f32_e32 v52, 0x4038aa3b, v52
	v_exp_f32_e32 v53, v53
	v_mul_f32_e32 v66, 0x4038aa3b, v66
	v_exp_f32_e32 v52, v52
	v_exp_f32_e32 v66, v66
	v_add_f32_e32 v53, 1.0, v53
	v_rcp_f32_e32 v53, v53
	v_add_f32_e32 v52, 1.0, v52
	v_add_f32_e32 v66, 1.0, v66
	v_rcp_f32_e32 v52, v52
	v_rcp_f32_e32 v66, v66
	v_mov_b32_e32 v71, v55
	v_mov_b32_e32 v69, v53
	v_pk_fma_f32 v[52:53], v[54:55], v[52:53], v[54:55] neg_lo:[1,0,0] neg_hi:[1,0,0]
	v_pk_fma_f32 v[54:55], v[70:71], v[68:69], v[70:71] neg_lo:[1,0,0] neg_hi:[1,0,0]
	v_fma_f32 v66, -v67, v66, v67
	v_cvt_pk_bf16_f32 v68, v48, v49
	v_cvt_pk_bf16_f32 v69, v52, v53
	v_cvt_pk_bf16_f32 v70, v50, v51
	v_cvt_pk_bf16_f32 v71, v54, v66
	global_store_dwordx4 v[64:65], v[68:71], off offset:256 sc1
	s_cbranch_vccnz .LBB0_210
; __device__ __forceinline__ unsigned cvt_pk_bf16(float lo, float hi) { unsigned r; asm volatile("v_cvt_pk_bf16_f32 %0, %1, %2" : "=v"(r) : "v"(lo), "v"(hi)); return r; }
;     __device__ __forceinline__ void operator()(const f32x4 (&acc)[2][2][4][2], const Unit& u, int wr, int wc, int fr, int fq) const {
;     ...
;                         for (int e = 0; e < 4; ++e) { v0[e] = gelu_tanh(v0[e]); v1[e] = gelu_tanh(v1[e]); s += v0[e] + v1[e]; q += v0[e] * v0[e] + v1[e] * v1[e]; } }
;                     u32x4 w; w.x = cvt_pk_bf16(v0[0], v0[1]); w.y = cvt_pk_bf16(v0[2], v0[3]); w.z = cvt_pk_bf16(v1[0], v1[1]); w.w = cvt_pk_bf16(v1[2], v1[3]);
;                     *(u32x4*)(rowp + bj * HALF) = w; }
;                 if (ACT == 2) { if (u.pn >= 8) { s += __shfl_xor(s, 16); s += __shfl_xor(s, 32); q += __shfl_xor(q, 16); q += __shfl_xor(q, 32);
;                     if (fq == 0) *(f32x2*)(stats + ((size_t)row * 32 + (u.pn - 8) * 4 + wc) * 2) = (f32x2){s, q}; } }
	v_pk_mul_f32 v[64:65], v[58:59], v[58:59]
	v_pk_mul_f32 v[68:69], v[62:63], v[62:63]
	v_pk_fma_f32 v[64:65], v[56:57], v[56:57], v[64:65]
	v_pk_fma_f32 v[68:69], v[60:61], v[60:61], v[68:69]
	v_add_f32_e32 v64, v64, v65
	v_pk_mul_f32 v[70:71], v[50:51], v[50:51]
	v_add_f32_e32 v64, v68, v64
	v_pk_fma_f32 v[70:71], v[48:49], v[48:49], v[70:71]
	v_add_f32_e32 v64, v69, v64
	v_add_f32_e32 v64, v70, v64
	v_pk_add_f32 v[64:65], v[70:71], v[64:65] op_sel_hi:[1,0]
	v_pk_add_f32 v[56:57], v[56:57], v[58:59]
	v_mov_b32_e32 v68, v52
	v_mov_b32_e32 v69, v54
	v_mul_f32_e32 v64, v52, v52
	v_pk_add_f32 v[70:71], v[52:53], v[54:55]
	v_pk_mul_f32 v[54:55], v[52:53], v[54:55]
	v_add_f32_e32 v52, 0, v56
	v_add_f32_e32 v52, v57, v52
	v_pk_add_f32 v[56:57], v[60:61], v[62:63]
	v_pk_add_f32 v[48:49], v[48:49], v[50:51]
	v_add_f32_e32 v52, v56, v52
	v_add_f32_e32 v52, v57, v52
	v_pk_fma_f32 v[68:69], v[68:69], v[68:69], v[64:65] op_sel_hi:[1,1,0]
	v_add_f32_e32 v48, v48, v52
	v_mov_b32_e32 v71, v55
	v_mul_f32_e32 v55, v66, v66
	v_add_f32_e32 v54, v49, v48
	v_mov_b32_e32 v68, v53
	v_mov_b32_e32 v67, v65
	v_pk_add_f32 v[48:49], v[70:71], v[54:55]
	v_pk_add_f32 v[50:51], v[68:69], v[66:67]
	s_nop 0
	v_pk_add_f32 v[48:49], v[48:49], v[50:51]
	ds_bpermute_b32 v50, v205, v48
	ds_bpermute_b32 v51, v205, v49
	s_waitcnt lgkmcnt(0)
	v_pk_add_f32 v[48:49], v[48:49], v[50:51]
	ds_bpermute_b32 v50, v206, v48
	ds_bpermute_b32 v51, v206, v49
	s_and_saveexec_b64 s[44:45], s[38:39]
	s_cbranch_execz .LBB0_209
	v_lshlrev_b64 v[52:53], 8, v[186:187]
	s_waitcnt lgkmcnt(0)
	v_pk_add_f32 v[48:49], v[48:49], v[50:51]
	v_lshl_add_u64 v[50:51], s[6:7], 0, v[52:53]
	v_lshl_add_u64 v[50:51], s[36:37], 3, v[50:51]
	global_store_dwordx2 v[50:51], v[48:49], off

; __device__ __forceinline__ unsigned cvt_pk_bf16(float lo, float hi) { unsigned r; asm volatile("v_cvt_pk_bf16_f32 %0, %1, %2" : "=v"(r) : "v"(lo), "v"(hi)); return r; }
;     __device__ __forceinline__ void operator()(const f32x4 (&acc)[2][2][4][2], const Unit& u, int wr, int wc, int fr, int fq) const {
;     ...
;             for (int m = 0; m < 4; ++m) { const int row = row0 + ai * HALF + m * 16; bf16_t* rowp = O + (size_t)row * ldc + col0; float s = 0.f, q = 0.f;
;                 const float rstd = rsv[ai][m];
; #pragma unroll
;                 for (int bj = 0; bj < 2; ++bj) { f32x4 v0 = acc[ai][bj][m][0] * rstd + bv[bj][0], v1 = acc[ai][bj][m][1] * rstd + bv[bj][1];
;                     if (ACT == 1) {
; #pragma unroll
;                         for (int e = 0; e < 4; ++e) { const float a = fmaxf(v0[e], 0.f), b2 = fmaxf(v1[e], 0.f); v0[e] = a * a; v1[e] = b2 * b2; } }
;                     if (ACT == 2) {
; #pragma unroll
;                         for (int e = 0; e < 4; ++e) { v0[e] = gelu_tanh(v0[e]); v1[e] = gelu_tanh(v1[e]); s += v0[e] + v1[e]; q += v0[e] * v0[e] + v1[e] * v1[e]; } }
;                     u32x4 w; w.x = cvt_pk_bf16(v0[0], v0[1]); w.y = cvt_pk_bf16(v0[2], v0[3]); w.z = cvt_pk_bf16(v1[0], v1[1]); w.w = cvt_pk_bf16(v1[2], v1[3]);
;                     *(u32x4*)(rowp + bj * HALF) = w; }
.LBB0_210:
	v_pk_add_f32 v[48:49], v[144:145], v[146:147]
	s_nop 0
	v_pk_fma_f32 v[48:49], v[48:49], s[16:17], v[214:215] op_sel_hi:[1,0,0]
	s_waitcnt lgkmcnt(1)
	v_mul_f32_e32 v50, 0x4b800000, v49
	v_cmp_gt_f32_e32 vcc, s27, v49
	v_cmp_gt_f32_e64 s[44:45], s27, v48
	s_nop 0
	v_cndmask_b32_e32 v49, v49, v50, vcc
	v_rsq_f32_e32 v49, v49
	s_nop 0
	v_mul_f32_e32 v50, 0x45800000, v49
	v_cndmask_b32_e32 v56, v49, v50, vcc
	v_pk_fma_f32 v[52:53], v[26:27], v[56:57], v[42:43] op_sel_hi:[1,0,1]
	v_pk_fma_f32 v[26:27], v[24:25], v[56:57], v[40:41] op_sel_hi:[1,0,1]
	v_pk_fma_f32 v[28:29], v[28:29], v[56:57], v[44:45] op_sel_hi:[1,0,1]
	v_mul_f32_e32 v25, 0x3d122279, v26
	v_fmaak_f32 v25, v26, v25, 0x3f4c422a
	v_mul_f32_e32 v25, v26, v25
	v_mul_f32_e32 v25, 0x4038aa3b, v25
	v_exp_f32_e32 v25, v25
	v_mul_f32_e32 v24, 0x3d122279, v28
	v_fmaak_f32 v24, v28, v24, 0x3f4c422a
	v_mul_f32_e32 v24, v28, v24
	v_add_f32_e32 v25, 1.0, v25
	v_rcp_f32_e32 v54, v25
	v_mul_f32_e32 v25, 0x3d122279, v29
	v_fmaak_f32 v25, v29, v25, 0x3f4c422a
	v_mul_f32_e32 v25, v29, v25
	v_mul_f32_e32 v24, 0x4038aa3b, v24
	v_mul_f32_e32 v25, 0x4038aa3b, v25
	v_exp_f32_e32 v24, v24
	v_exp_f32_e32 v25, v25
	v_mul_f32_e32 v49, 0x3d122279, v27
	v_fmaak_f32 v49, v27, v49, 0x3f4c422a
	v_add_f32_e32 v24, 1.0, v24
	v_add_f32_e32 v25, 1.0, v25
	v_rcp_f32_e32 v24, v24
	v_rcp_f32_e32 v25, v25
	v_mul_f32_e32 v49, v27, v49
	v_mul_f32_e32 v49, 0x4038aa3b, v49
	v_exp_f32_e32 v49, v49
	v_pk_fma_f32 v[24:25], v[28:29], v[24:25], v[28:29] neg_lo:[1,0,0] neg_hi:[1,0,0]
	v_mul_f32_e32 v29, 0x3d122279, v52
	v_fmaak_f32 v29, v52, v29, 0x3f4c422a
	v_mul_f32_e32 v29, v52, v29
	v_mul_f32_e32 v29, 0x4038aa3b, v29
	v_add_f32_e32 v49, 1.0, v49
	v_exp_f32_e32 v29, v29
	v_rcp_f32_e32 v55, v49
	v_pk_fma_f32 v[30:31], v[30:31], v[56:57], v[46:47] op_sel_hi:[1,0,1]
	v_mul_f32_e32 v49, 0x3d122279, v53
	v_add_f32_e32 v29, 1.0, v29
	v_pk_fma_f32 v[26:27], v[26:27], v[54:55], v[26:27] neg_lo:[1,0,0] neg_hi:[1,0,0]
	v_mul_f32_e32 v28, 0x3d122279, v30
	v_rcp_f32_e32 v54, v29
	v_mul_f32_e32 v29, 0x3d122279, v31
	v_fmaak_f32 v28, v30, v28, 0x3f4c422a
	v_fmaak_f32 v29, v31, v29, 0x3f4c422a
	v_fmaak_f32 v49, v53, v49, 0x3f4c422a
	v_mul_f32_e32 v28, v30, v28
	v_mul_f32_e32 v29, v31, v29
	v_mul_f32_e32 v49, v53, v49
	v_mul_f32_e32 v28, 0x4038aa3b, v28
	v_mul_f32_e32 v29, 0x4038aa3b, v29
	v_mul_f32_e32 v49, 0x4038aa3b, v49
	v_exp_f32_e32 v28, v28
	v_exp_f32_e32 v29, v29
	v_exp_f32_e32 v49, v49
	s_waitcnt lgkmcnt(0)
	v_lshlrev_b64 v[50:51], 13, v[184:185]
	v_add_f32_e32 v28, 1.0, v28
	v_add_f32_e32 v29, 1.0, v29
	v_add_f32_e32 v49, 1.0, v49
	v_rcp_f32_e32 v28, v28
	v_rcp_f32_e32 v29, v29
	v_rcp_f32_e32 v55, v49
	v_lshl_add_u64 v[50:51], s[2:3], 0, v[50:51]
	v_lshl_add_u64 v[50:51], v[182:183], 1, v[50:51]
	v_pk_fma_f32 v[28:29], v[30:31], v[28:29], v[30:31] neg_lo:[1,0,0] neg_hi:[1,0,0]
	v_pk_fma_f32 v[30:31], v[52:53], v[54:55], v[52:53] neg_lo:[1,0,0] neg_hi:[1,0,0]
	v_cvt_pk_bf16_f32 v52, v24, v25
	v_cvt_pk_bf16_f32 v53, v28, v29
	v_cvt_pk_bf16_f32 v54, v26, v27
	v_pk_fma_f32 v[20:21], v[20:21], v[56:57], v[36:37] op_sel_hi:[1,0,1]
	v_cvt_pk_bf16_f32 v55, v30, v31
	global_store_dwordx4 v[50:51], v[52:55], off sc1
	v_pk_fma_f32 v[22:23], v[22:23], v[56:57], v[38:39] op_sel_hi:[1,0,1]
	s_and_b64 vcc, exec, s[42:43]
	v_pk_fma_f32 v[52:53], v[18:19], v[56:57], v[34:35] op_sel_hi:[1,0,1]
	v_pk_fma_f32 v[18:19], v[16:17], v[56:57], v[32:33] op_sel_hi:[1,0,1]
	v_mul_f32_e32 v16, 0x3d122279, v20
	v_mul_f32_e32 v17, 0x3d122279, v18
	v_fmaak_f32 v17, v18, v17, 0x3f4c422a
	v_mul_f32_e32 v17, v18, v17
	v_mul_f32_e32 v17, 0x4038aa3b, v17
	v_exp_f32_e32 v17, v17
	v_fmaak_f32 v16, v20, v16, 0x3f4c422a
	v_mul_f32_e32 v16, v20, v16
	v_mul_f32_e32 v16, 0x4038aa3b, v16
	v_add_f32_e32 v17, 1.0, v17
	v_rcp_f32_e32 v54, v17
	v_mul_f32_e32 v17, 0x3d122279, v21
	v_fmaak_f32 v17, v21, v17, 0x3f4c422a
	v_mul_f32_e32 v17, v21, v17
	v_mul_f32_e32 v17, 0x4038aa3b, v17
	v_exp_f32_e32 v16, v16
	v_exp_f32_e32 v17, v17
	v_mul_f32_e32 v49, 0x3d122279, v19
	v_fmaak_f32 v49, v19, v49, 0x3f4c422a
	v_add_f32_e32 v16, 1.0, v16
	v_add_f32_e32 v17, 1.0, v17
	v_rcp_f32_e32 v16, v16
	v_rcp_f32_e32 v17, v17
	v_mul_f32_e32 v49, v19, v49
	v_mul_f32_e32 v49, 0x4038aa3b, v49
	v_exp_f32_e32 v49, v49
	v_pk_fma_f32 v[16:17], v[20:21], v[16:17], v[20:21] neg_lo:[1,0,0] neg_hi:[1,0,0]
	v_mul_f32_e32 v21, 0x3d122279, v52
	v_fmaak_f32 v21, v52, v21, 0x3f4c422a
	v_mul_f32_e32 v21, v52, v21
	v_mul_f32_e32 v21, 0x4038aa3b, v21
	v_add_f32_e32 v49, 1.0, v49
	v_exp_f32_e32 v21, v21
	v_rcp_f32_e32 v55, v49
	v_mul_f32_e32 v20, 0x3d122279, v22
	v_mul_f32_e32 v49, 0x3d122279, v53
	v_add_f32_e32 v21, 1.0, v21
	v_pk_fma_f32 v[18:19], v[18:19], v[54:55], v[18:19] neg_lo:[1,0,0] neg_hi:[1,0,0]
	v_rcp_f32_e32 v54, v21
	v_mul_f32_e32 v21, 0x3d122279, v23
	v_fmaak_f32 v21, v23, v21, 0x3f4c422a
	v_fmaak_f32 v20, v22, v20, 0x3f4c422a
	v_mul_f32_e32 v21, v23, v21
	v_fmaak_f32 v49, v53, v49, 0x3f4c422a
	v_mul_f32_e32 v20, v22, v20
	v_mul_f32_e32 v21, 0x4038aa3b, v21
	v_mul_f32_e32 v49, v53, v49
	v_mul_f32_e32 v20, 0x4038aa3b, v20
	v_exp_f32_e32 v21, v21
	v_mul_f32_e32 v49, 0x4038aa3b, v49
	v_exp_f32_e32 v20, v20
	v_exp_f32_e32 v49, v49
	v_add_f32_e32 v21, 1.0, v21
	v_rcp_f32_e32 v21, v21
	v_add_f32_e32 v20, 1.0, v20
	v_add_f32_e32 v49, 1.0, v49
	v_rcp_f32_e32 v20, v20
	v_rcp_f32_e32 v49, v49
	v_mov_b32_e32 v56, v52
	v_mov_b32_e32 v57, v23
	v_mov_b32_e32 v55, v21
	v_pk_fma_f32 v[20:21], v[22:23], v[20:21], v[22:23] neg_lo:[1,0,0] neg_hi:[1,0,0]
	v_pk_fma_f32 v[22:23], v[56:57], v[54:55], v[56:57] neg_lo:[1,0,0] neg_hi:[1,0,0]
	v_fma_f32 v52, -v53, v49, v53
	v_cvt_pk_bf16_f32 v54, v16, v17
	v_cvt_pk_bf16_f32 v55, v20, v21
	v_cvt_pk_bf16_f32 v56, v18, v19
	v_cvt_pk_bf16_f32 v57, v22, v52
	global_store_dwordx4 v[50:51], v[54:57], off offset:256 sc1
	s_cbranch_vccnz .LBB0_214
; __device__ __forceinline__ unsigned cvt_pk_bf16(float lo, float hi) { unsigned r; asm volatile("v_cvt_pk_bf16_f32 %0, %1, %2" : "=v"(r) : "v"(lo), "v"(hi)); return r; }
;     __device__ __forceinline__ void operator()(const f32x4 (&acc)[2][2][4][2], const Unit& u, int wr, int wc, int fr, int fq) const {
;     ...
;                         for (int e = 0; e < 4; ++e) { v0[e] = gelu_tanh(v0[e]); v1[e] = gelu_tanh(v1[e]); s += v0[e] + v1[e]; q += v0[e] * v0[e] + v1[e] * v1[e]; } }
;                     u32x4 w; w.x = cvt_pk_bf16(v0[0], v0[1]); w.y = cvt_pk_bf16(v0[2], v0[3]); w.z = cvt_pk_bf16(v1[0], v1[1]); w.w = cvt_pk_bf16(v1[2], v1[3]);
;                     *(u32x4*)(rowp + bj * HALF) = w; }
;                 if (ACT == 2) { if (u.pn >= 8) { s += __shfl_xor(s, 16); s += __shfl_xor(s, 32); q += __shfl_xor(q, 16); q += __shfl_xor(q, 32);
;                     if (fq == 0) *(f32x2*)(stats + ((size_t)row * 32 + (u.pn - 8) * 4 + wc) * 2) = (f32x2){s, q}; } }
	v_pk_mul_f32 v[50:51], v[26:27], v[26:27]
	v_pk_mul_f32 v[54:55], v[30:31], v[30:31]
	v_pk_fma_f32 v[50:51], v[24:25], v[24:25], v[50:51]
	v_pk_fma_f32 v[54:55], v[28:29], v[28:29], v[54:55]
	v_add_f32_e32 v49, v50, v51
	v_pk_mul_f32 v[56:57], v[18:19], v[18:19]
	v_add_f32_e32 v49, v54, v49
	v_pk_fma_f32 v[56:57], v[16:17], v[16:17], v[56:57]
	v_add_f32_e32 v49, v55, v49
	v_add_f32_e32 v50, v56, v49
	v_pk_add_f32 v[50:51], v[56:57], v[50:51] op_sel_hi:[1,0]
	v_pk_add_f32 v[24:25], v[24:25], v[26:27]
	v_mov_b32_e32 v54, v20
	v_mov_b32_e32 v55, v22
	v_mul_f32_e32 v50, v20, v20
	v_pk_add_f32 v[56:57], v[20:21], v[22:23]
	v_pk_mul_f32 v[22:23], v[20:21], v[22:23]
	v_add_f32_e32 v20, 0, v24
	v_add_f32_e32 v20, v25, v20
	v_pk_add_f32 v[24:25], v[28:29], v[30:31]
	v_pk_add_f32 v[16:17], v[16:17], v[18:19]
	v_add_f32_e32 v20, v24, v20
	v_add_f32_e32 v20, v25, v20
	v_pk_fma_f32 v[54:55], v[54:55], v[54:55], v[50:51] op_sel_hi:[1,1,0]
	v_add_f32_e32 v16, v16, v20
	v_mov_b32_e32 v57, v23
	v_mul_f32_e32 v23, v52, v52
	v_add_f32_e32 v22, v17, v16
	v_mov_b32_e32 v54, v21
	v_mov_b32_e32 v53, v51
	v_pk_add_f32 v[16:17], v[56:57], v[22:23]
	v_pk_add_f32 v[18:19], v[54:55], v[52:53]
	s_nop 0
	v_pk_add_f32 v[16:17], v[16:17], v[18:19]
	ds_bpermute_b32 v18, v205, v16
	ds_bpermute_b32 v19, v205, v17
	s_waitcnt lgkmcnt(0)
	v_pk_add_f32 v[16:17], v[16:17], v[18:19]
	ds_bpermute_b32 v18, v206, v16
	ds_bpermute_b32 v19, v206, v17
	s_and_saveexec_b64 s[46:47], s[38:39]
	s_cbranch_execz .LBB0_213
	v_lshlrev_b64 v[20:21], 8, v[184:185]
	s_waitcnt lgkmcnt(0)
	v_pk_add_f32 v[16:17], v[16:17], v[18:19]
	v_lshl_add_u64 v[18:19], s[6:7], 0, v[20:21]
	v_lshl_add_u64 v[18:19], s[36:37], 3, v[18:19]
	global_store_dwordx2 v[18:19], v[16:17], off

; __device__ __forceinline__ unsigned cvt_pk_bf16(float lo, float hi) { unsigned r; asm volatile("v_cvt_pk_bf16_f32 %0, %1, %2" : "=v"(r) : "v"(lo), "v"(hi)); return r; }
;     __device__ __forceinline__ void operator()(const f32x4 (&acc)[2][2][4][2], const Unit& u, int wr, int wc, int fr, int fq) const {
;     ...
;             for (int m = 0; m < 4; ++m) { const int row = row0 + ai * HALF + m * 16; bf16_t* rowp = O + (size_t)row * ldc + col0; float s = 0.f, q = 0.f;
;                 const float rstd = rsv[ai][m];
; #pragma unroll
;                 for (int bj = 0; bj < 2; ++bj) { f32x4 v0 = acc[ai][bj][m][0] * rstd + bv[bj][0], v1 = acc[ai][bj][m][1] * rstd + bv[bj][1];
;                     if (ACT == 1) {
; #pragma unroll
;                         for (int e = 0; e < 4; ++e) { const float a = fmaxf(v0[e], 0.f), b2 = fmaxf(v1[e], 0.f); v0[e] = a * a; v1[e] = b2 * b2; } }
;                     if (ACT == 2) {
; #pragma unroll
;                         for (int e = 0; e < 4; ++e) { v0[e] = gelu_tanh(v0[e]); v1[e] = gelu_tanh(v1[e]); s += v0[e] + v1[e]; q += v0[e] * v0[e] + v1[e] * v1[e]; } }
;                     u32x4 w; w.x = cvt_pk_bf16(v0[0], v0[1]); w.y = cvt_pk_bf16(v0[2], v0[3]); w.z = cvt_pk_bf16(v1[0], v1[1]); w.w = cvt_pk_bf16(v1[2], v1[3]);
;                     *(u32x4*)(rowp + bj * HALF) = w; }
.LBB0_214:
	v_mul_f32_e32 v16, 0x4b800000, v48
	v_cndmask_b32_e64 v16, v48, v16, s[44:45]
	s_waitcnt lgkmcnt(1)
	v_rsq_f32_e32 v18, v16
	v_lshlrev_b64 v[16:17], 13, v[180:181]
	v_lshl_add_u64 v[16:17], s[2:3], 0, v[16:17]
	v_lshl_add_u64 v[22:23], v[182:183], 1, v[16:17]
	v_mul_f32_e32 v16, 0x45800000, v18
	v_cndmask_b32_e64 v20, v18, v16, s[44:45]
	v_pk_fma_f32 v[12:13], v[12:13], v[20:21], v[44:45] op_sel_hi:[1,0,1]
	s_waitcnt lgkmcnt(0)
	v_pk_fma_f32 v[18:19], v[10:11], v[20:21], v[42:43] op_sel_hi:[1,0,1]
	v_mul_f32_e32 v10, 0x3d122279, v13
	v_fmaak_f32 v10, v13, v10, 0x3f4c422a
	v_pk_fma_f32 v[16:17], v[8:9], v[20:21], v[40:41] op_sel_hi:[1,0,1]
	v_mul_f32_e32 v10, v13, v10
	v_mul_f32_e32 v9, 0x3d122279, v16
	v_mul_f32_e32 v10, 0x4038aa3b, v10
	v_fmaak_f32 v9, v16, v9, 0x3f4c422a
	v_exp_f32_e32 v11, v10
	v_mul_f32_e32 v10, 0x3d122279, v17
	v_mul_f32_e32 v9, v16, v9
	v_fmaak_f32 v10, v17, v10, 0x3f4c422a
	v_mul_f32_e32 v9, 0x4038aa3b, v9
	v_mul_f32_e32 v10, v17, v10
	v_exp_f32_e32 v9, v9
	v_mul_f32_e32 v10, 0x4038aa3b, v10
	v_pk_fma_f32 v[14:15], v[14:15], v[20:21], v[46:47] op_sel_hi:[1,0,1]
	v_exp_f32_e32 v21, v10
	v_add_f32_e32 v9, 1.0, v9
	v_rcp_f32_e32 v10, v9
	v_add_f32_e32 v9, 1.0, v11
	v_add_f32_e32 v11, 1.0, v21
	v_mul_f32_e32 v21, 0x3d122279, v14
	v_fmaak_f32 v21, v14, v21, 0x3f4c422a
	v_mul_f32_e32 v24, 0x3d122279, v18
	v_mul_f32_e32 v21, v14, v21
	v_fmaak_f32 v24, v18, v24, 0x3f4c422a
	v_mul_f32_e32 v21, 0x4038aa3b, v21
	v_mul_f32_e32 v24, v18, v24
	v_exp_f32_e32 v21, v21
	v_mul_f32_e32 v24, 0x4038aa3b, v24
	v_exp_f32_e32 v25, v24
	v_mul_f32_e32 v8, 0x3d122279, v12
	v_add_f32_e32 v21, 1.0, v21
	v_rcp_f32_e32 v24, v21
	v_add_f32_e32 v21, 1.0, v25
	v_mul_f32_e32 v25, 0x3d122279, v15
	v_fmaak_f32 v25, v15, v25, 0x3f4c422a
	v_mul_f32_e32 v26, 0x3d122279, v19
	v_fmaak_f32 v8, v12, v8, 0x3f4c422a
	v_mul_f32_e32 v25, v15, v25
	v_fmaak_f32 v26, v19, v26, 0x3f4c422a
	v_mul_f32_e32 v8, v12, v8
	v_mul_f32_e32 v25, 0x4038aa3b, v25
	v_mul_f32_e32 v26, v19, v26
	v_mul_f32_e32 v8, 0x4038aa3b, v8
	v_exp_f32_e32 v25, v25
	v_mul_f32_e32 v26, 0x4038aa3b, v26
	v_exp_f32_e32 v8, v8
	v_exp_f32_e32 v27, v26
	v_rcp_f32_e32 v26, v21
	v_add_f32_e32 v21, 1.0, v25
	v_add_f32_e32 v8, 1.0, v8
	v_rcp_f32_e32 v25, v21
	v_add_f32_e32 v21, 1.0, v27
	v_rcp_f32_e32 v8, v8
	v_rcp_f32_e32 v9, v9
	v_rcp_f32_e32 v11, v11
	v_rcp_f32_e32 v27, v21
	v_pk_fma_f32 v[4:5], v[4:5], v[20:21], v[36:37] op_sel_hi:[1,0,1]
	v_pk_fma_f32 v[8:9], v[12:13], v[8:9], v[12:13] neg_lo:[1,0,0] neg_hi:[1,0,0]
	v_pk_fma_f32 v[10:11], v[16:17], v[10:11], v[16:17] neg_lo:[1,0,0] neg_hi:[1,0,0]
	v_pk_fma_f32 v[12:13], v[14:15], v[24:25], v[14:15] neg_lo:[1,0,0] neg_hi:[1,0,0]
	v_pk_fma_f32 v[14:15], v[18:19], v[26:27], v[18:19] neg_lo:[1,0,0] neg_hi:[1,0,0]
	v_cvt_pk_bf16_f32 v16, v8, v9
	v_cvt_pk_bf16_f32 v17, v12, v13
	v_cvt_pk_bf16_f32 v18, v10, v11
	v_pk_fma_f32 v[6:7], v[6:7], v[20:21], v[38:39] op_sel_hi:[1,0,1]
	v_cvt_pk_bf16_f32 v19, v14, v15
	global_store_dwordx4 v[22:23], v[16:19], off sc1
	s_and_b64 vcc, exec, s[42:43]
	s_nop 0
	v_mul_f32_e32 v18, 0x3d122279, v5
	v_fmaak_f32 v18, v5, v18, 0x3f4c422a
	v_pk_fma_f32 v[16:17], v[0:1], v[20:21], v[32:33] op_sel_hi:[1,0,1]
	v_mul_f32_e32 v18, v5, v18
	v_mul_f32_e32 v1, 0x3d122279, v16
	v_mul_f32_e32 v18, 0x4038aa3b, v18
	v_mul_f32_e32 v0, 0x3d122279, v4
	v_fmaak_f32 v1, v16, v1, 0x3f4c422a
	v_exp_f32_e32 v19, v18
	v_mul_f32_e32 v18, 0x3d122279, v17
	v_fmaak_f32 v0, v4, v0, 0x3f4c422a
	v_mul_f32_e32 v1, v16, v1
	v_fmaak_f32 v18, v17, v18, 0x3f4c422a
	v_mul_f32_e32 v0, v4, v0
	v_mul_f32_e32 v1, 0x4038aa3b, v1
	v_mul_f32_e32 v18, v17, v18
	v_mul_f32_e32 v0, 0x4038aa3b, v0
	v_exp_f32_e32 v1, v1
	v_mul_f32_e32 v18, 0x4038aa3b, v18
	v_exp_f32_e32 v0, v0
	v_exp_f32_e32 v21, v18
	v_add_f32_e32 v1, 1.0, v1
	v_rcp_f32_e32 v18, v1
	v_add_f32_e32 v0, 1.0, v0
	v_add_f32_e32 v1, 1.0, v19
	v_add_f32_e32 v19, 1.0, v21
	v_mul_f32_e32 v21, 0x3d122279, v6
	v_rcp_f32_e32 v0, v0
	v_rcp_f32_e32 v1, v1
	v_fmaak_f32 v21, v6, v21, 0x3f4c422a
	v_rcp_f32_e32 v19, v19
	v_mul_f32_e32 v21, v6, v21
	v_mul_f32_e32 v21, 0x4038aa3b, v21
	v_exp_f32_e32 v24, v21
	v_pk_fma_f32 v[20:21], v[2:3], v[20:21], v[34:35] op_sel_hi:[1,0,1]
	v_pk_fma_f32 v[0:1], v[4:5], v[0:1], v[4:5] neg_lo:[1,0,0] neg_hi:[1,0,0]
	v_mul_f32_e32 v5, 0x3d122279, v20
	v_pk_fma_f32 v[2:3], v[16:17], v[18:19], v[16:17] neg_lo:[1,0,0] neg_hi:[1,0,0]
	v_fmaak_f32 v5, v20, v5, 0x3f4c422a
	v_mul_f32_e32 v16, 0x3d122279, v7
	v_mul_f32_e32 v5, v20, v5
	v_fmaak_f32 v16, v7, v16, 0x3f4c422a
	v_mul_f32_e32 v5, 0x4038aa3b, v5
	v_mul_f32_e32 v16, v7, v16
	v_exp_f32_e32 v5, v5
	v_mul_f32_e32 v16, 0x4038aa3b, v16
	v_exp_f32_e32 v17, v16
	v_add_f32_e32 v4, 1.0, v24
	v_add_f32_e32 v5, 1.0, v5
	v_rcp_f32_e32 v16, v5
	v_add_f32_e32 v5, 1.0, v17
	v_mul_f32_e32 v17, 0x3d122279, v21
	v_fmaak_f32 v17, v21, v17, 0x3f4c422a
	v_mul_f32_e32 v17, v21, v17
	v_mul_f32_e32 v17, 0x4038aa3b, v17
	v_exp_f32_e32 v17, v17
	v_rcp_f32_e32 v5, v5
	v_rcp_f32_e32 v4, v4
	v_mov_b32_e32 v18, v20
	v_add_f32_e32 v17, 1.0, v17
	v_rcp_f32_e32 v20, v17
	v_mov_b32_e32 v19, v7
	v_mov_b32_e32 v17, v5
	v_pk_fma_f32 v[6:7], v[6:7], v[4:5], v[6:7] neg_lo:[1,0,0] neg_hi:[1,0,0]
	v_pk_fma_f32 v[16:17], v[18:19], v[16:17], v[18:19] neg_lo:[1,0,0] neg_hi:[1,0,0]
	v_fma_f32 v4, -v21, v20, v21
	v_cvt_pk_bf16_f32 v18, v0, v1
	v_cvt_pk_bf16_f32 v19, v6, v7
	v_cvt_pk_bf16_f32 v20, v2, v3
	v_cvt_pk_bf16_f32 v21, v16, v4
	global_store_dwordx4 v[22:23], v[18:21], off offset:256 sc1
	s_cbranch_vccnz .LBB0_218
; __device__ __forceinline__ unsigned cvt_pk_bf16(float lo, float hi) { unsigned r; asm volatile("v_cvt_pk_bf16_f32 %0, %1, %2" : "=v"(r) : "v"(lo), "v"(hi)); return r; }
;     __device__ __forceinline__ void operator()(const f32x4 (&acc)[2][2][4][2], const Unit& u, int wr, int wc, int fr, int fq) const {
;     ...
;                         for (int e = 0; e < 4; ++e) { v0[e] = gelu_tanh(v0[e]); v1[e] = gelu_tanh(v1[e]); s += v0[e] + v1[e]; q += v0[e] * v0[e] + v1[e] * v1[e]; } }
;                     u32x4 w; w.x = cvt_pk_bf16(v0[0], v0[1]); w.y = cvt_pk_bf16(v0[2], v0[3]); w.z = cvt_pk_bf16(v1[0], v1[1]); w.w = cvt_pk_bf16(v1[2], v1[3]);
;                     *(u32x4*)(rowp + bj * HALF) = w; }
;                 if (ACT == 2) { if (u.pn >= 8) { s += __shfl_xor(s, 16); s += __shfl_xor(s, 32); q += __shfl_xor(q, 16); q += __shfl_xor(q, 32);
;                     if (fq == 0) *(f32x2*)(stats + ((size_t)row * 32 + (u.pn - 8) * 4 + wc) * 2) = (f32x2){s, q}; } }
	s_nop 0
	v_pk_mul_f32 v[18:19], v[10:11], v[10:11]
	v_pk_mul_f32 v[20:21], v[14:15], v[14:15]
	v_pk_fma_f32 v[18:19], v[8:9], v[8:9], v[18:19]
	v_pk_fma_f32 v[20:21], v[12:13], v[12:13], v[20:21]
	v_add_f32_e32 v5, v18, v19
	v_pk_mul_f32 v[22:23], v[2:3], v[2:3]
	v_add_f32_e32 v5, v20, v5
	v_pk_fma_f32 v[22:23], v[0:1], v[0:1], v[22:23]
	v_add_f32_e32 v5, v21, v5
	v_pk_add_f32 v[8:9], v[8:9], v[10:11]
	v_add_f32_e32 v18, v22, v5
	v_add_f32_e32 v5, 0, v8
	v_add_f32_e32 v5, v9, v5
	v_pk_add_f32 v[8:9], v[12:13], v[14:15]
	v_pk_add_f32 v[18:19], v[22:23], v[18:19] op_sel_hi:[1,0]
	v_add_f32_e32 v5, v8, v5
	v_mov_b32_e32 v20, v6
	v_mov_b32_e32 v21, v16
	v_mul_f32_e32 v18, v6, v6
	v_add_f32_e32 v5, v9, v5
	v_pk_add_f32 v[0:1], v[0:1], v[2:3]
	v_pk_fma_f32 v[20:21], v[20:21], v[20:21], v[18:19] op_sel_hi:[1,1,0]
	v_pk_add_f32 v[22:23], v[6:7], v[16:17]
	v_pk_mul_f32 v[16:17], v[6:7], v[16:17]
	v_add_f32_e32 v0, v0, v5
	v_mov_b32_e32 v23, v17
	v_mul_f32_e32 v17, v4, v4
	v_add_f32_e32 v16, v1, v0
	v_mov_b32_e32 v20, v7
	v_mov_b32_e32 v5, v19
	v_pk_add_f32 v[0:1], v[22:23], v[16:17]
	v_pk_add_f32 v[2:3], v[20:21], v[4:5]
	s_nop 0
	v_pk_add_f32 v[0:1], v[0:1], v[2:3]
	ds_bpermute_b32 v2, v205, v0
	ds_bpermute_b32 v3, v205, v1
	s_waitcnt lgkmcnt(0)
	v_pk_add_f32 v[0:1], v[0:1], v[2:3]
	ds_bpermute_b32 v2, v206, v0
	ds_bpermute_b32 v3, v206, v1
	s_and_saveexec_b64 s[42:43], s[38:39]
	s_cbranch_execz .LBB0_217
	v_lshlrev_b64 v[4:5], 8, v[180:181]
	s_waitcnt lgkmcnt(0)
	v_pk_add_f32 v[0:1], v[0:1], v[2:3]
	v_lshl_add_u64 v[2:3], s[6:7], 0, v[4:5]
	v_lshl_add_u64 v[2:3], s[36:37], 3, v[2:3]
	global_store_dwordx2 v[2:3], v[0:1], off

;     __device__ __forceinline__ void operator()(const f32x4 (&acc)[2][2][4][2], const Unit& u, int wr, int wc, int fr, int fq) const {
;     ...
;         const int rowt = u.pm * BM, b = rowt >= MLAT ? 2 : (rowt >> 13);
;         const float* gp = gate + b * 6144; const int col0 = u.pn * BM + wc * 32 + 8 * fq;
;         f32x4 gv[2][2], wv[2][2];
; #pragma unroll
;         for (int bj = 0; bj < 2; ++bj)
; #pragma unroll
;             for (int n = 0; n < 2; ++n) { gv[bj][n] = *(const f32x4*)(gp + col0 + bj * HALF + n * 4); if (cs) gv[bj][n] = gv[bj][n] * *(const f32x4*)(cs + col0 + bj * HALF + n * 4);
;                 if (hb) wv[bj][n] = *(const f32x4*)(wn_g + col0 + bj * HALF + n * 4) * (*(const f32x4*)(wn_sc + b * 6144 + col0 + bj * HALF + n * 4) + 1.0f); }
;         const float* bb = base_lat ? (rowt >= MLAT ? base_ctx + (size_t)(rowt - MLAT) * DM : base_lat + (size_t)rowt * DM) : nullptr;
; #pragma unroll
;         for (int ai = 0; ai < 2; ++ai) {
;             u32x4 raw[4][2];
; #pragma unroll
;             for (int m = 0; m < 4; ++m)
; #pragma unroll
;                 for (int bj = 0; bj < 2; ++bj) raw[m][bj] = *(const u32x4*)(h16 + (size_t)rowt * DM + (size_t)(wr * 64 + fr + ai * HALF + m * 16) * DM + col0 + bj * HALF);
; #pragma unroll
;             for (int m = 0; m < 4; ++m) { const int rl = wr * 64 + fr + ai * HALF + m * 16; const size_t off = (size_t)rl * DM + col0; float sq = 0.f;
;                 bf16_t* hrow = h16 + (size_t)rowt * DM + off;
; #pragma unroll
;                 for (int bj = 0; bj < 2; ++bj) { f32x4 b0, b1;
;                     if (bb) { b0 = *(const f32x4*)(bb + off + bj * HALF); b1 = *(const f32x4*)(bb + off + bj * HALF + 4); }
;                     else { const u32x4 r = raw[m][bj];
;                         b0 = (f32x4){__uint_as_float(r.x << 16), __uint_as_float(r.x & 0xffff0000u), __uint_as_float(r.y << 16), __uint_as_float(r.y & 0xffff0000u)};
;                         b1 = (f32x4){__uint_as_float(r.z << 16), __uint_as_float(r.z & 0xffff0000u), __uint_as_float(r.w << 16), __uint_as_float(r.w & 0xffff0000u)}; }
;                     const f32x4 o0 = b0 + gv[bj][0] * acc[ai][bj][m][0], o1 = b1 + gv[bj][1] * acc[ai][bj][m][1];
;                     u32x4 w; w.x = cvt_pk_bf16(o0[0], o0[1]); w.y = cvt_pk_bf16(o0[2], o0[3]); w.z = cvt_pk_bf16(o1[0], o1[1]); w.w = cvt_pk_bf16(o1[2], o1[3]);
.LBB0_467:
	s_min_i32 s1, s40, 64
	s_lshr_b32 s1, s1, 5
	s_mul_i32 s22, s1, 0x1800
	s_ashr_i32 s23, s22, 31
	s_lshl_b32 s42, s40, 8
	s_lshl_b64 s[22:23], s[22:23], 2
	s_add_u32 s40, s62, s22
	s_addc_u32 s41, s63, s23
	s_lshl_b32 s1, s0, 8
	v_mov_b32_e32 v160, v229
	v_mov_b32_e32 v161, v228
	s_or_b32 s1, s1, s70
	s_add_u32 s22, s66, s22
	v_lshl_add_u32 v198, v161, 3, s1
	v_ashrrev_i32_e32 v199, 31, v198
	v_lshlrev_b64 v[56:57], 2, v[198:199]
	v_lshl_add_u64 v[152:153], s[40:41], 0, v[56:57]
	s_addc_u32 s23, s67, s23
	v_lshl_add_u64 v[154:155], s[6:7], 0, v[56:57]
	v_lshl_add_u64 v[156:157], s[22:23], 0, v[56:57]
	global_load_dwordx4 v[64:67], v[152:153], off offset:16
	global_load_dwordx4 v[68:71], v[152:153], off
	global_load_dwordx4 v[56:59], v[154:155], off offset:16
	global_load_dwordx4 v[60:63], v[154:155], off
	global_load_dwordx4 v[144:147], v[156:157], off offset:16
	global_load_dwordx4 v[148:151], v[156:157], off
	s_ashr_i32 s43, s42, 31
	s_lshl_b64 s[40:41], s[42:43], 11
	v_add_u32_e32 v200, s69, v160
	s_add_u32 s22, s31, s40
	s_addc_u32 s23, s61, s41
	v_ashrrev_i32_e32 v201, 31, v200
	v_add_u32_e32 v220, 16, v200
	v_lshl_add_u64 v[202:203], v[198:199], 1, s[22:23]
	v_ashrrev_i32_e32 v221, 31, v220
	v_add_u32_e32 v208, 32, v200
	v_ashrrev_i32_e32 v209, 31, v208
	v_add_u32_e32 v204, 48, v200
	v_ashrrev_i32_e32 v205, 31, v204
	v_lshlrev_b64 v[216:217], 10, v[200:201]
	v_cmp_eq_u32_e32 vcc, 0, v161
	v_lshl_add_u64 v[226:227], v[216:217], 0, v[198:199]
	s_add_u32 s44, s64, s40
	s_addc_u32 s45, s65, s41
	s_waitcnt vmcnt(0)
	v_pk_add_f32 v[150:151], v[150:151], 1.0 op_sel_hi:[1,0]
	v_pk_add_f32 v[148:149], v[148:149], 1.0 op_sel_hi:[1,0]
	v_pk_mul_f32 v[192:193], v[62:63], v[150:151]
	v_pk_mul_f32 v[196:197], v[60:61], v[148:149]
	v_pk_add_f32 v[60:61], v[146:147], 1.0 op_sel_hi:[1,0]
	v_pk_add_f32 v[62:63], v[144:145], 1.0 op_sel_hi:[1,0]
	v_pk_mul_f32 v[190:191], v[58:59], v[60:61]
	v_pk_mul_f32 v[194:195], v[56:57], v[62:63]
	global_load_dwordx4 v[56:59], v[152:153], off offset:528
	global_load_dwordx4 v[60:63], v[152:153], off offset:512
	global_load_dwordx4 v[144:147], v[154:155], off offset:528
	global_load_dwordx4 v[148:151], v[154:155], off offset:512
	s_nop 0
	global_load_dwordx4 v[152:155], v[156:157], off offset:528
	s_nop 0
	global_load_dwordx4 v[156:159], v[156:157], off offset:512
	s_waitcnt vmcnt(0)
	v_pk_add_f32 v[158:159], v[158:159], 1.0 op_sel_hi:[1,0]
	s_nop 0
	v_pk_mul_f32 v[188:189], v[150:151], v[158:159]
	v_pk_add_f32 v[150:151], v[152:153], 1.0 op_sel_hi:[1,0]
	v_pk_add_f32 v[156:157], v[156:157], 1.0 op_sel_hi:[1,0]
	v_pk_mul_f32 v[186:187], v[144:145], v[150:151]
	v_lshlrev_b64 v[144:145], 11, v[200:201]
	v_lshl_add_u64 v[224:225], v[202:203], 0, v[144:145]
	v_lshlrev_b64 v[144:145], 11, v[220:221]
	v_lshl_add_u64 v[222:223], v[202:203], 0, v[144:145]
	v_lshlrev_b64 v[144:145], 11, v[208:209]
	v_lshl_add_u64 v[210:211], v[202:203], 0, v[144:145]
	v_lshlrev_b64 v[144:145], 11, v[204:205]
	v_pk_mul_f32 v[182:183], v[148:149], v[156:157]
	v_pk_add_f32 v[148:149], v[154:155], 1.0 op_sel_hi:[1,0]
	v_lshl_add_u64 v[206:207], v[202:203], 0, v[144:145]
	v_pk_mul_f32 v[184:185], v[146:147], v[148:149]
	global_load_dwordx4 v[168:171], v[224:225], off offset:256
	global_load_dwordx4 v[164:167], v[222:223], off
	global_load_dwordx4 v[160:163], v[222:223], off offset:256
	global_load_dwordx4 v[156:159], v[210:211], off
	global_load_dwordx4 v[152:155], v[210:211], off offset:256
	global_load_dwordx4 v[148:151], v[206:207], off
	global_load_dwordx4 v[144:147], v[206:207], off offset:256
	global_load_dwordx4 v[216:219], v[224:225], off
	s_waitcnt vmcnt(0)
	v_lshlrev_b32_e32 v232, 16, v216
	v_and_b32_e32 v233, 0xffff0000, v216
	v_lshlrev_b32_e32 v216, 16, v217
	v_and_b32_e32 v217, 0xffff0000, v217
	v_lshlrev_b32_e32 v234, 16, v218
	v_and_b32_e32 v235, 0xffff0000, v218
	v_lshlrev_b32_e32 v218, 16, v219
	v_and_b32_e32 v219, 0xffff0000, v219
	v_pk_fma_f32 v[142:143], v[142:143], v[70:71], v[216:217]
	v_pk_fma_f32 v[140:141], v[140:141], v[68:69], v[232:233]
	v_pk_fma_f32 v[216:217], v[138:139], v[66:67], v[218:219]
	v_pk_fma_f32 v[218:219], v[136:137], v[64:65], v[234:235]
	v_cvt_pk_bf16_f32 v136, v140, v141
	v_cvt_pk_bf16_f32 v137, v142, v143
	s_nop 0
	v_cvt_pk_bf16_f32 v138, v218, v219
	v_cvt_pk_bf16_f32 v139, v216, v217
	global_store_dwordx4 v[224:225], v[136:139], off sc1
	s_nop 1
	v_mul_f32_e32 v136, v141, v141
	v_mul_f32_e32 v137, v143, v143
	v_fmac_f32_e32 v136, v140, v140
	v_fmac_f32_e32 v137, v142, v142
	v_add_f32_e32 v136, v136, v137
	v_mul_f32_e32 v137, v219, v219
	v_mul_f32_e32 v138, v217, v217
	v_fmac_f32_e32 v137, v218, v218
	v_fmac_f32_e32 v138, v216, v216
	v_add_f32_e32 v137, v137, v138
	v_add_f32_e32 v201, v136, v137
	v_pk_mul_f32 v[138:139], v[192:193], v[142:143]
	v_pk_mul_f32 v[136:137], v[196:197], v[140:141]
	v_pk_mul_f32 v[140:141], v[190:191], v[216:217]
	v_pk_mul_f32 v[142:143], v[194:195], v[218:219]
	v_cvt_pk_bf16_f32 v136, v136, v137
	v_cvt_pk_bf16_f32 v137, v138, v139
	s_nop 0
	v_cvt_pk_bf16_f32 v138, v142, v143
	v_cvt_pk_bf16_f32 v139, v140, v141
	v_lshl_add_u64 v[140:141], v[226:227], 1, s[44:45]
	global_store_dwordx4 v[140:141], v[136:139], off sc1
	v_lshlrev_b32_e32 v142, 16, v170
	v_and_b32_e32 v143, 0xffff0000, v170
	v_lshlrev_b32_e32 v136, 16, v168
	v_and_b32_e32 v137, 0xffff0000, v168
	v_lshlrev_b32_e32 v138, 16, v169
	v_and_b32_e32 v139, 0xffff0000, v169
	v_lshlrev_b32_e32 v168, 16, v171
	v_and_b32_e32 v169, 0xffff0000, v171
	v_pk_fma_f32 v[134:135], v[134:135], v[62:63], v[138:139]
	v_pk_fma_f32 v[132:133], v[132:133], v[60:61], v[136:137]
	v_pk_fma_f32 v[138:139], v[128:129], v[56:57], v[142:143]
; __device__ __forceinline__ unsigned cvt_pk_bf16(float lo, float hi) { unsigned r; asm volatile("v_cvt_pk_bf16_f32 %0, %1, %2" : "=v"(r) : "v"(lo), "v"(hi)); return r; }
;     __device__ __forceinline__ void operator()(const f32x4 (&acc)[2][2][4][2], const Unit& u, int wr, int wc, int fr, int fq) const {
;     ...
;             for (int m = 0; m < 4; ++m) { const int rl = wr * 64 + fr + ai * HALF + m * 16; const size_t off = (size_t)rl * DM + col0; float sq = 0.f;
;                 bf16_t* hrow = h16 + (size_t)rowt * DM + off;
; #pragma unroll
;                 for (int bj = 0; bj < 2; ++bj) { f32x4 b0, b1;
;                     if (bb) { b0 = *(const f32x4*)(bb + off + bj * HALF); b1 = *(const f32x4*)(bb + off + bj * HALF + 4); }
;                     else { const u32x4 r = raw[m][bj];
;                         b0 = (f32x4){__uint_as_float(r.x << 16), __uint_as_float(r.x & 0xffff0000u), __uint_as_float(r.y << 16), __uint_as_float(r.y & 0xffff0000u)};
;                         b1 = (f32x4){__uint_as_float(r.z << 16), __uint_as_float(r.z & 0xffff0000u), __uint_as_float(r.w << 16), __uint_as_float(r.w & 0xffff0000u)}; }
;                     const f32x4 o0 = b0 + gv[bj][0] * acc[ai][bj][m][0], o1 = b1 + gv[bj][1] * acc[ai][bj][m][1];
;                     u32x4 w; w.x = cvt_pk_bf16(o0[0], o0[1]); w.y = cvt_pk_bf16(o0[2], o0[3]); w.z = cvt_pk_bf16(o1[0], o1[1]); w.w = cvt_pk_bf16(o1[2], o1[3]);
;                     *(u32x4*)(hrow + bj * HALF) = w;
;                     sq += ((o0[0] * o0[0] + o0[1] * o0[1]) + (o0[2] * o0[2] + o0[3] * o0[3])) + ((o1[0] * o1[0] + o1[1] * o1[1]) + (o1[2] * o1[2] + o1[3] * o1[3]));
;                     if (hb) { const f32x4 y0 = o0 * wv[bj][0], y1 = o1 * wv[bj][1]; u32x4 z; z.x = cvt_pk_bf16(y0[0], y0[1]); z.y = cvt_pk_bf16(y0[2], y0[3]); z.z = cvt_pk_bf16(y1[0], y1[1]); z.w = cvt_pk_bf16(y1[2], y1[3]);
;                         *(u32x4*)(hb + (size_t)rowt * DM + off + bj * HALF) = z; } }
;                 if (ssq) { sq += __shfl_xor(sq, 16); sq += __shfl_xor(sq, 32); if (fq == 0) ssq[(size_t)(rowt + rl) * 16 + u.pn * 4 + wc] = sq; } }
	v_cvt_pk_bf16_f32 v128, v132, v133
	v_cvt_pk_bf16_f32 v129, v134, v135
	v_pk_fma_f32 v[136:137], v[130:131], v[58:59], v[168:169]
	v_cvt_pk_bf16_f32 v130, v138, v139
	s_nop 0
	v_cvt_pk_bf16_f32 v131, v136, v137
	global_store_dwordx4 v[224:225], v[128:131], off offset:256 sc1
	s_nop 1
	v_mul_f32_e32 v128, v133, v133
	v_mul_f32_e32 v129, v135, v135
	v_fmac_f32_e32 v128, v132, v132
	v_fmac_f32_e32 v129, v134, v134
	v_add_f32_e32 v128, v128, v129
	v_mul_f32_e32 v129, v139, v139
	v_mul_f32_e32 v130, v137, v137
	v_fmac_f32_e32 v129, v138, v138
	v_fmac_f32_e32 v130, v136, v136
	v_add_f32_e32 v129, v129, v130
	v_add_f32_e32 v128, v128, v129
	v_add_f32_e32 v142, v128, v201
	v_pk_mul_f32 v[128:129], v[182:183], v[132:133]
	v_pk_mul_f32 v[130:131], v[188:189], v[134:135]
	v_cvt_pk_bf16_f32 v128, v128, v129
	v_pk_mul_f32 v[132:133], v[184:185], v[136:137]
	v_cvt_pk_bf16_f32 v129, v130, v131
	v_pk_mul_f32 v[134:135], v[186:187], v[138:139]
	s_nop 0
	v_cvt_pk_bf16_f32 v130, v134, v135
	v_cvt_pk_bf16_f32 v131, v132, v133
	global_store_dwordx4 v[140:141], v[128:131], off offset:256 sc1
	s_nop 1
	v_and_b32_e32 v129, 64, v246
	v_xor_b32_e32 v128, 16, v246
	v_add_u32_e32 v129, 64, v129
	v_cmp_lt_i32_e64 s[40:41], v128, v129
	v_xor_b32_e32 v131, 32, v246
	s_nop 0
	v_cndmask_b32_e64 v128, v246, v128, s[40:41]
	v_lshlrev_b32_e32 v128, 2, v128
	ds_bpermute_b32 v130, v128, v142
	v_cmp_lt_i32_e64 s[40:41], v131, v129
	s_waitcnt lgkmcnt(0)
	v_add_f32_e32 v130, v142, v130
	v_cndmask_b32_e64 v129, v246, v131, s[40:41]
	v_lshlrev_b32_e32 v129, 2, v129
	ds_bpermute_b32 v131, v129, v130
	s_and_saveexec_b64 s[40:41], vcc
	s_cbranch_execz .LBB0_469
	s_waitcnt lgkmcnt(0)
	v_add_f32_e32 v132, v130, v131
	v_add_u32_e32 v130, s42, v200
	v_ashrrev_i32_e32 v131, 31, v130
	s_lshl_b32 s22, s0, 2
	v_lshlrev_b64 v[130:131], 6, v[130:131]
	s_ashr_i32 s23, s22, 31
	v_lshl_add_u64 v[130:131], s[12:13], 0, v[130:131]
	v_lshl_add_u64 v[130:131], s[22:23], 2, v[130:131]
	s_lshl_b32 s8, s68, 2
	v_lshl_add_u64 v[130:131], v[130:131], 0, s[8:9]
	global_store_dword v[130:131], v132, off
.LBB0_469:
	s_or_b64 exec, exec, s[40:41]
	v_lshlrev_b32_e32 v132, 16, v164
	v_and_b32_e32 v133, 0xffff0000, v164
	v_lshlrev_b32_e32 v134, 16, v165
	v_and_b32_e32 v135, 0xffff0000, v165
	v_lshlrev_b32_e32 v136, 16, v166
	v_and_b32_e32 v137, 0xffff0000, v166
	v_lshlrev_b32_e32 v138, 16, v167
	v_and_b32_e32 v139, 0xffff0000, v167
	v_pk_fma_f32 v[126:127], v[126:127], v[70:71], v[134:135]
	v_pk_fma_f32 v[124:125], v[124:125], v[68:69], v[132:133]
	v_pk_fma_f32 v[134:135], v[120:121], v[64:65], v[136:137]
	v_cvt_pk_bf16_f32 v120, v124, v125
	v_cvt_pk_bf16_f32 v121, v126, v127
	v_pk_fma_f32 v[132:133], v[122:123], v[66:67], v[138:139]
	v_cvt_pk_bf16_f32 v122, v134, v135
	s_waitcnt lgkmcnt(0)
	v_lshlrev_b64 v[130:131], 10, v[220:221]
	v_cvt_pk_bf16_f32 v123, v132, v133
	global_store_dwordx4 v[222:223], v[120:123], off sc1
	v_lshl_add_u64 v[130:131], v[130:131], 0, v[198:199]
	s_nop 0
	v_mul_f32_e32 v120, v125, v125
	v_mul_f32_e32 v121, v127, v127
	v_fmac_f32_e32 v120, v124, v124
	v_fmac_f32_e32 v121, v126, v126
	v_add_f32_e32 v120, v120, v121
	v_mul_f32_e32 v121, v135, v135
	v_mul_f32_e32 v122, v133, v133
	v_fmac_f32_e32 v121, v134, v134
	v_fmac_f32_e32 v122, v132, v132
	v_add_f32_e32 v121, v121, v122
	v_add_f32_e32 v136, v120, v121
	v_pk_mul_f32 v[122:123], v[192:193], v[126:127]
	v_pk_mul_f32 v[120:121], v[196:197], v[124:125]
	v_pk_mul_f32 v[124:125], v[190:191], v[132:133]
	v_pk_mul_f32 v[126:127], v[194:195], v[134:135]
	v_cvt_pk_bf16_f32 v120, v120, v121
	v_cvt_pk_bf16_f32 v121, v122, v123
	s_nop 0
	v_cvt_pk_bf16_f32 v122, v126, v127
	v_cvt_pk_bf16_f32 v123, v124, v125
	v_lshl_add_u64 v[124:125], v[130:131], 1, s[44:45]
	global_store_dwordx4 v[124:125], v[120:123], off sc1
	v_lshlrev_b32_e32 v126, 16, v162
	v_and_b32_e32 v127, 0xffff0000, v162
	v_lshlrev_b32_e32 v120, 16, v160
	v_and_b32_e32 v121, 0xffff0000, v160
	v_lshlrev_b32_e32 v122, 16, v161
	v_and_b32_e32 v123, 0xffff0000, v161
	v_lshlrev_b32_e32 v130, 16, v163
	v_and_b32_e32 v131, 0xffff0000, v163
	v_pk_fma_f32 v[118:119], v[118:119], v[62:63], v[122:123]
	v_pk_fma_f32 v[116:117], v[116:117], v[60:61], v[120:121]
	v_pk_fma_f32 v[122:123], v[112:113], v[56:57], v[126:127]
	v_cvt_pk_bf16_f32 v112, v116, v117
	v_cvt_pk_bf16_f32 v113, v118, v119
	v_pk_fma_f32 v[120:121], v[114:115], v[58:59], v[130:131]
	v_cvt_pk_bf16_f32 v114, v122, v123
	s_nop 0
	v_cvt_pk_bf16_f32 v115, v120, v121
	global_store_dwordx4 v[222:223], v[112:115], off offset:256 sc1
	s_nop 1
	v_mul_f32_e32 v112, v117, v117
	v_mul_f32_e32 v113, v119, v119
	v_fmac_f32_e32 v112, v116, v116
	v_fmac_f32_e32 v113, v118, v118
	v_add_f32_e32 v112, v112, v113
	v_mul_f32_e32 v113, v123, v123
	v_mul_f32_e32 v114, v121, v121
	v_fmac_f32_e32 v113, v122, v122
	v_fmac_f32_e32 v114, v120, v120
	v_add_f32_e32 v113, v113, v114
	v_add_f32_e32 v112, v112, v113
	v_add_f32_e32 v115, v136, v112
	ds_bpermute_b32 v126, v128, v115
	v_pk_mul_f32 v[112:113], v[182:183], v[116:117]
	v_pk_mul_f32 v[116:117], v[186:187], v[122:123]
	v_cvt_pk_bf16_f32 v114, v112, v113
	v_pk_mul_f32 v[118:119], v[188:189], v[118:119]
	s_waitcnt lgkmcnt(0)
	v_add_f32_e32 v112, v115, v126
	ds_bpermute_b32 v113, v129, v112
	v_pk_mul_f32 v[120:121], v[184:185], v[120:121]
	v_cvt_pk_bf16_f32 v115, v118, v119
	v_cvt_pk_bf16_f32 v116, v116, v117
	s_nop 0
	v_cvt_pk_bf16_f32 v117, v120, v121
	global_store_dwordx4 v[124:125], v[114:117], off offset:256 sc1
	s_and_saveexec_b64 s[40:41], vcc
	s_cbranch_execz .LBB0_471
	s_waitcnt lgkmcnt(0)
	v_add_f32_e32 v114, v112, v113
	v_add_u32_e32 v112, s42, v220
	v_ashrrev_i32_e32 v113, 31, v112
	s_lshl_b32 s22, s0, 2
	v_lshlrev_b64 v[112:113], 6, v[112:113]
	s_ashr_i32 s23, s22, 31
	v_lshl_add_u64 v[112:113], s[12:13], 0, v[112:113]
	v_lshl_add_u64 v[112:113], s[22:23], 2, v[112:113]
	s_lshl_b32 s8, s68, 2
	v_lshl_add_u64 v[112:113], v[112:113], 0, s[8:9]
	global_store_dword v[112:113], v114, off
; __device__ __forceinline__ unsigned cvt_pk_bf16(float lo, float hi) { unsigned r; asm volatile("v_cvt_pk_bf16_f32 %0, %1, %2" : "=v"(r) : "v"(lo), "v"(hi)); return r; }
;     __device__ __forceinline__ void operator()(const f32x4 (&acc)[2][2][4][2], const Unit& u, int wr, int wc, int fr, int fq) const {
;     ...
;             for (int m = 0; m < 4; ++m) { const int rl = wr * 64 + fr + ai * HALF + m * 16; const size_t off = (size_t)rl * DM + col0; float sq = 0.f;
;                 bf16_t* hrow = h16 + (size_t)rowt * DM + off;
; #pragma unroll
;                 for (int bj = 0; bj < 2; ++bj) { f32x4 b0, b1;
;                     if (bb) { b0 = *(const f32x4*)(bb + off + bj * HALF); b1 = *(const f32x4*)(bb + off + bj * HALF + 4); }
;                     else { const u32x4 r = raw[m][bj];
;                         b0 = (f32x4){__uint_as_float(r.x << 16), __uint_as_float(r.x & 0xffff0000u), __uint_as_float(r.y << 16), __uint_as_float(r.y & 0xffff0000u)};
;                         b1 = (f32x4){__uint_as_float(r.z << 16), __uint_as_float(r.z & 0xffff0000u), __uint_as_float(r.w << 16), __uint_as_float(r.w & 0xffff0000u)}; }
;                     const f32x4 o0 = b0 + gv[bj][0] * acc[ai][bj][m][0], o1 = b1 + gv[bj][1] * acc[ai][bj][m][1];
;                     u32x4 w; w.x = cvt_pk_bf16(o0[0], o0[1]); w.y = cvt_pk_bf16(o0[2], o0[3]); w.z = cvt_pk_bf16(o1[0], o1[1]); w.w = cvt_pk_bf16(o1[2], o1[3]);
;                     *(u32x4*)(hrow + bj * HALF) = w;
;                     sq += ((o0[0] * o0[0] + o0[1] * o0[1]) + (o0[2] * o0[2] + o0[3] * o0[3])) + ((o1[0] * o1[0] + o1[1] * o1[1]) + (o1[2] * o1[2] + o1[3] * o1[3]));
;                     if (hb) { const f32x4 y0 = o0 * wv[bj][0], y1 = o1 * wv[bj][1]; u32x4 z; z.x = cvt_pk_bf16(y0[0], y0[1]); z.y = cvt_pk_bf16(y0[2], y0[3]); z.z = cvt_pk_bf16(y1[0], y1[1]); z.w = cvt_pk_bf16(y1[2], y1[3]);
;                         *(u32x4*)(hb + (size_t)rowt * DM + off + bj * HALF) = z; } }
;                 if (ssq) { sq += __shfl_xor(sq, 16); sq += __shfl_xor(sq, 32); if (fq == 0) ssq[(size_t)(rowt + rl) * 16 + u.pn * 4 + wc] = sq; } }
.LBB0_471:
	s_or_b64 exec, exec, s[40:41]
	v_lshlrev_b32_e32 v114, 16, v156
	v_and_b32_e32 v115, 0xffff0000, v156
	v_lshlrev_b32_e32 v116, 16, v157
	v_and_b32_e32 v117, 0xffff0000, v157
	v_lshlrev_b32_e32 v118, 16, v158
	v_and_b32_e32 v119, 0xffff0000, v158
	v_lshlrev_b32_e32 v120, 16, v159
	v_and_b32_e32 v121, 0xffff0000, v159
	v_pk_fma_f32 v[110:111], v[110:111], v[70:71], v[116:117]
	v_pk_fma_f32 v[108:109], v[108:109], v[68:69], v[114:115]
	v_pk_fma_f32 v[116:117], v[104:105], v[64:65], v[118:119]
	v_cvt_pk_bf16_f32 v104, v108, v109
	v_cvt_pk_bf16_f32 v105, v110, v111
	v_pk_fma_f32 v[114:115], v[106:107], v[66:67], v[120:121]
	v_cvt_pk_bf16_f32 v106, v116, v117
	s_waitcnt lgkmcnt(0)
	v_lshlrev_b64 v[112:113], 10, v[208:209]
	v_cvt_pk_bf16_f32 v107, v114, v115
	global_store_dwordx4 v[210:211], v[104:107], off sc1
	v_lshl_add_u64 v[112:113], v[112:113], 0, v[198:199]
	s_nop 0
	v_mul_f32_e32 v104, v109, v109
	v_mul_f32_e32 v105, v111, v111
	v_fmac_f32_e32 v104, v108, v108
	v_fmac_f32_e32 v105, v110, v110
	v_add_f32_e32 v104, v104, v105
	v_mul_f32_e32 v105, v117, v117
	v_mul_f32_e32 v106, v115, v115
	v_fmac_f32_e32 v105, v116, v116
	v_fmac_f32_e32 v106, v114, v114
	v_add_f32_e32 v105, v105, v106
	v_add_f32_e32 v118, v104, v105
	v_pk_mul_f32 v[106:107], v[192:193], v[110:111]
	v_pk_mul_f32 v[104:105], v[196:197], v[108:109]
	v_pk_mul_f32 v[108:109], v[190:191], v[114:115]
	v_pk_mul_f32 v[110:111], v[194:195], v[116:117]
	v_cvt_pk_bf16_f32 v104, v104, v105
	v_cvt_pk_bf16_f32 v105, v106, v107
	s_nop 0
	v_cvt_pk_bf16_f32 v106, v110, v111
	v_cvt_pk_bf16_f32 v107, v108, v109
	v_lshl_add_u64 v[108:109], v[112:113], 1, s[44:45]
	global_store_dwordx4 v[108:109], v[104:107], off sc1
	v_lshlrev_b32_e32 v110, 16, v154
	v_and_b32_e32 v111, 0xffff0000, v154
	v_lshlrev_b32_e32 v104, 16, v152
	v_and_b32_e32 v105, 0xffff0000, v152
	v_lshlrev_b32_e32 v106, 16, v153
	v_and_b32_e32 v107, 0xffff0000, v153
	v_lshlrev_b32_e32 v112, 16, v155
	v_and_b32_e32 v113, 0xffff0000, v155
	v_pk_fma_f32 v[102:103], v[102:103], v[62:63], v[106:107]
	v_pk_fma_f32 v[100:101], v[100:101], v[60:61], v[104:105]
	v_pk_fma_f32 v[106:107], v[96:97], v[56:57], v[110:111]
	v_cvt_pk_bf16_f32 v96, v100, v101
	v_cvt_pk_bf16_f32 v97, v102, v103
	v_pk_fma_f32 v[104:105], v[98:99], v[58:59], v[112:113]
	v_cvt_pk_bf16_f32 v98, v106, v107
	s_nop 0
	v_cvt_pk_bf16_f32 v99, v104, v105
	global_store_dwordx4 v[210:211], v[96:99], off offset:256 sc1
	s_nop 1
	v_mul_f32_e32 v96, v101, v101
	v_mul_f32_e32 v97, v103, v103
	v_fmac_f32_e32 v96, v100, v100
	v_fmac_f32_e32 v97, v102, v102
	v_add_f32_e32 v96, v96, v97
	v_mul_f32_e32 v97, v107, v107
	v_mul_f32_e32 v98, v105, v105
	v_fmac_f32_e32 v97, v106, v106
	v_fmac_f32_e32 v98, v104, v104
	v_add_f32_e32 v97, v97, v98
	v_add_f32_e32 v96, v96, v97
	v_add_f32_e32 v99, v118, v96
	ds_bpermute_b32 v110, v128, v99
	v_pk_mul_f32 v[96:97], v[182:183], v[100:101]
	v_pk_mul_f32 v[100:101], v[186:187], v[106:107]
	v_cvt_pk_bf16_f32 v98, v96, v97
	v_pk_mul_f32 v[102:103], v[188:189], v[102:103]
	s_waitcnt lgkmcnt(0)
	v_add_f32_e32 v96, v99, v110
	ds_bpermute_b32 v97, v129, v96
	v_pk_mul_f32 v[104:105], v[184:185], v[104:105]
	v_cvt_pk_bf16_f32 v99, v102, v103
	v_cvt_pk_bf16_f32 v100, v100, v101
	s_nop 0
	v_cvt_pk_bf16_f32 v101, v104, v105
	global_store_dwordx4 v[108:109], v[98:101], off offset:256 sc1
	s_and_saveexec_b64 s[40:41], vcc
	s_cbranch_execz .LBB0_473
	s_waitcnt lgkmcnt(0)
	v_add_f32_e32 v98, v96, v97
	v_add_u32_e32 v96, s42, v208
	v_ashrrev_i32_e32 v97, 31, v96
	s_lshl_b32 s22, s0, 2
	v_lshlrev_b64 v[96:97], 6, v[96:97]
	s_ashr_i32 s23, s22, 31
	v_lshl_add_u64 v[96:97], s[12:13], 0, v[96:97]
	v_lshl_add_u64 v[96:97], s[22:23], 2, v[96:97]
	s_lshl_b32 s8, s68, 2
	v_lshl_add_u64 v[96:97], v[96:97], 0, s[8:9]
	global_store_dword v[96:97], v98, off
.LBB0_473:
	s_or_b64 exec, exec, s[40:41]
	v_lshlrev_b32_e32 v98, 16, v148
	v_and_b32_e32 v99, 0xffff0000, v148
	v_lshlrev_b32_e32 v100, 16, v149
	v_and_b32_e32 v101, 0xffff0000, v149
	v_lshlrev_b32_e32 v102, 16, v150
	v_and_b32_e32 v103, 0xffff0000, v150
	v_lshlrev_b32_e32 v104, 16, v151
	v_and_b32_e32 v105, 0xffff0000, v151
	v_pk_fma_f32 v[94:95], v[94:95], v[70:71], v[100:101]
	v_pk_fma_f32 v[92:93], v[92:93], v[68:69], v[98:99]
	v_pk_fma_f32 v[100:101], v[88:89], v[64:65], v[102:103]
	v_cvt_pk_bf16_f32 v88, v92, v93
	v_cvt_pk_bf16_f32 v89, v94, v95
	v_pk_fma_f32 v[98:99], v[90:91], v[66:67], v[104:105]
	v_cvt_pk_bf16_f32 v90, v100, v101
	s_waitcnt lgkmcnt(0)
	v_lshlrev_b64 v[96:97], 10, v[204:205]
	v_cvt_pk_bf16_f32 v91, v98, v99
	global_store_dwordx4 v[206:207], v[88:91], off sc1
	v_lshl_add_u64 v[96:97], v[96:97], 0, v[198:199]
	s_nop 0
	v_mul_f32_e32 v88, v93, v93
	v_mul_f32_e32 v89, v95, v95
	v_fmac_f32_e32 v88, v92, v92
	v_fmac_f32_e32 v89, v94, v94
	v_add_f32_e32 v88, v88, v89
	v_mul_f32_e32 v89, v101, v101
	v_mul_f32_e32 v90, v99, v99
	v_fmac_f32_e32 v89, v100, v100
	v_fmac_f32_e32 v90, v98, v98
	v_add_f32_e32 v89, v89, v90
	v_add_f32_e32 v102, v88, v89
	v_pk_mul_f32 v[90:91], v[192:193], v[94:95]
	v_pk_mul_f32 v[88:89], v[196:197], v[92:93]
	v_pk_mul_f32 v[92:93], v[190:191], v[98:99]
	v_pk_mul_f32 v[94:95], v[194:195], v[100:101]
	v_cvt_pk_bf16_f32 v88, v88, v89
	v_cvt_pk_bf16_f32 v89, v90, v91
	s_nop 0
	v_cvt_pk_bf16_f32 v90, v94, v95
	v_cvt_pk_bf16_f32 v91, v92, v93
	v_lshl_add_u64 v[92:93], v[96:97], 1, s[44:45]
	global_store_dwordx4 v[92:93], v[88:91], off sc1
	v_lshlrev_b32_e32 v94, 16, v146
	v_and_b32_e32 v95, 0xffff0000, v146
	v_lshlrev_b32_e32 v88, 16, v144
	v_and_b32_e32 v89, 0xffff0000, v144
	v_lshlrev_b32_e32 v90, 16, v145
	v_and_b32_e32 v91, 0xffff0000, v145
	v_lshlrev_b32_e32 v96, 16, v147
	v_and_b32_e32 v97, 0xffff0000, v147
	v_pk_fma_f32 v[86:87], v[86:87], v[62:63], v[90:91]
	v_pk_fma_f32 v[84:85], v[84:85], v[60:61], v[88:89]
	v_pk_fma_f32 v[90:91], v[80:81], v[56:57], v[94:95]
	v_cvt_pk_bf16_f32 v80, v84, v85
	v_cvt_pk_bf16_f32 v81, v86, v87
	v_pk_fma_f32 v[88:89], v[82:83], v[58:59], v[96:97]
	v_cvt_pk_bf16_f32 v82, v90, v91
	s_nop 0
	v_cvt_pk_bf16_f32 v83, v88, v89
	global_store_dwordx4 v[206:207], v[80:83], off offset:256 sc1
	s_nop 1
	v_mul_f32_e32 v80, v85, v85
	v_mul_f32_e32 v81, v87, v87
	v_fmac_f32_e32 v80, v84, v84
	v_fmac_f32_e32 v81, v86, v86
	v_add_f32_e32 v80, v80, v81
	v_mul_f32_e32 v81, v91, v91
	v_mul_f32_e32 v82, v89, v89
	v_fmac_f32_e32 v81, v90, v90
	v_fmac_f32_e32 v82, v88, v88
	v_add_f32_e32 v81, v81, v82
	v_add_f32_e32 v80, v80, v81
	v_add_f32_e32 v83, v102, v80
	ds_bpermute_b32 v94, v128, v83
	v_pk_mul_f32 v[80:81], v[182:183], v[84:85]
	v_pk_mul_f32 v[84:85], v[186:187], v[90:91]
	v_cvt_pk_bf16_f32 v82, v80, v81
	v_pk_mul_f32 v[86:87], v[188:189], v[86:87]
	s_waitcnt lgkmcnt(0)
	v_add_f32_e32 v80, v83, v94
	ds_bpermute_b32 v81, v129, v80
	v_pk_mul_f32 v[88:89], v[184:185], v[88:89]
	v_cvt_pk_bf16_f32 v83, v86, v87
	v_cvt_pk_bf16_f32 v84, v84, v85
	s_nop 0
	v_cvt_pk_bf16_f32 v85, v88, v89
	global_store_dwordx4 v[92:93], v[82:85], off offset:256 sc1
	s_and_saveexec_b64 s[40:41], vcc
	s_cbranch_execz .LBB0_475
;     __device__ __forceinline__ void operator()(const f32x4 (&acc)[2][2][4][2], const Unit& u, int wr, int wc, int fr, int fq) const {
;     ...
;         for (int ai = 0; ai < 2; ++ai) {
;             u32x4 raw[4][2];
; #pragma unroll
;             for (int m = 0; m < 4; ++m)
; #pragma unroll
;                 for (int bj = 0; bj < 2; ++bj) raw[m][bj] = *(const u32x4*)(h16 + (size_t)rowt * DM + (size_t)(wr * 64 + fr + ai * HALF + m * 16) * DM + col0 + bj * HALF);
; #pragma unroll
;             for (int m = 0; m < 4; ++m) { const int rl = wr * 64 + fr + ai * HALF + m * 16; const size_t off = (size_t)rl * DM + col0; float sq = 0.f;
;                 bf16_t* hrow = h16 + (size_t)rowt * DM + off;
; #pragma unroll
;                 for (int bj = 0; bj < 2; ++bj) { f32x4 b0, b1;
;                     if (bb) { b0 = *(const f32x4*)(bb + off + bj * HALF); b1 = *(const f32x4*)(bb + off + bj * HALF + 4); }
;                     else { const u32x4 r = raw[m][bj];
;                         b0 = (f32x4){__uint_as_float(r.x << 16), __uint_as_float(r.x & 0xffff0000u), __uint_as_float(r.y << 16), __uint_as_float(r.y & 0xffff0000u)};
;                         b1 = (f32x4){__uint_as_float(r.z << 16), __uint_as_float(r.z & 0xffff0000u), __uint_as_float(r.w << 16), __uint_as_float(r.w & 0xffff0000u)}; }
;                     const f32x4 o0 = b0 + gv[bj][0] * acc[ai][bj][m][0], o1 = b1 + gv[bj][1] * acc[ai][bj][m][1];
;                     u32x4 w; w.x = cvt_pk_bf16(o0[0], o0[1]); w.y = cvt_pk_bf16(o0[2], o0[3]); w.z = cvt_pk_bf16(o1[0], o1[1]); w.w = cvt_pk_bf16(o1[2], o1[3]);
;                     *(u32x4*)(hrow + bj * HALF) = w;
;                     sq += ((o0[0] * o0[0] + o0[1] * o0[1]) + (o0[2] * o0[2] + o0[3] * o0[3])) + ((o1[0] * o1[0] + o1[1] * o1[1]) + (o1[2] * o1[2] + o1[3] * o1[3]));
;                     if (hb) { const f32x4 y0 = o0 * wv[bj][0], y1 = o1 * wv[bj][1]; u32x4 z; z.x = cvt_pk_bf16(y0[0], y0[1]); z.y = cvt_pk_bf16(y0[2], y0[3]); z.z = cvt_pk_bf16(y1[0], y1[1]); z.w = cvt_pk_bf16(y1[2], y1[3]);
;                         *(u32x4*)(hb + (size_t)rowt * DM + off + bj * HALF) = z; } }
;                 if (ssq) { sq += __shfl_xor(sq, 16); sq += __shfl_xor(sq, 32); if (fq == 0) ssq[(size_t)(rowt + rl) * 16 + u.pn * 4 + wc] = sq; } }
	s_waitcnt lgkmcnt(0)
	v_add_f32_e32 v82, v80, v81
	v_add_u32_e32 v80, s42, v204
	v_ashrrev_i32_e32 v81, 31, v80
	s_lshl_b32 s22, s0, 2
	v_lshlrev_b64 v[80:81], 6, v[80:81]
	s_ashr_i32 s23, s22, 31
	v_lshl_add_u64 v[80:81], s[12:13], 0, v[80:81]
	v_lshl_add_u64 v[80:81], s[22:23], 2, v[80:81]
	s_lshl_b32 s8, s68, 2
	v_lshl_add_u64 v[80:81], v[80:81], 0, s[8:9]
	global_store_dword v[80:81], v82, off
.LBB0_475:
	s_or_b64 exec, exec, s[40:41]
	v_add_u32_e32 v120, 0x80, v200
	v_ashrrev_i32_e32 v121, 31, v120
	v_add_u32_e32 v116, 0x90, v200
	s_waitcnt lgkmcnt(0)
	v_lshlrev_b64 v[80:81], 11, v[120:121]
	v_ashrrev_i32_e32 v117, 31, v116
	v_add_u32_e32 v112, 0xa0, v200
	v_lshl_add_u64 v[122:123], v[202:203], 0, v[80:81]
	v_lshlrev_b64 v[80:81], 11, v[116:117]
	v_ashrrev_i32_e32 v113, 31, v112
	v_add_u32_e32 v108, 0xb0, v200
	v_lshl_add_u64 v[118:119], v[202:203], 0, v[80:81]
	v_lshlrev_b64 v[80:81], 11, v[112:113]
	v_ashrrev_i32_e32 v109, 31, v108
	v_lshl_add_u64 v[114:115], v[202:203], 0, v[80:81]
	v_lshlrev_b64 v[80:81], 11, v[108:109]
	v_lshl_add_u64 v[110:111], v[202:203], 0, v[80:81]
	global_load_dwordx4 v[104:107], v[122:123], off offset:256
	global_load_dwordx4 v[100:103], v[118:119], off
	global_load_dwordx4 v[96:99], v[118:119], off offset:256
	global_load_dwordx4 v[92:95], v[114:115], off
	global_load_dwordx4 v[88:91], v[114:115], off offset:256
	global_load_dwordx4 v[84:87], v[110:111], off
	global_load_dwordx4 v[80:83], v[110:111], off offset:256
	global_load_dwordx4 v[130:133], v[122:123], off
	v_lshlrev_b64 v[124:125], 10, v[120:121]
	v_lshl_add_u64 v[124:125], v[124:125], 0, v[198:199]
	s_waitcnt vmcnt(0)
	v_lshlrev_b32_e32 v126, 16, v130
	v_and_b32_e32 v127, 0xffff0000, v130
	v_lshlrev_b32_e32 v130, 16, v131
	v_and_b32_e32 v131, 0xffff0000, v131
	v_lshlrev_b32_e32 v134, 16, v132
	v_and_b32_e32 v135, 0xffff0000, v132
	v_lshlrev_b32_e32 v132, 16, v133
	v_and_b32_e32 v133, 0xffff0000, v133
	v_pk_fma_f32 v[130:131], v[78:79], v[70:71], v[130:131]
	v_pk_fma_f32 v[76:77], v[76:77], v[68:69], v[126:127]
	v_pk_fma_f32 v[126:127], v[74:75], v[66:67], v[132:133]
	v_pk_fma_f32 v[132:133], v[72:73], v[64:65], v[134:135]
	v_cvt_pk_bf16_f32 v72, v76, v77
	v_cvt_pk_bf16_f32 v73, v130, v131
	s_nop 0
	v_cvt_pk_bf16_f32 v74, v132, v133
	v_cvt_pk_bf16_f32 v75, v126, v127
	global_store_dwordx4 v[122:123], v[72:75], off sc1
	s_nop 1
	v_mul_f32_e32 v72, v77, v77
	v_mul_f32_e32 v73, v131, v131
	v_fmac_f32_e32 v72, v76, v76
	v_fmac_f32_e32 v73, v130, v130
	v_add_f32_e32 v72, v72, v73
	v_mul_f32_e32 v73, v133, v133
	v_mul_f32_e32 v74, v127, v127
	v_fmac_f32_e32 v73, v132, v132
	v_fmac_f32_e32 v74, v126, v126
	v_add_f32_e32 v73, v73, v74
	v_add_f32_e32 v78, v72, v73
	v_pk_mul_f32 v[74:75], v[192:193], v[130:131]
	v_pk_mul_f32 v[72:73], v[196:197], v[76:77]
	v_pk_mul_f32 v[76:77], v[190:191], v[126:127]
	v_pk_mul_f32 v[126:127], v[194:195], v[132:133]
	v_cvt_pk_bf16_f32 v72, v72, v73
	v_cvt_pk_bf16_f32 v73, v74, v75
	s_nop 0
	v_cvt_pk_bf16_f32 v74, v126, v127
	v_cvt_pk_bf16_f32 v75, v76, v77
	v_lshl_add_u64 v[76:77], v[124:125], 1, s[44:45]
	global_store_dwordx4 v[76:77], v[72:75], off sc1
	s_nop 1
	v_lshlrev_b32_e32 v72, 16, v104
	v_and_b32_e32 v73, 0xffff0000, v104
	v_lshlrev_b32_e32 v74, 16, v105
	v_and_b32_e32 v75, 0xffff0000, v105
	v_lshlrev_b32_e32 v104, 16, v106
	v_and_b32_e32 v105, 0xffff0000, v106
	v_lshlrev_b32_e32 v106, 16, v107
	v_and_b32_e32 v107, 0xffff0000, v107
	v_pk_fma_f32 v[54:55], v[54:55], v[62:63], v[74:75]
	v_pk_fma_f32 v[52:53], v[52:53], v[60:61], v[72:73]
	v_pk_fma_f32 v[74:75], v[48:49], v[56:57], v[104:105]
	v_cvt_pk_bf16_f32 v48, v52, v53
	v_cvt_pk_bf16_f32 v49, v54, v55
	v_pk_fma_f32 v[72:73], v[50:51], v[58:59], v[106:107]
	v_cvt_pk_bf16_f32 v50, v74, v75
	s_nop 0
	v_cvt_pk_bf16_f32 v51, v72, v73
	global_store_dwordx4 v[122:123], v[48:51], off offset:256 sc1
	s_nop 1
	v_mul_f32_e32 v48, v53, v53
	v_mul_f32_e32 v49, v55, v55
	v_fmac_f32_e32 v48, v52, v52
	v_fmac_f32_e32 v49, v54, v54
	v_add_f32_e32 v48, v48, v49
	v_mul_f32_e32 v49, v75, v75
	v_mul_f32_e32 v50, v73, v73
	v_fmac_f32_e32 v49, v74, v74
	v_fmac_f32_e32 v50, v72, v72
	v_add_f32_e32 v49, v49, v50
	v_add_f32_e32 v48, v48, v49
	v_add_f32_e32 v78, v48, v78
	v_pk_mul_f32 v[48:49], v[182:183], v[52:53]
	v_pk_mul_f32 v[50:51], v[188:189], v[54:55]
	v_cvt_pk_bf16_f32 v48, v48, v49
	v_pk_mul_f32 v[52:53], v[184:185], v[72:73]
	v_pk_mul_f32 v[54:55], v[186:187], v[74:75]
	v_cvt_pk_bf16_f32 v49, v50, v51
	s_nop 0
	v_cvt_pk_bf16_f32 v50, v54, v55
	v_cvt_pk_bf16_f32 v51, v52, v53
	global_store_dwordx4 v[76:77], v[48:51], off offset:256 sc1
	ds_bpermute_b32 v48, v128, v78
	s_waitcnt lgkmcnt(0)
	v_add_f32_e32 v48, v78, v48
	ds_bpermute_b32 v49, v129, v48
	s_and_saveexec_b64 s[40:41], vcc
	s_cbranch_execz .LBB0_477
	s_waitcnt lgkmcnt(0)
	v_add_f32_e32 v50, v48, v49
	v_add_u32_e32 v48, s42, v120
	v_ashrrev_i32_e32 v49, 31, v48
	s_lshl_b32 s22, s0, 2
	v_lshlrev_b64 v[48:49], 6, v[48:49]
	s_ashr_i32 s23, s22, 31
	v_lshl_add_u64 v[48:49], s[12:13], 0, v[48:49]
	v_lshl_add_u64 v[48:49], s[22:23], 2, v[48:49]
	s_lshl_b32 s8, s68, 2
	v_lshl_add_u64 v[48:49], v[48:49], 0, s[8:9]
	global_store_dword v[48:49], v50, off
; __device__ __forceinline__ unsigned cvt_pk_bf16(float lo, float hi) { unsigned r; asm volatile("v_cvt_pk_bf16_f32 %0, %1, %2" : "=v"(r) : "v"(lo), "v"(hi)); return r; }
;     __device__ __forceinline__ void operator()(const f32x4 (&acc)[2][2][4][2], const Unit& u, int wr, int wc, int fr, int fq) const {
;     ...
;             for (int m = 0; m < 4; ++m) { const int rl = wr * 64 + fr + ai * HALF + m * 16; const size_t off = (size_t)rl * DM + col0; float sq = 0.f;
;                 bf16_t* hrow = h16 + (size_t)rowt * DM + off;
; #pragma unroll
;                 for (int bj = 0; bj < 2; ++bj) { f32x4 b0, b1;
;                     if (bb) { b0 = *(const f32x4*)(bb + off + bj * HALF); b1 = *(const f32x4*)(bb + off + bj * HALF + 4); }
;                     else { const u32x4 r = raw[m][bj];
;                         b0 = (f32x4){__uint_as_float(r.x << 16), __uint_as_float(r.x & 0xffff0000u), __uint_as_float(r.y << 16), __uint_as_float(r.y & 0xffff0000u)};
;                         b1 = (f32x4){__uint_as_float(r.z << 16), __uint_as_float(r.z & 0xffff0000u), __uint_as_float(r.w << 16), __uint_as_float(r.w & 0xffff0000u)}; }
;                     const f32x4 o0 = b0 + gv[bj][0] * acc[ai][bj][m][0], o1 = b1 + gv[bj][1] * acc[ai][bj][m][1];
;                     u32x4 w; w.x = cvt_pk_bf16(o0[0], o0[1]); w.y = cvt_pk_bf16(o0[2], o0[3]); w.z = cvt_pk_bf16(o1[0], o1[1]); w.w = cvt_pk_bf16(o1[2], o1[3]);
;                     *(u32x4*)(hrow + bj * HALF) = w;
;                     sq += ((o0[0] * o0[0] + o0[1] * o0[1]) + (o0[2] * o0[2] + o0[3] * o0[3])) + ((o1[0] * o1[0] + o1[1] * o1[1]) + (o1[2] * o1[2] + o1[3] * o1[3]));
;                     if (hb) { const f32x4 y0 = o0 * wv[bj][0], y1 = o1 * wv[bj][1]; u32x4 z; z.x = cvt_pk_bf16(y0[0], y0[1]); z.y = cvt_pk_bf16(y0[2], y0[3]); z.z = cvt_pk_bf16(y1[0], y1[1]); z.w = cvt_pk_bf16(y1[2], y1[3]);
;                         *(u32x4*)(hb + (size_t)rowt * DM + off + bj * HALF) = z; } }
;                 if (ssq) { sq += __shfl_xor(sq, 16); sq += __shfl_xor(sq, 32); if (fq == 0) ssq[(size_t)(rowt + rl) * 16 + u.pn * 4 + wc] = sq; } }
.LBB0_477:
	s_or_b64 exec, exec, s[40:41]
	v_lshlrev_b32_e32 v50, 16, v100
	v_and_b32_e32 v51, 0xffff0000, v100
	v_lshlrev_b32_e32 v52, 16, v101
	v_and_b32_e32 v53, 0xffff0000, v101
	v_lshlrev_b32_e32 v54, 16, v102
	v_and_b32_e32 v55, 0xffff0000, v102
	v_lshlrev_b32_e32 v72, 16, v103
	v_and_b32_e32 v73, 0xffff0000, v103
	v_pk_fma_f32 v[46:47], v[46:47], v[70:71], v[52:53]
	v_pk_fma_f32 v[44:45], v[44:45], v[68:69], v[50:51]
	v_pk_fma_f32 v[52:53], v[40:41], v[64:65], v[54:55]
	v_cvt_pk_bf16_f32 v40, v44, v45
	v_cvt_pk_bf16_f32 v41, v46, v47
	v_pk_fma_f32 v[50:51], v[42:43], v[66:67], v[72:73]
	v_cvt_pk_bf16_f32 v42, v52, v53
	s_waitcnt lgkmcnt(0)
	v_lshlrev_b64 v[48:49], 10, v[116:117]
	v_cvt_pk_bf16_f32 v43, v50, v51
	global_store_dwordx4 v[118:119], v[40:43], off sc1
	v_lshl_add_u64 v[48:49], v[48:49], 0, v[198:199]
	s_nop 0
	v_mul_f32_e32 v40, v45, v45
	v_mul_f32_e32 v41, v47, v47
	v_fmac_f32_e32 v40, v44, v44
	v_fmac_f32_e32 v41, v46, v46
	v_add_f32_e32 v40, v40, v41
	v_mul_f32_e32 v41, v53, v53
	v_mul_f32_e32 v42, v51, v51
	v_fmac_f32_e32 v41, v52, v52
	v_fmac_f32_e32 v42, v50, v50
	v_add_f32_e32 v41, v41, v42
	v_add_f32_e32 v54, v40, v41
	v_pk_mul_f32 v[42:43], v[192:193], v[46:47]
	v_pk_mul_f32 v[40:41], v[196:197], v[44:45]
	v_pk_mul_f32 v[44:45], v[190:191], v[50:51]
	v_pk_mul_f32 v[46:47], v[194:195], v[52:53]
	v_cvt_pk_bf16_f32 v40, v40, v41
	v_cvt_pk_bf16_f32 v41, v42, v43
	s_nop 0
	v_cvt_pk_bf16_f32 v42, v46, v47
	v_cvt_pk_bf16_f32 v43, v44, v45
	v_lshl_add_u64 v[44:45], v[48:49], 1, s[44:45]
	global_store_dwordx4 v[44:45], v[40:43], off sc1
	v_lshlrev_b32_e32 v46, 16, v98
	v_and_b32_e32 v47, 0xffff0000, v98
	v_lshlrev_b32_e32 v40, 16, v96
	v_and_b32_e32 v41, 0xffff0000, v96
	v_lshlrev_b32_e32 v42, 16, v97
	v_and_b32_e32 v43, 0xffff0000, v97
	v_lshlrev_b32_e32 v48, 16, v99
	v_and_b32_e32 v49, 0xffff0000, v99
	v_pk_fma_f32 v[38:39], v[38:39], v[62:63], v[42:43]
	v_pk_fma_f32 v[36:37], v[36:37], v[60:61], v[40:41]
	v_pk_fma_f32 v[42:43], v[32:33], v[56:57], v[46:47]
	v_cvt_pk_bf16_f32 v32, v36, v37
	v_cvt_pk_bf16_f32 v33, v38, v39
	v_pk_fma_f32 v[40:41], v[34:35], v[58:59], v[48:49]
	v_cvt_pk_bf16_f32 v34, v42, v43
	s_nop 0
	v_cvt_pk_bf16_f32 v35, v40, v41
	global_store_dwordx4 v[118:119], v[32:35], off offset:256 sc1
	s_nop 1
	v_mul_f32_e32 v32, v37, v37
	v_mul_f32_e32 v33, v39, v39
	v_fmac_f32_e32 v32, v36, v36
	v_fmac_f32_e32 v33, v38, v38
	v_add_f32_e32 v32, v32, v33
	v_mul_f32_e32 v33, v43, v43
	v_mul_f32_e32 v34, v41, v41
	v_fmac_f32_e32 v33, v42, v42
	v_fmac_f32_e32 v34, v40, v40
	v_add_f32_e32 v33, v33, v34
	v_add_f32_e32 v32, v32, v33
	v_add_f32_e32 v35, v54, v32
	ds_bpermute_b32 v46, v128, v35
	v_pk_mul_f32 v[32:33], v[182:183], v[36:37]
	v_pk_mul_f32 v[36:37], v[186:187], v[42:43]
	v_cvt_pk_bf16_f32 v34, v32, v33
	v_pk_mul_f32 v[38:39], v[188:189], v[38:39]
	s_waitcnt lgkmcnt(0)
	v_add_f32_e32 v32, v35, v46
	ds_bpermute_b32 v33, v129, v32
	v_pk_mul_f32 v[40:41], v[184:185], v[40:41]
	v_cvt_pk_bf16_f32 v35, v38, v39
	v_cvt_pk_bf16_f32 v36, v36, v37
	s_nop 0
	v_cvt_pk_bf16_f32 v37, v40, v41
	global_store_dwordx4 v[44:45], v[34:37], off offset:256 sc1
	s_and_saveexec_b64 s[40:41], vcc
	s_cbranch_execz .LBB0_479
	s_waitcnt lgkmcnt(0)
	v_add_f32_e32 v34, v32, v33
	v_add_u32_e32 v32, s42, v116
	v_ashrrev_i32_e32 v33, 31, v32
	s_lshl_b32 s22, s0, 2
	v_lshlrev_b64 v[32:33], 6, v[32:33]
	s_ashr_i32 s23, s22, 31
	v_lshl_add_u64 v[32:33], s[12:13], 0, v[32:33]
	v_lshl_add_u64 v[32:33], s[22:23], 2, v[32:33]
	s_lshl_b32 s8, s68, 2
	v_lshl_add_u64 v[32:33], v[32:33], 0, s[8:9]
	global_store_dword v[32:33], v34, off
; __device__ __forceinline__ unsigned cvt_pk_bf16(float lo, float hi) { unsigned r; asm volatile("v_cvt_pk_bf16_f32 %0, %1, %2" : "=v"(r) : "v"(lo), "v"(hi)); return r; }
;     __device__ __forceinline__ void operator()(const f32x4 (&acc)[2][2][4][2], const Unit& u, int wr, int wc, int fr, int fq) const {
;     ...
;             for (int m = 0; m < 4; ++m) { const int rl = wr * 64 + fr + ai * HALF + m * 16; const size_t off = (size_t)rl * DM + col0; float sq = 0.f;
;                 bf16_t* hrow = h16 + (size_t)rowt * DM + off;
; #pragma unroll
;                 for (int bj = 0; bj < 2; ++bj) { f32x4 b0, b1;
;                     if (bb) { b0 = *(const f32x4*)(bb + off + bj * HALF); b1 = *(const f32x4*)(bb + off + bj * HALF + 4); }
;                     else { const u32x4 r = raw[m][bj];
;                         b0 = (f32x4){__uint_as_float(r.x << 16), __uint_as_float(r.x & 0xffff0000u), __uint_as_float(r.y << 16), __uint_as_float(r.y & 0xffff0000u)};
;                         b1 = (f32x4){__uint_as_float(r.z << 16), __uint_as_float(r.z & 0xffff0000u), __uint_as_float(r.w << 16), __uint_as_float(r.w & 0xffff0000u)}; }
;                     const f32x4 o0 = b0 + gv[bj][0] * acc[ai][bj][m][0], o1 = b1 + gv[bj][1] * acc[ai][bj][m][1];
;                     u32x4 w; w.x = cvt_pk_bf16(o0[0], o0[1]); w.y = cvt_pk_bf16(o0[2], o0[3]); w.z = cvt_pk_bf16(o1[0], o1[1]); w.w = cvt_pk_bf16(o1[2], o1[3]);
;                     *(u32x4*)(hrow + bj * HALF) = w;
;                     sq += ((o0[0] * o0[0] + o0[1] * o0[1]) + (o0[2] * o0[2] + o0[3] * o0[3])) + ((o1[0] * o1[0] + o1[1] * o1[1]) + (o1[2] * o1[2] + o1[3] * o1[3]));
;                     if (hb) { const f32x4 y0 = o0 * wv[bj][0], y1 = o1 * wv[bj][1]; u32x4 z; z.x = cvt_pk_bf16(y0[0], y0[1]); z.y = cvt_pk_bf16(y0[2], y0[3]); z.z = cvt_pk_bf16(y1[0], y1[1]); z.w = cvt_pk_bf16(y1[2], y1[3]);
;                         *(u32x4*)(hb + (size_t)rowt * DM + off + bj * HALF) = z; } }
;                 if (ssq) { sq += __shfl_xor(sq, 16); sq += __shfl_xor(sq, 32); if (fq == 0) ssq[(size_t)(rowt + rl) * 16 + u.pn * 4 + wc] = sq; } }
.LBB0_479:
	s_or_b64 exec, exec, s[40:41]
	v_lshlrev_b32_e32 v34, 16, v92
	v_and_b32_e32 v35, 0xffff0000, v92
	v_lshlrev_b32_e32 v36, 16, v93
	v_and_b32_e32 v37, 0xffff0000, v93
	v_lshlrev_b32_e32 v38, 16, v94
	v_and_b32_e32 v39, 0xffff0000, v94
	v_lshlrev_b32_e32 v40, 16, v95
	v_and_b32_e32 v41, 0xffff0000, v95
	v_pk_fma_f32 v[30:31], v[30:31], v[70:71], v[36:37]
	v_pk_fma_f32 v[28:29], v[28:29], v[68:69], v[34:35]
	v_pk_fma_f32 v[36:37], v[24:25], v[64:65], v[38:39]
	v_cvt_pk_bf16_f32 v24, v28, v29
	v_cvt_pk_bf16_f32 v25, v30, v31
	v_pk_fma_f32 v[34:35], v[26:27], v[66:67], v[40:41]
	v_cvt_pk_bf16_f32 v26, v36, v37
	s_waitcnt lgkmcnt(0)
	v_lshlrev_b64 v[32:33], 10, v[112:113]
	v_cvt_pk_bf16_f32 v27, v34, v35
	global_store_dwordx4 v[114:115], v[24:27], off sc1
	v_lshl_add_u64 v[32:33], v[32:33], 0, v[198:199]
	s_nop 0
	v_mul_f32_e32 v24, v29, v29
	v_mul_f32_e32 v25, v31, v31
	v_fmac_f32_e32 v24, v28, v28
	v_fmac_f32_e32 v25, v30, v30
	v_add_f32_e32 v24, v24, v25
	v_mul_f32_e32 v25, v37, v37
	v_mul_f32_e32 v26, v35, v35
	v_fmac_f32_e32 v25, v36, v36
	v_fmac_f32_e32 v26, v34, v34
	v_add_f32_e32 v25, v25, v26
	v_add_f32_e32 v38, v24, v25
	v_pk_mul_f32 v[26:27], v[192:193], v[30:31]
	v_pk_mul_f32 v[24:25], v[196:197], v[28:29]
	v_pk_mul_f32 v[28:29], v[190:191], v[34:35]
	v_pk_mul_f32 v[30:31], v[194:195], v[36:37]
	v_cvt_pk_bf16_f32 v24, v24, v25
	v_cvt_pk_bf16_f32 v25, v26, v27
	s_nop 0
	v_cvt_pk_bf16_f32 v26, v30, v31
	v_cvt_pk_bf16_f32 v27, v28, v29
	v_lshl_add_u64 v[28:29], v[32:33], 1, s[44:45]
	global_store_dwordx4 v[28:29], v[24:27], off sc1
	v_lshlrev_b32_e32 v30, 16, v90
	v_and_b32_e32 v31, 0xffff0000, v90
	v_lshlrev_b32_e32 v24, 16, v88
	v_and_b32_e32 v25, 0xffff0000, v88
	v_lshlrev_b32_e32 v26, 16, v89
	v_and_b32_e32 v27, 0xffff0000, v89
	v_lshlrev_b32_e32 v32, 16, v91
	v_and_b32_e32 v33, 0xffff0000, v91
	v_pk_fma_f32 v[22:23], v[22:23], v[62:63], v[26:27]
	v_pk_fma_f32 v[20:21], v[20:21], v[60:61], v[24:25]
	v_pk_fma_f32 v[26:27], v[16:17], v[56:57], v[30:31]
	v_cvt_pk_bf16_f32 v16, v20, v21
	v_cvt_pk_bf16_f32 v17, v22, v23
	v_pk_fma_f32 v[24:25], v[18:19], v[58:59], v[32:33]
	v_cvt_pk_bf16_f32 v18, v26, v27
	s_nop 0
	v_cvt_pk_bf16_f32 v19, v24, v25
	global_store_dwordx4 v[114:115], v[16:19], off offset:256 sc1
	s_nop 1
	v_mul_f32_e32 v16, v21, v21
	v_mul_f32_e32 v17, v23, v23
	v_fmac_f32_e32 v16, v20, v20
	v_fmac_f32_e32 v17, v22, v22
	v_add_f32_e32 v16, v16, v17
	v_mul_f32_e32 v17, v27, v27
	v_mul_f32_e32 v18, v25, v25
	v_fmac_f32_e32 v17, v26, v26
	v_fmac_f32_e32 v18, v24, v24
	v_add_f32_e32 v17, v17, v18
	v_add_f32_e32 v16, v16, v17
	v_add_f32_e32 v19, v38, v16
	ds_bpermute_b32 v30, v128, v19
	v_pk_mul_f32 v[16:17], v[182:183], v[20:21]
	v_pk_mul_f32 v[20:21], v[186:187], v[26:27]
	v_cvt_pk_bf16_f32 v18, v16, v17
	v_pk_mul_f32 v[22:23], v[188:189], v[22:23]
	s_waitcnt lgkmcnt(0)
	v_add_f32_e32 v16, v19, v30
	ds_bpermute_b32 v17, v129, v16
	v_pk_mul_f32 v[24:25], v[184:185], v[24:25]
	v_cvt_pk_bf16_f32 v19, v22, v23
	v_cvt_pk_bf16_f32 v20, v20, v21
	s_nop 0
	v_cvt_pk_bf16_f32 v21, v24, v25
	global_store_dwordx4 v[28:29], v[18:21], off offset:256 sc1
	s_and_saveexec_b64 s[40:41], vcc
	s_cbranch_execz .LBB0_481
	s_waitcnt lgkmcnt(0)
	v_add_f32_e32 v18, v16, v17
	v_add_u32_e32 v16, s42, v112
	v_ashrrev_i32_e32 v17, 31, v16
	s_lshl_b32 s22, s0, 2
	v_lshlrev_b64 v[16:17], 6, v[16:17]
	s_ashr_i32 s23, s22, 31
	v_lshl_add_u64 v[16:17], s[12:13], 0, v[16:17]
	v_lshl_add_u64 v[16:17], s[22:23], 2, v[16:17]
	s_lshl_b32 s8, s68, 2
	v_lshl_add_u64 v[16:17], v[16:17], 0, s[8:9]
	global_store_dword v[16:17], v18, off
.LBB0_481:
	s_or_b64 exec, exec, s[40:41]
	v_lshlrev_b32_e32 v18, 16, v84
	v_and_b32_e32 v19, 0xffff0000, v84
	v_lshlrev_b32_e32 v20, 16, v85
	v_and_b32_e32 v21, 0xffff0000, v85
	v_lshlrev_b32_e32 v22, 16, v86
	v_and_b32_e32 v23, 0xffff0000, v86
	v_lshlrev_b32_e32 v24, 16, v87
	v_and_b32_e32 v25, 0xffff0000, v87
	v_pk_fma_f32 v[14:15], v[14:15], v[70:71], v[20:21]
	v_pk_fma_f32 v[12:13], v[12:13], v[68:69], v[18:19]
	v_pk_fma_f32 v[20:21], v[8:9], v[64:65], v[22:23]
	v_cvt_pk_bf16_f32 v8, v12, v13
	v_cvt_pk_bf16_f32 v9, v14, v15
	v_pk_fma_f32 v[18:19], v[10:11], v[66:67], v[24:25]
	v_cvt_pk_bf16_f32 v10, v20, v21
	s_waitcnt lgkmcnt(0)
	v_lshlrev_b64 v[16:17], 10, v[108:109]
	v_cvt_pk_bf16_f32 v11, v18, v19
	global_store_dwordx4 v[110:111], v[8:11], off sc1
	v_lshl_add_u64 v[16:17], v[16:17], 0, v[198:199]
	s_nop 0
	v_mul_f32_e32 v8, v13, v13
	v_mul_f32_e32 v9, v15, v15
	v_fmac_f32_e32 v8, v12, v12
	v_fmac_f32_e32 v9, v14, v14
	v_add_f32_e32 v8, v8, v9
	v_mul_f32_e32 v9, v21, v21
	v_mul_f32_e32 v10, v19, v19
	v_fmac_f32_e32 v9, v20, v20
	v_fmac_f32_e32 v10, v18, v18
	v_add_f32_e32 v9, v9, v10
	v_add_f32_e32 v22, v8, v9
	v_pk_mul_f32 v[10:11], v[192:193], v[14:15]
	v_pk_mul_f32 v[8:9], v[196:197], v[12:13]
	v_pk_mul_f32 v[12:13], v[190:191], v[18:19]
	v_pk_mul_f32 v[14:15], v[194:195], v[20:21]
	v_cvt_pk_bf16_f32 v8, v8, v9
	v_cvt_pk_bf16_f32 v9, v10, v11
	s_nop 0
	v_cvt_pk_bf16_f32 v10, v14, v15
	v_cvt_pk_bf16_f32 v11, v12, v13
	v_lshl_add_u64 v[12:13], v[16:17], 1, s[44:45]
	global_store_dwordx4 v[12:13], v[8:11], off sc1
	v_lshlrev_b32_e32 v14, 16, v82
	v_and_b32_e32 v15, 0xffff0000, v82
	v_lshlrev_b32_e32 v8, 16, v80
	v_and_b32_e32 v9, 0xffff0000, v80
	v_lshlrev_b32_e32 v10, 16, v81
	v_and_b32_e32 v11, 0xffff0000, v81
	v_lshlrev_b32_e32 v16, 16, v83
	v_and_b32_e32 v17, 0xffff0000, v83
	v_pk_fma_f32 v[6:7], v[6:7], v[62:63], v[10:11]
	v_pk_fma_f32 v[4:5], v[4:5], v[60:61], v[8:9]
	v_pk_fma_f32 v[10:11], v[0:1], v[56:57], v[14:15]
	v_cvt_pk_bf16_f32 v0, v4, v5
	v_cvt_pk_bf16_f32 v1, v6, v7
	v_pk_fma_f32 v[8:9], v[2:3], v[58:59], v[16:17]
	v_cvt_pk_bf16_f32 v2, v10, v11
	s_nop 0
	v_cvt_pk_bf16_f32 v3, v8, v9
	global_store_dwordx4 v[110:111], v[0:3], off offset:256 sc1
	s_nop 1
	v_mul_f32_e32 v0, v5, v5
	v_mul_f32_e32 v1, v7, v7
	v_fmac_f32_e32 v0, v4, v4
	v_fmac_f32_e32 v1, v6, v6
	v_add_f32_e32 v0, v0, v1
	v_mul_f32_e32 v1, v11, v11
	v_mul_f32_e32 v2, v9, v9
	v_fmac_f32_e32 v1, v10, v10
	v_fmac_f32_e32 v2, v8, v8
	v_add_f32_e32 v1, v1, v2
	v_add_f32_e32 v0, v0, v1
	v_add_f32_e32 v3, v22, v0
	ds_bpermute_b32 v14, v128, v3
	v_pk_mul_f32 v[0:1], v[182:183], v[4:5]
	v_pk_mul_f32 v[4:5], v[186:187], v[10:11]
	v_cvt_pk_bf16_f32 v2, v0, v1
	v_pk_mul_f32 v[6:7], v[188:189], v[6:7]
	s_waitcnt lgkmcnt(0)
	v_add_f32_e32 v0, v3, v14
	ds_bpermute_b32 v1, v129, v0
	v_pk_mul_f32 v[8:9], v[184:185], v[8:9]
	v_cvt_pk_bf16_f32 v3, v6, v7
	v_cvt_pk_bf16_f32 v4, v4, v5
	s_nop 0
	v_cvt_pk_bf16_f32 v5, v8, v9
	global_store_dwordx4 v[12:13], v[2:5], off offset:256 sc1
	s_and_saveexec_b64 s[40:41], vcc
	s_cbranch_execz .LBB0_483
	s_waitcnt lgkmcnt(0)
	v_add_f32_e32 v2, v0, v1
	v_add_u32_e32 v0, s42, v108
	v_ashrrev_i32_e32 v1, 31, v0
	s_lshl_b32 s0, s0, 2
	v_lshlrev_b64 v[0:1], 6, v[0:1]
	s_ashr_i32 s1, s0, 31
	v_lshl_add_u64 v[0:1], s[12:13], 0, v[0:1]
	v_lshl_add_u64 v[0:1], s[0:1], 2, v[0:1]
	s_lshl_b32 s8, s68, 2
	v_lshl_add_u64 v[0:1], v[0:1], 0, s[8:9]
	global_store_dword v[0:1], v2, off

; #define PG8_LAS __attribute__((address_space(3)))
; __device__ __forceinline__ unsigned cvt_pk_bf16(float lo, float hi) { unsigned r; asm volatile("v_cvt_pk_bf16_f32 %0, %1, %2" : "=v"(r) : "v"(lo), "v"(hi)); return r; }
;     __device__ __forceinline__ void operator()(f32x4 (&acc)[2][2][4][2], const Unit& u, int wr, int wc, int fr, int fq) const {
;     ...
;                 for (int bj = 0; bj < 2; ++bj) { f32x4 v0 = acc[ai][bj][m][0], v1 = acc[ai][bj][m][1]; bf16_t* dst;
;                     if (qk) { const f32x4 pt = *(const PG8_LAS f32x4*)(P + (rl * 2 + bj) * 4);
;                         const float hr = rsqrtf(((pt[0] + pt[1]) + (pt[2] + pt[3])) * (1.f / 128.f) + EPS);
; #pragma unroll
;                         for (int e = 0; e < 4; ++e) { v0[e] = v0[e] * hr * gq[0][e]; v1[e] = v1[e] * hr * gq[1][e]; }
;                         const f32x4 r0 = {v0[0] * cs[0][0] - v0[1] * sn[0][0], v0[0] * sn[0][0] + v0[1] * cs[0][0], v0[2] * cs[0][1] - v0[3] * sn[0][1], v0[2] * sn[0][1] + v0[3] * cs[0][1]};
;                         const f32x4 r1 = {v1[0] * cs[1][0] - v1[1] * sn[1][0], v1[0] * sn[1][0] + v1[1] * cs[1][0], v1[2] * cs[1][1] - v1[3] * sn[1][1], v1[2] * sn[1][1] + v1[3] * cs[1][1]};
;                         v0 = r0; v1 = r1;
;                         dst = u.pn < 4 ? Q + (size_t)row * DM + (u.pn * 2 + bj) * 128 : K + (size_t)kvrow * 512 + ((u.pn - 4) * 2 + bj) * 128;
;                     } else dst = V + (size_t)kvrow * 512 + ((u.pn - 6) * 2 + bj) * 128;
;                     u32x4 w; w.x = cvt_pk_bf16(v0[0], v0[1]); w.y = cvt_pk_bf16(v0[2], v0[3]); w.z = cvt_pk_bf16(v1[0], v1[1]); w.w = cvt_pk_bf16(v1[2], v1[3]);
;                     *(u32x4*)(dst + wc * 32 + 8 * fq) = w; } }
.LBB0_648:
	s_lshl_b32 s8, s68, 1
	v_ashrrev_i32_e32 v175, 31, v174
	v_cvt_pk_bf16_f32 v150, v160, v151
	v_cvt_pk_bf16_f32 v151, v162, v153
	v_cvt_pk_bf16_f32 v152, v178, v149
	v_cvt_pk_bf16_f32 v153, v180, v147
	v_lshl_add_u64 v[146:147], v[182:183], 0, s[8:9]
	v_cndmask_b32_e64 v9, 0, 1, s[80:81]
	v_lshl_add_u64 v[146:147], v[174:175], 1, v[146:147]
	v_cmp_ne_u32_e64 s[44:45], 1, v9
	s_andn2_b64 vcc, exec, s[80:81]
	s_mov_b64 s[46:47], -1
	global_store_dwordx4 v[146:147], v[150:153], off sc1
	s_cbranch_vccnz .LBB0_650
	s_add_i32 s16, s72, 0xfffffa80
	s_ashr_i32 s17, s16, 31
	v_lshl_add_u64 v[160:161], s[16:17], 1, v[158:159]
	s_mov_b64 s[46:47], 0
	v_mov_b32_e32 v152, v142
	v_mov_b32_e32 v150, v144
	v_mov_b32_e32 v148, v140
	v_mov_b32_e32 v146, v138

; #define PG8_LAS __attribute__((address_space(3)))
;     __device__ __forceinline__ void operator()(f32x4 (&acc)[2][2][4][2], const Unit& u, int wr, int wc, int fr, int fq) const {
;     ...
;             for (int m = 0; m < 4; ++m) { const int rl = wr * 64 + fr + ai * HALF + m * 16, row = rowt + rl;
;                 int kvrow; float cs[2][2], sn[2][2];
;                 if (is_lat) { const int t = row & (SEQ - 1); kvrow = b * SKV + CTXL + t; const float pos = (float)((wc >> 1) ? (t & 63) : (t >> 6));
; #pragma unroll
;                     for (int n = 0; n < 2; ++n)
; #pragma unroll
;                         for (int pr = 0; pr < 2; ++pr) { const float a = pos * inv[n][pr]; cs[n][pr] = __cosf(a); sn[n][pr] = __sinf(a); } }
;                 else { kvrow = ((row - MLAT) >> 8) * SKV + ((row - MLAT) & (CTXL - 1));
; #pragma unroll
;                     for (int n = 0; n < 2; ++n)
; #pragma unroll
;                         for (int pr = 0; pr < 2; ++pr) { cs[n][pr] = 1.f; sn[n][pr] = 0.f; } }
; #pragma unroll
;                 for (int bj = 0; bj < 2; ++bj) { f32x4 v0 = acc[ai][bj][m][0], v1 = acc[ai][bj][m][1]; bf16_t* dst;
;                     if (qk) { const f32x4 pt = *(const PG8_LAS f32x4*)(P + (rl * 2 + bj) * 4);
;                         const float hr = rsqrtf(((pt[0] + pt[1]) + (pt[2] + pt[3])) * (1.f / 128.f) + EPS);
; #pragma unroll
;                         for (int e = 0; e < 4; ++e) { v0[e] = v0[e] * hr * gq[0][e]; v1[e] = v1[e] * hr * gq[1][e]; }
;                         const f32x4 r0 = {v0[0] * cs[0][0] - v0[1] * sn[0][0], v0[0] * sn[0][0] + v0[1] * cs[0][0], v0[2] * cs[0][1] - v0[3] * sn[0][1], v0[2] * sn[0][1] + v0[3] * cs[0][1]};
;                         const f32x4 r1 = {v1[0] * cs[1][0] - v1[1] * sn[1][0], v1[0] * sn[1][0] + v1[1] * cs[1][0], v1[2] * cs[1][1] - v1[3] * sn[1][1], v1[2] * sn[1][1] + v1[3] * cs[1][1]};
;                         v0 = r0; v1 = r1;
;                         dst = u.pn < 4 ? Q + (size_t)row * DM + (u.pn * 2 + bj) * 128 : K + (size_t)kvrow * 512 + ((u.pn - 4) * 2 + bj) * 128;
;                     } else dst = V + (size_t)kvrow * 512 + ((u.pn - 6) * 2 + bj) * 128;
;                     u32x4 w; w.x = cvt_pk_bf16(v0[0], v0[1]); w.y = cvt_pk_bf16(v0[2], v0[3]); w.z = cvt_pk_bf16(v1[0], v1[1]); w.w = cvt_pk_bf16(v1[2], v1[3]);
;                     *(u32x4*)(dst + wc * 32 + 8 * fq) = w; } }
.LBB0_655:
	v_add_u32_e32 v9, 16, v193
	v_and_b32_e32 v77, 63, v9
	v_lshl_add_u64 v[70:71], v[160:161], 0, s[8:9]
	v_add_u32_e32 v9, 16, v191
	v_cvt_pk_bf16_f32 v78, v146, v139
	v_cvt_pk_bf16_f32 v79, v148, v141
	v_cvt_pk_bf16_f32 v80, v150, v145
	v_lshl_add_u64 v[70:71], v[174:175], 1, v[70:71]
	v_add_u32_e32 v140, s35, v9
	s_and_b64 vcc, exec, s[42:43]
	s_mov_b64 s[48:49], -1
	v_cvt_pk_bf16_f32 v81, v152, v143
	global_store_dwordx4 v[70:71], v[78:81], off sc1
	s_cbranch_vccnz .LBB0_657
	v_bfe_u32 v68, v140, 6, 7
	v_cndmask_b32_e64 v68, v77, v68, s[38:39]
	v_cvt_f32_ubyte0_e32 v68, v68
	v_mul_f32_e32 v70, v7, v68
	v_mul_f32_e32 v70, 0.15915494, v70
	v_cos_f32_e32 v82, v70
	v_sin_f32_e32 v86, v70
	v_mul_f32_e32 v70, v192, v68
	v_mul_f32_e32 v70, 0.15915494, v70
	v_cos_f32_e32 v80, v70
	v_sin_f32_e32 v84, v70
	v_mul_f32_e32 v70, v185, v68
	v_mul_f32_e32 v68, v184, v68
	v_mul_f32_e32 v70, 0.15915494, v70
	v_mul_f32_e32 v68, 0.15915494, v68
	v_cos_f32_e32 v76, v70
	v_sin_f32_e32 v78, v70
	v_cos_f32_e32 v70, v68
	v_sin_f32_e32 v68, v68
	v_and_b32_e32 v71, 0x1fff, v140
	v_add_u32_e32 v138, s59, v71
	s_mov_b64 s[48:49], 0

; #define PG8_LAS __attribute__((address_space(3)))
; __device__ __forceinline__ unsigned cvt_pk_bf16(float lo, float hi) { unsigned r; asm volatile("v_cvt_pk_bf16_f32 %0, %1, %2" : "=v"(r) : "v"(lo), "v"(hi)); return r; }
;     __device__ __forceinline__ void operator()(f32x4 (&acc)[2][2][4][2], const Unit& u, int wr, int wc, int fr, int fq) const {
;     ...
;                 for (int bj = 0; bj < 2; ++bj) { f32x4 v0 = acc[ai][bj][m][0], v1 = acc[ai][bj][m][1]; bf16_t* dst;
;                     if (qk) { const f32x4 pt = *(const PG8_LAS f32x4*)(P + (rl * 2 + bj) * 4);
;                         const float hr = rsqrtf(((pt[0] + pt[1]) + (pt[2] + pt[3])) * (1.f / 128.f) + EPS);
; #pragma unroll
;                         for (int e = 0; e < 4; ++e) { v0[e] = v0[e] * hr * gq[0][e]; v1[e] = v1[e] * hr * gq[1][e]; }
;                         const f32x4 r0 = {v0[0] * cs[0][0] - v0[1] * sn[0][0], v0[0] * sn[0][0] + v0[1] * cs[0][0], v0[2] * cs[0][1] - v0[3] * sn[0][1], v0[2] * sn[0][1] + v0[3] * cs[0][1]};
;                         const f32x4 r1 = {v1[0] * cs[1][0] - v1[1] * sn[1][0], v1[0] * sn[1][0] + v1[1] * cs[1][0], v1[2] * cs[1][1] - v1[3] * sn[1][1], v1[2] * sn[1][1] + v1[3] * cs[1][1]};
;                         v0 = r0; v1 = r1;
;                         dst = u.pn < 4 ? Q + (size_t)row * DM + (u.pn * 2 + bj) * 128 : K + (size_t)kvrow * 512 + ((u.pn - 4) * 2 + bj) * 128;
;                     } else dst = V + (size_t)kvrow * 512 + ((u.pn - 6) * 2 + bj) * 128;
;                     u32x4 w; w.x = cvt_pk_bf16(v0[0], v0[1]); w.y = cvt_pk_bf16(v0[2], v0[3]); w.z = cvt_pk_bf16(v1[0], v1[1]); w.w = cvt_pk_bf16(v1[2], v1[3]);
;                     *(u32x4*)(dst + wc * 32 + 8 * fq) = w; } }
.LBB0_666:
	v_cvt_pk_bf16_f32 v124, v144, v125
	v_cvt_pk_bf16_f32 v125, v146, v137
	v_cvt_pk_bf16_f32 v126, v148, v127
	v_cvt_pk_bf16_f32 v127, v150, v123
	v_lshl_add_u64 v[122:123], v[152:153], 0, s[8:9]
	v_lshl_add_u64 v[122:123], v[174:175], 1, v[122:123]
	s_and_b64 vcc, exec, s[44:45]
	s_mov_b64 s[48:49], -1
	global_store_dwordx4 v[122:123], v[124:127], off sc1
	s_cbranch_vccnz .LBB0_668
	s_add_i32 s16, s72, 0xfffffa80
	s_ashr_i32 s17, s16, 31
	v_lshl_add_u64 v[122:123], s[16:17], 1, v[142:143]
	s_mov_b64 s[48:49], 0

; #define PG8_LAS __attribute__((address_space(3)))
;     __device__ __forceinline__ void operator()(f32x4 (&acc)[2][2][4][2], const Unit& u, int wr, int wc, int fr, int fq) const {
;     ...
;             for (int m = 0; m < 4; ++m) { const int rl = wr * 64 + fr + ai * HALF + m * 16, row = rowt + rl;
;                 int kvrow; float cs[2][2], sn[2][2];
;                 if (is_lat) { const int t = row & (SEQ - 1); kvrow = b * SKV + CTXL + t; const float pos = (float)((wc >> 1) ? (t & 63) : (t >> 6));
; #pragma unroll
;                     for (int n = 0; n < 2; ++n)
; #pragma unroll
;                         for (int pr = 0; pr < 2; ++pr) { const float a = pos * inv[n][pr]; cs[n][pr] = __cosf(a); sn[n][pr] = __sinf(a); } }
;                 else { kvrow = ((row - MLAT) >> 8) * SKV + ((row - MLAT) & (CTXL - 1));
; #pragma unroll
;                     for (int n = 0; n < 2; ++n)
; #pragma unroll
;                         for (int pr = 0; pr < 2; ++pr) { cs[n][pr] = 1.f; sn[n][pr] = 0.f; } }
; #pragma unroll
;                 for (int bj = 0; bj < 2; ++bj) { f32x4 v0 = acc[ai][bj][m][0], v1 = acc[ai][bj][m][1]; bf16_t* dst;
;                     if (qk) { const f32x4 pt = *(const PG8_LAS f32x4*)(P + (rl * 2 + bj) * 4);
;                         const float hr = rsqrtf(((pt[0] + pt[1]) + (pt[2] + pt[3])) * (1.f / 128.f) + EPS);
; #pragma unroll
;                         for (int e = 0; e < 4; ++e) { v0[e] = v0[e] * hr * gq[0][e]; v1[e] = v1[e] * hr * gq[1][e]; }
;                         const f32x4 r0 = {v0[0] * cs[0][0] - v0[1] * sn[0][0], v0[0] * sn[0][0] + v0[1] * cs[0][0], v0[2] * cs[0][1] - v0[3] * sn[0][1], v0[2] * sn[0][1] + v0[3] * cs[0][1]};
;                         const f32x4 r1 = {v1[0] * cs[1][0] - v1[1] * sn[1][0], v1[0] * sn[1][0] + v1[1] * cs[1][0], v1[2] * cs[1][1] - v1[3] * sn[1][1], v1[2] * sn[1][1] + v1[3] * cs[1][1]};
;                         v0 = r0; v1 = r1;
;                         dst = u.pn < 4 ? Q + (size_t)row * DM + (u.pn * 2 + bj) * 128 : K + (size_t)kvrow * 512 + ((u.pn - 4) * 2 + bj) * 128;
;                     } else dst = V + (size_t)kvrow * 512 + ((u.pn - 6) * 2 + bj) * 128;
;                     u32x4 w; w.x = cvt_pk_bf16(v0[0], v0[1]); w.y = cvt_pk_bf16(v0[2], v0[3]); w.z = cvt_pk_bf16(v1[0], v1[1]); w.w = cvt_pk_bf16(v1[2], v1[3]);
;                     *(u32x4*)(dst + wc * 32 + 8 * fq) = w; } }
.LBB0_674:
	v_lshl_add_u64 v[82:83], v[122:123], 0, s[8:9]
	v_add_u32_e32 v9, 32, v191
	v_xor_b32_e32 v71, 32, v69
	v_cvt_pk_bf16_f32 v78, v130, v131
	v_cvt_pk_bf16_f32 v79, v132, v133
	v_cvt_pk_bf16_f32 v80, v128, v129
	v_lshl_add_u64 v[82:83], v[174:175], 1, v[82:83]
	v_add_u32_e32 v124, s35, v9
	s_and_b64 vcc, exec, s[42:43]
	s_mov_b64 s[48:49], -1
	v_cvt_pk_bf16_f32 v81, v134, v135
	global_store_dwordx4 v[82:83], v[78:81], off sc1
	s_cbranch_vccnz .LBB0_676
	v_bfe_u32 v68, v124, 6, 7
	v_cndmask_b32_e64 v68, v71, v68, s[38:39]
	v_cvt_f32_ubyte0_e32 v68, v68
	v_mul_f32_e32 v70, v7, v68
	v_mul_f32_e32 v70, 0.15915494, v70
	v_cos_f32_e32 v82, v70
	v_sin_f32_e32 v86, v70
	v_mul_f32_e32 v70, v192, v68
	v_mul_f32_e32 v70, 0.15915494, v70
	v_cos_f32_e32 v80, v70
	v_sin_f32_e32 v84, v70
	v_mul_f32_e32 v70, v185, v68
	v_mul_f32_e32 v68, v184, v68
	v_mul_f32_e32 v70, 0.15915494, v70
	v_mul_f32_e32 v68, 0.15915494, v68
	v_cos_f32_e32 v76, v70
	v_sin_f32_e32 v78, v70
	v_cos_f32_e32 v70, v68
	v_sin_f32_e32 v68, v68
	v_and_b32_e32 v79, 0x1fff, v124
	v_add_u32_e32 v122, s59, v79
	s_mov_b64 s[48:49], 0

; #define PG8_LAS __attribute__((address_space(3)))
; __device__ __forceinline__ unsigned cvt_pk_bf16(float lo, float hi) { unsigned r; asm volatile("v_cvt_pk_bf16_f32 %0, %1, %2" : "=v"(r) : "v"(lo), "v"(hi)); return r; }
;     __device__ __forceinline__ void operator()(f32x4 (&acc)[2][2][4][2], const Unit& u, int wr, int wc, int fr, int fq) const {
;     ...
;                 for (int bj = 0; bj < 2; ++bj) { f32x4 v0 = acc[ai][bj][m][0], v1 = acc[ai][bj][m][1]; bf16_t* dst;
;                     if (qk) { const f32x4 pt = *(const PG8_LAS f32x4*)(P + (rl * 2 + bj) * 4);
;                         const float hr = rsqrtf(((pt[0] + pt[1]) + (pt[2] + pt[3])) * (1.f / 128.f) + EPS);
; #pragma unroll
;                         for (int e = 0; e < 4; ++e) { v0[e] = v0[e] * hr * gq[0][e]; v1[e] = v1[e] * hr * gq[1][e]; }
;                         const f32x4 r0 = {v0[0] * cs[0][0] - v0[1] * sn[0][0], v0[0] * sn[0][0] + v0[1] * cs[0][0], v0[2] * cs[0][1] - v0[3] * sn[0][1], v0[2] * sn[0][1] + v0[3] * cs[0][1]};
;                         const f32x4 r1 = {v1[0] * cs[1][0] - v1[1] * sn[1][0], v1[0] * sn[1][0] + v1[1] * cs[1][0], v1[2] * cs[1][1] - v1[3] * sn[1][1], v1[2] * sn[1][1] + v1[3] * cs[1][1]};
;                         v0 = r0; v1 = r1;
;                         dst = u.pn < 4 ? Q + (size_t)row * DM + (u.pn * 2 + bj) * 128 : K + (size_t)kvrow * 512 + ((u.pn - 4) * 2 + bj) * 128;
;                     } else dst = V + (size_t)kvrow * 512 + ((u.pn - 6) * 2 + bj) * 128;
;                     u32x4 w; w.x = cvt_pk_bf16(v0[0], v0[1]); w.y = cvt_pk_bf16(v0[2], v0[3]); w.z = cvt_pk_bf16(v1[0], v1[1]); w.w = cvt_pk_bf16(v1[2], v1[3]);
;                     *(u32x4*)(dst + wc * 32 + 8 * fq) = w; } }
.LBB0_685:
	v_cvt_pk_bf16_f32 v108, v128, v109
	v_cvt_pk_bf16_f32 v109, v130, v121
	v_cvt_pk_bf16_f32 v110, v132, v111
	v_cvt_pk_bf16_f32 v111, v134, v107
	v_lshl_add_u64 v[106:107], v[136:137], 0, s[8:9]
	v_lshl_add_u64 v[106:107], v[174:175], 1, v[106:107]
	s_and_b64 vcc, exec, s[44:45]
	s_mov_b64 s[48:49], -1
	global_store_dwordx4 v[106:107], v[108:111], off sc1
	s_cbranch_vccnz .LBB0_687
	s_add_i32 s16, s72, 0xfffffa80
	s_ashr_i32 s17, s16, 31
	v_lshl_add_u64 v[106:107], s[16:17], 1, v[126:127]
	s_mov_b64 s[48:49], 0

; #define PG8_LAS __attribute__((address_space(3)))
;     __device__ __forceinline__ void operator()(f32x4 (&acc)[2][2][4][2], const Unit& u, int wr, int wc, int fr, int fq) const {
;     ...
;             for (int m = 0; m < 4; ++m) { const int rl = wr * 64 + fr + ai * HALF + m * 16, row = rowt + rl;
;                 int kvrow; float cs[2][2], sn[2][2];
;                 if (is_lat) { const int t = row & (SEQ - 1); kvrow = b * SKV + CTXL + t; const float pos = (float)((wc >> 1) ? (t & 63) : (t >> 6));
; #pragma unroll
;                     for (int n = 0; n < 2; ++n)
; #pragma unroll
;                         for (int pr = 0; pr < 2; ++pr) { const float a = pos * inv[n][pr]; cs[n][pr] = __cosf(a); sn[n][pr] = __sinf(a); } }
;                 else { kvrow = ((row - MLAT) >> 8) * SKV + ((row - MLAT) & (CTXL - 1));
; #pragma unroll
;                     for (int n = 0; n < 2; ++n)
; #pragma unroll
;                         for (int pr = 0; pr < 2; ++pr) { cs[n][pr] = 1.f; sn[n][pr] = 0.f; } }
; #pragma unroll
;                 for (int bj = 0; bj < 2; ++bj) { f32x4 v0 = acc[ai][bj][m][0], v1 = acc[ai][bj][m][1]; bf16_t* dst;
;                     if (qk) { const f32x4 pt = *(const PG8_LAS f32x4*)(P + (rl * 2 + bj) * 4);
;                         const float hr = rsqrtf(((pt[0] + pt[1]) + (pt[2] + pt[3])) * (1.f / 128.f) + EPS);
; #pragma unroll
;                         for (int e = 0; e < 4; ++e) { v0[e] = v0[e] * hr * gq[0][e]; v1[e] = v1[e] * hr * gq[1][e]; }
;                         const f32x4 r0 = {v0[0] * cs[0][0] - v0[1] * sn[0][0], v0[0] * sn[0][0] + v0[1] * cs[0][0], v0[2] * cs[0][1] - v0[3] * sn[0][1], v0[2] * sn[0][1] + v0[3] * cs[0][1]};
;                         const f32x4 r1 = {v1[0] * cs[1][0] - v1[1] * sn[1][0], v1[0] * sn[1][0] + v1[1] * cs[1][0], v1[2] * cs[1][1] - v1[3] * sn[1][1], v1[2] * sn[1][1] + v1[3] * cs[1][1]};
;                         v0 = r0; v1 = r1;
;                         dst = u.pn < 4 ? Q + (size_t)row * DM + (u.pn * 2 + bj) * 128 : K + (size_t)kvrow * 512 + ((u.pn - 4) * 2 + bj) * 128;
;                     } else dst = V + (size_t)kvrow * 512 + ((u.pn - 6) * 2 + bj) * 128;
;                     u32x4 w; w.x = cvt_pk_bf16(v0[0], v0[1]); w.y = cvt_pk_bf16(v0[2], v0[3]); w.z = cvt_pk_bf16(v1[0], v1[1]); w.w = cvt_pk_bf16(v1[2], v1[3]);
;                     *(u32x4*)(dst + wc * 32 + 8 * fq) = w; } }
.LBB0_693:
	v_add_u32_e32 v9, 48, v193
	v_and_b32_e32 v122, 63, v9
	v_lshl_add_u64 v[82:83], v[106:107], 0, s[8:9]
	v_add_u32_e32 v9, 48, v191
	v_cvt_pk_bf16_f32 v78, v114, v115
	v_cvt_pk_bf16_f32 v79, v116, v117
	v_cvt_pk_bf16_f32 v80, v112, v113
	v_lshl_add_u64 v[82:83], v[174:175], 1, v[82:83]
	v_add_u32_e32 v108, s35, v9
	s_and_b64 vcc, exec, s[42:43]
	s_mov_b64 s[48:49], -1
	v_cvt_pk_bf16_f32 v81, v118, v119
	global_store_dwordx4 v[82:83], v[78:81], off sc1
	s_cbranch_vccnz .LBB0_695
	v_bfe_u32 v68, v108, 6, 7
	v_cndmask_b32_e64 v68, v122, v68, s[38:39]
	v_cvt_f32_ubyte0_e32 v68, v68
	v_mul_f32_e32 v70, v7, v68
	v_mul_f32_e32 v70, 0.15915494, v70
	v_cos_f32_e32 v82, v70
	v_sin_f32_e32 v86, v70
	v_mul_f32_e32 v70, v192, v68
	v_mul_f32_e32 v70, 0.15915494, v70
	v_cos_f32_e32 v80, v70
	v_sin_f32_e32 v84, v70
	v_mul_f32_e32 v70, v185, v68
	v_mul_f32_e32 v68, v184, v68
	v_mul_f32_e32 v70, 0.15915494, v70
	v_mul_f32_e32 v68, 0.15915494, v68
	v_cos_f32_e32 v76, v70
	v_sin_f32_e32 v78, v70
	v_cos_f32_e32 v70, v68
	v_sin_f32_e32 v68, v68
	v_and_b32_e32 v79, 0x1fff, v108
	v_add_u32_e32 v106, s59, v79
	s_mov_b64 s[48:49], 0

; #define PG8_LAS __attribute__((address_space(3)))
; __device__ __forceinline__ unsigned cvt_pk_bf16(float lo, float hi) { unsigned r; asm volatile("v_cvt_pk_bf16_f32 %0, %1, %2" : "=v"(r) : "v"(lo), "v"(hi)); return r; }
;     __device__ __forceinline__ void operator()(f32x4 (&acc)[2][2][4][2], const Unit& u, int wr, int wc, int fr, int fq) const {
;     ...
;                 for (int bj = 0; bj < 2; ++bj) { f32x4 v0 = acc[ai][bj][m][0], v1 = acc[ai][bj][m][1]; bf16_t* dst;
;                     if (qk) { const f32x4 pt = *(const PG8_LAS f32x4*)(P + (rl * 2 + bj) * 4);
;                         const float hr = rsqrtf(((pt[0] + pt[1]) + (pt[2] + pt[3])) * (1.f / 128.f) + EPS);
; #pragma unroll
;                         for (int e = 0; e < 4; ++e) { v0[e] = v0[e] * hr * gq[0][e]; v1[e] = v1[e] * hr * gq[1][e]; }
;                         const f32x4 r0 = {v0[0] * cs[0][0] - v0[1] * sn[0][0], v0[0] * sn[0][0] + v0[1] * cs[0][0], v0[2] * cs[0][1] - v0[3] * sn[0][1], v0[2] * sn[0][1] + v0[3] * cs[0][1]};
;                         const f32x4 r1 = {v1[0] * cs[1][0] - v1[1] * sn[1][0], v1[0] * sn[1][0] + v1[1] * cs[1][0], v1[2] * cs[1][1] - v1[3] * sn[1][1], v1[2] * sn[1][1] + v1[3] * cs[1][1]};
;                         v0 = r0; v1 = r1;
;                         dst = u.pn < 4 ? Q + (size_t)row * DM + (u.pn * 2 + bj) * 128 : K + (size_t)kvrow * 512 + ((u.pn - 4) * 2 + bj) * 128;
;                     } else dst = V + (size_t)kvrow * 512 + ((u.pn - 6) * 2 + bj) * 128;
;                     u32x4 w; w.x = cvt_pk_bf16(v0[0], v0[1]); w.y = cvt_pk_bf16(v0[2], v0[3]); w.z = cvt_pk_bf16(v1[0], v1[1]); w.w = cvt_pk_bf16(v1[2], v1[3]);
;                     *(u32x4*)(dst + wc * 32 + 8 * fq) = w; } }
.LBB0_704:
	v_cvt_pk_bf16_f32 v92, v112, v93
	v_cvt_pk_bf16_f32 v93, v114, v105
	v_cvt_pk_bf16_f32 v94, v116, v95
	v_cvt_pk_bf16_f32 v95, v118, v91
	v_lshl_add_u64 v[90:91], v[120:121], 0, s[8:9]
	v_lshl_add_u64 v[90:91], v[174:175], 1, v[90:91]
	s_and_b64 vcc, exec, s[44:45]
	s_mov_b64 s[48:49], -1
	global_store_dwordx4 v[90:91], v[92:95], off sc1
	s_cbranch_vccnz .LBB0_706
	s_add_i32 s16, s72, 0xfffffa80
	s_ashr_i32 s17, s16, 31
	v_lshl_add_u64 v[90:91], s[16:17], 1, v[110:111]
	s_mov_b64 s[48:49], 0

; #define PG8_LAS __attribute__((address_space(3)))
;     __device__ __forceinline__ void operator()(f32x4 (&acc)[2][2][4][2], const Unit& u, int wr, int wc, int fr, int fq) const {
;     ...
;             for (int m = 0; m < 4; ++m) { const int rl = wr * 64 + fr + ai * HALF + m * 16, row = rowt + rl;
;                 int kvrow; float cs[2][2], sn[2][2];
;                 if (is_lat) { const int t = row & (SEQ - 1); kvrow = b * SKV + CTXL + t; const float pos = (float)((wc >> 1) ? (t & 63) : (t >> 6));
; #pragma unroll
;                     for (int n = 0; n < 2; ++n)
; #pragma unroll
;                         for (int pr = 0; pr < 2; ++pr) { const float a = pos * inv[n][pr]; cs[n][pr] = __cosf(a); sn[n][pr] = __sinf(a); } }
;                 else { kvrow = ((row - MLAT) >> 8) * SKV + ((row - MLAT) & (CTXL - 1));
; #pragma unroll
;                     for (int n = 0; n < 2; ++n)
; #pragma unroll
;                         for (int pr = 0; pr < 2; ++pr) { cs[n][pr] = 1.f; sn[n][pr] = 0.f; } }
; #pragma unroll
;                 for (int bj = 0; bj < 2; ++bj) { f32x4 v0 = acc[ai][bj][m][0], v1 = acc[ai][bj][m][1]; bf16_t* dst;
;                     if (qk) { const f32x4 pt = *(const PG8_LAS f32x4*)(P + (rl * 2 + bj) * 4);
;                         const float hr = rsqrtf(((pt[0] + pt[1]) + (pt[2] + pt[3])) * (1.f / 128.f) + EPS);
; #pragma unroll
;                         for (int e = 0; e < 4; ++e) { v0[e] = v0[e] * hr * gq[0][e]; v1[e] = v1[e] * hr * gq[1][e]; }
;                         const f32x4 r0 = {v0[0] * cs[0][0] - v0[1] * sn[0][0], v0[0] * sn[0][0] + v0[1] * cs[0][0], v0[2] * cs[0][1] - v0[3] * sn[0][1], v0[2] * sn[0][1] + v0[3] * cs[0][1]};
;                         const f32x4 r1 = {v1[0] * cs[1][0] - v1[1] * sn[1][0], v1[0] * sn[1][0] + v1[1] * cs[1][0], v1[2] * cs[1][1] - v1[3] * sn[1][1], v1[2] * sn[1][1] + v1[3] * cs[1][1]};
;                         v0 = r0; v1 = r1;
;                         dst = u.pn < 4 ? Q + (size_t)row * DM + (u.pn * 2 + bj) * 128 : K + (size_t)kvrow * 512 + ((u.pn - 4) * 2 + bj) * 128;
;                     } else dst = V + (size_t)kvrow * 512 + ((u.pn - 6) * 2 + bj) * 128;
;                     u32x4 w; w.x = cvt_pk_bf16(v0[0], v0[1]); w.y = cvt_pk_bf16(v0[2], v0[3]); w.z = cvt_pk_bf16(v1[0], v1[1]); w.w = cvt_pk_bf16(v1[2], v1[3]);
;                     *(u32x4*)(dst + wc * 32 + 8 * fq) = w; } }
.LBB0_712:
	v_lshl_add_u64 v[82:83], v[90:91], 0, s[8:9]
	v_add_u32_e32 v9, 0x80, v191
	v_cvt_pk_bf16_f32 v78, v98, v99
	v_cvt_pk_bf16_f32 v79, v100, v101
	v_cvt_pk_bf16_f32 v80, v96, v97
	v_lshl_add_u64 v[82:83], v[174:175], 1, v[82:83]
	v_add_u32_e32 v92, s35, v9
	s_and_b64 vcc, exec, s[42:43]
	s_mov_b64 s[48:49], -1
	v_cvt_pk_bf16_f32 v81, v102, v103
	global_store_dwordx4 v[82:83], v[78:81], off sc1
	s_cbranch_vccnz .LBB0_714
	v_bfe_u32 v68, v92, 6, 7
	v_cndmask_b32_e64 v68, v69, v68, s[38:39]
	v_cvt_f32_ubyte0_e32 v68, v68
	v_mul_f32_e32 v69, v7, v68
	v_mul_f32_e32 v69, 0.15915494, v69
	v_cos_f32_e32 v82, v69
	v_sin_f32_e32 v86, v69
	v_mul_f32_e32 v69, v192, v68
	v_mul_f32_e32 v69, 0.15915494, v69
	v_cos_f32_e32 v80, v69
	v_sin_f32_e32 v84, v69
	v_mul_f32_e32 v69, v185, v68
	v_mul_f32_e32 v68, v184, v68
	v_mul_f32_e32 v69, 0.15915494, v69
	v_mul_f32_e32 v68, 0.15915494, v68
	v_cos_f32_e32 v76, v69
	v_sin_f32_e32 v78, v69
	v_cos_f32_e32 v70, v68
	v_sin_f32_e32 v68, v68
	v_and_b32_e32 v69, 0x1fff, v92
	v_add_u32_e32 v90, s59, v69
	s_mov_b64 s[48:49], 0

; #define PG8_LAS __attribute__((address_space(3)))
; __device__ __forceinline__ unsigned cvt_pk_bf16(float lo, float hi) { unsigned r; asm volatile("v_cvt_pk_bf16_f32 %0, %1, %2" : "=v"(r) : "v"(lo), "v"(hi)); return r; }
;     __device__ __forceinline__ void operator()(f32x4 (&acc)[2][2][4][2], const Unit& u, int wr, int wc, int fr, int fq) const {
;     ...
;                 for (int bj = 0; bj < 2; ++bj) { f32x4 v0 = acc[ai][bj][m][0], v1 = acc[ai][bj][m][1]; bf16_t* dst;
;                     if (qk) { const f32x4 pt = *(const PG8_LAS f32x4*)(P + (rl * 2 + bj) * 4);
;                         const float hr = rsqrtf(((pt[0] + pt[1]) + (pt[2] + pt[3])) * (1.f / 128.f) + EPS);
; #pragma unroll
;                         for (int e = 0; e < 4; ++e) { v0[e] = v0[e] * hr * gq[0][e]; v1[e] = v1[e] * hr * gq[1][e]; }
;                         const f32x4 r0 = {v0[0] * cs[0][0] - v0[1] * sn[0][0], v0[0] * sn[0][0] + v0[1] * cs[0][0], v0[2] * cs[0][1] - v0[3] * sn[0][1], v0[2] * sn[0][1] + v0[3] * cs[0][1]};
;                         const f32x4 r1 = {v1[0] * cs[1][0] - v1[1] * sn[1][0], v1[0] * sn[1][0] + v1[1] * cs[1][0], v1[2] * cs[1][1] - v1[3] * sn[1][1], v1[2] * sn[1][1] + v1[3] * cs[1][1]};
;                         v0 = r0; v1 = r1;
;                         dst = u.pn < 4 ? Q + (size_t)row * DM + (u.pn * 2 + bj) * 128 : K + (size_t)kvrow * 512 + ((u.pn - 4) * 2 + bj) * 128;
;                     } else dst = V + (size_t)kvrow * 512 + ((u.pn - 6) * 2 + bj) * 128;
;                     u32x4 w; w.x = cvt_pk_bf16(v0[0], v0[1]); w.y = cvt_pk_bf16(v0[2], v0[3]); w.z = cvt_pk_bf16(v1[0], v1[1]); w.w = cvt_pk_bf16(v1[2], v1[3]);
;                     *(u32x4*)(dst + wc * 32 + 8 * fq) = w; } }
.LBB0_723:
	v_cvt_pk_bf16_f32 v60, v96, v61
	v_cvt_pk_bf16_f32 v61, v98, v89
	v_cvt_pk_bf16_f32 v62, v100, v63
	v_cvt_pk_bf16_f32 v63, v102, v59
	v_lshl_add_u64 v[58:59], v[104:105], 0, s[8:9]
	v_lshl_add_u64 v[58:59], v[174:175], 1, v[58:59]
	s_and_b64 vcc, exec, s[44:45]
	s_mov_b64 s[48:49], -1
	global_store_dwordx4 v[58:59], v[60:63], off sc1
	s_cbranch_vccnz .LBB0_725
	s_add_i32 s16, s72, 0xfffffa80
	s_ashr_i32 s17, s16, 31
	v_lshl_add_u64 v[58:59], s[16:17], 1, v[94:95]
	s_mov_b64 s[48:49], 0

; #define PG8_LAS __attribute__((address_space(3)))
;     __device__ __forceinline__ void operator()(f32x4 (&acc)[2][2][4][2], const Unit& u, int wr, int wc, int fr, int fq) const {
;     ...
;             for (int m = 0; m < 4; ++m) { const int rl = wr * 64 + fr + ai * HALF + m * 16, row = rowt + rl;
;                 int kvrow; float cs[2][2], sn[2][2];
;                 if (is_lat) { const int t = row & (SEQ - 1); kvrow = b * SKV + CTXL + t; const float pos = (float)((wc >> 1) ? (t & 63) : (t >> 6));
; #pragma unroll
;                     for (int n = 0; n < 2; ++n)
; #pragma unroll
;                         for (int pr = 0; pr < 2; ++pr) { const float a = pos * inv[n][pr]; cs[n][pr] = __cosf(a); sn[n][pr] = __sinf(a); } }
;                 else { kvrow = ((row - MLAT) >> 8) * SKV + ((row - MLAT) & (CTXL - 1));
; #pragma unroll
;                     for (int n = 0; n < 2; ++n)
; #pragma unroll
;                         for (int pr = 0; pr < 2; ++pr) { cs[n][pr] = 1.f; sn[n][pr] = 0.f; } }
; #pragma unroll
;                 for (int bj = 0; bj < 2; ++bj) { f32x4 v0 = acc[ai][bj][m][0], v1 = acc[ai][bj][m][1]; bf16_t* dst;
;                     if (qk) { const f32x4 pt = *(const PG8_LAS f32x4*)(P + (rl * 2 + bj) * 4);
;                         const float hr = rsqrtf(((pt[0] + pt[1]) + (pt[2] + pt[3])) * (1.f / 128.f) + EPS);
; #pragma unroll
;                         for (int e = 0; e < 4; ++e) { v0[e] = v0[e] * hr * gq[0][e]; v1[e] = v1[e] * hr * gq[1][e]; }
;                         const f32x4 r0 = {v0[0] * cs[0][0] - v0[1] * sn[0][0], v0[0] * sn[0][0] + v0[1] * cs[0][0], v0[2] * cs[0][1] - v0[3] * sn[0][1], v0[2] * sn[0][1] + v0[3] * cs[0][1]};
;                         const f32x4 r1 = {v1[0] * cs[1][0] - v1[1] * sn[1][0], v1[0] * sn[1][0] + v1[1] * cs[1][0], v1[2] * cs[1][1] - v1[3] * sn[1][1], v1[2] * sn[1][1] + v1[3] * cs[1][1]};
;                         v0 = r0; v1 = r1;
;                         dst = u.pn < 4 ? Q + (size_t)row * DM + (u.pn * 2 + bj) * 128 : K + (size_t)kvrow * 512 + ((u.pn - 4) * 2 + bj) * 128;
;                     } else dst = V + (size_t)kvrow * 512 + ((u.pn - 6) * 2 + bj) * 128;
;                     u32x4 w; w.x = cvt_pk_bf16(v0[0], v0[1]); w.y = cvt_pk_bf16(v0[2], v0[3]); w.z = cvt_pk_bf16(v1[0], v1[1]); w.w = cvt_pk_bf16(v1[2], v1[3]);
;                     *(u32x4*)(dst + wc * 32 + 8 * fq) = w; } }
.LBB0_731:
	v_lshl_add_u64 v[58:59], v[58:59], 0, s[8:9]
	v_add_u32_e32 v9, 0x90, v191
	v_cvt_pk_bf16_f32 v60, v66, v67
	v_cvt_pk_bf16_f32 v61, v72, v73
	v_cvt_pk_bf16_f32 v62, v64, v65
	v_lshl_add_u64 v[58:59], v[174:175], 1, v[58:59]
	v_add_u32_e32 v76, s35, v9
	s_and_b64 vcc, exec, s[42:43]
	s_mov_b64 s[48:49], -1
	v_cvt_pk_bf16_f32 v63, v74, v75
	global_store_dwordx4 v[58:59], v[60:63], off sc1
	s_cbranch_vccnz .LBB0_733
	v_bfe_u32 v58, v76, 6, 7
	v_cndmask_b32_e64 v58, v77, v58, s[38:39]
	v_cvt_f32_ubyte0_e32 v58, v58
	v_mul_f32_e32 v59, v7, v58
	v_mul_f32_e32 v59, 0.15915494, v59
	v_cos_f32_e32 v68, v59
	v_sin_f32_e32 v72, v59
	v_mul_f32_e32 v59, v192, v58
	v_mul_f32_e32 v59, 0.15915494, v59
	v_cos_f32_e32 v66, v59
	v_sin_f32_e32 v70, v59
	v_mul_f32_e32 v59, v185, v58
	v_mul_f32_e32 v58, v184, v58
	v_mul_f32_e32 v59, 0.15915494, v59
	v_mul_f32_e32 v58, 0.15915494, v58
	v_cos_f32_e32 v62, v59
	v_sin_f32_e32 v64, v59
	v_cos_f32_e32 v60, v58
	v_sin_f32_e32 v58, v58
	v_and_b32_e32 v59, 0x1fff, v76
	v_add_u32_e32 v74, s59, v59
	s_mov_b64 s[48:49], 0

; #define PG8_LAS __attribute__((address_space(3)))
; __device__ __forceinline__ unsigned cvt_pk_bf16(float lo, float hi) { unsigned r; asm volatile("v_cvt_pk_bf16_f32 %0, %1, %2" : "=v"(r) : "v"(lo), "v"(hi)); return r; }
;     __device__ __forceinline__ void operator()(f32x4 (&acc)[2][2][4][2], const Unit& u, int wr, int wc, int fr, int fq) const {
;     ...
;                 for (int bj = 0; bj < 2; ++bj) { f32x4 v0 = acc[ai][bj][m][0], v1 = acc[ai][bj][m][1]; bf16_t* dst;
;                     if (qk) { const f32x4 pt = *(const PG8_LAS f32x4*)(P + (rl * 2 + bj) * 4);
;                         const float hr = rsqrtf(((pt[0] + pt[1]) + (pt[2] + pt[3])) * (1.f / 128.f) + EPS);
; #pragma unroll
;                         for (int e = 0; e < 4; ++e) { v0[e] = v0[e] * hr * gq[0][e]; v1[e] = v1[e] * hr * gq[1][e]; }
;                         const f32x4 r0 = {v0[0] * cs[0][0] - v0[1] * sn[0][0], v0[0] * sn[0][0] + v0[1] * cs[0][0], v0[2] * cs[0][1] - v0[3] * sn[0][1], v0[2] * sn[0][1] + v0[3] * cs[0][1]};
;                         const f32x4 r1 = {v1[0] * cs[1][0] - v1[1] * sn[1][0], v1[0] * sn[1][0] + v1[1] * cs[1][0], v1[2] * cs[1][1] - v1[3] * sn[1][1], v1[2] * sn[1][1] + v1[3] * cs[1][1]};
;                         v0 = r0; v1 = r1;
;                         dst = u.pn < 4 ? Q + (size_t)row * DM + (u.pn * 2 + bj) * 128 : K + (size_t)kvrow * 512 + ((u.pn - 4) * 2 + bj) * 128;
;                     } else dst = V + (size_t)kvrow * 512 + ((u.pn - 6) * 2 + bj) * 128;
;                     u32x4 w; w.x = cvt_pk_bf16(v0[0], v0[1]); w.y = cvt_pk_bf16(v0[2], v0[3]); w.z = cvt_pk_bf16(v1[0], v1[1]); w.w = cvt_pk_bf16(v1[2], v1[3]);
;                     *(u32x4*)(dst + wc * 32 + 8 * fq) = w; } }
.LBB0_742:
	v_cvt_pk_bf16_f32 v44, v80, v45
	v_cvt_pk_bf16_f32 v45, v82, v57
	v_cvt_pk_bf16_f32 v46, v84, v47
	v_cvt_pk_bf16_f32 v47, v86, v43
	v_lshl_add_u64 v[42:43], v[88:89], 0, s[8:9]
	v_lshl_add_u64 v[42:43], v[174:175], 1, v[42:43]
	s_and_b64 vcc, exec, s[44:45]
	s_mov_b64 s[48:49], -1
	global_store_dwordx4 v[42:43], v[44:47], off sc1
	s_cbranch_vccnz .LBB0_744
	s_add_i32 s16, s72, 0xfffffa80
	s_ashr_i32 s17, s16, 31
	v_lshl_add_u64 v[42:43], s[16:17], 1, v[78:79]
	s_mov_b64 s[48:49], 0

; #define PG8_LAS __attribute__((address_space(3)))
;     __device__ __forceinline__ void operator()(f32x4 (&acc)[2][2][4][2], const Unit& u, int wr, int wc, int fr, int fq) const {
;     ...
;             for (int m = 0; m < 4; ++m) { const int rl = wr * 64 + fr + ai * HALF + m * 16, row = rowt + rl;
;                 int kvrow; float cs[2][2], sn[2][2];
;                 if (is_lat) { const int t = row & (SEQ - 1); kvrow = b * SKV + CTXL + t; const float pos = (float)((wc >> 1) ? (t & 63) : (t >> 6));
; #pragma unroll
;                     for (int n = 0; n < 2; ++n)
; #pragma unroll
;                         for (int pr = 0; pr < 2; ++pr) { const float a = pos * inv[n][pr]; cs[n][pr] = __cosf(a); sn[n][pr] = __sinf(a); } }
;                 else { kvrow = ((row - MLAT) >> 8) * SKV + ((row - MLAT) & (CTXL - 1));
; #pragma unroll
;                     for (int n = 0; n < 2; ++n)
; #pragma unroll
;                         for (int pr = 0; pr < 2; ++pr) { cs[n][pr] = 1.f; sn[n][pr] = 0.f; } }
; #pragma unroll
;                 for (int bj = 0; bj < 2; ++bj) { f32x4 v0 = acc[ai][bj][m][0], v1 = acc[ai][bj][m][1]; bf16_t* dst;
;                     if (qk) { const f32x4 pt = *(const PG8_LAS f32x4*)(P + (rl * 2 + bj) * 4);
;                         const float hr = rsqrtf(((pt[0] + pt[1]) + (pt[2] + pt[3])) * (1.f / 128.f) + EPS);
; #pragma unroll
;                         for (int e = 0; e < 4; ++e) { v0[e] = v0[e] * hr * gq[0][e]; v1[e] = v1[e] * hr * gq[1][e]; }
;                         const f32x4 r0 = {v0[0] * cs[0][0] - v0[1] * sn[0][0], v0[0] * sn[0][0] + v0[1] * cs[0][0], v0[2] * cs[0][1] - v0[3] * sn[0][1], v0[2] * sn[0][1] + v0[3] * cs[0][1]};
;                         const f32x4 r1 = {v1[0] * cs[1][0] - v1[1] * sn[1][0], v1[0] * sn[1][0] + v1[1] * cs[1][0], v1[2] * cs[1][1] - v1[3] * sn[1][1], v1[2] * sn[1][1] + v1[3] * cs[1][1]};
;                         v0 = r0; v1 = r1;
;                         dst = u.pn < 4 ? Q + (size_t)row * DM + (u.pn * 2 + bj) * 128 : K + (size_t)kvrow * 512 + ((u.pn - 4) * 2 + bj) * 128;
;                     } else dst = V + (size_t)kvrow * 512 + ((u.pn - 6) * 2 + bj) * 128;
;                     u32x4 w; w.x = cvt_pk_bf16(v0[0], v0[1]); w.y = cvt_pk_bf16(v0[2], v0[3]); w.z = cvt_pk_bf16(v1[0], v1[1]); w.w = cvt_pk_bf16(v1[2], v1[3]);
;                     *(u32x4*)(dst + wc * 32 + 8 * fq) = w; } }
.LBB0_750:
	v_lshl_add_u64 v[42:43], v[42:43], 0, s[8:9]
	v_add_u32_e32 v9, 0xa0, v191
	v_cvt_pk_bf16_f32 v44, v50, v51
	v_cvt_pk_bf16_f32 v45, v52, v53
	v_cvt_pk_bf16_f32 v46, v48, v49
	v_lshl_add_u64 v[42:43], v[174:175], 1, v[42:43]
	v_add_u32_e32 v60, s35, v9
	s_and_b64 vcc, exec, s[42:43]
	s_mov_b64 s[48:49], -1
	v_cvt_pk_bf16_f32 v47, v54, v55
	global_store_dwordx4 v[42:43], v[44:47], off sc1
	s_cbranch_vccnz .LBB0_752
	v_bfe_u32 v42, v60, 6, 7
	v_cndmask_b32_e64 v42, v71, v42, s[38:39]
	v_cvt_f32_ubyte0_e32 v42, v42
	v_mul_f32_e32 v43, v7, v42
	v_mul_f32_e32 v43, 0.15915494, v43
	v_cos_f32_e32 v52, v43
	v_sin_f32_e32 v56, v43
	v_mul_f32_e32 v43, v192, v42
	v_mul_f32_e32 v43, 0.15915494, v43
	v_cos_f32_e32 v50, v43
	v_sin_f32_e32 v54, v43
	v_mul_f32_e32 v43, v185, v42
	v_mul_f32_e32 v42, v184, v42
	v_mul_f32_e32 v43, 0.15915494, v43
	v_mul_f32_e32 v42, 0.15915494, v42
	v_cos_f32_e32 v46, v43
	v_sin_f32_e32 v48, v43
	v_cos_f32_e32 v44, v42
	v_sin_f32_e32 v42, v42
	v_and_b32_e32 v43, 0x1fff, v60
	v_add_u32_e32 v58, s59, v43
	s_mov_b64 s[48:49], 0

; #define PG8_LAS __attribute__((address_space(3)))
; __device__ __forceinline__ unsigned cvt_pk_bf16(float lo, float hi) { unsigned r; asm volatile("v_cvt_pk_bf16_f32 %0, %1, %2" : "=v"(r) : "v"(lo), "v"(hi)); return r; }
;     __device__ __forceinline__ void operator()(f32x4 (&acc)[2][2][4][2], const Unit& u, int wr, int wc, int fr, int fq) const {
;     ...
;                 for (int bj = 0; bj < 2; ++bj) { f32x4 v0 = acc[ai][bj][m][0], v1 = acc[ai][bj][m][1]; bf16_t* dst;
;                     if (qk) { const f32x4 pt = *(const PG8_LAS f32x4*)(P + (rl * 2 + bj) * 4);
;                         const float hr = rsqrtf(((pt[0] + pt[1]) + (pt[2] + pt[3])) * (1.f / 128.f) + EPS);
; #pragma unroll
;                         for (int e = 0; e < 4; ++e) { v0[e] = v0[e] * hr * gq[0][e]; v1[e] = v1[e] * hr * gq[1][e]; }
;                         const f32x4 r0 = {v0[0] * cs[0][0] - v0[1] * sn[0][0], v0[0] * sn[0][0] + v0[1] * cs[0][0], v0[2] * cs[0][1] - v0[3] * sn[0][1], v0[2] * sn[0][1] + v0[3] * cs[0][1]};
;                         const f32x4 r1 = {v1[0] * cs[1][0] - v1[1] * sn[1][0], v1[0] * sn[1][0] + v1[1] * cs[1][0], v1[2] * cs[1][1] - v1[3] * sn[1][1], v1[2] * sn[1][1] + v1[3] * cs[1][1]};
;                         v0 = r0; v1 = r1;
;                         dst = u.pn < 4 ? Q + (size_t)row * DM + (u.pn * 2 + bj) * 128 : K + (size_t)kvrow * 512 + ((u.pn - 4) * 2 + bj) * 128;
;                     } else dst = V + (size_t)kvrow * 512 + ((u.pn - 6) * 2 + bj) * 128;
;                     u32x4 w; w.x = cvt_pk_bf16(v0[0], v0[1]); w.y = cvt_pk_bf16(v0[2], v0[3]); w.z = cvt_pk_bf16(v1[0], v1[1]); w.w = cvt_pk_bf16(v1[2], v1[3]);
;                     *(u32x4*)(dst + wc * 32 + 8 * fq) = w; } }
.LBB0_761:
	v_cvt_pk_bf16_f32 v28, v64, v29
	v_cvt_pk_bf16_f32 v29, v66, v41
	v_cvt_pk_bf16_f32 v30, v68, v31
	v_cvt_pk_bf16_f32 v31, v70, v27
	v_lshl_add_u64 v[26:27], v[72:73], 0, s[8:9]
	v_lshl_add_u64 v[26:27], v[174:175], 1, v[26:27]
	s_and_b64 vcc, exec, s[44:45]
	s_mov_b64 s[48:49], -1
	global_store_dwordx4 v[26:27], v[28:31], off sc1
	s_cbranch_vccnz .LBB0_763
	s_add_i32 s16, s72, 0xfffffa80
	s_ashr_i32 s17, s16, 31
	v_lshl_add_u64 v[26:27], s[16:17], 1, v[62:63]
	s_mov_b64 s[48:49], 0

; #define PG8_LAS __attribute__((address_space(3)))
;     __device__ __forceinline__ void operator()(f32x4 (&acc)[2][2][4][2], const Unit& u, int wr, int wc, int fr, int fq) const {
;     ...
;             for (int m = 0; m < 4; ++m) { const int rl = wr * 64 + fr + ai * HALF + m * 16, row = rowt + rl;
;                 int kvrow; float cs[2][2], sn[2][2];
;                 if (is_lat) { const int t = row & (SEQ - 1); kvrow = b * SKV + CTXL + t; const float pos = (float)((wc >> 1) ? (t & 63) : (t >> 6));
; #pragma unroll
;                     for (int n = 0; n < 2; ++n)
; #pragma unroll
;                         for (int pr = 0; pr < 2; ++pr) { const float a = pos * inv[n][pr]; cs[n][pr] = __cosf(a); sn[n][pr] = __sinf(a); } }
;                 else { kvrow = ((row - MLAT) >> 8) * SKV + ((row - MLAT) & (CTXL - 1));
; #pragma unroll
;                     for (int n = 0; n < 2; ++n)
; #pragma unroll
;                         for (int pr = 0; pr < 2; ++pr) { cs[n][pr] = 1.f; sn[n][pr] = 0.f; } }
; #pragma unroll
;                 for (int bj = 0; bj < 2; ++bj) { f32x4 v0 = acc[ai][bj][m][0], v1 = acc[ai][bj][m][1]; bf16_t* dst;
;                     if (qk) { const f32x4 pt = *(const PG8_LAS f32x4*)(P + (rl * 2 + bj) * 4);
;                         const float hr = rsqrtf(((pt[0] + pt[1]) + (pt[2] + pt[3])) * (1.f / 128.f) + EPS);
; #pragma unroll
;                         for (int e = 0; e < 4; ++e) { v0[e] = v0[e] * hr * gq[0][e]; v1[e] = v1[e] * hr * gq[1][e]; }
;                         const f32x4 r0 = {v0[0] * cs[0][0] - v0[1] * sn[0][0], v0[0] * sn[0][0] + v0[1] * cs[0][0], v0[2] * cs[0][1] - v0[3] * sn[0][1], v0[2] * sn[0][1] + v0[3] * cs[0][1]};
;                         const f32x4 r1 = {v1[0] * cs[1][0] - v1[1] * sn[1][0], v1[0] * sn[1][0] + v1[1] * cs[1][0], v1[2] * cs[1][1] - v1[3] * sn[1][1], v1[2] * sn[1][1] + v1[3] * cs[1][1]};
;                         v0 = r0; v1 = r1;
;                         dst = u.pn < 4 ? Q + (size_t)row * DM + (u.pn * 2 + bj) * 128 : K + (size_t)kvrow * 512 + ((u.pn - 4) * 2 + bj) * 128;
;                     } else dst = V + (size_t)kvrow * 512 + ((u.pn - 6) * 2 + bj) * 128;
;                     u32x4 w; w.x = cvt_pk_bf16(v0[0], v0[1]); w.y = cvt_pk_bf16(v0[2], v0[3]); w.z = cvt_pk_bf16(v1[0], v1[1]); w.w = cvt_pk_bf16(v1[2], v1[3]);
;                     *(u32x4*)(dst + wc * 32 + 8 * fq) = w; } }
.LBB0_769:
	v_lshl_add_u64 v[26:27], v[26:27], 0, s[8:9]
	v_add_u32_e32 v9, 0xb0, v191
	v_cvt_pk_bf16_f32 v28, v34, v35
	v_cvt_pk_bf16_f32 v29, v36, v37
	v_cvt_pk_bf16_f32 v30, v32, v33
	v_lshl_add_u64 v[26:27], v[174:175], 1, v[26:27]
	v_add_u32_e32 v44, s35, v9
	s_and_b64 vcc, exec, s[42:43]
	s_mov_b64 s[42:43], -1
	v_cvt_pk_bf16_f32 v31, v38, v39
	global_store_dwordx4 v[26:27], v[28:31], off sc1
	s_cbranch_vccnz .LBB0_771
	v_bfe_u32 v26, v44, 6, 7
	v_cndmask_b32_e64 v26, v122, v26, s[38:39]
	v_cvt_f32_ubyte0_e32 v26, v26
	v_mul_f32_e32 v7, v7, v26
	v_mul_f32_e32 v7, 0.15915494, v7
	v_cos_f32_e32 v36, v7
	v_sin_f32_e32 v40, v7
	v_mul_f32_e32 v7, v192, v26
	v_mul_f32_e32 v7, 0.15915494, v7
	v_cos_f32_e32 v34, v7
	v_sin_f32_e32 v38, v7
	v_mul_f32_e32 v7, v185, v26
	v_mul_f32_e32 v7, 0.15915494, v7
	v_cos_f32_e32 v30, v7
	v_sin_f32_e32 v32, v7
	v_mul_f32_e32 v7, v184, v26
	v_mul_f32_e32 v7, 0.15915494, v7
	v_cos_f32_e32 v28, v7
	v_sin_f32_e32 v26, v7
	v_and_b32_e32 v7, 0x1fff, v44
	v_add_u32_e32 v42, s59, v7
	s_mov_b64 s[42:43], 0

; #define PG8_LAS __attribute__((address_space(3)))
; __device__ __forceinline__ unsigned cvt_pk_bf16(float lo, float hi) { unsigned r; asm volatile("v_cvt_pk_bf16_f32 %0, %1, %2" : "=v"(r) : "v"(lo), "v"(hi)); return r; }
;     __device__ __forceinline__ void operator()(f32x4 (&acc)[2][2][4][2], const Unit& u, int wr, int wc, int fr, int fq) const {
;     ...
;                 for (int bj = 0; bj < 2; ++bj) { f32x4 v0 = acc[ai][bj][m][0], v1 = acc[ai][bj][m][1]; bf16_t* dst;
;                     if (qk) { const f32x4 pt = *(const PG8_LAS f32x4*)(P + (rl * 2 + bj) * 4);
;                         const float hr = rsqrtf(((pt[0] + pt[1]) + (pt[2] + pt[3])) * (1.f / 128.f) + EPS);
; #pragma unroll
;                         for (int e = 0; e < 4; ++e) { v0[e] = v0[e] * hr * gq[0][e]; v1[e] = v1[e] * hr * gq[1][e]; }
;                         const f32x4 r0 = {v0[0] * cs[0][0] - v0[1] * sn[0][0], v0[0] * sn[0][0] + v0[1] * cs[0][0], v0[2] * cs[0][1] - v0[3] * sn[0][1], v0[2] * sn[0][1] + v0[3] * cs[0][1]};
;                         const f32x4 r1 = {v1[0] * cs[1][0] - v1[1] * sn[1][0], v1[0] * sn[1][0] + v1[1] * cs[1][0], v1[2] * cs[1][1] - v1[3] * sn[1][1], v1[2] * sn[1][1] + v1[3] * cs[1][1]};
;                         v0 = r0; v1 = r1;
;                         dst = u.pn < 4 ? Q + (size_t)row * DM + (u.pn * 2 + bj) * 128 : K + (size_t)kvrow * 512 + ((u.pn - 4) * 2 + bj) * 128;
;                     } else dst = V + (size_t)kvrow * 512 + ((u.pn - 6) * 2 + bj) * 128;
;                     u32x4 w; w.x = cvt_pk_bf16(v0[0], v0[1]); w.y = cvt_pk_bf16(v0[2], v0[3]); w.z = cvt_pk_bf16(v1[0], v1[1]); w.w = cvt_pk_bf16(v1[2], v1[3]);
;                     *(u32x4*)(dst + wc * 32 + 8 * fq) = w; } }
.LBB0_780:
	v_cvt_pk_bf16_f32 v12, v48, v13
	v_cvt_pk_bf16_f32 v13, v50, v25
	v_cvt_pk_bf16_f32 v14, v52, v15
	v_cvt_pk_bf16_f32 v15, v54, v11
	v_lshl_add_u64 v[10:11], v[56:57], 0, s[8:9]
	v_lshl_add_u64 v[10:11], v[174:175], 1, v[10:11]
	s_and_b64 vcc, exec, s[44:45]
	s_mov_b64 s[42:43], -1
	global_store_dwordx4 v[10:11], v[12:15], off sc1
	s_cbranch_vccnz .LBB0_782
	s_add_i32 s16, s72, 0xfffffa80
	s_ashr_i32 s17, s16, 31
	v_lshl_add_u64 v[10:11], s[16:17], 1, v[46:47]
	s_mov_b64 s[42:43], 0

; __device__ __forceinline__ unsigned cvt_pk_bf16(float lo, float hi) { unsigned r; asm volatile("v_cvt_pk_bf16_f32 %0, %1, %2" : "=v"(r) : "v"(lo), "v"(hi)); return r; }
;     __device__ __forceinline__ void operator()(f32x4 (&acc)[2][2][4][2], const Unit& u, int wr, int wc, int fr, int fq) const {
;     ...
;                     u32x4 w; w.x = cvt_pk_bf16(v0[0], v0[1]); w.y = cvt_pk_bf16(v0[2], v0[3]); w.z = cvt_pk_bf16(v1[0], v1[1]); w.w = cvt_pk_bf16(v1[2], v1[3]);
;                     *(u32x4*)(dst + wc * 32 + 8 * fq) = w; } }
.LBB0_788:
	s_waitcnt vmcnt(15)
	v_lshl_add_u64 v[4:5], v[10:11], 0, s[8:9]
	v_lshl_add_u64 v[4:5], v[174:175], 1, v[4:5]
	v_cvt_pk_bf16_f32 v0, v18, v19
	v_cvt_pk_bf16_f32 v1, v20, v21
	v_cvt_pk_bf16_f32 v2, v16, v17
	v_cvt_pk_bf16_f32 v3, v22, v23
	global_store_dwordx4 v[4:5], v[0:3], off sc1

; __device__ __forceinline__ int v_st(int k, int c) { const int kk = (k & ~0xC) | ((k & 4) << 1) | ((k & 8) >> 1); return ((kk >> 3) * 4 + (c >> 5)) * 512 + ((kk & 7) * 32 + (c & 31)) * 2; }
; __device__ __forceinline__ int v_rd_base(int lane) { return ((lane & 3) << 3) | (((lane >> 2) & 3) << 6) | (((lane >> 4) & 1) << 5) | (((lane >> 5) & 1) << 8); }
; #define SLOAD0(k0) do { s0_vs0 = ld8(&Vh[(long)((k0) + sr) * LDK + sc]); s0_vs1 = ld8(&Vh[(long)((k0) + 32 + sr) * LDK + sc]); \
;     s0_ks0 = ld8(&Kh[(long)((k0) + sr) * LDK + sc]); s0_ks1 = ld8(&Kh[(long)((k0) + 32 + sr) * LDK + sc]); } while (0)
; #define SWRITE0(b) do { *(bf16x8*)((char*)V_lds + (b) * SHM_V + vst0) = s0_vs0; *(bf16x8*)((char*)V_lds + (b) * SHM_V + vst1) = s0_vs1; const int kc = sc * 2; \
;     *(bf16x8*)((char*)K_lds + (b) * SHM_K + KSWZ(sr, kc)) = s0_ks0; *(bf16x8*)((char*)K_lds + (b) * SHM_K + KSWZ(32 + sr, kc)) = s0_ks1; } while (0)
; __device__ __forceinline__ void attn_dense_body(const bf16* __restrict__ Qb, const bf16* __restrict__ Kh, const bf16* __restrict__ Vh,
;                                                 bf16* __restrict__ Ob, int seq, char* lds, const int tid, const float mnC) {
;   const int wid = tid >> 6, lane = tid & 63, r32 = lane & 31, hi = lane >> 5;
;   bf16* V_lds = (bf16*)lds; bf16* K_lds = (bf16*)(lds + 2 * SHM_V);
;   float* ws = (float*)(lds + 2 * SHM_V + 2 * SHM_K) + wid * 64; float* li_l = ws;
;   float l_reg = 0; f32x16 o[4] = {}; bf16x8 qr[8];
;   const bf16* Qw = Qb + (long)(wid * QBLK + r32) * LDQ + hi * 8;
; #pragma unroll
;   for (int d0 = 0; d0 < 8; ++d0) qr[d0] = ld8(Qw + d0 * 16);
;   const int sr = tid >> 4, sc = (tid & 15) * 8, vst0 = v_st(sr, sc), vst1 = v_st(32 + sr, sc);
;   const int vb0 = (int)(uintptr_t)V_lds + v_rd_base(lane);
;   bf16x8 s0_vs0, s0_vs1, s0_ks0, s0_ks1;
;     ...
;   f32x16 pA0, pA1, pB0, pB1; bf16x8 pa0, pa1, pa2, pa3; const int NT = seq / KVBLK;
;   SLOAD0(0);
;   bf16x8 t1_vs0 = ld8(&Vh[(long)(KVBLK + sr) * LDK + sc]), t1_vs1 = ld8(&Vh[(long)(KVBLK + 32 + sr) * LDK + sc]);
;   bf16x8 t1_ks0 = ld8(&Kh[(long)(KVBLK + sr) * LDK + sc]), t1_ks1 = ld8(&Kh[(long)(KVBLK + 32 + sr) * LDK + sc]);
;   asm volatile("s_waitcnt vmcnt(4)" ::: "memory"); SWRITE0(0); __syncthreads();
.LBB0_1037:
	s_bfe_u32 s12, s8, 0x10002
	s_lshl_b32 s3, s8, 15
	s_lshl_b32 s2, s12, 23
	s_and_b32 s3, s3, 0x7c0000
	s_or_b32 s6, s2, s3
	s_lshl_b32 s2, s8, 8
	s_and_b32 s13, s2, 0x300
	s_ashr_i32 s2, s8, 1
	v_mov_b32_e32 v174, v170
	s_and_b32 s2, s2, 0xffffff80
	s_add_i32 s7, s13, s2
	s_load_dwordx2 s[2:3], s[0:1], 0xb8
	s_ashr_i32 s14, s7, 31
	s_add_u32 s6, s6, s7
	s_addc_u32 s7, 0, s14
	s_lshl_b64 s[6:7], s[6:7], 1
	s_waitcnt lgkmcnt(0)
	s_add_u32 s16, s2, s6
	s_mul_i32 s12, s12, 0x840000
	s_addc_u32 s17, s3, s7
	s_or_b32 s12, s13, s12
	s_add_u32 s14, s2, s12
	s_addc_u32 s15, s3, 0
	s_add_u32 s12, s14, 0xda00000
	v_ashrrev_i32_e32 v16, 4, v174
	v_lshlrev_b32_e32 v26, 3, v174
	s_addc_u32 s13, s15, 0
	v_and_b32_e32 v0, 0x78, v26
	v_ashrrev_i32_e32 v17, 31, v16
	s_add_u32 s14, s14, 0xeb00000
	v_lshlrev_b32_e32 v28, 1, v0
	v_lshlrev_b64 v[32:33], 10, v[16:17]
	s_addc_u32 s15, s15, 0
	v_or_b32_e32 v20, v32, v28
	v_mov_b32_e32 v21, v33
	v_lshl_add_u64 v[0:1], s[14:15], 0, v[20:21]
	global_load_dwordx4 v[0:3], v[0:1], off
	v_add_u32_e32 v18, 32, v16
	v_ashrrev_i32_e32 v19, 31, v18
	v_lshlrev_b64 v[12:13], 10, v[18:19]
	v_or_b32_e32 v12, v12, v28
	v_lshl_add_u64 v[4:5], s[14:15], 0, v[12:13]
	v_lshl_add_u64 v[8:9], s[12:13], 0, v[20:21]
	v_lshl_add_u64 v[12:13], s[12:13], 0, v[12:13]
	global_load_dwordx4 v[4:7], v[4:5], off
	v_ashrrev_i32_e32 v54, 6, v174
	global_load_dwordx4 v[8:11], v[8:9], off
	v_and_b32_e32 v171, 31, v174
	global_load_dwordx4 v[12:15], v[12:13], off
	v_lshlrev_b32_e32 v158, 5, v54
	v_or_b32_e32 v22, v158, v171
	v_ashrrev_i32_e32 v23, 31, v22
	v_bfe_u32 v172, v174, 5, 1
	v_lshlrev_b64 v[22:23], 11, v[22:23]
	v_lshl_add_u64 v[22:23], s[16:17], 0, v[22:23]
	v_lshlrev_b32_e32 v212, 4, v172
	v_lshl_add_u64 v[22:23], v[22:23], 0, v[212:213]
	s_mov_b32 s16, 0xba00000
	v_add_co_u32_e32 v24, vcc, s16, v22
	s_mov_b64 s[16:17], 0xba00000
	s_nop 0
	v_addc_co_u32_e32 v25, vcc, 0, v23, vcc
	global_load_dwordx4 v[124:127], v[24:25], off
	v_lshl_add_u64 v[22:23], v[22:23], 0, s[16:17]
	global_load_dwordx4 v[120:123], v[22:23], off offset:32
	global_load_dwordx4 v[116:119], v[22:23], off offset:64
	global_load_dwordx4 v[112:115], v[22:23], off offset:96
	global_load_dwordx4 v[108:111], v[22:23], off offset:128
	global_load_dwordx4 v[104:107], v[22:23], off offset:160
	global_load_dwordx4 v[100:103], v[22:23], off offset:192
	global_load_dwordx4 v[96:99], v[22:23], off offset:224
	v_and_b32_e32 v17, 0xfffff0, v16
	v_lshlrev_b32_e32 v19, 1, v16
	v_and_b32_e32 v24, 0xfffff0, v18
	v_lshlrev_b32_e32 v25, 1, v18
	v_and_or_b32 v17, v19, 8, v17
	v_and_or_b32 v24, v25, 8, v24
	v_lshrrev_b32_e32 v19, 1, v16
	v_lshrrev_b32_e32 v17, 1, v17
	v_bfe_u32 v22, v26, 5, 2
	v_and_b32_e32 v23, 3, v16
	v_lshrrev_b32_e32 v24, 1, v24
	v_or_b32_e32 v17, v17, v22
	v_and_or_b32 v19, v19, 4, v23
	v_or_b32_e32 v22, v24, v22
	v_lshlrev_b32_e32 v17, 9, v17
	v_lshlrev_b32_e32 v19, 6, v19
	v_and_b32_e32 v23, 48, v28
	v_lshlrev_b32_e32 v22, 9, v22
	s_mov_b64 s[16:17], 0x10000
	v_or3_b32 v17, v17, v19, v23
	v_or3_b32 v19, v22, v19, v23
	v_lshl_add_u64 v[22:23], v[20:21], 0, s[16:17]
	s_mov_b64 s[16:17], 0x18000
	v_lshl_add_u64 v[24:25], s[14:15], 0, v[22:23]
	v_lshl_add_u64 v[20:21], v[20:21], 0, s[16:17]
	v_lshl_add_u64 v[22:23], s[12:13], 0, v[22:23]
	v_add_u32_e32 v175, 0, v17
	v_lshl_add_u64 v[26:27], s[14:15], 0, v[20:21]
	global_load_dwordx4 v[34:37], v[24:25], off
	global_load_dwordx4 v[38:41], v[26:27], off
	v_lshl_add_u64 v[20:21], s[12:13], 0, v[20:21]
	global_load_dwordx4 v[42:45], v[22:23], off
	global_load_dwordx4 v[46:49], v[20:21], off
	s_waitcnt vmcnt(4)
	v_lshlrev_b32_e32 v55, 8, v171
	v_add_u32_e32 v176, 0, v19
	v_or_b32_e32 v50, 32, v212
	v_readfirstlane_b32 s12, v54
	s_cmp_lt_i32 s12, 4
	s_waitcnt vmcnt(15)
	ds_write_b128 v175, v[0:3]
	v_lshlrev_b32_e32 v0, 8, v16
	v_and_b32_e32 v1, 0xf0, v174
	v_bitop3_b32 v0, v28, v0, v1 bitop3:0xde
	v_add_u32_e32 v177, 0, v0
	v_lshlrev_b32_e32 v0, 8, v18
	v_bitop3_b32 v0, v28, v0, v1 bitop3:0xde
	v_add_u32_e32 v178, 0, v0
	v_lshlrev_b32_e32 v0, 4, v174
	v_and_b32_e32 v56, 0xf0, v0
	v_bitop3_b32 v0, v212, v55, v56 bitop3:0xde
	v_add_u32_e32 v179, 0, v0
	s_waitcnt vmcnt(14)
	ds_write_b128 v176, v[4:7]
	s_waitcnt vmcnt(13)
	ds_write_b128 v177, v[8:11] offset:32768
	s_waitcnt vmcnt(12)
	ds_write_b128 v178, v[12:15] offset:32768
	s_waitcnt lgkmcnt(0)
	s_barrier
; #define SWRITE0(b) do { *(bf16x8*)((char*)V_lds + (b) * SHM_V + vst0) = s0_vs0; *(bf16x8*)((char*)V_lds + (b) * SHM_V + vst1) = s0_vs1; const int kc = sc * 2; \
;     *(bf16x8*)((char*)K_lds + (b) * SHM_K + KSWZ(sr, kc)) = s0_ks0; *(bf16x8*)((char*)K_lds + (b) * SHM_K + KSWZ(32 + sr, kc)) = s0_ks1; } while (0)
; #define SWAIT() asm volatile("s_waitcnt vmcnt(0)" ::: "memory")
; __device__ __forceinline__ void qkt(f32x16& p0, f32x16& p1, const bf16* Ks, const bf16x8* qr, int r32, int hi) {
;   p0 = f32x16{}; p1 = f32x16{};
; #pragma unroll
;   for (int d0 = 0; d0 < 8; ++d0) { int cb = (d0 * 16 + hi * 8) * 2;
;     bf16x8 b0 = *reinterpret_cast<const bf16x8*>((const char*)Ks + KSWZ(r32, cb));
;     bf16x8 b1 = *reinterpret_cast<const bf16x8*>((const char*)Ks + KSWZ(32 + r32, cb));
;     p0 = __builtin_amdgcn_mfma_f32_32x32x16_bf16(b0, qr[d0], p0, 0, 0, 0);
;     p1 = __builtin_amdgcn_mfma_f32_32x32x16_bf16(b1, qr[d0], p1, 0, 0, 0); }
; }
; __device__ __forceinline__ void attn_dense_body(const bf16* __restrict__ Qb, const bf16* __restrict__ Kh, const bf16* __restrict__ Vh,
;                                                 bf16* __restrict__ Ob, int seq, char* lds, const int tid, const float mnC) {
;     ...
;   asm volatile("s_waitcnt vmcnt(4)" ::: "memory"); SWRITE0(0); __syncthreads();
;   qkt(pA0, pA1, K_lds, qr, r32, hi); partialSM(pA0, pA1, mnC);
;   s0_vs0 = t1_vs0; s0_vs1 = t1_vs1; s0_ks0 = t1_ks0; s0_ks1 = t1_ks1;
;   SWAIT(); SWRITE0(1); __syncthreads();
;   if (__builtin_amdgcn_readfirstlane(wid) >= 4) __builtin_amdgcn_s_setprio(1);
	ds_read_b128 v[0:3], v179 offset:32768
	v_bitop3_b32 v50, v50, v55, v56 bitop3:0xde
	v_add_u32_e32 v182, 0, v50
	ds_read_b128 v[50:53], v182 offset:32768
	s_waitcnt vmcnt(11) lgkmcnt(1)
	v_mfma_f32_32x32x16_bf16 v[16:31], v[0:3], v[124:127], 0
	ds_read_b128 v[0:3], v179 offset:40960
	s_waitcnt vmcnt(10) lgkmcnt(1)
	v_mfma_f32_32x32x16_bf16 v[16:31], v[50:53], v[120:123], v[16:31]
	ds_read_b128 v[50:53], v182 offset:40960
	s_waitcnt lgkmcnt(1)
	v_mfma_f32_32x32x16_bf16 v[0:15], v[0:3], v[124:127], 0
	s_waitcnt lgkmcnt(0)
	v_mfma_f32_32x32x16_bf16 v[0:15], v[50:53], v[120:123], v[0:15]
	v_or_b32_e32 v50, 64, v212
	v_bitop3_b32 v50, v50, v55, v56 bitop3:0xde
	v_add_u32_e32 v183, 0, v50
	ds_read_b128 v[50:53], v183 offset:32768
	s_waitcnt vmcnt(9) lgkmcnt(0)
	v_mfma_f32_32x32x16_bf16 v[16:31], v[50:53], v[116:119], v[16:31]
	ds_read_b128 v[50:53], v183 offset:40960
	s_waitcnt lgkmcnt(0)
	v_mfma_f32_32x32x16_bf16 v[0:15], v[50:53], v[116:119], v[0:15]
	v_or_b32_e32 v50, 0x60, v212
	v_bitop3_b32 v50, v50, v55, v56 bitop3:0xde
	v_add_u32_e32 v184, 0, v50
	ds_read_b128 v[50:53], v184 offset:32768
	s_waitcnt vmcnt(8) lgkmcnt(0)
	v_mfma_f32_32x32x16_bf16 v[16:31], v[50:53], v[112:115], v[16:31]
	ds_read_b128 v[50:53], v184 offset:40960
	s_waitcnt lgkmcnt(0)
	v_mfma_f32_32x32x16_bf16 v[0:15], v[50:53], v[112:115], v[0:15]
	v_or_b32_e32 v50, 0x80, v212
	v_bitop3_b32 v50, v50, v55, v56 bitop3:0xde
	v_add_u32_e32 v185, 0, v50
	ds_read_b128 v[50:53], v185 offset:32768
	s_waitcnt vmcnt(7) lgkmcnt(0)
	v_mfma_f32_32x32x16_bf16 v[16:31], v[50:53], v[108:111], v[16:31]
	ds_read_b128 v[50:53], v185 offset:40960
	s_waitcnt lgkmcnt(0)
	v_mfma_f32_32x32x16_bf16 v[0:15], v[50:53], v[108:111], v[0:15]
	v_or_b32_e32 v50, 0xa0, v212
	v_bitop3_b32 v50, v50, v55, v56 bitop3:0xde
	v_add_u32_e32 v186, 0, v50
	ds_read_b128 v[50:53], v186 offset:32768
	s_waitcnt vmcnt(6) lgkmcnt(0)
	v_mfma_f32_32x32x16_bf16 v[16:31], v[50:53], v[104:107], v[16:31]
	ds_read_b128 v[50:53], v186 offset:40960
	s_waitcnt lgkmcnt(0)
	v_mfma_f32_32x32x16_bf16 v[0:15], v[50:53], v[104:107], v[0:15]
	v_or_b32_e32 v50, 0xc0, v212
	v_bitop3_b32 v50, v50, v55, v56 bitop3:0xde
	v_add_u32_e32 v180, 0, v50
	ds_read_b128 v[50:53], v180 offset:32768
	s_waitcnt vmcnt(5) lgkmcnt(0)
	v_mfma_f32_32x32x16_bf16 v[16:31], v[50:53], v[100:103], v[16:31]
	ds_read_b128 v[50:53], v180 offset:40960
	s_waitcnt lgkmcnt(0)
	v_mfma_f32_32x32x16_bf16 v[0:15], v[50:53], v[100:103], v[0:15]
	v_or_b32_e32 v50, 0xe0, v212
	v_bitop3_b32 v50, v50, v55, v56 bitop3:0xde
	v_add_u32_e32 v181, 0, v50
	ds_read_b128 v[50:53], v181 offset:32768
	s_waitcnt vmcnt(4) lgkmcnt(0)
	v_mfma_f32_32x32x16_bf16 v[16:31], v[50:53], v[96:99], v[16:31]
	ds_read_b128 v[50:53], v181 offset:40960
	s_waitcnt vmcnt(0)
	s_waitcnt vmcnt(3)
	ds_write_b128 v175, v[34:37] offset:16384
	s_waitcnt vmcnt(2)
	ds_write_b128 v176, v[38:41] offset:16384
	s_waitcnt vmcnt(1)
	ds_write_b128 v177, v[42:45] offset:49152
	s_waitcnt vmcnt(0)
	ds_write_b128 v178, v[46:49] offset:49152
	s_waitcnt lgkmcnt(0)
	s_barrier
	v_mfma_f32_32x32x16_bf16 v[0:15], v[50:53], v[96:99], v[0:15]
	s_cbranch_scc1 .LBB0_1039
	s_setprio 1
; __device__ __forceinline__ int v_st(int k, int c) { const int kk = (k & ~0xC) | ((k & 4) << 1) | ((k & 8) >> 1); return ((kk >> 3) * 4 + (c >> 5)) * 512 + ((kk & 7) * 32 + (c & 31)) * 2; }
; __device__ __forceinline__ int v_rd_base(int lane) { return ((lane & 3) << 3) | (((lane >> 2) & 3) << 6) | (((lane >> 4) & 1) << 5) | (((lane >> 5) & 1) << 8); }
; __device__ __forceinline__ void partialSM(f32x16& p0, f32x16& p1, float mnC) {
;   constexpr float C = SCALE * 1.4426950408889634f;
; #pragma unroll
;   for (int r = 0; r < 16; ++r) p0[r] = fmaf(p0[r], C, mnC);
; #pragma unroll
;   for (int r = 0; r < 16; ++r) p1[r] = fmaf(p1[r], C, mnC);
; #pragma unroll
;   for (int r = 0; r < 16; ++r) p0[r] = __builtin_amdgcn_exp2f(p0[r]);
; }
; __device__ __forceinline__ void attn_dense_body(const bf16* __restrict__ Qb, const bf16* __restrict__ Kh, const bf16* __restrict__ Vh,
;                                                 bf16* __restrict__ Ob, int seq, char* lds, const int tid, const float mnC) {
;   const int wid = tid >> 6, lane = tid & 63, r32 = lane & 31, hi = lane >> 5;
;   bf16* V_lds = (bf16*)lds; bf16* K_lds = (bf16*)(lds + 2 * SHM_V);
;   float* ws = (float*)(lds + 2 * SHM_V + 2 * SHM_K) + wid * 64; float* li_l = ws;
;   float l_reg = 0; f32x16 o[4] = {}; bf16x8 qr[8];
;   const bf16* Qw = Qb + (long)(wid * QBLK + r32) * LDQ + hi * 8;
; #pragma unroll
;   for (int d0 = 0; d0 < 8; ++d0) qr[d0] = ld8(Qw + d0 * 16);
;   const int sr = tid >> 4, sc = (tid & 15) * 8, vst0 = v_st(sr, sc), vst1 = v_st(32 + sr, sc);
;   const int vb0 = (int)(uintptr_t)V_lds + v_rd_base(lane);
;   bf16x8 s0_vs0, s0_vs1, s0_ks0, s0_ks1;
;     ...
;   f32x16 pA0, pA1, pB0, pB1; bf16x8 pa0, pa1, pa2, pa3; const int NT = seq / KVBLK;
;   SLOAD0(0);
;   bf16x8 t1_vs0 = ld8(&Vh[(long)(KVBLK + sr) * LDK + sc]), t1_vs1 = ld8(&Vh[(long)(KVBLK + 32 + sr) * LDK + sc]);
;   bf16x8 t1_ks0 = ld8(&Kh[(long)(KVBLK + sr) * LDK + sc]), t1_ks1 = ld8(&Kh[(long)(KVBLK + 32 + sr) * LDK + sc]);
;   asm volatile("s_waitcnt vmcnt(4)" ::: "memory"); SWRITE0(0); __syncthreads();
;   qkt(pA0, pA1, K_lds, qr, r32, hi); partialSM(pA0, pA1, mnC);
;   s0_vs0 = t1_vs0; s0_vs1 = t1_vs1; s0_ks0 = t1_ks0; s0_ks1 = t1_ks1;
;   SWAIT(); SWRITE0(1); __syncthreads();
;   if (__builtin_amdgcn_readfirstlane(wid) >= 4) __builtin_amdgcn_s_setprio(1);
;   for (int j = 1; j + 1 < NT; j += 2) {
.LBB0_1039:
	s_lshr_b32 s12, s8, 2
	v_and_b32_e32 v159, 63, v174
	s_and_b32 s12, s12, 1
	s_and_b32 s13, s4, 3
	v_mov_b32_e32 v153, v152
	s_nop 5
	v_pk_fma_f32 v[168:169], v[0:1], s[26:27], v[156:157] op_sel_hi:[1,0,1]
	s_mul_i32 s12, s12, 0x840000
	s_lshl_b32 s13, s13, 8
	v_lshlrev_b32_e32 v1, 4, v159
	v_pk_fma_f32 v[166:167], v[2:3], s[26:27], v[152:153] op_sel_hi:[1,0,1]
	s_or_b32 s13, s13, s12
	v_lshlrev_b32_e32 v0, 3, v159
	v_and_b32_e32 v1, 0xc0, v1
	v_lshlrev_b32_e32 v2, 1, v159
	v_and_or_b32 v1, v0, 24, v1
	v_and_b32_e32 v2, 32, v2
	v_and_b32_e32 v0, 0x100, v0
	s_cmp_lg_u32 0, -1
	v_or3_b32 v0, v1, v2, v0
	s_cselect_b32 s14, 0, 0
	v_fmamk_f32 v16, v16, 0x3e0293ee, v152
	v_fmamk_f32 v17, v17, 0x3e0293ee, v152
	v_fmamk_f32 v18, v18, 0x3e0293ee, v152
	v_fmamk_f32 v19, v19, 0x3e0293ee, v152
	v_fmamk_f32 v20, v20, 0x3e0293ee, v152
	v_fmamk_f32 v21, v21, 0x3e0293ee, v152
	v_fmamk_f32 v22, v22, 0x3e0293ee, v152
	v_fmamk_f32 v23, v23, 0x3e0293ee, v152
	v_fmamk_f32 v24, v24, 0x3e0293ee, v152
	v_fmamk_f32 v25, v25, 0x3e0293ee, v152
	v_fmamk_f32 v26, v26, 0x3e0293ee, v152
	v_fmamk_f32 v27, v27, 0x3e0293ee, v152
	v_fmamk_f32 v28, v28, 0x3e0293ee, v152
	v_fmamk_f32 v29, v29, 0x3e0293ee, v152
	v_fmamk_f32 v30, v30, 0x3e0293ee, v152
	v_fmamk_f32 v31, v31, 0x3e0293ee, v152
	v_add_u32_e32 v173, s14, v0
	s_addk_i32 s14, 0x4000
	v_pk_fma_f32 v[144:145], v[14:15], s[26:27], v[152:153] op_sel_hi:[1,0,1]
	v_pk_fma_f32 v[146:147], v[12:13], s[26:27], v[152:153] op_sel_hi:[1,0,1]
	v_pk_fma_f32 v[148:149], v[10:11], s[26:27], v[152:153] op_sel_hi:[1,0,1]
	v_pk_fma_f32 v[162:163], v[8:9], s[26:27], v[152:153] op_sel_hi:[1,0,1]
	v_pk_fma_f32 v[150:151], v[6:7], s[26:27], v[152:153] op_sel_hi:[1,0,1]
	v_pk_fma_f32 v[164:165], v[4:5], s[26:27], v[152:153] op_sel_hi:[1,0,1]
	v_exp_f32_e32 v199, v16
	v_exp_f32_e32 v201, v17
	v_exp_f32_e32 v198, v18
	v_exp_f32_e32 v203, v19
	v_exp_f32_e32 v200, v20
	v_exp_f32_e32 v202, v21
	v_exp_f32_e32 v196, v22
	v_exp_f32_e32 v197, v23
	v_exp_f32_e32 v193, v24
	v_exp_f32_e32 v195, v25
	v_exp_f32_e32 v192, v26
	v_exp_f32_e32 v194, v27
	v_exp_f32_e32 v189, v28
	v_exp_f32_e32 v191, v29
	v_exp_f32_e32 v188, v30
	v_exp_f32_e32 v190, v31
	v_add_u32_e32 v153, s14, v0
	v_and_b32_e32 v0, 15, v174
	s_add_u32 s14, s2, s13
	v_lshl_or_b32 v32, v0, 4, v32
	s_addc_u32 s15, s3, 0
	v_lshl_add_u64 v[0:1], s[14:15], 0, v[32:33]
	s_mov_b64 s[14:15], 0xeb38000
	v_mov_b32_e32 v187, 0
	s_mov_b32 s12, -1
	v_lshl_add_u64 v[160:161], v[0:1], 0, s[14:15]
	v_mov_b32_e32 v0, 0
	v_mov_b32_e32 v1, v187
	v_mov_b32_e32 v2, v187
	v_mov_b32_e32 v3, v187
	v_mov_b32_e32 v4, v187
	v_mov_b32_e32 v5, v187
	v_mov_b32_e32 v6, v187
	v_mov_b32_e32 v7, v187
	v_mov_b32_e32 v8, v187
	v_mov_b32_e32 v9, v187
	v_mov_b32_e32 v10, v187
	v_mov_b32_e32 v11, v187
	v_mov_b32_e32 v12, v187
	v_mov_b32_e32 v13, v187
	v_mov_b32_e32 v14, v187
	v_mov_b32_e32 v15, v187
	v_mov_b32_e32 v16, 0
	v_mov_b32_e32 v17, v187
	v_mov_b32_e32 v18, v187
	v_mov_b32_e32 v19, v187
	v_mov_b32_e32 v20, v187
	v_mov_b32_e32 v21, v187
	v_mov_b32_e32 v22, v187
	v_mov_b32_e32 v23, v187
	v_mov_b32_e32 v24, v187
	v_mov_b32_e32 v25, v187
	v_mov_b32_e32 v26, v187
	v_mov_b32_e32 v27, v187
	v_mov_b32_e32 v28, v187
	v_mov_b32_e32 v29, v187
	v_mov_b32_e32 v30, v187
	v_mov_b32_e32 v31, v187
	v_mov_b32_e32 v32, 0
	v_mov_b32_e32 v33, v187
	v_mov_b32_e32 v34, v187
	v_mov_b32_e32 v35, v187
	v_mov_b32_e32 v36, v187
	v_mov_b32_e32 v37, v187
	v_mov_b32_e32 v38, v187
	v_mov_b32_e32 v39, v187
	v_mov_b32_e32 v40, v187
	v_mov_b32_e32 v41, v187
	v_mov_b32_e32 v42, v187
	v_mov_b32_e32 v43, v187
	v_mov_b32_e32 v44, v187
	v_mov_b32_e32 v45, v187
	v_mov_b32_e32 v46, v187
	v_mov_b32_e32 v47, v187
	v_mov_b32_e32 v48, 0
	v_mov_b32_e32 v49, v187
	v_mov_b32_e32 v50, v187
	v_mov_b32_e32 v51, v187
	v_mov_b32_e32 v52, v187
	v_mov_b32_e32 v53, v187
	v_mov_b32_e32 v54, v187
	v_mov_b32_e32 v55, v187
	v_mov_b32_e32 v56, v187
	v_mov_b32_e32 v57, v187
	v_mov_b32_e32 v58, v187
	v_mov_b32_e32 v59, v187
	v_mov_b32_e32 v60, v187
	v_mov_b32_e32 v61, v187
	v_mov_b32_e32 v62, v187
	v_mov_b32_e32 v63, v187
	v_lshrrev_b32_e32 v216, 6, v174
	v_lshrrev_b32_e32 v217, 4, v159
	v_and_b32_e32 v218, 15, v159
	v_readfirstlane_b32 s98, v216
	v_xor_b32_e32 v218, v218, v217
	v_and_b32_e32 v219, 1, v216
	v_lshlrev_b32_e32 v219, 3, v219
	v_xor_b32_e32 v218, v218, v219
	v_lshlrev_b32_e32 v218, 4, v218
	v_lshl_or_b32 v218, v217, 10, v218
	v_lshl_or_b32 v216, v216, 13, v218
	v_xor_b32_e32 v217, 64, v216
	v_add_u32_e32 v217, 0x1000, v217
	s_and_b32 s99, s98, 1
	s_lshl_b32 s99, s99, 2
	s_lshr_b32 s100, s98, 1
	s_lshl_b32 s100, s100, 4
	s_or_b32 s99, s99, s100
	s_lshl_b32 s99, s99, 10
	v_bfe_u32 v218, v159, 2, 2
	v_bfe_u32 v219, v159, 4, 1
	v_lshl_or_b32 v218, v219, 3, v218
	v_lshlrev_b32_e32 v218, 10, v218
	v_lshrrev_b32_e32 v219, 5, v159
	v_lshl_or_b32 v218, v219, 6, v218
	v_and_b32_e32 v219, 3, v159
	v_lshl_or_b32 v218, v219, 4, v218
	v_add_u32_e32 v218, s99, v218
	v_add_u32_e32 v219, 0x80, v218
	s_lshl_b32 s98, s98, 11
	s_bfe_u32 s100, s8, 0x10002
	s_mul_i32 s100, s100, 0x840000
	s_and_b32 s101, s8, 3
	s_lshl_b32 s101, s101, 8
	s_add_u32 s100, s100, s101
	s_add_u32 s14, s2, s100
	s_addc_u32 s15, s3, 0
	s_add_u32 s16, s14, 0xeb10000
	s_addc_u32 s17, s15, 0
	s_add_u32 s14, s14, 0xda20000
	s_addc_u32 s15, s15, 0
	v_mov_b32_e32 v136, 0
	v_mov_b32_e32 v137, 0
	v_mov_b32_e32 v138, 0
	v_mov_b32_e32 v139, 0
	v_mov_b32_e32 v140, 0
	v_mov_b32_e32 v141, 0
	v_mov_b32_e32 v142, 0
	v_mov_b32_e32 v143, 0
	v_mov_b32_e32 v208, 0
	v_mov_b32_e32 v209, 0
	v_mov_b32_e32 v210, 0
	v_mov_b32_e32 v211, 0
	v_mov_b32_e32 v228, 0
	v_mov_b32_e32 v229, 0
	v_mov_b32_e32 v230, 0
	v_mov_b32_e32 v231, 0
	v_mov_b32_e32 v232, 0
	v_mov_b32_e32 v233, 0
	v_mov_b32_e32 v234, 0
	v_mov_b32_e32 v235, 0
	v_mov_b32_e32 v236, 0
	v_mov_b32_e32 v237, 0
	v_mov_b32_e32 v238, 0
	v_mov_b32_e32 v239, 0
	v_mov_b32_e32 v240, 0
	v_mov_b32_e32 v241, 0
	v_mov_b32_e32 v242, 0
	v_mov_b32_e32 v243, 0
	v_mov_b32_e32 v204, 0
	v_mov_b32_e32 v205, 0
	v_mov_b32_e32 v206, 0
	v_mov_b32_e32 v207, 0

;     __device__ __forceinline__ void operator()(const f32x4 (&acc)[2][2][4][2], const Unit& u, int wr, int wc, int fr, int fq) const {
;     ...
;         const int rowt = u.pm * BM, b = rowt >= MLAT ? 2 : (rowt >> 13);
;         const float* gp = gate + b * 6144; const int col0 = u.pn * BM + wc * 32 + 8 * fq;
;         f32x4 gv[2][2], wv[2][2];
; #pragma unroll
;         for (int bj = 0; bj < 2; ++bj)
; #pragma unroll
;             for (int n = 0; n < 2; ++n) { gv[bj][n] = *(const f32x4*)(gp + col0 + bj * HALF + n * 4); if (cs) gv[bj][n] = gv[bj][n] * *(const f32x4*)(cs + col0 + bj * HALF + n * 4);
;                 if (hb) wv[bj][n] = *(const f32x4*)(wn_g + col0 + bj * HALF + n * 4) * (*(const f32x4*)(wn_sc + b * 6144 + col0 + bj * HALF + n * 4) + 1.0f); }
;         const float* bb = base_lat ? (rowt >= MLAT ? base_ctx + (size_t)(rowt - MLAT) * DM : base_lat + (size_t)rowt * DM) : nullptr;
; #pragma unroll
;         for (int ai = 0; ai < 2; ++ai) {
;             u32x4 raw[4][2];
; #pragma unroll
;             for (int m = 0; m < 4; ++m)
; #pragma unroll
;                 for (int bj = 0; bj < 2; ++bj) raw[m][bj] = *(const u32x4*)(h16 + (size_t)rowt * DM + (size_t)(wr * 64 + fr + ai * HALF + m * 16) * DM + col0 + bj * HALF);
.LBB0_1134:
	s_min_i32 s1, s40, 64
	s_lshr_b32 s1, s1, 5
	s_mul_i32 s22, s1, 0x1800
	s_ashr_i32 s23, s22, 31
	s_lshl_b32 s42, s40, 8
	s_lshl_b64 s[22:23], s[22:23], 2
	s_add_u32 s40, s62, s22
	s_addc_u32 s41, s63, s23
	s_lshl_b32 s1, s0, 8
	v_mov_b32_e32 v160, v229
	v_mov_b32_e32 v161, v228
	s_or_b32 s1, s1, s70
	s_add_u32 s22, s66, s22
	v_lshl_add_u32 v198, v161, 3, s1
	v_ashrrev_i32_e32 v199, 31, v198
	v_lshlrev_b64 v[56:57], 2, v[198:199]
	v_lshl_add_u64 v[152:153], s[40:41], 0, v[56:57]
	s_addc_u32 s23, s67, s23
	v_lshl_add_u64 v[154:155], s[6:7], 0, v[56:57]
	v_lshl_add_u64 v[156:157], s[22:23], 0, v[56:57]
	global_load_dwordx4 v[64:67], v[152:153], off offset:16
	global_load_dwordx4 v[68:71], v[152:153], off
	global_load_dwordx4 v[56:59], v[154:155], off offset:16
	global_load_dwordx4 v[60:63], v[154:155], off
	global_load_dwordx4 v[144:147], v[156:157], off offset:16
	global_load_dwordx4 v[148:151], v[156:157], off
	s_ashr_i32 s43, s42, 31
	s_lshl_b64 s[40:41], s[42:43], 11
	v_add_u32_e32 v200, s69, v160
	s_add_u32 s22, s31, s40
	s_addc_u32 s23, s61, s41
	v_ashrrev_i32_e32 v201, 31, v200
	v_add_u32_e32 v220, 16, v200
	v_lshl_add_u64 v[202:203], v[198:199], 1, s[22:23]
	v_ashrrev_i32_e32 v221, 31, v220
	v_add_u32_e32 v208, 32, v200
	v_ashrrev_i32_e32 v209, 31, v208
	v_add_u32_e32 v204, 48, v200
	v_ashrrev_i32_e32 v205, 31, v204
	v_cmp_eq_u32_e32 vcc, 0, v161
	v_lshlrev_b64 v[216:217], 10, v[200:201]
	v_lshl_add_u64 v[226:227], v[216:217], 0, v[198:199]
	s_add_u32 s44, s64, s40
	s_addc_u32 s45, s65, s41
	s_waitcnt vmcnt(0)
	v_pk_add_f32 v[150:151], v[150:151], 1.0 op_sel_hi:[1,0]
	v_pk_add_f32 v[148:149], v[148:149], 1.0 op_sel_hi:[1,0]
	v_pk_mul_f32 v[192:193], v[62:63], v[150:151]
	v_pk_mul_f32 v[196:197], v[60:61], v[148:149]
	v_pk_add_f32 v[60:61], v[146:147], 1.0 op_sel_hi:[1,0]
	v_pk_add_f32 v[62:63], v[144:145], 1.0 op_sel_hi:[1,0]
	v_pk_mul_f32 v[190:191], v[58:59], v[60:61]
	v_pk_mul_f32 v[194:195], v[56:57], v[62:63]
	global_load_dwordx4 v[56:59], v[152:153], off offset:528
	global_load_dwordx4 v[60:63], v[152:153], off offset:512
	global_load_dwordx4 v[144:147], v[154:155], off offset:528
	global_load_dwordx4 v[148:151], v[154:155], off offset:512
	s_nop 0
	global_load_dwordx4 v[152:155], v[156:157], off offset:528
	s_nop 0
	global_load_dwordx4 v[156:159], v[156:157], off offset:512
	s_waitcnt vmcnt(0)
	v_pk_add_f32 v[158:159], v[158:159], 1.0 op_sel_hi:[1,0]
	s_nop 0
	v_pk_mul_f32 v[188:189], v[150:151], v[158:159]
	v_pk_add_f32 v[150:151], v[152:153], 1.0 op_sel_hi:[1,0]
	v_pk_add_f32 v[156:157], v[156:157], 1.0 op_sel_hi:[1,0]
	v_pk_mul_f32 v[186:187], v[144:145], v[150:151]
	v_lshlrev_b64 v[144:145], 11, v[200:201]
	v_lshl_add_u64 v[224:225], v[202:203], 0, v[144:145]
	v_lshlrev_b64 v[144:145], 11, v[220:221]
	v_lshl_add_u64 v[222:223], v[202:203], 0, v[144:145]
	v_lshlrev_b64 v[144:145], 11, v[208:209]
	v_lshl_add_u64 v[210:211], v[202:203], 0, v[144:145]
	v_lshlrev_b64 v[144:145], 11, v[204:205]
	v_pk_mul_f32 v[182:183], v[148:149], v[156:157]
	v_pk_add_f32 v[148:149], v[154:155], 1.0 op_sel_hi:[1,0]
	v_lshl_add_u64 v[206:207], v[202:203], 0, v[144:145]
	v_pk_mul_f32 v[184:185], v[146:147], v[148:149]
	global_load_dwordx4 v[168:171], v[224:225], off offset:256
	global_load_dwordx4 v[164:167], v[222:223], off
	global_load_dwordx4 v[160:163], v[222:223], off offset:256
	global_load_dwordx4 v[156:159], v[210:211], off
	global_load_dwordx4 v[152:155], v[210:211], off offset:256
	global_load_dwordx4 v[148:151], v[206:207], off
	global_load_dwordx4 v[144:147], v[206:207], off offset:256
	global_load_dwordx4 v[232:235], v[224:225], off
	s_waitcnt vmcnt(0)
; __device__ __forceinline__ unsigned cvt_pk_bf16(float lo, float hi) { unsigned r; asm volatile("v_cvt_pk_bf16_f32 %0, %1, %2" : "=v"(r) : "v"(lo), "v"(hi)); return r; }
;     __device__ __forceinline__ void operator()(const f32x4 (&acc)[2][2][4][2], const Unit& u, int wr, int wc, int fr, int fq) const {
;     ...
;             for (int m = 0; m < 4; ++m) { const int rl = wr * 64 + fr + ai * HALF + m * 16; const size_t off = (size_t)rl * DM + col0; float sq = 0.f;
;                 bf16_t* hrow = h16 + (size_t)rowt * DM + off;
; #pragma unroll
;                 for (int bj = 0; bj < 2; ++bj) { f32x4 b0, b1;
;                     if (bb) { b0 = *(const f32x4*)(bb + off + bj * HALF); b1 = *(const f32x4*)(bb + off + bj * HALF + 4); }
;                     else { const u32x4 r = raw[m][bj];
;                         b0 = (f32x4){__uint_as_float(r.x << 16), __uint_as_float(r.x & 0xffff0000u), __uint_as_float(r.y << 16), __uint_as_float(r.y & 0xffff0000u)};
;                         b1 = (f32x4){__uint_as_float(r.z << 16), __uint_as_float(r.z & 0xffff0000u), __uint_as_float(r.w << 16), __uint_as_float(r.w & 0xffff0000u)}; }
;                     const f32x4 o0 = b0 + gv[bj][0] * acc[ai][bj][m][0], o1 = b1 + gv[bj][1] * acc[ai][bj][m][1];
;                     u32x4 w; w.x = cvt_pk_bf16(o0[0], o0[1]); w.y = cvt_pk_bf16(o0[2], o0[3]); w.z = cvt_pk_bf16(o1[0], o1[1]); w.w = cvt_pk_bf16(o1[2], o1[3]);
;                     *(u32x4*)(hrow + bj * HALF) = w;
;                     sq += ((o0[0] * o0[0] + o0[1] * o0[1]) + (o0[2] * o0[2] + o0[3] * o0[3])) + ((o1[0] * o1[0] + o1[1] * o1[1]) + (o1[2] * o1[2] + o1[3] * o1[3]));
;                     if (hb) { const f32x4 y0 = o0 * wv[bj][0], y1 = o1 * wv[bj][1]; u32x4 z; z.x = cvt_pk_bf16(y0[0], y0[1]); z.y = cvt_pk_bf16(y0[2], y0[3]); z.z = cvt_pk_bf16(y1[0], y1[1]); z.w = cvt_pk_bf16(y1[2], y1[3]);
;                         *(u32x4*)(hb + (size_t)rowt * DM + off + bj * HALF) = z; } }
;                 if (ssq) { sq += __shfl_xor(sq, 16); sq += __shfl_xor(sq, 32); if (fq == 0) ssq[(size_t)(rowt + rl) * 16 + u.pn * 4 + wc] = sq; } }
	v_lshlrev_b32_e32 v216, 16, v232
	v_and_b32_e32 v217, 0xffff0000, v232
	v_lshlrev_b32_e32 v218, 16, v233
	v_and_b32_e32 v219, 0xffff0000, v233
	v_lshlrev_b32_e32 v232, 16, v234
	v_and_b32_e32 v233, 0xffff0000, v234
	v_lshlrev_b32_e32 v234, 16, v235
	v_and_b32_e32 v235, 0xffff0000, v235
	v_pk_fma_f32 v[142:143], v[142:143], v[70:71], v[218:219]
	v_pk_fma_f32 v[140:141], v[140:141], v[68:69], v[216:217]
	v_pk_fma_f32 v[218:219], v[136:137], v[64:65], v[232:233]
	v_cvt_pk_bf16_f32 v136, v140, v141
	v_cvt_pk_bf16_f32 v137, v142, v143
	v_pk_fma_f32 v[216:217], v[138:139], v[66:67], v[234:235]
	v_cvt_pk_bf16_f32 v138, v218, v219
	s_nop 0
	v_cvt_pk_bf16_f32 v139, v216, v217
	global_store_dwordx4 v[224:225], v[136:139], off sc1
	s_nop 1
	v_mul_f32_e32 v136, v141, v141
	v_mul_f32_e32 v137, v143, v143
	v_fmac_f32_e32 v136, v140, v140
	v_fmac_f32_e32 v137, v142, v142
	v_add_f32_e32 v136, v136, v137
	v_mul_f32_e32 v137, v219, v219
	v_mul_f32_e32 v138, v217, v217
	v_fmac_f32_e32 v137, v218, v218
	v_fmac_f32_e32 v138, v216, v216
	v_add_f32_e32 v137, v137, v138
	v_add_f32_e32 v201, v136, v137
	v_pk_mul_f32 v[138:139], v[192:193], v[142:143]
	v_pk_mul_f32 v[136:137], v[196:197], v[140:141]
	v_pk_mul_f32 v[140:141], v[190:191], v[216:217]
	v_pk_mul_f32 v[142:143], v[194:195], v[218:219]
	v_cvt_pk_bf16_f32 v136, v136, v137
	v_cvt_pk_bf16_f32 v137, v138, v139
	s_nop 0
	v_cvt_pk_bf16_f32 v138, v142, v143
	v_cvt_pk_bf16_f32 v139, v140, v141
	v_lshl_add_u64 v[140:141], v[226:227], 1, s[44:45]
	global_store_dwordx4 v[140:141], v[136:139], off sc1
	v_lshlrev_b32_e32 v142, 16, v170
	v_and_b32_e32 v143, 0xffff0000, v170
	v_lshlrev_b32_e32 v136, 16, v168
	v_and_b32_e32 v137, 0xffff0000, v168
	v_lshlrev_b32_e32 v138, 16, v169
	v_and_b32_e32 v139, 0xffff0000, v169
	v_lshlrev_b32_e32 v168, 16, v171
	v_and_b32_e32 v169, 0xffff0000, v171
	v_pk_fma_f32 v[134:135], v[134:135], v[62:63], v[138:139]
	v_pk_fma_f32 v[132:133], v[132:133], v[60:61], v[136:137]
	v_pk_fma_f32 v[138:139], v[128:129], v[56:57], v[142:143]
	v_cvt_pk_bf16_f32 v128, v132, v133
	v_cvt_pk_bf16_f32 v129, v134, v135
	v_pk_fma_f32 v[136:137], v[130:131], v[58:59], v[168:169]
	v_cvt_pk_bf16_f32 v130, v138, v139
	s_nop 0
	v_cvt_pk_bf16_f32 v131, v136, v137
	global_store_dwordx4 v[224:225], v[128:131], off offset:256 sc1
	s_nop 1
	v_mul_f32_e32 v128, v133, v133
	v_mul_f32_e32 v129, v135, v135
	v_fmac_f32_e32 v128, v132, v132
	v_fmac_f32_e32 v129, v134, v134
	v_add_f32_e32 v128, v128, v129
	v_mul_f32_e32 v129, v139, v139
	v_mul_f32_e32 v130, v137, v137
	v_fmac_f32_e32 v129, v138, v138
	v_fmac_f32_e32 v130, v136, v136
	v_add_f32_e32 v129, v129, v130
	v_add_f32_e32 v128, v128, v129
	v_add_f32_e32 v142, v128, v201
	v_pk_mul_f32 v[128:129], v[182:183], v[132:133]
	v_pk_mul_f32 v[130:131], v[188:189], v[134:135]
	v_cvt_pk_bf16_f32 v128, v128, v129
	v_pk_mul_f32 v[132:133], v[184:185], v[136:137]
	v_cvt_pk_bf16_f32 v129, v130, v131
	v_pk_mul_f32 v[134:135], v[186:187], v[138:139]
	s_nop 0
	v_cvt_pk_bf16_f32 v130, v134, v135
	v_cvt_pk_bf16_f32 v131, v132, v133
	global_store_dwordx4 v[140:141], v[128:131], off offset:256 sc1
	s_nop 1
	v_and_b32_e32 v129, 64, v246
	v_xor_b32_e32 v128, 16, v246
	v_add_u32_e32 v129, 64, v129
	v_cmp_lt_i32_e64 s[40:41], v128, v129
	v_xor_b32_e32 v131, 32, v246
	s_nop 0
	v_cndmask_b32_e64 v128, v246, v128, s[40:41]
	v_lshlrev_b32_e32 v128, 2, v128
	ds_bpermute_b32 v130, v128, v142
	v_cmp_lt_i32_e64 s[40:41], v131, v129
	s_waitcnt lgkmcnt(0)
	v_add_f32_e32 v130, v142, v130
	v_cndmask_b32_e64 v129, v246, v131, s[40:41]
	v_lshlrev_b32_e32 v129, 2, v129
	ds_bpermute_b32 v131, v129, v130
	s_and_saveexec_b64 s[40:41], vcc
	s_cbranch_execz .LBB0_1136
	s_waitcnt lgkmcnt(0)
	v_add_f32_e32 v132, v130, v131
	v_add_u32_e32 v130, s42, v200
	v_ashrrev_i32_e32 v131, 31, v130
	s_lshl_b32 s22, s0, 2
	v_lshlrev_b64 v[130:131], 6, v[130:131]
	s_ashr_i32 s23, s22, 31
	v_lshl_add_u64 v[130:131], s[12:13], 0, v[130:131]
	v_lshl_add_u64 v[130:131], s[22:23], 2, v[130:131]
	s_lshl_b32 s8, s68, 2
	v_lshl_add_u64 v[130:131], v[130:131], 0, s[8:9]
	global_store_dword v[130:131], v132, off

; __device__ __forceinline__ unsigned cvt_pk_bf16(float lo, float hi) { unsigned r; asm volatile("v_cvt_pk_bf16_f32 %0, %1, %2" : "=v"(r) : "v"(lo), "v"(hi)); return r; }
;     __device__ __forceinline__ void operator()(const f32x4 (&acc)[2][2][4][2], const Unit& u, int wr, int wc, int fr, int fq) const {
;     ...
;             for (int m = 0; m < 4; ++m) { const int rl = wr * 64 + fr + ai * HALF + m * 16; const size_t off = (size_t)rl * DM + col0; float sq = 0.f;
;                 bf16_t* hrow = h16 + (size_t)rowt * DM + off;
; #pragma unroll
;                 for (int bj = 0; bj < 2; ++bj) { f32x4 b0, b1;
;                     if (bb) { b0 = *(const f32x4*)(bb + off + bj * HALF); b1 = *(const f32x4*)(bb + off + bj * HALF + 4); }
;                     else { const u32x4 r = raw[m][bj];
;                         b0 = (f32x4){__uint_as_float(r.x << 16), __uint_as_float(r.x & 0xffff0000u), __uint_as_float(r.y << 16), __uint_as_float(r.y & 0xffff0000u)};
;                         b1 = (f32x4){__uint_as_float(r.z << 16), __uint_as_float(r.z & 0xffff0000u), __uint_as_float(r.w << 16), __uint_as_float(r.w & 0xffff0000u)}; }
;                     const f32x4 o0 = b0 + gv[bj][0] * acc[ai][bj][m][0], o1 = b1 + gv[bj][1] * acc[ai][bj][m][1];
;                     u32x4 w; w.x = cvt_pk_bf16(o0[0], o0[1]); w.y = cvt_pk_bf16(o0[2], o0[3]); w.z = cvt_pk_bf16(o1[0], o1[1]); w.w = cvt_pk_bf16(o1[2], o1[3]);
;                     *(u32x4*)(hrow + bj * HALF) = w;
;                     sq += ((o0[0] * o0[0] + o0[1] * o0[1]) + (o0[2] * o0[2] + o0[3] * o0[3])) + ((o1[0] * o1[0] + o1[1] * o1[1]) + (o1[2] * o1[2] + o1[3] * o1[3]));
;                     if (hb) { const f32x4 y0 = o0 * wv[bj][0], y1 = o1 * wv[bj][1]; u32x4 z; z.x = cvt_pk_bf16(y0[0], y0[1]); z.y = cvt_pk_bf16(y0[2], y0[3]); z.z = cvt_pk_bf16(y1[0], y1[1]); z.w = cvt_pk_bf16(y1[2], y1[3]);
;                         *(u32x4*)(hb + (size_t)rowt * DM + off + bj * HALF) = z; } }
;                 if (ssq) { sq += __shfl_xor(sq, 16); sq += __shfl_xor(sq, 32); if (fq == 0) ssq[(size_t)(rowt + rl) * 16 + u.pn * 4 + wc] = sq; } }
.LBB0_1414:
	s_waitcnt vmcnt(0)
	v_pk_add_f32 v[198:199], v[198:199], 1.0 op_sel_hi:[1,0]
	v_pk_add_f32 v[196:197], v[196:197], 1.0 op_sel_hi:[1,0]
	v_pk_add_f32 v[190:191], v[190:191], 1.0 op_sel_hi:[1,0]
	v_pk_add_f32 v[188:189], v[188:189], 1.0 op_sel_hi:[1,0]
	v_lshl_add_u64 v[238:239], v[244:245], 1, v[228:229]
	v_pk_mul_f32 v[194:195], v[194:195], v[198:199]
	v_pk_mul_f32 v[192:193], v[192:193], v[196:197]
	v_pk_mul_f32 v[186:187], v[186:187], v[190:191]
	v_pk_mul_f32 v[184:185], v[184:185], v[188:189]
	v_pk_fma_f32 v[190:191], v[146:147], v[66:67], v[210:211]
	v_pk_fma_f32 v[198:199], v[144:145], v[64:65], v[208:209]
	v_pk_fma_f32 v[196:197], v[142:143], v[70:71], v[206:207]
	v_pk_fma_f32 v[204:205], v[140:141], v[68:69], v[204:205]
	v_cvt_pk_bf16_f32 v140, v198, v199
	v_cvt_pk_bf16_f32 v141, v190, v191
	v_pk_mul_f32 v[144:145], v[194:195], v[196:197]
	v_cvt_pk_bf16_f32 v142, v204, v205
	v_cvt_pk_bf16_f32 v143, v196, v197
	global_store_dwordx4 v[238:239], v[140:143], off sc1
	s_add_u32 s74, s88, s44
	v_pk_mul_f32 v[146:147], v[192:193], v[204:205]
	v_pk_mul_f32 v[142:143], v[186:187], v[190:191]
	v_pk_mul_f32 v[140:141], v[184:185], v[198:199]
	s_addc_u32 s75, s89, s45
	v_cvt_pk_bf16_f32 v140, v140, v141
	v_cvt_pk_bf16_f32 v141, v142, v143
	v_cvt_pk_bf16_f32 v142, v146, v147
	v_cvt_pk_bf16_f32 v143, v144, v145
	v_cndmask_b32_e64 v144, 0, 1, s[42:43]
	v_lshl_add_u64 v[188:189], v[242:243], 1, s[74:75]
	v_cmp_ne_u32_e64 s[44:45], 1, v144
	s_andn2_b64 vcc, exec, s[42:43]
	global_store_dwordx4 v[188:189], v[140:143], off sc1
	s_cbranch_vccnz .LBB0_1479
	global_load_dwordx4 v[140:143], v[240:241], off offset:528
	global_load_dwordx4 v[144:147], v[240:241], off offset:512
	s_cbranch_execnz .LBB0_1417

; __device__ __forceinline__ unsigned cvt_pk_bf16(float lo, float hi) { unsigned r; asm volatile("v_cvt_pk_bf16_f32 %0, %1, %2" : "=v"(r) : "v"(lo), "v"(hi)); return r; }
;     __device__ __forceinline__ void operator()(const f32x4 (&acc)[2][2][4][2], const Unit& u, int wr, int wc, int fr, int fq) const {
;     ...
;             for (int m = 0; m < 4; ++m) { const int rl = wr * 64 + fr + ai * HALF + m * 16; const size_t off = (size_t)rl * DM + col0; float sq = 0.f;
;                 bf16_t* hrow = h16 + (size_t)rowt * DM + off;
; #pragma unroll
;                 for (int bj = 0; bj < 2; ++bj) { f32x4 b0, b1;
;                     if (bb) { b0 = *(const f32x4*)(bb + off + bj * HALF); b1 = *(const f32x4*)(bb + off + bj * HALF + 4); }
;                     else { const u32x4 r = raw[m][bj];
;                         b0 = (f32x4){__uint_as_float(r.x << 16), __uint_as_float(r.x & 0xffff0000u), __uint_as_float(r.y << 16), __uint_as_float(r.y & 0xffff0000u)};
;                         b1 = (f32x4){__uint_as_float(r.z << 16), __uint_as_float(r.z & 0xffff0000u), __uint_as_float(r.w << 16), __uint_as_float(r.w & 0xffff0000u)}; }
;                     const f32x4 o0 = b0 + gv[bj][0] * acc[ai][bj][m][0], o1 = b1 + gv[bj][1] * acc[ai][bj][m][1];
;                     u32x4 w; w.x = cvt_pk_bf16(o0[0], o0[1]); w.y = cvt_pk_bf16(o0[2], o0[3]); w.z = cvt_pk_bf16(o1[0], o1[1]); w.w = cvt_pk_bf16(o1[2], o1[3]);
;                     *(u32x4*)(hrow + bj * HALF) = w;
;                     sq += ((o0[0] * o0[0] + o0[1] * o0[1]) + (o0[2] * o0[2] + o0[3] * o0[3])) + ((o1[0] * o1[0] + o1[1] * o1[1]) + (o1[2] * o1[2] + o1[3] * o1[3]));
;                     if (hb) { const f32x4 y0 = o0 * wv[bj][0], y1 = o1 * wv[bj][1]; u32x4 z; z.x = cvt_pk_bf16(y0[0], y0[1]); z.y = cvt_pk_bf16(y0[2], y0[3]); z.z = cvt_pk_bf16(y1[0], y1[1]); z.w = cvt_pk_bf16(y1[2], y1[3]);
;                         *(u32x4*)(hb + (size_t)rowt * DM + off + bj * HALF) = z; } }
;                 if (ssq) { sq += __shfl_xor(sq, 16); sq += __shfl_xor(sq, 32); if (fq == 0) ssq[(size_t)(rowt + rl) * 16 + u.pn * 4 + wc] = sq; } }
.LBB0_1417:
	s_waitcnt vmcnt(0)
	v_pk_fma_f32 v[134:135], v[134:135], v[50:51], v[146:147]
	v_pk_fma_f32 v[132:133], v[132:133], v[48:49], v[144:145]
	v_pk_fma_f32 v[140:141], v[128:129], v[52:53], v[140:141]
	v_cvt_pk_bf16_f32 v128, v132, v133
	v_cvt_pk_bf16_f32 v129, v134, v135
	v_mul_f32_e32 v199, v199, v199
	v_mul_f32_e32 v191, v191, v191
	v_pk_fma_f32 v[142:143], v[130:131], v[54:55], v[142:143]
	v_cvt_pk_bf16_f32 v130, v140, v141
	v_fmac_f32_e32 v199, v198, v198
	v_cvt_pk_bf16_f32 v131, v142, v143
	global_store_dwordx4 v[238:239], v[128:131], off offset:256 sc1
	v_fmac_f32_e32 v191, v190, v190
	v_add_f32_e32 v190, v199, v191
	v_mul_f32_e32 v128, v133, v133
	v_mul_f32_e32 v129, v135, v135
	v_fmac_f32_e32 v128, v132, v132
	v_fmac_f32_e32 v129, v134, v134
	v_mul_f32_e32 v191, v205, v205
	v_mul_f32_e32 v197, v197, v197
	v_add_f32_e32 v128, v128, v129
	v_mul_f32_e32 v129, v141, v141
	v_mul_f32_e32 v130, v143, v143
	v_fmac_f32_e32 v191, v204, v204
	v_fmac_f32_e32 v197, v196, v196
	v_fmac_f32_e32 v129, v140, v140
	v_fmac_f32_e32 v130, v142, v142
	v_add_f32_e32 v191, v191, v197
	v_add_f32_e32 v129, v129, v130
	v_add_f32_e32 v190, v190, v191
	v_add_f32_e32 v128, v128, v129
	v_and_b32_e32 v129, 64, v246
	v_add_f32_e32 v131, v190, v128
	v_xor_b32_e32 v128, 16, v246
	v_add_u32_e32 v144, 64, v129
	v_cmp_lt_i32_e32 vcc, v128, v144
	v_pk_add_f32 v[172:173], v[172:173], 1.0 op_sel_hi:[1,0]
	v_pk_add_f32 v[180:181], v[180:181], 1.0 op_sel_hi:[1,0]
	v_cndmask_b32_e32 v128, v246, v128, vcc
	v_pk_mul_f32 v[168:169], v[168:169], v[172:173]
	v_lshlrev_b32_e32 v172, 2, v128
	ds_bpermute_b32 v145, v172, v131
	v_pk_mul_f32 v[128:129], v[168:169], v[132:133]
	v_pk_add_f32 v[182:183], v[182:183], 1.0 op_sel_hi:[1,0]
	v_cvt_pk_bf16_f32 v130, v128, v129
	v_xor_b32_e32 v129, 32, v246
	v_cmp_lt_i32_e32 vcc, v129, v144
	s_waitcnt lgkmcnt(0)
	v_add_f32_e32 v128, v131, v145
	v_pk_mul_f32 v[176:177], v[176:177], v[180:181]
	v_cndmask_b32_e32 v129, v246, v129, vcc
	v_lshlrev_b32_e32 v173, 2, v129
	ds_bpermute_b32 v129, v173, v128
	v_pk_add_f32 v[174:175], v[174:175], 1.0 op_sel_hi:[1,0]
	v_cmp_eq_u32_e64 s[42:43], 0, v253
	v_pk_mul_f32 v[178:179], v[178:179], v[182:183]
	v_pk_mul_f32 v[170:171], v[170:171], v[174:175]
	v_pk_mul_f32 v[132:133], v[176:177], v[140:141]
	v_pk_mul_f32 v[134:135], v[170:171], v[134:135]
	v_pk_mul_f32 v[142:143], v[178:179], v[142:143]
	v_cvt_pk_bf16_f32 v131, v134, v135
	v_cvt_pk_bf16_f32 v132, v132, v133
	s_nop 0
	v_cvt_pk_bf16_f32 v133, v142, v143
	global_store_dwordx4 v[188:189], v[130:133], off offset:256 sc1
	s_and_saveexec_b64 s[76:77], s[42:43]
	s_cbranch_execz .LBB0_1419
	s_waitcnt lgkmcnt(0)
	v_add_f32_e32 v130, v128, v129
	v_add_u32_e32 v128, s70, v230
	v_ashrrev_i32_e32 v129, 31, v128
	s_lshl_b32 s52, s18, 2
	v_lshlrev_b64 v[128:129], 6, v[128:129]
	s_ashr_i32 s53, s52, 31
	v_lshl_add_u64 v[128:129], s[46:47], 0, v[128:129]
	v_lshl_add_u64 v[128:129], s[52:53], 2, v[128:129]
	s_lshl_b32 s8, s38, 2
	v_lshl_add_u64 v[128:129], v[128:129], 0, s[8:9]
	global_store_dword v[128:129], v130, off

; __device__ __forceinline__ unsigned cvt_pk_bf16(float lo, float hi) { unsigned r; asm volatile("v_cvt_pk_bf16_f32 %0, %1, %2" : "=v"(r) : "v"(lo), "v"(hi)); return r; }
;     __device__ __forceinline__ void operator()(const f32x4 (&acc)[2][2][4][2], const Unit& u, int wr, int wc, int fr, int fq) const {
;     ...
;             for (int m = 0; m < 4; ++m) { const int rl = wr * 64 + fr + ai * HALF + m * 16; const size_t off = (size_t)rl * DM + col0; float sq = 0.f;
;                 bf16_t* hrow = h16 + (size_t)rowt * DM + off;
; #pragma unroll
;                 for (int bj = 0; bj < 2; ++bj) { f32x4 b0, b1;
;                     if (bb) { b0 = *(const f32x4*)(bb + off + bj * HALF); b1 = *(const f32x4*)(bb + off + bj * HALF + 4); }
;                     else { const u32x4 r = raw[m][bj];
;                         b0 = (f32x4){__uint_as_float(r.x << 16), __uint_as_float(r.x & 0xffff0000u), __uint_as_float(r.y << 16), __uint_as_float(r.y & 0xffff0000u)};
;                         b1 = (f32x4){__uint_as_float(r.z << 16), __uint_as_float(r.z & 0xffff0000u), __uint_as_float(r.w << 16), __uint_as_float(r.w & 0xffff0000u)}; }
;                     const f32x4 o0 = b0 + gv[bj][0] * acc[ai][bj][m][0], o1 = b1 + gv[bj][1] * acc[ai][bj][m][1];
;                     u32x4 w; w.x = cvt_pk_bf16(o0[0], o0[1]); w.y = cvt_pk_bf16(o0[2], o0[3]); w.z = cvt_pk_bf16(o1[0], o1[1]); w.w = cvt_pk_bf16(o1[2], o1[3]);
;                     *(u32x4*)(hrow + bj * HALF) = w;
;                     sq += ((o0[0] * o0[0] + o0[1] * o0[1]) + (o0[2] * o0[2] + o0[3] * o0[3])) + ((o1[0] * o1[0] + o1[1] * o1[1]) + (o1[2] * o1[2] + o1[3] * o1[3]));
;                     if (hb) { const f32x4 y0 = o0 * wv[bj][0], y1 = o1 * wv[bj][1]; u32x4 z; z.x = cvt_pk_bf16(y0[0], y0[1]); z.y = cvt_pk_bf16(y0[2], y0[3]); z.z = cvt_pk_bf16(y1[0], y1[1]); z.w = cvt_pk_bf16(y1[2], y1[3]);
;                         *(u32x4*)(hb + (size_t)rowt * DM + off + bj * HALF) = z; } }
;                 if (ssq) { sq += __shfl_xor(sq, 16); sq += __shfl_xor(sq, 32); if (fq == 0) ssq[(size_t)(rowt + rl) * 16 + u.pn * 4 + wc] = sq; } }
.LBB0_1422:
	v_lshl_add_u64 v[140:141], v[140:141], 1, v[228:229]
	s_waitcnt vmcnt(0)
	v_pk_fma_f32 v[134:135], v[126:127], v[66:67], v[134:135]
	v_pk_fma_f32 v[132:133], v[124:125], v[64:65], v[132:133]
	v_pk_fma_f32 v[130:131], v[122:123], v[70:71], v[130:131]
	s_waitcnt lgkmcnt(0)
	v_pk_fma_f32 v[146:147], v[120:121], v[68:69], v[128:129]
	v_cvt_pk_bf16_f32 v120, v132, v133
	v_cvt_pk_bf16_f32 v121, v134, v135
	v_lshl_add_u64 v[128:129], v[144:145], 1, s[74:75]
	v_cvt_pk_bf16_f32 v122, v146, v147
	v_cvt_pk_bf16_f32 v123, v130, v131
	global_store_dwordx4 v[140:141], v[120:123], off sc1
	s_and_b64 vcc, exec, s[44:45]
	v_pk_mul_f32 v[124:125], v[194:195], v[130:131]
	v_pk_mul_f32 v[122:123], v[186:187], v[134:135]
	v_pk_mul_f32 v[120:121], v[184:185], v[132:133]
	v_pk_mul_f32 v[126:127], v[192:193], v[146:147]
	v_cvt_pk_bf16_f32 v120, v120, v121
	v_cvt_pk_bf16_f32 v121, v122, v123
	s_nop 0
	v_cvt_pk_bf16_f32 v122, v126, v127
	v_cvt_pk_bf16_f32 v123, v124, v125
	global_store_dwordx4 v[128:129], v[120:123], off sc1
	s_cbranch_vccnz .LBB0_1481
	global_load_dwordx4 v[120:123], v[142:143], off offset:528
	global_load_dwordx4 v[124:127], v[142:143], off offset:512
	s_cbranch_execnz .LBB0_1425

; __device__ __forceinline__ unsigned cvt_pk_bf16(float lo, float hi) { unsigned r; asm volatile("v_cvt_pk_bf16_f32 %0, %1, %2" : "=v"(r) : "v"(lo), "v"(hi)); return r; }
;     __device__ __forceinline__ void operator()(const f32x4 (&acc)[2][2][4][2], const Unit& u, int wr, int wc, int fr, int fq) const {
;     ...
;             for (int m = 0; m < 4; ++m) { const int rl = wr * 64 + fr + ai * HALF + m * 16; const size_t off = (size_t)rl * DM + col0; float sq = 0.f;
;                 bf16_t* hrow = h16 + (size_t)rowt * DM + off;
; #pragma unroll
;                 for (int bj = 0; bj < 2; ++bj) { f32x4 b0, b1;
;                     if (bb) { b0 = *(const f32x4*)(bb + off + bj * HALF); b1 = *(const f32x4*)(bb + off + bj * HALF + 4); }
;                     else { const u32x4 r = raw[m][bj];
;                         b0 = (f32x4){__uint_as_float(r.x << 16), __uint_as_float(r.x & 0xffff0000u), __uint_as_float(r.y << 16), __uint_as_float(r.y & 0xffff0000u)};
;                         b1 = (f32x4){__uint_as_float(r.z << 16), __uint_as_float(r.z & 0xffff0000u), __uint_as_float(r.w << 16), __uint_as_float(r.w & 0xffff0000u)}; }
;                     const f32x4 o0 = b0 + gv[bj][0] * acc[ai][bj][m][0], o1 = b1 + gv[bj][1] * acc[ai][bj][m][1];
;                     u32x4 w; w.x = cvt_pk_bf16(o0[0], o0[1]); w.y = cvt_pk_bf16(o0[2], o0[3]); w.z = cvt_pk_bf16(o1[0], o1[1]); w.w = cvt_pk_bf16(o1[2], o1[3]);
;                     *(u32x4*)(hrow + bj * HALF) = w;
;                     sq += ((o0[0] * o0[0] + o0[1] * o0[1]) + (o0[2] * o0[2] + o0[3] * o0[3])) + ((o1[0] * o1[0] + o1[1] * o1[1]) + (o1[2] * o1[2] + o1[3] * o1[3]));
;                     if (hb) { const f32x4 y0 = o0 * wv[bj][0], y1 = o1 * wv[bj][1]; u32x4 z; z.x = cvt_pk_bf16(y0[0], y0[1]); z.y = cvt_pk_bf16(y0[2], y0[3]); z.z = cvt_pk_bf16(y1[0], y1[1]); z.w = cvt_pk_bf16(y1[2], y1[3]);
;                         *(u32x4*)(hb + (size_t)rowt * DM + off + bj * HALF) = z; } }
;                 if (ssq) { sq += __shfl_xor(sq, 16); sq += __shfl_xor(sq, 32); if (fq == 0) ssq[(size_t)(rowt + rl) * 16 + u.pn * 4 + wc] = sq; } }
.LBB0_1425:
	v_mul_f32_e32 v133, v133, v133
	s_waitcnt vmcnt(0)
	v_pk_fma_f32 v[118:119], v[118:119], v[50:51], v[126:127]
	v_pk_fma_f32 v[116:117], v[116:117], v[48:49], v[124:125]
	v_pk_fma_f32 v[120:121], v[112:113], v[52:53], v[120:121]
	v_cvt_pk_bf16_f32 v112, v116, v117
	v_cvt_pk_bf16_f32 v113, v118, v119
	v_fmac_f32_e32 v133, v132, v132
	v_mul_f32_e32 v132, v135, v135
	v_pk_fma_f32 v[122:123], v[114:115], v[54:55], v[122:123]
	v_cvt_pk_bf16_f32 v114, v120, v121
	v_fmac_f32_e32 v132, v134, v134
	v_cvt_pk_bf16_f32 v115, v122, v123
	global_store_dwordx4 v[140:141], v[112:115], off offset:256 sc1
	v_add_f32_e32 v132, v133, v132
	v_mul_f32_e32 v133, v147, v147
	v_mul_f32_e32 v112, v117, v117
	v_mul_f32_e32 v113, v119, v119
	v_fmac_f32_e32 v112, v116, v116
	v_fmac_f32_e32 v113, v118, v118
	v_mul_f32_e32 v131, v131, v131
	v_add_f32_e32 v112, v112, v113
	v_mul_f32_e32 v113, v121, v121
	v_mul_f32_e32 v114, v123, v123
	v_fmac_f32_e32 v133, v146, v146
	v_fmac_f32_e32 v131, v130, v130
	v_fmac_f32_e32 v113, v120, v120
	v_fmac_f32_e32 v114, v122, v122
	v_add_f32_e32 v130, v133, v131
	v_add_f32_e32 v113, v113, v114
	v_add_f32_e32 v130, v132, v130
	v_add_f32_e32 v112, v112, v113
	v_add_f32_e32 v115, v130, v112
	ds_bpermute_b32 v124, v172, v115
	v_pk_mul_f32 v[112:113], v[168:169], v[116:117]
	v_pk_mul_f32 v[116:117], v[176:177], v[120:121]
	v_cvt_pk_bf16_f32 v114, v112, v113
	v_pk_mul_f32 v[118:119], v[170:171], v[118:119]
	s_waitcnt lgkmcnt(0)
	v_add_f32_e32 v112, v115, v124
	ds_bpermute_b32 v113, v173, v112
	v_pk_mul_f32 v[122:123], v[178:179], v[122:123]
	v_cvt_pk_bf16_f32 v115, v118, v119
	v_cvt_pk_bf16_f32 v116, v116, v117
	s_nop 0
	v_cvt_pk_bf16_f32 v117, v122, v123
	global_store_dwordx4 v[128:129], v[114:117], off offset:256 sc1
	s_and_saveexec_b64 s[76:77], s[42:43]
	s_cbranch_execz .LBB0_1427
	s_waitcnt lgkmcnt(0)
	v_add_f32_e32 v114, v112, v113
	v_add_u32_e32 v112, s70, v236
	v_ashrrev_i32_e32 v113, 31, v112
	s_lshl_b32 s52, s18, 2
	v_lshlrev_b64 v[112:113], 6, v[112:113]
	s_ashr_i32 s53, s52, 31
	v_lshl_add_u64 v[112:113], s[46:47], 0, v[112:113]
	v_lshl_add_u64 v[112:113], s[52:53], 2, v[112:113]
	s_lshl_b32 s8, s38, 2
	v_lshl_add_u64 v[112:113], v[112:113], 0, s[8:9]
	global_store_dword v[112:113], v114, off

; __device__ __forceinline__ unsigned cvt_pk_bf16(float lo, float hi) { unsigned r; asm volatile("v_cvt_pk_bf16_f32 %0, %1, %2" : "=v"(r) : "v"(lo), "v"(hi)); return r; }
;     __device__ __forceinline__ void operator()(const f32x4 (&acc)[2][2][4][2], const Unit& u, int wr, int wc, int fr, int fq) const {
;     ...
;             for (int m = 0; m < 4; ++m) { const int rl = wr * 64 + fr + ai * HALF + m * 16; const size_t off = (size_t)rl * DM + col0; float sq = 0.f;
;                 bf16_t* hrow = h16 + (size_t)rowt * DM + off;
; #pragma unroll
;                 for (int bj = 0; bj < 2; ++bj) { f32x4 b0, b1;
;                     if (bb) { b0 = *(const f32x4*)(bb + off + bj * HALF); b1 = *(const f32x4*)(bb + off + bj * HALF + 4); }
;                     else { const u32x4 r = raw[m][bj];
;                         b0 = (f32x4){__uint_as_float(r.x << 16), __uint_as_float(r.x & 0xffff0000u), __uint_as_float(r.y << 16), __uint_as_float(r.y & 0xffff0000u)};
;                         b1 = (f32x4){__uint_as_float(r.z << 16), __uint_as_float(r.z & 0xffff0000u), __uint_as_float(r.w << 16), __uint_as_float(r.w & 0xffff0000u)}; }
;                     const f32x4 o0 = b0 + gv[bj][0] * acc[ai][bj][m][0], o1 = b1 + gv[bj][1] * acc[ai][bj][m][1];
;                     u32x4 w; w.x = cvt_pk_bf16(o0[0], o0[1]); w.y = cvt_pk_bf16(o0[2], o0[3]); w.z = cvt_pk_bf16(o1[0], o1[1]); w.w = cvt_pk_bf16(o1[2], o1[3]);
;                     *(u32x4*)(hrow + bj * HALF) = w;
;                     sq += ((o0[0] * o0[0] + o0[1] * o0[1]) + (o0[2] * o0[2] + o0[3] * o0[3])) + ((o1[0] * o1[0] + o1[1] * o1[1]) + (o1[2] * o1[2] + o1[3] * o1[3]));
;                     if (hb) { const f32x4 y0 = o0 * wv[bj][0], y1 = o1 * wv[bj][1]; u32x4 z; z.x = cvt_pk_bf16(y0[0], y0[1]); z.y = cvt_pk_bf16(y0[2], y0[3]); z.z = cvt_pk_bf16(y1[0], y1[1]); z.w = cvt_pk_bf16(y1[2], y1[3]);
;                         *(u32x4*)(hb + (size_t)rowt * DM + off + bj * HALF) = z; } }
;                 if (ssq) { sq += __shfl_xor(sq, 16); sq += __shfl_xor(sq, 32); if (fq == 0) ssq[(size_t)(rowt + rl) * 16 + u.pn * 4 + wc] = sq; } }
.LBB0_1430:
	v_lshl_add_u64 v[120:121], v[120:121], 1, v[228:229]
	s_waitcnt vmcnt(0)
	v_pk_fma_f32 v[118:119], v[110:111], v[66:67], v[118:119]
	v_pk_fma_f32 v[116:117], v[108:109], v[64:65], v[116:117]
	v_pk_fma_f32 v[114:115], v[106:107], v[70:71], v[114:115]
	s_waitcnt lgkmcnt(0)
	v_pk_fma_f32 v[126:127], v[104:105], v[68:69], v[112:113]
	v_cvt_pk_bf16_f32 v104, v116, v117
	v_cvt_pk_bf16_f32 v105, v118, v119
	v_lshl_add_u64 v[112:113], v[124:125], 1, s[74:75]
	v_cvt_pk_bf16_f32 v106, v126, v127
	v_cvt_pk_bf16_f32 v107, v114, v115
	global_store_dwordx4 v[120:121], v[104:107], off sc1
	s_and_b64 vcc, exec, s[44:45]
	v_pk_mul_f32 v[108:109], v[194:195], v[114:115]
	v_pk_mul_f32 v[106:107], v[186:187], v[118:119]
	v_pk_mul_f32 v[104:105], v[184:185], v[116:117]
	v_pk_mul_f32 v[110:111], v[192:193], v[126:127]
	v_cvt_pk_bf16_f32 v104, v104, v105
	v_cvt_pk_bf16_f32 v105, v106, v107
	s_nop 0
	v_cvt_pk_bf16_f32 v106, v110, v111
	v_cvt_pk_bf16_f32 v107, v108, v109
	global_store_dwordx4 v[112:113], v[104:107], off sc1
	s_cbranch_vccnz .LBB0_1483
	global_load_dwordx4 v[104:107], v[122:123], off offset:528
	global_load_dwordx4 v[108:111], v[122:123], off offset:512
	s_cbranch_execnz .LBB0_1433

; __device__ __forceinline__ unsigned cvt_pk_bf16(float lo, float hi) { unsigned r; asm volatile("v_cvt_pk_bf16_f32 %0, %1, %2" : "=v"(r) : "v"(lo), "v"(hi)); return r; }
;     __device__ __forceinline__ void operator()(const f32x4 (&acc)[2][2][4][2], const Unit& u, int wr, int wc, int fr, int fq) const {
;     ...
;             for (int m = 0; m < 4; ++m) { const int rl = wr * 64 + fr + ai * HALF + m * 16; const size_t off = (size_t)rl * DM + col0; float sq = 0.f;
;                 bf16_t* hrow = h16 + (size_t)rowt * DM + off;
; #pragma unroll
;                 for (int bj = 0; bj < 2; ++bj) { f32x4 b0, b1;
;                     if (bb) { b0 = *(const f32x4*)(bb + off + bj * HALF); b1 = *(const f32x4*)(bb + off + bj * HALF + 4); }
;                     else { const u32x4 r = raw[m][bj];
;                         b0 = (f32x4){__uint_as_float(r.x << 16), __uint_as_float(r.x & 0xffff0000u), __uint_as_float(r.y << 16), __uint_as_float(r.y & 0xffff0000u)};
;                         b1 = (f32x4){__uint_as_float(r.z << 16), __uint_as_float(r.z & 0xffff0000u), __uint_as_float(r.w << 16), __uint_as_float(r.w & 0xffff0000u)}; }
;                     const f32x4 o0 = b0 + gv[bj][0] * acc[ai][bj][m][0], o1 = b1 + gv[bj][1] * acc[ai][bj][m][1];
;                     u32x4 w; w.x = cvt_pk_bf16(o0[0], o0[1]); w.y = cvt_pk_bf16(o0[2], o0[3]); w.z = cvt_pk_bf16(o1[0], o1[1]); w.w = cvt_pk_bf16(o1[2], o1[3]);
;                     *(u32x4*)(hrow + bj * HALF) = w;
;                     sq += ((o0[0] * o0[0] + o0[1] * o0[1]) + (o0[2] * o0[2] + o0[3] * o0[3])) + ((o1[0] * o1[0] + o1[1] * o1[1]) + (o1[2] * o1[2] + o1[3] * o1[3]));
;                     if (hb) { const f32x4 y0 = o0 * wv[bj][0], y1 = o1 * wv[bj][1]; u32x4 z; z.x = cvt_pk_bf16(y0[0], y0[1]); z.y = cvt_pk_bf16(y0[2], y0[3]); z.z = cvt_pk_bf16(y1[0], y1[1]); z.w = cvt_pk_bf16(y1[2], y1[3]);
;                         *(u32x4*)(hb + (size_t)rowt * DM + off + bj * HALF) = z; } }
;                 if (ssq) { sq += __shfl_xor(sq, 16); sq += __shfl_xor(sq, 32); if (fq == 0) ssq[(size_t)(rowt + rl) * 16 + u.pn * 4 + wc] = sq; } }
.LBB0_1433:
	v_mul_f32_e32 v117, v117, v117
	s_waitcnt vmcnt(0)
	v_pk_fma_f32 v[102:103], v[102:103], v[50:51], v[110:111]
	v_pk_fma_f32 v[100:101], v[100:101], v[48:49], v[108:109]
	v_pk_fma_f32 v[104:105], v[96:97], v[52:53], v[104:105]
	v_cvt_pk_bf16_f32 v96, v100, v101
	v_cvt_pk_bf16_f32 v97, v102, v103
	v_fmac_f32_e32 v117, v116, v116
	v_mul_f32_e32 v116, v119, v119
	v_pk_fma_f32 v[106:107], v[98:99], v[54:55], v[106:107]
	v_cvt_pk_bf16_f32 v98, v104, v105
	v_fmac_f32_e32 v116, v118, v118
	v_cvt_pk_bf16_f32 v99, v106, v107
	global_store_dwordx4 v[120:121], v[96:99], off offset:256 sc1
	v_add_f32_e32 v116, v117, v116
	v_mul_f32_e32 v117, v127, v127
	v_mul_f32_e32 v96, v101, v101
	v_mul_f32_e32 v97, v103, v103
	v_fmac_f32_e32 v96, v100, v100
	v_fmac_f32_e32 v97, v102, v102
	v_mul_f32_e32 v115, v115, v115
	v_add_f32_e32 v96, v96, v97
	v_mul_f32_e32 v97, v105, v105
	v_mul_f32_e32 v98, v107, v107
	v_fmac_f32_e32 v117, v126, v126
	v_fmac_f32_e32 v115, v114, v114
	v_fmac_f32_e32 v97, v104, v104
	v_fmac_f32_e32 v98, v106, v106
	v_add_f32_e32 v114, v117, v115
	v_add_f32_e32 v97, v97, v98
	v_add_f32_e32 v114, v116, v114
	v_add_f32_e32 v96, v96, v97
	v_add_f32_e32 v99, v114, v96
	ds_bpermute_b32 v108, v172, v99
	v_pk_mul_f32 v[96:97], v[168:169], v[100:101]
	v_pk_mul_f32 v[100:101], v[176:177], v[104:105]
	v_cvt_pk_bf16_f32 v98, v96, v97
	v_pk_mul_f32 v[102:103], v[170:171], v[102:103]
	s_waitcnt lgkmcnt(0)
	v_add_f32_e32 v96, v99, v108
	ds_bpermute_b32 v97, v173, v96
	v_pk_mul_f32 v[106:107], v[178:179], v[106:107]
	v_cvt_pk_bf16_f32 v99, v102, v103
	v_cvt_pk_bf16_f32 v100, v100, v101
	s_nop 0
	v_cvt_pk_bf16_f32 v101, v106, v107
	global_store_dwordx4 v[112:113], v[98:101], off offset:256 sc1
	s_and_saveexec_b64 s[76:77], s[42:43]
	s_cbranch_execz .LBB0_1435
	s_waitcnt lgkmcnt(0)
	v_add_f32_e32 v98, v96, v97
	v_add_u32_e32 v96, s70, v234
	v_ashrrev_i32_e32 v97, 31, v96
	s_lshl_b32 s52, s18, 2
	v_lshlrev_b64 v[96:97], 6, v[96:97]
	s_ashr_i32 s53, s52, 31
	v_lshl_add_u64 v[96:97], s[46:47], 0, v[96:97]
	v_lshl_add_u64 v[96:97], s[52:53], 2, v[96:97]
	s_lshl_b32 s8, s38, 2
	v_lshl_add_u64 v[96:97], v[96:97], 0, s[8:9]
	global_store_dword v[96:97], v98, off

; __device__ __forceinline__ unsigned cvt_pk_bf16(float lo, float hi) { unsigned r; asm volatile("v_cvt_pk_bf16_f32 %0, %1, %2" : "=v"(r) : "v"(lo), "v"(hi)); return r; }
;     __device__ __forceinline__ void operator()(const f32x4 (&acc)[2][2][4][2], const Unit& u, int wr, int wc, int fr, int fq) const {
;     ...
;             for (int m = 0; m < 4; ++m) { const int rl = wr * 64 + fr + ai * HALF + m * 16; const size_t off = (size_t)rl * DM + col0; float sq = 0.f;
;                 bf16_t* hrow = h16 + (size_t)rowt * DM + off;
; #pragma unroll
;                 for (int bj = 0; bj < 2; ++bj) { f32x4 b0, b1;
;                     if (bb) { b0 = *(const f32x4*)(bb + off + bj * HALF); b1 = *(const f32x4*)(bb + off + bj * HALF + 4); }
;                     else { const u32x4 r = raw[m][bj];
;                         b0 = (f32x4){__uint_as_float(r.x << 16), __uint_as_float(r.x & 0xffff0000u), __uint_as_float(r.y << 16), __uint_as_float(r.y & 0xffff0000u)};
;                         b1 = (f32x4){__uint_as_float(r.z << 16), __uint_as_float(r.z & 0xffff0000u), __uint_as_float(r.w << 16), __uint_as_float(r.w & 0xffff0000u)}; }
;                     const f32x4 o0 = b0 + gv[bj][0] * acc[ai][bj][m][0], o1 = b1 + gv[bj][1] * acc[ai][bj][m][1];
;                     u32x4 w; w.x = cvt_pk_bf16(o0[0], o0[1]); w.y = cvt_pk_bf16(o0[2], o0[3]); w.z = cvt_pk_bf16(o1[0], o1[1]); w.w = cvt_pk_bf16(o1[2], o1[3]);
;                     *(u32x4*)(hrow + bj * HALF) = w;
;                     sq += ((o0[0] * o0[0] + o0[1] * o0[1]) + (o0[2] * o0[2] + o0[3] * o0[3])) + ((o1[0] * o1[0] + o1[1] * o1[1]) + (o1[2] * o1[2] + o1[3] * o1[3]));
;                     if (hb) { const f32x4 y0 = o0 * wv[bj][0], y1 = o1 * wv[bj][1]; u32x4 z; z.x = cvt_pk_bf16(y0[0], y0[1]); z.y = cvt_pk_bf16(y0[2], y0[3]); z.z = cvt_pk_bf16(y1[0], y1[1]); z.w = cvt_pk_bf16(y1[2], y1[3]);
;                         *(u32x4*)(hb + (size_t)rowt * DM + off + bj * HALF) = z; } }
;                 if (ssq) { sq += __shfl_xor(sq, 16); sq += __shfl_xor(sq, 32); if (fq == 0) ssq[(size_t)(rowt + rl) * 16 + u.pn * 4 + wc] = sq; } }
.LBB0_1438:
	v_lshl_add_u64 v[104:105], v[104:105], 1, v[228:229]
	s_waitcnt vmcnt(0)
	v_pk_fma_f32 v[102:103], v[94:95], v[66:67], v[102:103]
	v_pk_fma_f32 v[100:101], v[92:93], v[64:65], v[100:101]
	v_pk_fma_f32 v[98:99], v[90:91], v[70:71], v[98:99]
	s_waitcnt lgkmcnt(0)
	v_pk_fma_f32 v[110:111], v[88:89], v[68:69], v[96:97]
	v_cvt_pk_bf16_f32 v88, v100, v101
	v_cvt_pk_bf16_f32 v89, v102, v103
	v_lshl_add_u64 v[96:97], v[108:109], 1, s[74:75]
	v_cvt_pk_bf16_f32 v90, v110, v111
	v_cvt_pk_bf16_f32 v91, v98, v99
	global_store_dwordx4 v[104:105], v[88:91], off sc1
	s_and_b64 vcc, exec, s[44:45]
	v_pk_mul_f32 v[92:93], v[194:195], v[98:99]
	v_pk_mul_f32 v[90:91], v[186:187], v[102:103]
	v_pk_mul_f32 v[88:89], v[184:185], v[100:101]
	v_pk_mul_f32 v[94:95], v[192:193], v[110:111]
	v_cvt_pk_bf16_f32 v88, v88, v89
	v_cvt_pk_bf16_f32 v89, v90, v91
	s_nop 0
	v_cvt_pk_bf16_f32 v90, v94, v95
	v_cvt_pk_bf16_f32 v91, v92, v93
	global_store_dwordx4 v[96:97], v[88:91], off sc1
	s_cbranch_vccnz .LBB0_1485
	global_load_dwordx4 v[88:91], v[106:107], off offset:528
	global_load_dwordx4 v[92:95], v[106:107], off offset:512
	s_cbranch_execnz .LBB0_1441

; __device__ __forceinline__ unsigned cvt_pk_bf16(float lo, float hi) { unsigned r; asm volatile("v_cvt_pk_bf16_f32 %0, %1, %2" : "=v"(r) : "v"(lo), "v"(hi)); return r; }
;     __device__ __forceinline__ void operator()(const f32x4 (&acc)[2][2][4][2], const Unit& u, int wr, int wc, int fr, int fq) const {
;     ...
;             for (int m = 0; m < 4; ++m) { const int rl = wr * 64 + fr + ai * HALF + m * 16; const size_t off = (size_t)rl * DM + col0; float sq = 0.f;
;                 bf16_t* hrow = h16 + (size_t)rowt * DM + off;
; #pragma unroll
;                 for (int bj = 0; bj < 2; ++bj) { f32x4 b0, b1;
;                     if (bb) { b0 = *(const f32x4*)(bb + off + bj * HALF); b1 = *(const f32x4*)(bb + off + bj * HALF + 4); }
;                     else { const u32x4 r = raw[m][bj];
;                         b0 = (f32x4){__uint_as_float(r.x << 16), __uint_as_float(r.x & 0xffff0000u), __uint_as_float(r.y << 16), __uint_as_float(r.y & 0xffff0000u)};
;                         b1 = (f32x4){__uint_as_float(r.z << 16), __uint_as_float(r.z & 0xffff0000u), __uint_as_float(r.w << 16), __uint_as_float(r.w & 0xffff0000u)}; }
;                     const f32x4 o0 = b0 + gv[bj][0] * acc[ai][bj][m][0], o1 = b1 + gv[bj][1] * acc[ai][bj][m][1];
;                     u32x4 w; w.x = cvt_pk_bf16(o0[0], o0[1]); w.y = cvt_pk_bf16(o0[2], o0[3]); w.z = cvt_pk_bf16(o1[0], o1[1]); w.w = cvt_pk_bf16(o1[2], o1[3]);
;                     *(u32x4*)(hrow + bj * HALF) = w;
;                     sq += ((o0[0] * o0[0] + o0[1] * o0[1]) + (o0[2] * o0[2] + o0[3] * o0[3])) + ((o1[0] * o1[0] + o1[1] * o1[1]) + (o1[2] * o1[2] + o1[3] * o1[3]));
;                     if (hb) { const f32x4 y0 = o0 * wv[bj][0], y1 = o1 * wv[bj][1]; u32x4 z; z.x = cvt_pk_bf16(y0[0], y0[1]); z.y = cvt_pk_bf16(y0[2], y0[3]); z.z = cvt_pk_bf16(y1[0], y1[1]); z.w = cvt_pk_bf16(y1[2], y1[3]);
;                         *(u32x4*)(hb + (size_t)rowt * DM + off + bj * HALF) = z; } }
;                 if (ssq) { sq += __shfl_xor(sq, 16); sq += __shfl_xor(sq, 32); if (fq == 0) ssq[(size_t)(rowt + rl) * 16 + u.pn * 4 + wc] = sq; } }
.LBB0_1441:
	v_mul_f32_e32 v101, v101, v101
	s_waitcnt vmcnt(0)
	v_pk_fma_f32 v[86:87], v[86:87], v[50:51], v[94:95]
	v_pk_fma_f32 v[84:85], v[84:85], v[48:49], v[92:93]
	v_pk_fma_f32 v[88:89], v[80:81], v[52:53], v[88:89]
	v_cvt_pk_bf16_f32 v80, v84, v85
	v_cvt_pk_bf16_f32 v81, v86, v87
	v_fmac_f32_e32 v101, v100, v100
	v_mul_f32_e32 v100, v103, v103
	v_pk_fma_f32 v[90:91], v[82:83], v[54:55], v[90:91]
	v_cvt_pk_bf16_f32 v82, v88, v89
	v_fmac_f32_e32 v100, v102, v102
	v_cvt_pk_bf16_f32 v83, v90, v91
	global_store_dwordx4 v[104:105], v[80:83], off offset:256 sc1
	v_add_f32_e32 v100, v101, v100
	v_mul_f32_e32 v101, v111, v111
	v_mul_f32_e32 v80, v85, v85
	v_mul_f32_e32 v81, v87, v87
	v_fmac_f32_e32 v80, v84, v84
	v_fmac_f32_e32 v81, v86, v86
	v_mul_f32_e32 v99, v99, v99
	v_add_f32_e32 v80, v80, v81
	v_mul_f32_e32 v81, v89, v89
	v_mul_f32_e32 v82, v91, v91
	v_fmac_f32_e32 v101, v110, v110
	v_fmac_f32_e32 v99, v98, v98
	v_fmac_f32_e32 v81, v88, v88
	v_fmac_f32_e32 v82, v90, v90
	v_add_f32_e32 v98, v101, v99
	v_add_f32_e32 v81, v81, v82
	v_add_f32_e32 v98, v100, v98
	v_add_f32_e32 v80, v80, v81
	v_add_f32_e32 v83, v98, v80
	ds_bpermute_b32 v92, v172, v83
	v_pk_mul_f32 v[80:81], v[168:169], v[84:85]
	v_pk_mul_f32 v[84:85], v[176:177], v[88:89]
	v_cvt_pk_bf16_f32 v82, v80, v81
	v_pk_mul_f32 v[86:87], v[170:171], v[86:87]
	s_waitcnt lgkmcnt(0)
	v_add_f32_e32 v80, v83, v92
	ds_bpermute_b32 v81, v173, v80
	v_pk_mul_f32 v[90:91], v[178:179], v[90:91]
	v_cvt_pk_bf16_f32 v83, v86, v87
	v_cvt_pk_bf16_f32 v84, v84, v85
	s_nop 0
	v_cvt_pk_bf16_f32 v85, v90, v91
	global_store_dwordx4 v[96:97], v[82:85], off offset:256 sc1
	s_and_saveexec_b64 s[76:77], s[42:43]
	s_cbranch_execz .LBB0_1443
	s_waitcnt lgkmcnt(0)
	v_add_f32_e32 v82, v80, v81
	v_add_u32_e32 v80, s70, v232
	v_ashrrev_i32_e32 v81, 31, v80
	s_lshl_b32 s52, s18, 2
	v_lshlrev_b64 v[80:81], 6, v[80:81]
	s_ashr_i32 s53, s52, 31
	v_lshl_add_u64 v[80:81], s[46:47], 0, v[80:81]
	v_lshl_add_u64 v[80:81], s[52:53], 2, v[80:81]
	s_lshl_b32 s8, s38, 2
	v_lshl_add_u64 v[80:81], v[80:81], 0, s[8:9]
	global_store_dword v[80:81], v82, off

; __device__ __forceinline__ unsigned cvt_pk_bf16(float lo, float hi) { unsigned r; asm volatile("v_cvt_pk_bf16_f32 %0, %1, %2" : "=v"(r) : "v"(lo), "v"(hi)); return r; }
;     __device__ __forceinline__ void operator()(const f32x4 (&acc)[2][2][4][2], const Unit& u, int wr, int wc, int fr, int fq) const {
;     ...
;             for (int m = 0; m < 4; ++m) { const int rl = wr * 64 + fr + ai * HALF + m * 16; const size_t off = (size_t)rl * DM + col0; float sq = 0.f;
;                 bf16_t* hrow = h16 + (size_t)rowt * DM + off;
; #pragma unroll
;                 for (int bj = 0; bj < 2; ++bj) { f32x4 b0, b1;
;                     if (bb) { b0 = *(const f32x4*)(bb + off + bj * HALF); b1 = *(const f32x4*)(bb + off + bj * HALF + 4); }
;                     else { const u32x4 r = raw[m][bj];
;                         b0 = (f32x4){__uint_as_float(r.x << 16), __uint_as_float(r.x & 0xffff0000u), __uint_as_float(r.y << 16), __uint_as_float(r.y & 0xffff0000u)};
;                         b1 = (f32x4){__uint_as_float(r.z << 16), __uint_as_float(r.z & 0xffff0000u), __uint_as_float(r.w << 16), __uint_as_float(r.w & 0xffff0000u)}; }
;                     const f32x4 o0 = b0 + gv[bj][0] * acc[ai][bj][m][0], o1 = b1 + gv[bj][1] * acc[ai][bj][m][1];
;                     u32x4 w; w.x = cvt_pk_bf16(o0[0], o0[1]); w.y = cvt_pk_bf16(o0[2], o0[3]); w.z = cvt_pk_bf16(o1[0], o1[1]); w.w = cvt_pk_bf16(o1[2], o1[3]);
;                     *(u32x4*)(hrow + bj * HALF) = w;
;                     sq += ((o0[0] * o0[0] + o0[1] * o0[1]) + (o0[2] * o0[2] + o0[3] * o0[3])) + ((o1[0] * o1[0] + o1[1] * o1[1]) + (o1[2] * o1[2] + o1[3] * o1[3]));
;                     if (hb) { const f32x4 y0 = o0 * wv[bj][0], y1 = o1 * wv[bj][1]; u32x4 z; z.x = cvt_pk_bf16(y0[0], y0[1]); z.y = cvt_pk_bf16(y0[2], y0[3]); z.z = cvt_pk_bf16(y1[0], y1[1]); z.w = cvt_pk_bf16(y1[2], y1[3]);
;                         *(u32x4*)(hb + (size_t)rowt * DM + off + bj * HALF) = z; } }
;                 if (ssq) { sq += __shfl_xor(sq, 16); sq += __shfl_xor(sq, 32); if (fq == 0) ssq[(size_t)(rowt + rl) * 16 + u.pn * 4 + wc] = sq; } }
.LBB0_1446:
	v_lshl_add_u64 v[124:125], v[130:131], 1, v[228:229]
	s_waitcnt vmcnt(0)
	v_pk_fma_f32 v[114:115], v[78:79], v[66:67], v[114:115]
	v_pk_fma_f32 v[112:113], v[76:77], v[64:65], v[112:113]
	v_pk_fma_f32 v[110:111], v[74:75], v[70:71], v[110:111]
	v_pk_fma_f32 v[130:131], v[72:73], v[68:69], v[108:109]
	v_cvt_pk_bf16_f32 v72, v112, v113
	v_cvt_pk_bf16_f32 v73, v114, v115
	v_lshl_add_u64 v[108:109], v[128:129], 1, s[74:75]
	v_cvt_pk_bf16_f32 v74, v130, v131
	v_cvt_pk_bf16_f32 v75, v110, v111
	global_store_dwordx4 v[124:125], v[72:75], off sc1
	s_and_b64 vcc, exec, s[44:45]
	v_pk_mul_f32 v[76:77], v[194:195], v[110:111]
	v_pk_mul_f32 v[74:75], v[186:187], v[114:115]
	v_pk_mul_f32 v[72:73], v[184:185], v[112:113]
	v_pk_mul_f32 v[78:79], v[192:193], v[130:131]
	v_cvt_pk_bf16_f32 v72, v72, v73
	v_cvt_pk_bf16_f32 v73, v74, v75
	s_nop 0
	v_cvt_pk_bf16_f32 v74, v78, v79
	v_cvt_pk_bf16_f32 v75, v76, v77
	global_store_dwordx4 v[108:109], v[72:75], off sc1
	s_cbranch_vccnz .LBB0_1487
	global_load_dwordx4 v[72:75], v[126:127], off offset:528
	global_load_dwordx4 v[76:79], v[126:127], off offset:512
	s_cbranch_execnz .LBB0_1449

; __device__ __forceinline__ unsigned cvt_pk_bf16(float lo, float hi) { unsigned r; asm volatile("v_cvt_pk_bf16_f32 %0, %1, %2" : "=v"(r) : "v"(lo), "v"(hi)); return r; }
;     __device__ __forceinline__ void operator()(const f32x4 (&acc)[2][2][4][2], const Unit& u, int wr, int wc, int fr, int fq) const {
;     ...
;             for (int m = 0; m < 4; ++m) { const int rl = wr * 64 + fr + ai * HALF + m * 16; const size_t off = (size_t)rl * DM + col0; float sq = 0.f;
;                 bf16_t* hrow = h16 + (size_t)rowt * DM + off;
; #pragma unroll
;                 for (int bj = 0; bj < 2; ++bj) { f32x4 b0, b1;
;                     if (bb) { b0 = *(const f32x4*)(bb + off + bj * HALF); b1 = *(const f32x4*)(bb + off + bj * HALF + 4); }
;                     else { const u32x4 r = raw[m][bj];
;                         b0 = (f32x4){__uint_as_float(r.x << 16), __uint_as_float(r.x & 0xffff0000u), __uint_as_float(r.y << 16), __uint_as_float(r.y & 0xffff0000u)};
;                         b1 = (f32x4){__uint_as_float(r.z << 16), __uint_as_float(r.z & 0xffff0000u), __uint_as_float(r.w << 16), __uint_as_float(r.w & 0xffff0000u)}; }
;                     const f32x4 o0 = b0 + gv[bj][0] * acc[ai][bj][m][0], o1 = b1 + gv[bj][1] * acc[ai][bj][m][1];
;                     u32x4 w; w.x = cvt_pk_bf16(o0[0], o0[1]); w.y = cvt_pk_bf16(o0[2], o0[3]); w.z = cvt_pk_bf16(o1[0], o1[1]); w.w = cvt_pk_bf16(o1[2], o1[3]);
;                     *(u32x4*)(hrow + bj * HALF) = w;
;                     sq += ((o0[0] * o0[0] + o0[1] * o0[1]) + (o0[2] * o0[2] + o0[3] * o0[3])) + ((o1[0] * o1[0] + o1[1] * o1[1]) + (o1[2] * o1[2] + o1[3] * o1[3]));
;                     if (hb) { const f32x4 y0 = o0 * wv[bj][0], y1 = o1 * wv[bj][1]; u32x4 z; z.x = cvt_pk_bf16(y0[0], y0[1]); z.y = cvt_pk_bf16(y0[2], y0[3]); z.z = cvt_pk_bf16(y1[0], y1[1]); z.w = cvt_pk_bf16(y1[2], y1[3]);
;                         *(u32x4*)(hb + (size_t)rowt * DM + off + bj * HALF) = z; } }
;                 if (ssq) { sq += __shfl_xor(sq, 16); sq += __shfl_xor(sq, 32); if (fq == 0) ssq[(size_t)(rowt + rl) * 16 + u.pn * 4 + wc] = sq; } }
.LBB0_1449:
	s_waitcnt vmcnt(0)
	v_pk_fma_f32 v[62:63], v[62:63], v[50:51], v[78:79]
	v_pk_fma_f32 v[60:61], v[60:61], v[48:49], v[76:77]
	v_pk_fma_f32 v[72:73], v[56:57], v[52:53], v[72:73]
	v_cvt_pk_bf16_f32 v56, v60, v61
	v_cvt_pk_bf16_f32 v57, v62, v63
	v_mul_f32_e32 v104, v113, v113
	v_mul_f32_e32 v105, v115, v115
	v_pk_fma_f32 v[74:75], v[58:59], v[54:55], v[74:75]
	v_cvt_pk_bf16_f32 v58, v72, v73
	v_fmac_f32_e32 v104, v112, v112
	v_cvt_pk_bf16_f32 v59, v74, v75
	global_store_dwordx4 v[124:125], v[56:59], off offset:256 sc1
	v_fmac_f32_e32 v105, v114, v114
	v_add_f32_e32 v104, v104, v105
	v_mul_f32_e32 v56, v61, v61
	v_mul_f32_e32 v57, v63, v63
	v_fmac_f32_e32 v56, v60, v60
	v_fmac_f32_e32 v57, v62, v62
	v_mul_f32_e32 v105, v131, v131
	v_mul_f32_e32 v106, v111, v111
	v_add_f32_e32 v56, v56, v57
	v_mul_f32_e32 v57, v73, v73
	v_mul_f32_e32 v58, v75, v75
	v_fmac_f32_e32 v105, v130, v130
	v_fmac_f32_e32 v106, v110, v110
	v_fmac_f32_e32 v57, v72, v72
	v_fmac_f32_e32 v58, v74, v74
	v_add_f32_e32 v105, v105, v106
	v_add_f32_e32 v57, v57, v58
	v_add_f32_e32 v104, v104, v105
	v_add_f32_e32 v56, v56, v57
	v_add_f32_e32 v59, v104, v56
	ds_bpermute_b32 v76, v172, v59
	v_pk_mul_f32 v[56:57], v[168:169], v[60:61]
	v_pk_mul_f32 v[60:61], v[176:177], v[72:73]
	v_cvt_pk_bf16_f32 v58, v56, v57
	v_pk_mul_f32 v[62:63], v[170:171], v[62:63]
	s_waitcnt lgkmcnt(0)
	v_add_f32_e32 v56, v59, v76
	ds_bpermute_b32 v57, v173, v56
	v_pk_mul_f32 v[74:75], v[178:179], v[74:75]
	v_cvt_pk_bf16_f32 v59, v62, v63
	v_cvt_pk_bf16_f32 v60, v60, v61
	s_nop 0
	v_cvt_pk_bf16_f32 v61, v74, v75
	global_store_dwordx4 v[108:109], v[58:61], off offset:256 sc1
	s_and_saveexec_b64 s[76:77], s[42:43]
	s_cbranch_execz .LBB0_1451
	s_waitcnt lgkmcnt(0)
	v_add_f32_e32 v58, v56, v57
	v_add_u32_e32 v56, s70, v122
	v_ashrrev_i32_e32 v57, 31, v56
	s_lshl_b32 s52, s18, 2
	v_lshlrev_b64 v[56:57], 6, v[56:57]
	s_ashr_i32 s53, s52, 31
	v_lshl_add_u64 v[56:57], s[46:47], 0, v[56:57]
	v_lshl_add_u64 v[56:57], s[52:53], 2, v[56:57]
	s_lshl_b32 s8, s38, 2
	v_lshl_add_u64 v[56:57], v[56:57], 0, s[8:9]
	global_store_dword v[56:57], v58, off

; __device__ __forceinline__ unsigned cvt_pk_bf16(float lo, float hi) { unsigned r; asm volatile("v_cvt_pk_bf16_f32 %0, %1, %2" : "=v"(r) : "v"(lo), "v"(hi)); return r; }
;     __device__ __forceinline__ void operator()(const f32x4 (&acc)[2][2][4][2], const Unit& u, int wr, int wc, int fr, int fq) const {
;     ...
;             for (int m = 0; m < 4; ++m) { const int rl = wr * 64 + fr + ai * HALF + m * 16; const size_t off = (size_t)rl * DM + col0; float sq = 0.f;
;                 bf16_t* hrow = h16 + (size_t)rowt * DM + off;
; #pragma unroll
;                 for (int bj = 0; bj < 2; ++bj) { f32x4 b0, b1;
;                     if (bb) { b0 = *(const f32x4*)(bb + off + bj * HALF); b1 = *(const f32x4*)(bb + off + bj * HALF + 4); }
;                     else { const u32x4 r = raw[m][bj];
;                         b0 = (f32x4){__uint_as_float(r.x << 16), __uint_as_float(r.x & 0xffff0000u), __uint_as_float(r.y << 16), __uint_as_float(r.y & 0xffff0000u)};
;                         b1 = (f32x4){__uint_as_float(r.z << 16), __uint_as_float(r.z & 0xffff0000u), __uint_as_float(r.w << 16), __uint_as_float(r.w & 0xffff0000u)}; }
;                     const f32x4 o0 = b0 + gv[bj][0] * acc[ai][bj][m][0], o1 = b1 + gv[bj][1] * acc[ai][bj][m][1];
;                     u32x4 w; w.x = cvt_pk_bf16(o0[0], o0[1]); w.y = cvt_pk_bf16(o0[2], o0[3]); w.z = cvt_pk_bf16(o1[0], o1[1]); w.w = cvt_pk_bf16(o1[2], o1[3]);
;                     *(u32x4*)(hrow + bj * HALF) = w;
;                     sq += ((o0[0] * o0[0] + o0[1] * o0[1]) + (o0[2] * o0[2] + o0[3] * o0[3])) + ((o1[0] * o1[0] + o1[1] * o1[1]) + (o1[2] * o1[2] + o1[3] * o1[3]));
;                     if (hb) { const f32x4 y0 = o0 * wv[bj][0], y1 = o1 * wv[bj][1]; u32x4 z; z.x = cvt_pk_bf16(y0[0], y0[1]); z.y = cvt_pk_bf16(y0[2], y0[3]); z.z = cvt_pk_bf16(y1[0], y1[1]); z.w = cvt_pk_bf16(y1[2], y1[3]);
;                         *(u32x4*)(hb + (size_t)rowt * DM + off + bj * HALF) = z; } }
;                 if (ssq) { sq += __shfl_xor(sq, 16); sq += __shfl_xor(sq, 32); if (fq == 0) ssq[(size_t)(rowt + rl) * 16 + u.pn * 4 + wc] = sq; } }
.LBB0_1454:
	v_lshl_add_u64 v[72:73], v[72:73], 1, v[228:229]
	s_waitcnt vmcnt(0)
	v_pk_fma_f32 v[62:63], v[46:47], v[66:67], v[62:63]
	v_pk_fma_f32 v[60:61], v[44:45], v[64:65], v[60:61]
	v_pk_fma_f32 v[58:59], v[42:43], v[70:71], v[58:59]
	s_waitcnt lgkmcnt(0)
	v_pk_fma_f32 v[78:79], v[40:41], v[68:69], v[56:57]
	v_cvt_pk_bf16_f32 v40, v60, v61
	v_cvt_pk_bf16_f32 v41, v62, v63
	v_lshl_add_u64 v[56:57], v[76:77], 1, s[74:75]
	v_cvt_pk_bf16_f32 v42, v78, v79
	v_cvt_pk_bf16_f32 v43, v58, v59
	global_store_dwordx4 v[72:73], v[40:43], off sc1
	s_and_b64 vcc, exec, s[44:45]
	v_pk_mul_f32 v[44:45], v[194:195], v[58:59]
	v_pk_mul_f32 v[42:43], v[186:187], v[62:63]
	v_pk_mul_f32 v[40:41], v[184:185], v[60:61]
	v_pk_mul_f32 v[46:47], v[192:193], v[78:79]
	v_cvt_pk_bf16_f32 v40, v40, v41
	v_cvt_pk_bf16_f32 v41, v42, v43
	s_nop 0
	v_cvt_pk_bf16_f32 v42, v46, v47
	v_cvt_pk_bf16_f32 v43, v44, v45
	global_store_dwordx4 v[56:57], v[40:43], off sc1
	s_cbranch_vccnz .LBB0_1489
	global_load_dwordx4 v[40:43], v[74:75], off offset:528
	global_load_dwordx4 v[44:47], v[74:75], off offset:512
	s_cbranch_execnz .LBB0_1457

; __device__ __forceinline__ unsigned cvt_pk_bf16(float lo, float hi) { unsigned r; asm volatile("v_cvt_pk_bf16_f32 %0, %1, %2" : "=v"(r) : "v"(lo), "v"(hi)); return r; }
;     __device__ __forceinline__ void operator()(const f32x4 (&acc)[2][2][4][2], const Unit& u, int wr, int wc, int fr, int fq) const {
;     ...
;             for (int m = 0; m < 4; ++m) { const int rl = wr * 64 + fr + ai * HALF + m * 16; const size_t off = (size_t)rl * DM + col0; float sq = 0.f;
;                 bf16_t* hrow = h16 + (size_t)rowt * DM + off;
; #pragma unroll
;                 for (int bj = 0; bj < 2; ++bj) { f32x4 b0, b1;
;                     if (bb) { b0 = *(const f32x4*)(bb + off + bj * HALF); b1 = *(const f32x4*)(bb + off + bj * HALF + 4); }
;                     else { const u32x4 r = raw[m][bj];
;                         b0 = (f32x4){__uint_as_float(r.x << 16), __uint_as_float(r.x & 0xffff0000u), __uint_as_float(r.y << 16), __uint_as_float(r.y & 0xffff0000u)};
;                         b1 = (f32x4){__uint_as_float(r.z << 16), __uint_as_float(r.z & 0xffff0000u), __uint_as_float(r.w << 16), __uint_as_float(r.w & 0xffff0000u)}; }
;                     const f32x4 o0 = b0 + gv[bj][0] * acc[ai][bj][m][0], o1 = b1 + gv[bj][1] * acc[ai][bj][m][1];
;                     u32x4 w; w.x = cvt_pk_bf16(o0[0], o0[1]); w.y = cvt_pk_bf16(o0[2], o0[3]); w.z = cvt_pk_bf16(o1[0], o1[1]); w.w = cvt_pk_bf16(o1[2], o1[3]);
;                     *(u32x4*)(hrow + bj * HALF) = w;
;                     sq += ((o0[0] * o0[0] + o0[1] * o0[1]) + (o0[2] * o0[2] + o0[3] * o0[3])) + ((o1[0] * o1[0] + o1[1] * o1[1]) + (o1[2] * o1[2] + o1[3] * o1[3]));
;                     if (hb) { const f32x4 y0 = o0 * wv[bj][0], y1 = o1 * wv[bj][1]; u32x4 z; z.x = cvt_pk_bf16(y0[0], y0[1]); z.y = cvt_pk_bf16(y0[2], y0[3]); z.z = cvt_pk_bf16(y1[0], y1[1]); z.w = cvt_pk_bf16(y1[2], y1[3]);
;                         *(u32x4*)(hb + (size_t)rowt * DM + off + bj * HALF) = z; } }
;                 if (ssq) { sq += __shfl_xor(sq, 16); sq += __shfl_xor(sq, 32); if (fq == 0) ssq[(size_t)(rowt + rl) * 16 + u.pn * 4 + wc] = sq; } }
.LBB0_1457:
	v_mul_f32_e32 v61, v61, v61
	s_waitcnt vmcnt(0)
	v_pk_fma_f32 v[38:39], v[38:39], v[50:51], v[46:47]
	v_pk_fma_f32 v[36:37], v[36:37], v[48:49], v[44:45]
	v_pk_fma_f32 v[40:41], v[32:33], v[52:53], v[40:41]
	v_cvt_pk_bf16_f32 v32, v36, v37
	v_cvt_pk_bf16_f32 v33, v38, v39
	v_fmac_f32_e32 v61, v60, v60
	v_mul_f32_e32 v60, v63, v63
	v_pk_fma_f32 v[42:43], v[34:35], v[54:55], v[42:43]
	v_cvt_pk_bf16_f32 v34, v40, v41
	v_fmac_f32_e32 v60, v62, v62
	v_cvt_pk_bf16_f32 v35, v42, v43
	global_store_dwordx4 v[72:73], v[32:35], off offset:256 sc1
	v_add_f32_e32 v60, v61, v60
	v_mul_f32_e32 v61, v79, v79
	v_mul_f32_e32 v32, v37, v37
	v_mul_f32_e32 v33, v39, v39
	v_fmac_f32_e32 v32, v36, v36
	v_fmac_f32_e32 v33, v38, v38
	v_mul_f32_e32 v59, v59, v59
	v_add_f32_e32 v32, v32, v33
	v_mul_f32_e32 v33, v41, v41
	v_mul_f32_e32 v34, v43, v43
	v_fmac_f32_e32 v61, v78, v78
	v_fmac_f32_e32 v59, v58, v58
	v_fmac_f32_e32 v33, v40, v40
	v_fmac_f32_e32 v34, v42, v42
	v_add_f32_e32 v58, v61, v59
	v_add_f32_e32 v33, v33, v34
	v_add_f32_e32 v58, v60, v58
	v_add_f32_e32 v32, v32, v33
	v_add_f32_e32 v35, v58, v32
	ds_bpermute_b32 v44, v172, v35
	v_pk_mul_f32 v[32:33], v[168:169], v[36:37]
	v_pk_mul_f32 v[36:37], v[176:177], v[40:41]
	v_cvt_pk_bf16_f32 v34, v32, v33
	v_pk_mul_f32 v[38:39], v[170:171], v[38:39]
	s_waitcnt lgkmcnt(0)
	v_add_f32_e32 v32, v35, v44
	ds_bpermute_b32 v33, v173, v32
	v_pk_mul_f32 v[42:43], v[178:179], v[42:43]
	v_cvt_pk_bf16_f32 v35, v38, v39
	v_cvt_pk_bf16_f32 v36, v36, v37
	s_nop 0
	v_cvt_pk_bf16_f32 v37, v42, v43
	global_store_dwordx4 v[56:57], v[34:37], off offset:256 sc1
	s_and_saveexec_b64 s[76:77], s[42:43]
	s_cbranch_execz .LBB0_1459
	s_waitcnt lgkmcnt(0)
	v_add_f32_e32 v34, v32, v33
	v_add_u32_e32 v32, s70, v120
	v_ashrrev_i32_e32 v33, 31, v32
	s_lshl_b32 s52, s18, 2
	v_lshlrev_b64 v[32:33], 6, v[32:33]
	s_ashr_i32 s53, s52, 31
	v_lshl_add_u64 v[32:33], s[46:47], 0, v[32:33]
	v_lshl_add_u64 v[32:33], s[52:53], 2, v[32:33]
	s_lshl_b32 s8, s38, 2
	v_lshl_add_u64 v[32:33], v[32:33], 0, s[8:9]
	global_store_dword v[32:33], v34, off

; __device__ __forceinline__ unsigned cvt_pk_bf16(float lo, float hi) { unsigned r; asm volatile("v_cvt_pk_bf16_f32 %0, %1, %2" : "=v"(r) : "v"(lo), "v"(hi)); return r; }
;     __device__ __forceinline__ void operator()(const f32x4 (&acc)[2][2][4][2], const Unit& u, int wr, int wc, int fr, int fq) const {
;     ...
;             for (int m = 0; m < 4; ++m) { const int rl = wr * 64 + fr + ai * HALF + m * 16; const size_t off = (size_t)rl * DM + col0; float sq = 0.f;
;                 bf16_t* hrow = h16 + (size_t)rowt * DM + off;
; #pragma unroll
;                 for (int bj = 0; bj < 2; ++bj) { f32x4 b0, b1;
;                     if (bb) { b0 = *(const f32x4*)(bb + off + bj * HALF); b1 = *(const f32x4*)(bb + off + bj * HALF + 4); }
;                     else { const u32x4 r = raw[m][bj];
;                         b0 = (f32x4){__uint_as_float(r.x << 16), __uint_as_float(r.x & 0xffff0000u), __uint_as_float(r.y << 16), __uint_as_float(r.y & 0xffff0000u)};
;                         b1 = (f32x4){__uint_as_float(r.z << 16), __uint_as_float(r.z & 0xffff0000u), __uint_as_float(r.w << 16), __uint_as_float(r.w & 0xffff0000u)}; }
;                     const f32x4 o0 = b0 + gv[bj][0] * acc[ai][bj][m][0], o1 = b1 + gv[bj][1] * acc[ai][bj][m][1];
;                     u32x4 w; w.x = cvt_pk_bf16(o0[0], o0[1]); w.y = cvt_pk_bf16(o0[2], o0[3]); w.z = cvt_pk_bf16(o1[0], o1[1]); w.w = cvt_pk_bf16(o1[2], o1[3]);
;                     *(u32x4*)(hrow + bj * HALF) = w;
;                     sq += ((o0[0] * o0[0] + o0[1] * o0[1]) + (o0[2] * o0[2] + o0[3] * o0[3])) + ((o1[0] * o1[0] + o1[1] * o1[1]) + (o1[2] * o1[2] + o1[3] * o1[3]));
;                     if (hb) { const f32x4 y0 = o0 * wv[bj][0], y1 = o1 * wv[bj][1]; u32x4 z; z.x = cvt_pk_bf16(y0[0], y0[1]); z.y = cvt_pk_bf16(y0[2], y0[3]); z.z = cvt_pk_bf16(y1[0], y1[1]); z.w = cvt_pk_bf16(y1[2], y1[3]);
;                         *(u32x4*)(hb + (size_t)rowt * DM + off + bj * HALF) = z; } }
;                 if (ssq) { sq += __shfl_xor(sq, 16); sq += __shfl_xor(sq, 32); if (fq == 0) ssq[(size_t)(rowt + rl) * 16 + u.pn * 4 + wc] = sq; } }
.LBB0_1462:
	v_lshl_add_u64 v[40:41], v[40:41], 1, v[228:229]
	s_waitcnt vmcnt(0)
	v_pk_fma_f32 v[38:39], v[30:31], v[66:67], v[38:39]
	v_pk_fma_f32 v[36:37], v[28:29], v[64:65], v[36:37]
	v_pk_fma_f32 v[34:35], v[26:27], v[70:71], v[34:35]
	s_waitcnt lgkmcnt(0)
	v_pk_fma_f32 v[46:47], v[24:25], v[68:69], v[32:33]
	v_cvt_pk_bf16_f32 v24, v36, v37
	v_cvt_pk_bf16_f32 v25, v38, v39
	v_lshl_add_u64 v[32:33], v[44:45], 1, s[74:75]
	v_cvt_pk_bf16_f32 v26, v46, v47
	v_cvt_pk_bf16_f32 v27, v34, v35
	global_store_dwordx4 v[40:41], v[24:27], off sc1
	s_and_b64 vcc, exec, s[44:45]
	v_pk_mul_f32 v[28:29], v[194:195], v[34:35]
	v_pk_mul_f32 v[26:27], v[186:187], v[38:39]
	v_pk_mul_f32 v[24:25], v[184:185], v[36:37]
	v_pk_mul_f32 v[30:31], v[192:193], v[46:47]
	v_cvt_pk_bf16_f32 v24, v24, v25
	v_cvt_pk_bf16_f32 v25, v26, v27
	s_nop 0
	v_cvt_pk_bf16_f32 v26, v30, v31
	v_cvt_pk_bf16_f32 v27, v28, v29
	global_store_dwordx4 v[32:33], v[24:27], off sc1
	s_cbranch_vccnz .LBB0_1491
	global_load_dwordx4 v[24:27], v[42:43], off offset:528
	global_load_dwordx4 v[28:31], v[42:43], off offset:512
	s_cbranch_execnz .LBB0_1465

; __device__ __forceinline__ unsigned cvt_pk_bf16(float lo, float hi) { unsigned r; asm volatile("v_cvt_pk_bf16_f32 %0, %1, %2" : "=v"(r) : "v"(lo), "v"(hi)); return r; }
;     __device__ __forceinline__ void operator()(const f32x4 (&acc)[2][2][4][2], const Unit& u, int wr, int wc, int fr, int fq) const {
;     ...
;             for (int m = 0; m < 4; ++m) { const int rl = wr * 64 + fr + ai * HALF + m * 16; const size_t off = (size_t)rl * DM + col0; float sq = 0.f;
;                 bf16_t* hrow = h16 + (size_t)rowt * DM + off;
; #pragma unroll
;                 for (int bj = 0; bj < 2; ++bj) { f32x4 b0, b1;
;                     if (bb) { b0 = *(const f32x4*)(bb + off + bj * HALF); b1 = *(const f32x4*)(bb + off + bj * HALF + 4); }
;                     else { const u32x4 r = raw[m][bj];
;                         b0 = (f32x4){__uint_as_float(r.x << 16), __uint_as_float(r.x & 0xffff0000u), __uint_as_float(r.y << 16), __uint_as_float(r.y & 0xffff0000u)};
;                         b1 = (f32x4){__uint_as_float(r.z << 16), __uint_as_float(r.z & 0xffff0000u), __uint_as_float(r.w << 16), __uint_as_float(r.w & 0xffff0000u)}; }
;                     const f32x4 o0 = b0 + gv[bj][0] * acc[ai][bj][m][0], o1 = b1 + gv[bj][1] * acc[ai][bj][m][1];
;                     u32x4 w; w.x = cvt_pk_bf16(o0[0], o0[1]); w.y = cvt_pk_bf16(o0[2], o0[3]); w.z = cvt_pk_bf16(o1[0], o1[1]); w.w = cvt_pk_bf16(o1[2], o1[3]);
;                     *(u32x4*)(hrow + bj * HALF) = w;
;                     sq += ((o0[0] * o0[0] + o0[1] * o0[1]) + (o0[2] * o0[2] + o0[3] * o0[3])) + ((o1[0] * o1[0] + o1[1] * o1[1]) + (o1[2] * o1[2] + o1[3] * o1[3]));
;                     if (hb) { const f32x4 y0 = o0 * wv[bj][0], y1 = o1 * wv[bj][1]; u32x4 z; z.x = cvt_pk_bf16(y0[0], y0[1]); z.y = cvt_pk_bf16(y0[2], y0[3]); z.z = cvt_pk_bf16(y1[0], y1[1]); z.w = cvt_pk_bf16(y1[2], y1[3]);
;                         *(u32x4*)(hb + (size_t)rowt * DM + off + bj * HALF) = z; } }
;                 if (ssq) { sq += __shfl_xor(sq, 16); sq += __shfl_xor(sq, 32); if (fq == 0) ssq[(size_t)(rowt + rl) * 16 + u.pn * 4 + wc] = sq; } }
.LBB0_1465:
	v_mul_f32_e32 v37, v37, v37
	s_waitcnt vmcnt(0)
	v_pk_fma_f32 v[22:23], v[22:23], v[50:51], v[30:31]
	v_pk_fma_f32 v[20:21], v[20:21], v[48:49], v[28:29]
	v_pk_fma_f32 v[24:25], v[16:17], v[52:53], v[24:25]
	v_cvt_pk_bf16_f32 v16, v20, v21
	v_cvt_pk_bf16_f32 v17, v22, v23
	v_fmac_f32_e32 v37, v36, v36
	v_mul_f32_e32 v36, v39, v39
	v_pk_fma_f32 v[26:27], v[18:19], v[54:55], v[26:27]
	v_cvt_pk_bf16_f32 v18, v24, v25
	v_fmac_f32_e32 v36, v38, v38
	v_cvt_pk_bf16_f32 v19, v26, v27
	global_store_dwordx4 v[40:41], v[16:19], off offset:256 sc1
	v_add_f32_e32 v36, v37, v36
	v_mul_f32_e32 v37, v47, v47
	v_mul_f32_e32 v16, v21, v21
	v_mul_f32_e32 v17, v23, v23
	v_fmac_f32_e32 v16, v20, v20
	v_fmac_f32_e32 v17, v22, v22
	v_mul_f32_e32 v35, v35, v35
	v_add_f32_e32 v16, v16, v17
	v_mul_f32_e32 v17, v25, v25
	v_mul_f32_e32 v18, v27, v27
	v_fmac_f32_e32 v37, v46, v46
	v_fmac_f32_e32 v35, v34, v34
	v_fmac_f32_e32 v17, v24, v24
	v_fmac_f32_e32 v18, v26, v26
	v_add_f32_e32 v34, v37, v35
	v_add_f32_e32 v17, v17, v18
	v_add_f32_e32 v34, v36, v34
	v_add_f32_e32 v16, v16, v17
	v_add_f32_e32 v19, v34, v16
	ds_bpermute_b32 v28, v172, v19
	v_pk_mul_f32 v[16:17], v[168:169], v[20:21]
	v_pk_mul_f32 v[20:21], v[176:177], v[24:25]
	v_cvt_pk_bf16_f32 v18, v16, v17
	v_pk_mul_f32 v[22:23], v[170:171], v[22:23]
	s_waitcnt lgkmcnt(0)
	v_add_f32_e32 v16, v19, v28
	ds_bpermute_b32 v17, v173, v16
	v_pk_mul_f32 v[26:27], v[178:179], v[26:27]
	v_cvt_pk_bf16_f32 v19, v22, v23
	v_cvt_pk_bf16_f32 v20, v20, v21
	s_nop 0
	v_cvt_pk_bf16_f32 v21, v26, v27
	global_store_dwordx4 v[32:33], v[18:21], off offset:256 sc1
	s_and_saveexec_b64 s[76:77], s[42:43]
	s_cbranch_execz .LBB0_1467
	s_waitcnt lgkmcnt(0)
	v_add_f32_e32 v18, v16, v17
	v_add_u32_e32 v16, s70, v118
	v_ashrrev_i32_e32 v17, 31, v16
	s_lshl_b32 s52, s18, 2
	v_lshlrev_b64 v[16:17], 6, v[16:17]
	s_ashr_i32 s53, s52, 31
	v_lshl_add_u64 v[16:17], s[46:47], 0, v[16:17]
	v_lshl_add_u64 v[16:17], s[52:53], 2, v[16:17]
	s_lshl_b32 s8, s38, 2
	v_lshl_add_u64 v[16:17], v[16:17], 0, s[8:9]
	global_store_dword v[16:17], v18, off

; __device__ __forceinline__ unsigned cvt_pk_bf16(float lo, float hi) { unsigned r; asm volatile("v_cvt_pk_bf16_f32 %0, %1, %2" : "=v"(r) : "v"(lo), "v"(hi)); return r; }
;     __device__ __forceinline__ void operator()(const f32x4 (&acc)[2][2][4][2], const Unit& u, int wr, int wc, int fr, int fq) const {
;     ...
;             for (int m = 0; m < 4; ++m) { const int rl = wr * 64 + fr + ai * HALF + m * 16; const size_t off = (size_t)rl * DM + col0; float sq = 0.f;
;                 bf16_t* hrow = h16 + (size_t)rowt * DM + off;
; #pragma unroll
;                 for (int bj = 0; bj < 2; ++bj) { f32x4 b0, b1;
;                     if (bb) { b0 = *(const f32x4*)(bb + off + bj * HALF); b1 = *(const f32x4*)(bb + off + bj * HALF + 4); }
;                     else { const u32x4 r = raw[m][bj];
;                         b0 = (f32x4){__uint_as_float(r.x << 16), __uint_as_float(r.x & 0xffff0000u), __uint_as_float(r.y << 16), __uint_as_float(r.y & 0xffff0000u)};
;                         b1 = (f32x4){__uint_as_float(r.z << 16), __uint_as_float(r.z & 0xffff0000u), __uint_as_float(r.w << 16), __uint_as_float(r.w & 0xffff0000u)}; }
;                     const f32x4 o0 = b0 + gv[bj][0] * acc[ai][bj][m][0], o1 = b1 + gv[bj][1] * acc[ai][bj][m][1];
;                     u32x4 w; w.x = cvt_pk_bf16(o0[0], o0[1]); w.y = cvt_pk_bf16(o0[2], o0[3]); w.z = cvt_pk_bf16(o1[0], o1[1]); w.w = cvt_pk_bf16(o1[2], o1[3]);
;                     *(u32x4*)(hrow + bj * HALF) = w;
;                     sq += ((o0[0] * o0[0] + o0[1] * o0[1]) + (o0[2] * o0[2] + o0[3] * o0[3])) + ((o1[0] * o1[0] + o1[1] * o1[1]) + (o1[2] * o1[2] + o1[3] * o1[3]));
;                     if (hb) { const f32x4 y0 = o0 * wv[bj][0], y1 = o1 * wv[bj][1]; u32x4 z; z.x = cvt_pk_bf16(y0[0], y0[1]); z.y = cvt_pk_bf16(y0[2], y0[3]); z.z = cvt_pk_bf16(y1[0], y1[1]); z.w = cvt_pk_bf16(y1[2], y1[3]);
;                         *(u32x4*)(hb + (size_t)rowt * DM + off + bj * HALF) = z; } }
;                 if (ssq) { sq += __shfl_xor(sq, 16); sq += __shfl_xor(sq, 32); if (fq == 0) ssq[(size_t)(rowt + rl) * 16 + u.pn * 4 + wc] = sq; } }
.LBB0_1470:
	v_lshl_add_u64 v[24:25], v[24:25], 1, v[228:229]
	s_waitcnt vmcnt(0)
	v_pk_fma_f32 v[22:23], v[14:15], v[66:67], v[22:23]
	v_pk_fma_f32 v[20:21], v[12:13], v[64:65], v[20:21]
	v_pk_fma_f32 v[18:19], v[10:11], v[70:71], v[18:19]
	s_waitcnt lgkmcnt(0)
	v_pk_fma_f32 v[30:31], v[8:9], v[68:69], v[16:17]
	v_cvt_pk_bf16_f32 v8, v20, v21
	v_cvt_pk_bf16_f32 v9, v22, v23
	v_lshl_add_u64 v[16:17], v[28:29], 1, s[74:75]
	v_cvt_pk_bf16_f32 v10, v30, v31
	v_cvt_pk_bf16_f32 v11, v18, v19
	global_store_dwordx4 v[24:25], v[8:11], off sc1
	s_and_b64 vcc, exec, s[44:45]
	v_pk_mul_f32 v[12:13], v[194:195], v[18:19]
	v_pk_mul_f32 v[10:11], v[186:187], v[22:23]
	v_pk_mul_f32 v[8:9], v[184:185], v[20:21]
	v_pk_mul_f32 v[14:15], v[192:193], v[30:31]
	v_cvt_pk_bf16_f32 v8, v8, v9
	v_cvt_pk_bf16_f32 v9, v10, v11
	s_nop 0
	v_cvt_pk_bf16_f32 v10, v14, v15
	v_cvt_pk_bf16_f32 v11, v12, v13
	global_store_dwordx4 v[16:17], v[8:11], off sc1
	s_cbranch_vccnz .LBB0_1493
	global_load_dwordx4 v[8:11], v[26:27], off offset:528
	global_load_dwordx4 v[12:15], v[26:27], off offset:512
	s_movk_i32 s75, 0x4000
	s_cbranch_execnz .LBB0_1473

; __device__ __forceinline__ unsigned cvt_pk_bf16(float lo, float hi) { unsigned r; asm volatile("v_cvt_pk_bf16_f32 %0, %1, %2" : "=v"(r) : "v"(lo), "v"(hi)); return r; }
;     __device__ __forceinline__ void operator()(const f32x4 (&acc)[2][2][4][2], const Unit& u, int wr, int wc, int fr, int fq) const {
;     ...
;             for (int m = 0; m < 4; ++m) { const int rl = wr * 64 + fr + ai * HALF + m * 16; const size_t off = (size_t)rl * DM + col0; float sq = 0.f;
;                 bf16_t* hrow = h16 + (size_t)rowt * DM + off;
; #pragma unroll
;                 for (int bj = 0; bj < 2; ++bj) { f32x4 b0, b1;
;                     if (bb) { b0 = *(const f32x4*)(bb + off + bj * HALF); b1 = *(const f32x4*)(bb + off + bj * HALF + 4); }
;                     else { const u32x4 r = raw[m][bj];
;                         b0 = (f32x4){__uint_as_float(r.x << 16), __uint_as_float(r.x & 0xffff0000u), __uint_as_float(r.y << 16), __uint_as_float(r.y & 0xffff0000u)};
;                         b1 = (f32x4){__uint_as_float(r.z << 16), __uint_as_float(r.z & 0xffff0000u), __uint_as_float(r.w << 16), __uint_as_float(r.w & 0xffff0000u)}; }
;                     const f32x4 o0 = b0 + gv[bj][0] * acc[ai][bj][m][0], o1 = b1 + gv[bj][1] * acc[ai][bj][m][1];
;                     u32x4 w; w.x = cvt_pk_bf16(o0[0], o0[1]); w.y = cvt_pk_bf16(o0[2], o0[3]); w.z = cvt_pk_bf16(o1[0], o1[1]); w.w = cvt_pk_bf16(o1[2], o1[3]);
;                     *(u32x4*)(hrow + bj * HALF) = w;
;                     sq += ((o0[0] * o0[0] + o0[1] * o0[1]) + (o0[2] * o0[2] + o0[3] * o0[3])) + ((o1[0] * o1[0] + o1[1] * o1[1]) + (o1[2] * o1[2] + o1[3] * o1[3]));
;                     if (hb) { const f32x4 y0 = o0 * wv[bj][0], y1 = o1 * wv[bj][1]; u32x4 z; z.x = cvt_pk_bf16(y0[0], y0[1]); z.y = cvt_pk_bf16(y0[2], y0[3]); z.z = cvt_pk_bf16(y1[0], y1[1]); z.w = cvt_pk_bf16(y1[2], y1[3]);
;                         *(u32x4*)(hb + (size_t)rowt * DM + off + bj * HALF) = z; } }
;                 if (ssq) { sq += __shfl_xor(sq, 16); sq += __shfl_xor(sq, 32); if (fq == 0) ssq[(size_t)(rowt + rl) * 16 + u.pn * 4 + wc] = sq; } }
.LBB0_1473:
	v_mul_f32_e32 v21, v21, v21
	s_waitcnt vmcnt(0)
	v_pk_fma_f32 v[6:7], v[6:7], v[50:51], v[14:15]
	v_pk_fma_f32 v[4:5], v[4:5], v[48:49], v[12:13]
	v_pk_fma_f32 v[8:9], v[0:1], v[52:53], v[8:9]
	v_cvt_pk_bf16_f32 v0, v4, v5
	v_cvt_pk_bf16_f32 v1, v6, v7
	v_fmac_f32_e32 v21, v20, v20
	v_mul_f32_e32 v20, v23, v23
	v_pk_fma_f32 v[10:11], v[2:3], v[54:55], v[10:11]
	v_cvt_pk_bf16_f32 v2, v8, v9
	v_fmac_f32_e32 v20, v22, v22
	v_cvt_pk_bf16_f32 v3, v10, v11
	global_store_dwordx4 v[24:25], v[0:3], off offset:256 sc1
	v_add_f32_e32 v20, v21, v20
	v_mul_f32_e32 v21, v31, v31
	v_mul_f32_e32 v0, v5, v5
	v_mul_f32_e32 v1, v7, v7
	v_fmac_f32_e32 v0, v4, v4
	v_fmac_f32_e32 v1, v6, v6
	v_mul_f32_e32 v19, v19, v19
	v_add_f32_e32 v0, v0, v1
	v_mul_f32_e32 v1, v9, v9
	v_mul_f32_e32 v2, v11, v11
	v_fmac_f32_e32 v21, v30, v30
	v_fmac_f32_e32 v19, v18, v18
	v_fmac_f32_e32 v1, v8, v8
	v_fmac_f32_e32 v2, v10, v10
	v_add_f32_e32 v18, v21, v19
	v_add_f32_e32 v1, v1, v2
	v_add_f32_e32 v18, v20, v18
	v_add_f32_e32 v0, v0, v1
	v_add_f32_e32 v3, v18, v0
	ds_bpermute_b32 v12, v172, v3
	v_pk_mul_f32 v[0:1], v[168:169], v[4:5]
	v_pk_mul_f32 v[4:5], v[176:177], v[8:9]
	v_cvt_pk_bf16_f32 v2, v0, v1
	v_pk_mul_f32 v[6:7], v[170:171], v[6:7]
	s_waitcnt lgkmcnt(0)
	v_add_f32_e32 v0, v3, v12
	ds_bpermute_b32 v1, v173, v0
	v_pk_mul_f32 v[10:11], v[178:179], v[10:11]
	v_cvt_pk_bf16_f32 v3, v6, v7
	v_cvt_pk_bf16_f32 v4, v4, v5
	s_nop 0
	v_cvt_pk_bf16_f32 v5, v10, v11
	global_store_dwordx4 v[16:17], v[2:5], off offset:256 sc1
	s_and_saveexec_b64 s[44:45], s[42:43]
	s_cbranch_execz .LBB0_1475
	s_waitcnt lgkmcnt(0)
	v_add_f32_e32 v2, v0, v1
	v_add_u32_e32 v0, s70, v116
	v_ashrrev_i32_e32 v1, 31, v0
	s_lshl_b32 s18, s18, 2
	v_lshlrev_b64 v[0:1], 6, v[0:1]
	s_ashr_i32 s19, s18, 31
	v_lshl_add_u64 v[0:1], s[46:47], 0, v[0:1]
	v_lshl_add_u64 v[0:1], s[18:19], 2, v[0:1]
	s_lshl_b32 s8, s38, 2
	v_lshl_add_u64 v[0:1], v[0:1], 0, s[8:9]
	global_store_dword v[0:1], v2, off

;     __device__ __forceinline__ void operator()(const f32x4 (&acc)[2][2][4][2], const Unit& u, int wr, int wc, int fr, int fq) const {
;         const int rowt = u.pm * BM, b = rowt >= MLAT ? 2 : (rowt >> 13);
;         const int row0 = rowt + wr * 64 + fr, col0 = u.pn * BM + wc * 32 + 8 * fq;
;         f32x4 bv[2][2];
; #pragma unroll
;         for (int bj = 0; bj < 2; ++bj)
; #pragma unroll
;             for (int n = 0; n < 2; ++n) bv[bj][n] = *(const f32x4*)(bias + (size_t)b * nbias + col0 + bj * HALF + 4 * n);
;         float rsv[2][4];
;         { f32x4 pq[2][4];
; #pragma unroll
;           for (int ai = 0; ai < 2; ++ai)
; #pragma unroll
;               for (int m = 0; m < 4; ++m) pq[ai][m] = *(const f32x4*)(ssq + (size_t)(row0 + ai * HALF + m * 16) * 16 + 4 * fq);
; #pragma unroll
;           for (int ai = 0; ai < 2; ++ai)
; #pragma unroll
;               for (int m = 0; m < 4; ++m) { float t = (pq[ai][m][0] + pq[ai][m][1]) + (pq[ai][m][2] + pq[ai][m][3]); t += __shfl_xor(t, 16); t += __shfl_xor(t, 32);
;                   rsv[ai][m] = rsqrtf(t * (1.f / DM) + EPS); } }
.LBB0_1696:
	s_min_i32 s16, s40, 64
	s_ashr_i32 s44, s16, 5
	s_ashr_i32 s45, s44, 31
	s_lshl_b64 s[44:45], s[44:45], 14
	v_lshl_add_u32 v196, s40, 8, v201
	v_lshl_or_b32 v192, s41, 8, v205
	s_add_u32 s44, s63, s44
	v_ashrrev_i32_e32 v197, 31, v196
	s_addc_u32 s45, s64, s45
	v_ashrrev_i32_e32 v193, 31, v192
	v_lshlrev_b64 v[144:145], 6, v[196:197]
	v_or_b32_e32 v194, 16, v196
	v_lshl_add_u64 v[132:133], v[192:193], 2, s[44:45]
	v_lshl_add_u64 v[144:145], v[174:175], 0, v[144:145]
	v_ashrrev_i32_e32 v195, 31, v194
	global_load_dwordx4 v[136:139], v[132:133], off offset:16
	global_load_dwordx4 v[140:143], v[132:133], off
	global_load_dwordx4 v[128:131], v[132:133], off offset:528
	s_nop 0
	global_load_dwordx4 v[132:135], v[132:133], off offset:512
	v_or_b32_e32 v190, 32, v196
	global_load_dwordx4 v[216:219], v[144:145], off
	v_lshlrev_b64 v[144:145], 6, v[194:195]
	v_lshl_add_u64 v[144:145], v[174:175], 0, v[144:145]
	global_load_dwordx4 v[220:223], v[144:145], off
	v_ashrrev_i32_e32 v191, 31, v190
	v_lshlrev_b64 v[144:145], 6, v[190:191]
	v_or_b32_e32 v188, 48, v196
	v_lshl_add_u64 v[144:145], v[174:175], 0, v[144:145]
	v_ashrrev_i32_e32 v189, 31, v188
	global_load_dwordx4 v[164:167], v[144:145], off
	v_lshlrev_b64 v[144:145], 6, v[188:189]
	v_lshl_add_u64 v[144:145], v[174:175], 0, v[144:145]
	global_load_dwordx4 v[160:163], v[144:145], off
	v_add_u32_e32 v186, 0x80, v196
	v_ashrrev_i32_e32 v187, 31, v186
	v_lshlrev_b64 v[144:145], 6, v[186:187]
	v_add_u32_e32 v184, 0x90, v196
	v_lshl_add_u64 v[144:145], v[174:175], 0, v[144:145]
	v_ashrrev_i32_e32 v185, 31, v184
	global_load_dwordx4 v[156:159], v[144:145], off
	v_lshlrev_b64 v[144:145], 6, v[184:185]
	v_lshl_add_u64 v[144:145], v[174:175], 0, v[144:145]
	global_load_dwordx4 v[152:155], v[144:145], off
	v_add_u32_e32 v182, 0xa0, v196
	v_ashrrev_i32_e32 v183, 31, v182
	v_lshlrev_b64 v[144:145], 6, v[182:183]
	v_add_u32_e32 v180, 0xb0, v196
	v_lshl_add_u64 v[144:145], v[174:175], 0, v[144:145]
	v_ashrrev_i32_e32 v181, 31, v180
	global_load_dwordx4 v[148:151], v[144:145], off
	v_lshlrev_b64 v[144:145], 6, v[180:181]
	v_lshl_add_u64 v[144:145], v[174:175], 0, v[144:145]
	global_load_dwordx4 v[144:147], v[144:145], off
	v_and_b32_e32 v200, 64, v246
	v_xor_b32_e32 v198, 16, v246
	v_add_u32_e32 v200, 64, v200
	v_cmp_lt_i32_e32 vcc, v198, v200
	s_mov_b32 s16, 0x358637bd
	s_waitcnt vmcnt(0)
	v_mov_b32_e32 v202, v217
	v_mov_b32_e32 v203, v218
	v_mov_b32_e32 v217, v219
	v_mov_b32_e32 v210, v221
	v_mov_b32_e32 v211, v222
	v_mov_b32_e32 v221, v223
	v_pk_add_f32 v[202:203], v[202:203], v[216:217]
	v_pk_add_f32 v[210:211], v[210:211], v[220:221]
	v_cndmask_b32_e32 v198, v246, v198, vcc
	v_mov_b32_e32 v216, v210
	v_mov_b32_e32 v217, v202
	v_mov_b32_e32 v202, v211
	v_lshlrev_b32_e32 v208, 2, v198
	v_pk_add_f32 v[202:203], v[216:217], v[202:203]
	ds_bpermute_b32 v211, v208, v203
	ds_bpermute_b32 v210, v208, v202
	v_xor_b32_e32 v198, 32, v246
	v_cmp_lt_i32_e32 vcc, v198, v200
	s_waitcnt lgkmcnt(0)
	v_pk_add_f32 v[202:203], v[202:203], v[210:211]
	v_cndmask_b32_e32 v198, v246, v198, vcc
	v_lshlrev_b32_e32 v207, 2, v198
	ds_bpermute_b32 v211, v207, v203
	ds_bpermute_b32 v210, v207, v202
	s_waitcnt lgkmcnt(0)
	v_pk_add_f32 v[210:211], v[202:203], v[210:211]
	v_mov_b64_e32 v[202:203], s[16:17]
	s_mov_b32 s16, 0x3a800000
	v_pk_fma_f32 v[210:211], v[210:211], s[16:17], v[202:203] op_sel_hi:[1,0,0]
	s_nop 0
	v_mul_f32_e32 v198, 0x4b800000, v211
	v_cmp_gt_f32_e64 s[40:41], s27, v211
	v_cmp_gt_f32_e32 vcc, s27, v210
	s_nop 0
	v_cndmask_b32_e64 v198, v211, v198, s[40:41]
	v_rsq_f32_e32 v198, v198
	v_mov_b32_e32 v211, v166
	v_mov_b32_e32 v166, v161
	v_mov_b32_e32 v161, v163
	v_mul_f32_e32 v200, 0x45800000, v198
	v_cndmask_b32_e64 v200, v198, v200, s[40:41]
	v_mul_f32_e32 v198, 0x4b800000, v210
	v_cndmask_b32_e32 v198, v210, v198, vcc
	v_mov_b32_e32 v210, v165
	v_mov_b32_e32 v165, v167
	v_mov_b32_e32 v167, v162
	v_pk_add_f32 v[164:165], v[210:211], v[164:165]
	v_pk_add_f32 v[160:161], v[166:167], v[160:161]
	v_mov_b32_e32 v163, v164
	v_mov_b32_e32 v162, v160
	v_mov_b32_e32 v164, v161
	v_pk_add_f32 v[160:161], v[162:163], v[164:165]
	ds_bpermute_b32 v163, v208, v161
	ds_bpermute_b32 v162, v208, v160
	v_mov_b32_e32 v164, v157
	v_mov_b32_e32 v165, v158
	v_mov_b32_e32 v157, v159
	v_mov_b32_e32 v158, v153
	v_mov_b32_e32 v159, v154
	v_mov_b32_e32 v153, v155
	v_pk_add_f32 v[156:157], v[164:165], v[156:157]
	v_pk_add_f32 v[152:153], v[158:159], v[152:153]
	s_waitcnt lgkmcnt(0)
	v_pk_add_f32 v[160:161], v[160:161], v[162:163]
	v_mov_b32_e32 v154, v152
	v_mov_b32_e32 v155, v156
	v_mov_b32_e32 v156, v153
	ds_bpermute_b32 v163, v207, v161
	ds_bpermute_b32 v162, v207, v160
	v_pk_add_f32 v[152:153], v[154:155], v[156:157]
	ds_bpermute_b32 v155, v208, v153
	ds_bpermute_b32 v154, v208, v152
	v_mov_b32_e32 v156, v149
	v_mov_b32_e32 v157, v150
	v_mov_b32_e32 v149, v151
	v_mov_b32_e32 v150, v145
	v_mov_b32_e32 v151, v146
	v_mov_b32_e32 v145, v147
	s_waitcnt lgkmcnt(2)
	v_pk_add_f32 v[160:161], v[160:161], v[162:163]
	v_pk_add_f32 v[148:149], v[156:157], v[148:149]
	v_pk_add_f32 v[144:145], v[150:151], v[144:145]
	v_pk_fma_f32 v[160:161], v[160:161], s[16:17], v[202:203] op_sel_hi:[1,0,0]
	s_waitcnt lgkmcnt(0)
	v_pk_add_f32 v[152:153], v[152:153], v[154:155]
	v_mov_b32_e32 v146, v144
	v_mov_b32_e32 v147, v148
	v_mov_b32_e32 v148, v145
	v_mul_f32_e32 v162, 0x4b800000, v161
	v_cmp_gt_f32_e64 s[40:41], s27, v161
	ds_bpermute_b32 v155, v207, v153
	ds_bpermute_b32 v154, v207, v152
	v_pk_add_f32 v[144:145], v[146:147], v[148:149]
	v_cndmask_b32_e64 v161, v161, v162, s[40:41]
	ds_bpermute_b32 v147, v208, v145
	ds_bpermute_b32 v146, v208, v144
	v_rsq_f32_e32 v198, v198
	v_rsq_f32_e32 v161, v161
	s_waitcnt lgkmcnt(2)
; __device__ __forceinline__ unsigned cvt_pk_bf16(float lo, float hi) { unsigned r; asm volatile("v_cvt_pk_bf16_f32 %0, %1, %2" : "=v"(r) : "v"(lo), "v"(hi)); return r; }
;     __device__ __forceinline__ void operator()(const f32x4 (&acc)[2][2][4][2], const Unit& u, int wr, int wc, int fr, int fq) const {
;     ...
;         for (int ai = 0; ai < 2; ++ai)
; #pragma unroll
;             for (int m = 0; m < 4; ++m) { const int row = row0 + ai * HALF + m * 16; bf16_t* rowp = O + (size_t)row * ldc + col0; float s = 0.f, q = 0.f;
;                 const float rstd = rsv[ai][m];
; #pragma unroll
;                 for (int bj = 0; bj < 2; ++bj) { f32x4 v0 = acc[ai][bj][m][0] * rstd + bv[bj][0], v1 = acc[ai][bj][m][1] * rstd + bv[bj][1];
;                     if (ACT == 1) {
; #pragma unroll
;                         for (int e = 0; e < 4; ++e) { const float a = fmaxf(v0[e], 0.f), b2 = fmaxf(v1[e], 0.f); v0[e] = a * a; v1[e] = b2 * b2; } }
;                     if (ACT == 2) {
; #pragma unroll
;                         for (int e = 0; e < 4; ++e) { v0[e] = gelu_tanh(v0[e]); v1[e] = gelu_tanh(v1[e]); s += v0[e] + v1[e]; q += v0[e] * v0[e] + v1[e] * v1[e]; } }
;                     u32x4 w; w.x = cvt_pk_bf16(v0[0], v0[1]); w.y = cvt_pk_bf16(v0[2], v0[3]); w.z = cvt_pk_bf16(v1[0], v1[1]); w.w = cvt_pk_bf16(v1[2], v1[3]);
;                     *(u32x4*)(rowp + bj * HALF) = w; }
	v_pk_add_f32 v[152:153], v[152:153], v[154:155]
	v_pk_fma_f32 v[120:121], v[120:121], v[200:201], v[136:137] op_sel_hi:[1,0,1]
	v_mul_f32_e32 v209, 0x45800000, v198
	v_mul_f32_e32 v162, 0x45800000, v161
	v_pk_fma_f32 v[152:153], v[152:153], s[16:17], v[202:203] op_sel_hi:[1,0,0]
	s_waitcnt lgkmcnt(0)
	v_pk_add_f32 v[144:145], v[144:145], v[146:147]
	v_cndmask_b32_e32 v198, v198, v209, vcc
	v_cmp_gt_f32_e32 vcc, s27, v160
	v_cndmask_b32_e64 v162, v161, v162, s[40:41]
	v_mul_f32_e32 v161, 0x4b800000, v160
	v_mul_f32_e32 v154, 0x4b800000, v153
	v_cmp_gt_f32_e64 s[40:41], s27, v153
	ds_bpermute_b32 v147, v207, v145
	ds_bpermute_b32 v146, v207, v144
	v_cndmask_b32_e32 v160, v160, v161, vcc
	v_cndmask_b32_e64 v153, v153, v154, s[40:41]
	v_rsq_f32_e32 v160, v160
	v_rsq_f32_e32 v153, v153
	s_waitcnt lgkmcnt(0)
	v_pk_add_f32 v[144:145], v[144:145], v[146:147]
	v_pk_fma_f32 v[124:125], v[124:125], v[200:201], v[140:141] op_sel_hi:[1,0,1]
	v_mul_f32_e32 v161, 0x45800000, v160
	v_mul_f32_e32 v154, 0x45800000, v153
	v_pk_fma_f32 v[144:145], v[144:145], s[16:17], v[202:203] op_sel_hi:[1,0,0]
	v_cndmask_b32_e32 v160, v160, v161, vcc
	v_cmp_gt_f32_e32 vcc, s27, v152
	v_cndmask_b32_e64 v154, v153, v154, s[40:41]
	v_mul_f32_e32 v153, 0x4b800000, v152
	v_mul_f32_e32 v146, 0x4b800000, v145
	v_cmp_gt_f32_e64 s[40:41], s27, v145
	v_cndmask_b32_e32 v152, v152, v153, vcc
	v_rsq_f32_e32 v152, v152
	v_cndmask_b32_e64 v145, v145, v146, s[40:41]
	v_rsq_f32_e32 v145, v145
	v_pk_fma_f32 v[122:123], v[122:123], v[200:201], v[138:139] op_sel_hi:[1,0,1]
	v_mul_f32_e32 v153, 0x45800000, v152
	v_cndmask_b32_e32 v152, v152, v153, vcc
	v_mul_f32_e32 v146, 0x45800000, v145
	v_cmp_gt_f32_e32 vcc, s27, v144
	v_cndmask_b32_e64 v146, v145, v146, s[40:41]
	v_mul_f32_e32 v145, 0x4b800000, v144
	v_cndmask_b32_e32 v144, v144, v145, vcc
	v_rsq_f32_e32 v144, v144
	v_max_f32_e32 v120, 0, v120
	v_lshlrev_b64 v[148:149], 13, v[196:197]
	v_pk_fma_f32 v[126:127], v[126:127], v[200:201], v[142:143] op_sel_hi:[1,0,1]
	v_mul_f32_e32 v145, 0x45800000, v144
	v_cndmask_b32_e32 v144, v144, v145, vcc
	v_mul_f32_e32 v145, v120, v120
	v_max_f32_e32 v120, 0, v125
	v_max_f32_e32 v121, 0, v121
	v_max_f32_e32 v122, 0, v122
	v_lshl_add_u64 v[150:151], s[14:15], 0, v[148:149]
	v_lshlrev_b64 v[148:149], 1, v[192:193]
	v_max_f32_e32 v124, 0, v124
	v_mul_f32_e32 v120, v120, v120
	v_mul_f32_e32 v125, v121, v121
	v_max_f32_e32 v121, 0, v126
	v_mul_f32_e32 v126, v122, v122
	v_max_f32_e32 v122, 0, v127
	v_max_f32_e32 v123, 0, v123
	v_pk_fma_f32 v[114:115], v[114:115], v[200:201], v[130:131] op_sel_hi:[1,0,1]
	v_pk_fma_f32 v[112:113], v[112:113], v[200:201], v[128:129] op_sel_hi:[1,0,1]
	v_lshl_add_u64 v[150:151], v[150:151], 0, v[148:149]
	v_mul_f32_e32 v124, v124, v124
	v_mul_f32_e32 v121, v121, v121
	v_mul_f32_e32 v122, v122, v122
	v_mul_f32_e32 v123, v123, v123
	v_cvt_pk_bf16_f32 v120, v124, v120
	v_pk_fma_f32 v[118:119], v[118:119], v[200:201], v[134:135] op_sel_hi:[1,0,1]
	v_pk_fma_f32 v[116:117], v[116:117], v[200:201], v[132:133] op_sel_hi:[1,0,1]
	v_max_f32_e32 v112, 0, v112
	v_max_f32_e32 v113, 0, v113
	v_max_f32_e32 v114, 0, v114
	v_cvt_pk_bf16_f32 v121, v121, v122
	v_cvt_pk_bf16_f32 v122, v145, v125
	v_cvt_pk_bf16_f32 v123, v126, v123
	global_store_dwordx4 v[150:151], v[120:123], off sc1
	v_max_f32_e32 v116, 0, v116
	v_max_f32_e32 v115, 0, v115
	v_mul_f32_e32 v120, v112, v112
	v_max_f32_e32 v112, 0, v117
	v_mul_f32_e32 v117, v113, v113
	v_max_f32_e32 v113, 0, v118
	v_mul_f32_e32 v118, v114, v114
	v_max_f32_e32 v114, 0, v119
	v_mul_f32_e32 v112, v112, v112
	v_mul_f32_e32 v113, v113, v113
	v_mul_f32_e32 v114, v114, v114
	v_pk_fma_f32 v[104:105], v[104:105], v[198:199], v[136:137] op_sel_hi:[1,0,1]
	v_mul_f32_e32 v116, v116, v116
	v_mul_f32_e32 v115, v115, v115
	v_cvt_pk_bf16_f32 v112, v116, v112
	v_cvt_pk_bf16_f32 v113, v113, v114
	v_cvt_pk_bf16_f32 v114, v120, v117
	v_pk_fma_f32 v[108:109], v[108:109], v[198:199], v[140:141] op_sel_hi:[1,0,1]
	v_pk_fma_f32 v[106:107], v[106:107], v[198:199], v[138:139] op_sel_hi:[1,0,1]
	v_max_f32_e32 v104, 0, v104
	v_cvt_pk_bf16_f32 v115, v118, v115
	global_store_dwordx4 v[150:151], v[112:115], off offset:256 sc1
	v_pk_fma_f32 v[110:111], v[110:111], v[198:199], v[142:143] op_sel_hi:[1,0,1]
	v_max_f32_e32 v105, 0, v105
	v_lshlrev_b64 v[112:113], 13, v[194:195]
	v_mul_f32_e32 v114, v104, v104
	v_max_f32_e32 v104, 0, v109
	v_max_f32_e32 v106, 0, v106
	v_lshl_add_u64 v[112:113], s[14:15], 0, v[112:113]
	v_max_f32_e32 v108, 0, v108
	v_mul_f32_e32 v104, v104, v104
	v_mul_f32_e32 v109, v105, v105
	v_max_f32_e32 v105, 0, v110
	v_mul_f32_e32 v110, v106, v106
	v_max_f32_e32 v106, 0, v111
	v_max_f32_e32 v107, 0, v107
	v_pk_fma_f32 v[98:99], v[98:99], v[198:199], v[130:131] op_sel_hi:[1,0,1]
	v_pk_fma_f32 v[96:97], v[96:97], v[198:199], v[128:129] op_sel_hi:[1,0,1]
	v_lshl_add_u64 v[112:113], v[112:113], 0, v[148:149]
	v_mul_f32_e32 v108, v108, v108
	v_mul_f32_e32 v105, v105, v105
	v_mul_f32_e32 v106, v106, v106
	v_mul_f32_e32 v107, v107, v107
	v_cvt_pk_bf16_f32 v104, v108, v104
	v_pk_fma_f32 v[102:103], v[102:103], v[198:199], v[134:135] op_sel_hi:[1,0,1]
	v_pk_fma_f32 v[100:101], v[100:101], v[198:199], v[132:133] op_sel_hi:[1,0,1]
	v_max_f32_e32 v96, 0, v96
	v_max_f32_e32 v97, 0, v97
	v_max_f32_e32 v98, 0, v98
	v_cvt_pk_bf16_f32 v105, v105, v106
	v_cvt_pk_bf16_f32 v106, v114, v109
	v_cvt_pk_bf16_f32 v107, v110, v107
	global_store_dwordx4 v[112:113], v[104:107], off sc1
	v_max_f32_e32 v100, 0, v100
	v_max_f32_e32 v99, 0, v99
	v_mul_f32_e32 v104, v96, v96
	v_max_f32_e32 v96, 0, v101
	v_mul_f32_e32 v101, v97, v97
	v_max_f32_e32 v97, 0, v102
	v_mul_f32_e32 v102, v98, v98
; __device__ __forceinline__ unsigned cvt_pk_bf16(float lo, float hi) { unsigned r; asm volatile("v_cvt_pk_bf16_f32 %0, %1, %2" : "=v"(r) : "v"(lo), "v"(hi)); return r; }
;     __device__ __forceinline__ void operator()(const f32x4 (&acc)[2][2][4][2], const Unit& u, int wr, int wc, int fr, int fq) const {
;     ...
;         for (int ai = 0; ai < 2; ++ai)
; #pragma unroll
;             for (int m = 0; m < 4; ++m) { const int row = row0 + ai * HALF + m * 16; bf16_t* rowp = O + (size_t)row * ldc + col0; float s = 0.f, q = 0.f;
;                 const float rstd = rsv[ai][m];
; #pragma unroll
;                 for (int bj = 0; bj < 2; ++bj) { f32x4 v0 = acc[ai][bj][m][0] * rstd + bv[bj][0], v1 = acc[ai][bj][m][1] * rstd + bv[bj][1];
;                     if (ACT == 1) {
; #pragma unroll
;                         for (int e = 0; e < 4; ++e) { const float a = fmaxf(v0[e], 0.f), b2 = fmaxf(v1[e], 0.f); v0[e] = a * a; v1[e] = b2 * b2; } }
;                     if (ACT == 2) {
; #pragma unroll
;                         for (int e = 0; e < 4; ++e) { v0[e] = gelu_tanh(v0[e]); v1[e] = gelu_tanh(v1[e]); s += v0[e] + v1[e]; q += v0[e] * v0[e] + v1[e] * v1[e]; } }
;                     u32x4 w; w.x = cvt_pk_bf16(v0[0], v0[1]); w.y = cvt_pk_bf16(v0[2], v0[3]); w.z = cvt_pk_bf16(v1[0], v1[1]); w.w = cvt_pk_bf16(v1[2], v1[3]);
;                     *(u32x4*)(rowp + bj * HALF) = w; }
	v_max_f32_e32 v98, 0, v103
	v_mul_f32_e32 v96, v96, v96
	v_mul_f32_e32 v97, v97, v97
	v_mul_f32_e32 v98, v98, v98
	v_pk_fma_f32 v[88:89], v[88:89], v[162:163], v[136:137] op_sel_hi:[1,0,1]
	v_mul_f32_e32 v100, v100, v100
	v_mul_f32_e32 v99, v99, v99
	v_cvt_pk_bf16_f32 v96, v100, v96
	v_cvt_pk_bf16_f32 v97, v97, v98
	v_cvt_pk_bf16_f32 v98, v104, v101
	v_pk_fma_f32 v[92:93], v[92:93], v[162:163], v[140:141] op_sel_hi:[1,0,1]
	v_pk_fma_f32 v[90:91], v[90:91], v[162:163], v[138:139] op_sel_hi:[1,0,1]
	v_max_f32_e32 v88, 0, v88
	v_cvt_pk_bf16_f32 v99, v102, v99
	global_store_dwordx4 v[112:113], v[96:99], off offset:256 sc1
	v_pk_fma_f32 v[94:95], v[94:95], v[162:163], v[142:143] op_sel_hi:[1,0,1]
	v_max_f32_e32 v89, 0, v89
	v_lshlrev_b64 v[96:97], 13, v[190:191]
	v_mul_f32_e32 v98, v88, v88
	v_max_f32_e32 v88, 0, v93
	v_max_f32_e32 v90, 0, v90
	v_lshl_add_u64 v[96:97], s[14:15], 0, v[96:97]
	v_max_f32_e32 v92, 0, v92
	v_mul_f32_e32 v88, v88, v88
	v_mul_f32_e32 v93, v89, v89
	v_max_f32_e32 v89, 0, v94
	v_mul_f32_e32 v94, v90, v90
	v_max_f32_e32 v90, 0, v95
	v_max_f32_e32 v91, 0, v91
	v_pk_fma_f32 v[82:83], v[82:83], v[162:163], v[130:131] op_sel_hi:[1,0,1]
	v_pk_fma_f32 v[80:81], v[80:81], v[162:163], v[128:129] op_sel_hi:[1,0,1]
	v_lshl_add_u64 v[96:97], v[96:97], 0, v[148:149]
	v_mul_f32_e32 v92, v92, v92
	v_mul_f32_e32 v89, v89, v89
	v_mul_f32_e32 v90, v90, v90
	v_mul_f32_e32 v91, v91, v91
	v_cvt_pk_bf16_f32 v88, v92, v88
	v_pk_fma_f32 v[86:87], v[86:87], v[162:163], v[134:135] op_sel_hi:[1,0,1]
	v_pk_fma_f32 v[84:85], v[84:85], v[162:163], v[132:133] op_sel_hi:[1,0,1]
	v_max_f32_e32 v80, 0, v80
	v_max_f32_e32 v81, 0, v81
	v_max_f32_e32 v82, 0, v82
	v_cvt_pk_bf16_f32 v89, v89, v90
	v_cvt_pk_bf16_f32 v90, v98, v93
	v_cvt_pk_bf16_f32 v91, v94, v91
	global_store_dwordx4 v[96:97], v[88:91], off sc1
	v_max_f32_e32 v84, 0, v84
	v_max_f32_e32 v83, 0, v83
	v_mul_f32_e32 v88, v80, v80
	v_max_f32_e32 v80, 0, v85
	v_mul_f32_e32 v85, v81, v81
	v_max_f32_e32 v81, 0, v86
	v_mul_f32_e32 v86, v82, v82
	v_max_f32_e32 v82, 0, v87
	v_mul_f32_e32 v80, v80, v80
	v_mul_f32_e32 v81, v81, v81
	v_mul_f32_e32 v82, v82, v82
	v_pk_fma_f32 v[72:73], v[72:73], v[160:161], v[136:137] op_sel_hi:[1,0,1]
	v_mul_f32_e32 v84, v84, v84
	v_mul_f32_e32 v83, v83, v83
	v_cvt_pk_bf16_f32 v80, v84, v80
	v_cvt_pk_bf16_f32 v81, v81, v82
	v_cvt_pk_bf16_f32 v82, v88, v85
	v_pk_fma_f32 v[76:77], v[76:77], v[160:161], v[140:141] op_sel_hi:[1,0,1]
	v_pk_fma_f32 v[74:75], v[74:75], v[160:161], v[138:139] op_sel_hi:[1,0,1]
	v_max_f32_e32 v72, 0, v72
	v_cvt_pk_bf16_f32 v83, v86, v83
	global_store_dwordx4 v[96:97], v[80:83], off offset:256 sc1
	v_pk_fma_f32 v[78:79], v[78:79], v[160:161], v[142:143] op_sel_hi:[1,0,1]
	v_max_f32_e32 v73, 0, v73
	v_lshlrev_b64 v[80:81], 13, v[188:189]
	v_mul_f32_e32 v82, v72, v72
	v_max_f32_e32 v72, 0, v77
	v_max_f32_e32 v74, 0, v74
	v_lshl_add_u64 v[80:81], s[14:15], 0, v[80:81]
	v_max_f32_e32 v76, 0, v76
	v_mul_f32_e32 v72, v72, v72
	v_mul_f32_e32 v77, v73, v73
	v_max_f32_e32 v73, 0, v78
	v_mul_f32_e32 v78, v74, v74
	v_max_f32_e32 v74, 0, v79
	v_max_f32_e32 v75, 0, v75
	v_pk_fma_f32 v[66:67], v[66:67], v[160:161], v[130:131] op_sel_hi:[1,0,1]
	v_pk_fma_f32 v[64:65], v[64:65], v[160:161], v[128:129] op_sel_hi:[1,0,1]
	v_lshl_add_u64 v[80:81], v[80:81], 0, v[148:149]
	v_mul_f32_e32 v76, v76, v76
	v_mul_f32_e32 v73, v73, v73
	v_mul_f32_e32 v74, v74, v74
	v_mul_f32_e32 v75, v75, v75
	v_cvt_pk_bf16_f32 v72, v76, v72
	v_pk_fma_f32 v[70:71], v[70:71], v[160:161], v[134:135] op_sel_hi:[1,0,1]
	v_pk_fma_f32 v[68:69], v[68:69], v[160:161], v[132:133] op_sel_hi:[1,0,1]
	v_max_f32_e32 v64, 0, v64
	v_max_f32_e32 v65, 0, v65
	v_max_f32_e32 v66, 0, v66
	v_cvt_pk_bf16_f32 v73, v73, v74
	v_cvt_pk_bf16_f32 v74, v82, v77
	v_cvt_pk_bf16_f32 v75, v78, v75
	global_store_dwordx4 v[80:81], v[72:75], off sc1
	v_max_f32_e32 v68, 0, v68
	v_max_f32_e32 v67, 0, v67
	v_mul_f32_e32 v72, v64, v64
	v_max_f32_e32 v64, 0, v69
	v_mul_f32_e32 v69, v65, v65
	v_max_f32_e32 v65, 0, v70
	v_mul_f32_e32 v70, v66, v66
	v_max_f32_e32 v66, 0, v71
	v_mul_f32_e32 v64, v64, v64
	v_mul_f32_e32 v65, v65, v65
	v_mul_f32_e32 v66, v66, v66
	v_pk_fma_f32 v[56:57], v[56:57], v[154:155], v[136:137] op_sel_hi:[1,0,1]
	v_mul_f32_e32 v68, v68, v68
	v_mul_f32_e32 v67, v67, v67
	v_cvt_pk_bf16_f32 v64, v68, v64
	v_cvt_pk_bf16_f32 v65, v65, v66
	v_cvt_pk_bf16_f32 v66, v72, v69
	v_pk_fma_f32 v[60:61], v[60:61], v[154:155], v[140:141] op_sel_hi:[1,0,1]
	v_pk_fma_f32 v[58:59], v[58:59], v[154:155], v[138:139] op_sel_hi:[1,0,1]
	v_max_f32_e32 v56, 0, v56
	v_cvt_pk_bf16_f32 v67, v70, v67
	global_store_dwordx4 v[80:81], v[64:67], off offset:256 sc1
	v_pk_fma_f32 v[62:63], v[62:63], v[154:155], v[142:143] op_sel_hi:[1,0,1]
	v_max_f32_e32 v57, 0, v57
	v_lshlrev_b64 v[64:65], 13, v[186:187]
	v_mul_f32_e32 v66, v56, v56
	v_max_f32_e32 v56, 0, v61
	v_max_f32_e32 v58, 0, v58
	v_lshl_add_u64 v[64:65], s[14:15], 0, v[64:65]
	v_max_f32_e32 v60, 0, v60
	v_mul_f32_e32 v56, v56, v56
	v_mul_f32_e32 v61, v57, v57
	v_max_f32_e32 v57, 0, v62
	v_mul_f32_e32 v62, v58, v58
	v_max_f32_e32 v58, 0, v63
	v_max_f32_e32 v59, 0, v59
	v_pk_fma_f32 v[50:51], v[50:51], v[154:155], v[130:131] op_sel_hi:[1,0,1]
	v_pk_fma_f32 v[48:49], v[48:49], v[154:155], v[128:129] op_sel_hi:[1,0,1]
	v_lshl_add_u64 v[64:65], v[64:65], 0, v[148:149]
	v_mul_f32_e32 v60, v60, v60
	v_mul_f32_e32 v57, v57, v57
	v_mul_f32_e32 v58, v58, v58
	v_mul_f32_e32 v59, v59, v59
	v_cvt_pk_bf16_f32 v56, v60, v56
	v_pk_fma_f32 v[54:55], v[54:55], v[154:155], v[134:135] op_sel_hi:[1,0,1]
	v_pk_fma_f32 v[52:53], v[52:53], v[154:155], v[132:133] op_sel_hi:[1,0,1]
	v_max_f32_e32 v48, 0, v48
; __device__ __forceinline__ unsigned cvt_pk_bf16(float lo, float hi) { unsigned r; asm volatile("v_cvt_pk_bf16_f32 %0, %1, %2" : "=v"(r) : "v"(lo), "v"(hi)); return r; }
; #define PG8_BAR __builtin_amdgcn_s_barrier()
;     __device__ __forceinline__ void operator()(const f32x4 (&acc)[2][2][4][2], const Unit& u, int wr, int wc, int fr, int fq) const {
;     ...
;             for (int m = 0; m < 4; ++m) { const int row = row0 + ai * HALF + m * 16; bf16_t* rowp = O + (size_t)row * ldc + col0; float s = 0.f, q = 0.f;
;                 const float rstd = rsv[ai][m];
; #pragma unroll
;                 for (int bj = 0; bj < 2; ++bj) { f32x4 v0 = acc[ai][bj][m][0] * rstd + bv[bj][0], v1 = acc[ai][bj][m][1] * rstd + bv[bj][1];
;                     if (ACT == 1) {
; #pragma unroll
;                         for (int e = 0; e < 4; ++e) { const float a = fmaxf(v0[e], 0.f), b2 = fmaxf(v1[e], 0.f); v0[e] = a * a; v1[e] = b2 * b2; } }
;                     if (ACT == 2) {
; #pragma unroll
;                         for (int e = 0; e < 4; ++e) { v0[e] = gelu_tanh(v0[e]); v1[e] = gelu_tanh(v1[e]); s += v0[e] + v1[e]; q += v0[e] * v0[e] + v1[e] * v1[e]; } }
;                     u32x4 w; w.x = cvt_pk_bf16(v0[0], v0[1]); w.y = cvt_pk_bf16(v0[2], v0[3]); w.z = cvt_pk_bf16(v1[0], v1[1]); w.w = cvt_pk_bf16(v1[2], v1[3]);
;                     *(u32x4*)(rowp + bj * HALF) = w; }
; template <class Epi, class Sched>
; __device__ __forceinline__ void gemm_phase(PG8_LAS unsigned char* lds, const Gemm g, const Sched& S, const Epi& E, const int tid) {
;     ...
;         if (wr == 0) PG8_BAR;
;         E(acc, cur, wr, wc, fr, fq);
;         if (!has_next) break;
; #pragma unroll
;         for (int a = 0; a < 2; ++a)
; #pragma unroll
;             for (int b = 0; b < 2; ++b)
; #pragma unroll
;                 for (int m = 0; m < 4; ++m)
; #pragma unroll
;                     for (int n = 0; n < 2; ++n) acc[a][b][m][n] = (f32x4){0.f, 0.f, 0.f, 0.f};
;         cur = nxt; cA = nA; cB = nB; ++ui;
;         if (wr == 1) PG8_BAR;
	v_max_f32_e32 v49, 0, v49
	v_max_f32_e32 v50, 0, v50
	v_cvt_pk_bf16_f32 v57, v57, v58
	v_cvt_pk_bf16_f32 v58, v66, v61
	v_cvt_pk_bf16_f32 v59, v62, v59
	global_store_dwordx4 v[64:65], v[56:59], off sc1
	v_max_f32_e32 v52, 0, v52
	v_max_f32_e32 v51, 0, v51
	v_mul_f32_e32 v56, v48, v48
	v_max_f32_e32 v48, 0, v53
	v_mul_f32_e32 v53, v49, v49
	v_max_f32_e32 v49, 0, v54
	v_mul_f32_e32 v54, v50, v50
	v_max_f32_e32 v50, 0, v55
	v_mul_f32_e32 v48, v48, v48
	v_mul_f32_e32 v49, v49, v49
	v_mul_f32_e32 v50, v50, v50
	v_pk_fma_f32 v[40:41], v[40:41], v[152:153], v[136:137] op_sel_hi:[1,0,1]
	v_mul_f32_e32 v52, v52, v52
	v_mul_f32_e32 v51, v51, v51
	v_cvt_pk_bf16_f32 v48, v52, v48
	v_cvt_pk_bf16_f32 v49, v49, v50
	v_cvt_pk_bf16_f32 v50, v56, v53
	v_pk_fma_f32 v[44:45], v[44:45], v[152:153], v[140:141] op_sel_hi:[1,0,1]
	v_pk_fma_f32 v[42:43], v[42:43], v[152:153], v[138:139] op_sel_hi:[1,0,1]
	v_max_f32_e32 v40, 0, v40
	v_cvt_pk_bf16_f32 v51, v54, v51
	global_store_dwordx4 v[64:65], v[48:51], off offset:256 sc1
	v_pk_fma_f32 v[46:47], v[46:47], v[152:153], v[142:143] op_sel_hi:[1,0,1]
	v_max_f32_e32 v41, 0, v41
	v_lshlrev_b64 v[48:49], 13, v[184:185]
	v_mul_f32_e32 v50, v40, v40
	v_max_f32_e32 v40, 0, v45
	v_max_f32_e32 v42, 0, v42
	v_lshl_add_u64 v[48:49], s[14:15], 0, v[48:49]
	v_max_f32_e32 v44, 0, v44
	v_mul_f32_e32 v40, v40, v40
	v_mul_f32_e32 v45, v41, v41
	v_max_f32_e32 v41, 0, v46
	v_mul_f32_e32 v46, v42, v42
	v_max_f32_e32 v42, 0, v47
	v_max_f32_e32 v43, 0, v43
	v_pk_fma_f32 v[34:35], v[34:35], v[152:153], v[130:131] op_sel_hi:[1,0,1]
	v_pk_fma_f32 v[32:33], v[32:33], v[152:153], v[128:129] op_sel_hi:[1,0,1]
	v_lshl_add_u64 v[48:49], v[48:49], 0, v[148:149]
	v_mul_f32_e32 v44, v44, v44
	v_mul_f32_e32 v41, v41, v41
	v_mul_f32_e32 v42, v42, v42
	v_mul_f32_e32 v43, v43, v43
	v_cvt_pk_bf16_f32 v40, v44, v40
	v_pk_fma_f32 v[38:39], v[38:39], v[152:153], v[134:135] op_sel_hi:[1,0,1]
	v_pk_fma_f32 v[36:37], v[36:37], v[152:153], v[132:133] op_sel_hi:[1,0,1]
	v_max_f32_e32 v32, 0, v32
	v_max_f32_e32 v33, 0, v33
	v_max_f32_e32 v34, 0, v34
	v_cvt_pk_bf16_f32 v41, v41, v42
	v_cvt_pk_bf16_f32 v42, v50, v45
	v_cvt_pk_bf16_f32 v43, v46, v43
	global_store_dwordx4 v[48:49], v[40:43], off sc1
	v_max_f32_e32 v36, 0, v36
	v_max_f32_e32 v35, 0, v35
	v_mul_f32_e32 v40, v32, v32
	v_max_f32_e32 v32, 0, v37
	v_mul_f32_e32 v37, v33, v33
	v_max_f32_e32 v33, 0, v38
	v_mul_f32_e32 v38, v34, v34
	v_max_f32_e32 v34, 0, v39
	v_mul_f32_e32 v32, v32, v32
	v_mul_f32_e32 v33, v33, v33
	v_mul_f32_e32 v34, v34, v34
	v_pk_fma_f32 v[24:25], v[24:25], v[146:147], v[136:137] op_sel_hi:[1,0,1]
	v_mul_f32_e32 v36, v36, v36
	v_mul_f32_e32 v35, v35, v35
	v_cvt_pk_bf16_f32 v32, v36, v32
	v_cvt_pk_bf16_f32 v33, v33, v34
	v_cvt_pk_bf16_f32 v34, v40, v37
	v_pk_fma_f32 v[28:29], v[28:29], v[146:147], v[140:141] op_sel_hi:[1,0,1]
	v_pk_fma_f32 v[26:27], v[26:27], v[146:147], v[138:139] op_sel_hi:[1,0,1]
	v_max_f32_e32 v24, 0, v24
	v_cvt_pk_bf16_f32 v35, v38, v35
	global_store_dwordx4 v[48:49], v[32:35], off offset:256 sc1
	v_pk_fma_f32 v[30:31], v[30:31], v[146:147], v[142:143] op_sel_hi:[1,0,1]
	v_max_f32_e32 v25, 0, v25
	v_lshlrev_b64 v[32:33], 13, v[182:183]
	v_mul_f32_e32 v34, v24, v24
	v_max_f32_e32 v24, 0, v29
	v_max_f32_e32 v26, 0, v26
	v_lshl_add_u64 v[32:33], s[14:15], 0, v[32:33]
	v_max_f32_e32 v28, 0, v28
	v_mul_f32_e32 v24, v24, v24
	v_mul_f32_e32 v29, v25, v25
	v_max_f32_e32 v25, 0, v30
	v_mul_f32_e32 v30, v26, v26
	v_max_f32_e32 v26, 0, v31
	v_max_f32_e32 v27, 0, v27
	v_pk_fma_f32 v[18:19], v[18:19], v[146:147], v[130:131] op_sel_hi:[1,0,1]
	v_pk_fma_f32 v[16:17], v[16:17], v[146:147], v[128:129] op_sel_hi:[1,0,1]
	v_lshl_add_u64 v[32:33], v[32:33], 0, v[148:149]
	v_mul_f32_e32 v28, v28, v28
	v_mul_f32_e32 v25, v25, v25
	v_mul_f32_e32 v26, v26, v26
	v_mul_f32_e32 v27, v27, v27
	v_cvt_pk_bf16_f32 v24, v28, v24
	v_pk_fma_f32 v[22:23], v[22:23], v[146:147], v[134:135] op_sel_hi:[1,0,1]
	v_pk_fma_f32 v[20:21], v[20:21], v[146:147], v[132:133] op_sel_hi:[1,0,1]
	v_max_f32_e32 v16, 0, v16
	v_max_f32_e32 v17, 0, v17
	v_max_f32_e32 v18, 0, v18
	v_cvt_pk_bf16_f32 v25, v25, v26
	v_cvt_pk_bf16_f32 v26, v34, v29
	v_cvt_pk_bf16_f32 v27, v30, v27
	global_store_dwordx4 v[32:33], v[24:27], off sc1
	v_max_f32_e32 v20, 0, v20
	v_max_f32_e32 v19, 0, v19
	v_mul_f32_e32 v24, v16, v16
	v_max_f32_e32 v16, 0, v21
	v_mul_f32_e32 v21, v17, v17
	v_max_f32_e32 v17, 0, v22
	v_mul_f32_e32 v22, v18, v18
	v_max_f32_e32 v18, 0, v23
	v_mul_f32_e32 v16, v16, v16
	v_mul_f32_e32 v17, v17, v17
	v_mul_f32_e32 v18, v18, v18
	v_pk_fma_f32 v[8:9], v[8:9], v[144:145], v[136:137] op_sel_hi:[1,0,1]
	v_mul_f32_e32 v20, v20, v20
	v_mul_f32_e32 v19, v19, v19
	v_cvt_pk_bf16_f32 v16, v20, v16
	v_cvt_pk_bf16_f32 v17, v17, v18
	v_cvt_pk_bf16_f32 v18, v24, v21
	v_pk_fma_f32 v[12:13], v[12:13], v[144:145], v[140:141] op_sel_hi:[1,0,1]
	v_pk_fma_f32 v[10:11], v[10:11], v[144:145], v[138:139] op_sel_hi:[1,0,1]
	v_max_f32_e32 v8, 0, v8
	v_cvt_pk_bf16_f32 v19, v22, v19
	global_store_dwordx4 v[32:33], v[16:19], off offset:256 sc1
	v_pk_fma_f32 v[14:15], v[14:15], v[144:145], v[142:143] op_sel_hi:[1,0,1]
	v_max_f32_e32 v9, 0, v9
	v_lshlrev_b64 v[16:17], 13, v[180:181]
	v_mul_f32_e32 v18, v8, v8
	v_max_f32_e32 v8, 0, v13
	v_max_f32_e32 v10, 0, v10
	v_lshl_add_u64 v[16:17], s[14:15], 0, v[16:17]
	v_max_f32_e32 v12, 0, v12
	v_mul_f32_e32 v8, v8, v8
	v_mul_f32_e32 v13, v9, v9
	v_max_f32_e32 v9, 0, v14
	v_mul_f32_e32 v14, v10, v10
	v_max_f32_e32 v10, 0, v15
	v_max_f32_e32 v11, 0, v11
	v_pk_fma_f32 v[2:3], v[2:3], v[144:145], v[130:131] op_sel_hi:[1,0,1]
	v_pk_fma_f32 v[0:1], v[0:1], v[144:145], v[128:129] op_sel_hi:[1,0,1]
	v_lshl_add_u64 v[16:17], v[16:17], 0, v[148:149]
	v_mul_f32_e32 v12, v12, v12
	v_mul_f32_e32 v9, v9, v9
	v_mul_f32_e32 v10, v10, v10
	v_mul_f32_e32 v11, v11, v11
	v_cvt_pk_bf16_f32 v8, v12, v8
	v_pk_fma_f32 v[6:7], v[6:7], v[144:145], v[134:135] op_sel_hi:[1,0,1]
	v_pk_fma_f32 v[4:5], v[4:5], v[144:145], v[132:133] op_sel_hi:[1,0,1]
	v_max_f32_e32 v0, 0, v0
	v_max_f32_e32 v1, 0, v1
	v_max_f32_e32 v2, 0, v2
	v_cvt_pk_bf16_f32 v9, v9, v10
	v_cvt_pk_bf16_f32 v10, v18, v13
	v_cvt_pk_bf16_f32 v11, v14, v11
	global_store_dwordx4 v[16:17], v[8:11], off sc1
	v_max_f32_e32 v3, 0, v3
	v_max_f32_e32 v4, 0, v4
	v_mul_f32_e32 v8, v0, v0
	v_max_f32_e32 v0, 0, v5
	v_mul_f32_e32 v5, v1, v1
	v_max_f32_e32 v1, 0, v6
	v_mul_f32_e32 v6, v2, v2
	v_max_f32_e32 v2, 0, v7
	v_mul_f32_e32 v0, v0, v0
	v_mul_f32_e32 v1, v1, v1
	v_mul_f32_e32 v2, v2, v2
	v_mul_f32_e32 v3, v3, v3
	s_mov_b64 s[40:41], -1
	s_andn2_b64 vcc, exec, s[38:39]
	v_mul_f32_e32 v4, v4, v4
	v_cvt_pk_bf16_f32 v0, v4, v0
	v_cvt_pk_bf16_f32 v1, v1, v2
	v_cvt_pk_bf16_f32 v2, v8, v5
	v_cvt_pk_bf16_f32 v3, v6, v3
	global_store_dwordx4 v[16:17], v[0:3], off offset:256 sc1
	s_cbranch_vccnz .LBB0_1689
	s_andn2_b64 vcc, exec, s[12:13]
	s_cbranch_vccnz .LBB0_1688
	s_barrier
	s_branch .LBB0_1688

; __device__ __forceinline__ unsigned cvt_pk_bf16(float lo, float hi) { unsigned r; asm volatile("v_cvt_pk_bf16_f32 %0, %1, %2" : "=v"(r) : "v"(lo), "v"(hi)); return r; }
;     __device__ __forceinline__ void operator()(const f32x4 (&acc)[2][2][4][2], const Unit& u, int wr, int wc, int fr, int fq) const {
;     ...
;             for (int m = 0; m < 4; ++m) { const int rl = wr * 64 + fr + ai * HALF + m * 16; const size_t off = (size_t)rl * DM + col0; float sq = 0.f;
;                 bf16_t* hrow = h16 + (size_t)rowt * DM + off;
; #pragma unroll
;                 for (int bj = 0; bj < 2; ++bj) { f32x4 b0, b1;
;                     if (bb) { b0 = *(const f32x4*)(bb + off + bj * HALF); b1 = *(const f32x4*)(bb + off + bj * HALF + 4); }
;                     else { const u32x4 r = raw[m][bj];
;                         b0 = (f32x4){__uint_as_float(r.x << 16), __uint_as_float(r.x & 0xffff0000u), __uint_as_float(r.y << 16), __uint_as_float(r.y & 0xffff0000u)};
;                         b1 = (f32x4){__uint_as_float(r.z << 16), __uint_as_float(r.z & 0xffff0000u), __uint_as_float(r.w << 16), __uint_as_float(r.w & 0xffff0000u)}; }
;                     const f32x4 o0 = b0 + gv[bj][0] * acc[ai][bj][m][0], o1 = b1 + gv[bj][1] * acc[ai][bj][m][1];
;                     u32x4 w; w.x = cvt_pk_bf16(o0[0], o0[1]); w.y = cvt_pk_bf16(o0[2], o0[3]); w.z = cvt_pk_bf16(o1[0], o1[1]); w.w = cvt_pk_bf16(o1[2], o1[3]);
;                     *(u32x4*)(hrow + bj * HALF) = w;
;                     sq += ((o0[0] * o0[0] + o0[1] * o0[1]) + (o0[2] * o0[2] + o0[3] * o0[3])) + ((o1[0] * o1[0] + o1[1] * o1[1]) + (o1[2] * o1[2] + o1[3] * o1[3]));
;                     if (hb) { const f32x4 y0 = o0 * wv[bj][0], y1 = o1 * wv[bj][1]; u32x4 z; z.x = cvt_pk_bf16(y0[0], y0[1]); z.y = cvt_pk_bf16(y0[2], y0[3]); z.z = cvt_pk_bf16(y1[0], y1[1]); z.w = cvt_pk_bf16(y1[2], y1[3]);
;                         *(u32x4*)(hb + (size_t)rowt * DM + off + bj * HALF) = z; } }
;                 if (ssq) { sq += __shfl_xor(sq, 16); sq += __shfl_xor(sq, 32); if (fq == 0) ssq[(size_t)(rowt + rl) * 16 + u.pn * 4 + wc] = sq; } }
.LBB0_1876:
	s_lshl_b32 s48, s42, 8
	s_ashr_i32 s49, s48, 31
	s_lshl_b64 s[42:43], s[48:49], 11
	s_lshl_b64 s[56:57], s[48:49], 10
	v_add_u32_e32 v200, s71, v148
	s_add_u32 s42, s51, s42
	s_addc_u32 s43, s60, s43
	v_ashrrev_i32_e32 v201, 31, v200
	v_add_u32_e32 v220, 16, v200
	v_lshl_add_u64 v[202:203], v[196:197], 1, s[42:43]
	v_lshlrev_b64 v[144:145], 11, v[200:201]
	v_ashrrev_i32_e32 v221, 31, v220
	v_add_u32_e32 v208, 32, v200
	v_lshl_add_u64 v[224:225], v[202:203], 0, v[144:145]
	v_lshlrev_b64 v[144:145], 11, v[220:221]
	v_ashrrev_i32_e32 v209, 31, v208
	v_add_u32_e32 v204, 48, v200
	v_lshl_add_u64 v[222:223], v[202:203], 0, v[144:145]
	v_lshlrev_b64 v[144:145], 11, v[208:209]
	v_ashrrev_i32_e32 v205, 31, v204
	global_load_dwordx4 v[168:171], v[224:225], off offset:256
	global_load_dwordx4 v[216:219], v[224:225], off
	v_lshl_add_u64 v[210:211], v[202:203], 0, v[144:145]
	v_lshlrev_b64 v[144:145], 11, v[204:205]
	v_lshl_add_u64 v[206:207], v[202:203], 0, v[144:145]
	global_load_dwordx4 v[164:167], v[222:223], off
	global_load_dwordx4 v[160:163], v[222:223], off offset:256
	global_load_dwordx4 v[156:159], v[210:211], off
	global_load_dwordx4 v[152:155], v[210:211], off offset:256
	global_load_dwordx4 v[148:151], v[206:207], off
	global_load_dwordx4 v[144:147], v[206:207], off offset:256
	v_lshlrev_b64 v[226:227], 10, v[200:201]
	v_lshl_add_u64 v[226:227], v[226:227], 0, v[196:197]
	s_and_b64 vcc, exec, s[40:41]
	s_waitcnt vmcnt(0)
	v_lshlrev_b32_e32 v234, 16, v216
	v_and_b32_e32 v235, 0xffff0000, v216
	v_lshlrev_b32_e32 v216, 16, v217
	v_and_b32_e32 v217, 0xffff0000, v217
	v_lshlrev_b32_e32 v236, 16, v218
	v_and_b32_e32 v237, 0xffff0000, v218
	v_lshlrev_b32_e32 v218, 16, v219
	v_and_b32_e32 v219, 0xffff0000, v219
	v_pk_fma_f32 v[142:143], v[142:143], v[70:71], v[216:217]
	v_pk_fma_f32 v[140:141], v[140:141], v[68:69], v[234:235]
	v_pk_fma_f32 v[138:139], v[138:139], v[78:79], v[218:219]
	v_pk_fma_f32 v[136:137], v[136:137], v[76:77], v[236:237]
	v_cvt_pk_bf16_f32 v216, v140, v141
	v_cvt_pk_bf16_f32 v217, v142, v143
	s_nop 0
	v_cvt_pk_bf16_f32 v218, v136, v137
	v_cvt_pk_bf16_f32 v219, v138, v139
	global_store_dwordx4 v[224:225], v[216:219], off sc1
	s_cbranch_vccnz .LBB0_1878
	s_lshl_b64 s[42:43], s[56:57], 1
	s_add_u32 s42, s63, s42
	v_pk_mul_f32 v[218:219], v[188:189], v[142:143]
	v_pk_mul_f32 v[216:217], v[186:187], v[140:141]
	v_pk_mul_f32 v[234:235], v[198:199], v[138:139]
	s_addc_u32 s43, s64, s43
	v_pk_mul_f32 v[236:237], v[194:195], v[136:137]
	v_cvt_pk_bf16_f32 v216, v216, v217
	v_cvt_pk_bf16_f32 v217, v218, v219
	s_nop 0
	v_cvt_pk_bf16_f32 v218, v236, v237
	v_cvt_pk_bf16_f32 v219, v234, v235
	v_lshl_add_u64 v[234:235], v[226:227], 1, s[42:43]
	global_store_dwordx4 v[234:235], v[216:219], off sc1
.LBB0_1878:
	s_nop 1
	v_lshlrev_b32_e32 v216, 16, v168
	v_and_b32_e32 v217, 0xffff0000, v168
	v_lshlrev_b32_e32 v168, 16, v169
	v_and_b32_e32 v169, 0xffff0000, v169
	v_lshlrev_b32_e32 v218, 16, v170
	v_and_b32_e32 v219, 0xffff0000, v170
	v_lshlrev_b32_e32 v170, 16, v171
	v_and_b32_e32 v171, 0xffff0000, v171
	v_pk_fma_f32 v[134:135], v[134:135], v[66:67], v[168:169]
	v_pk_fma_f32 v[132:133], v[132:133], v[64:65], v[216:217]
	v_pk_fma_f32 v[130:131], v[130:131], v[74:75], v[170:171]
	v_pk_fma_f32 v[128:129], v[128:129], v[72:73], v[218:219]
	s_and_b64 vcc, exec, s[40:41]
	v_cvt_pk_bf16_f32 v168, v132, v133
	v_cvt_pk_bf16_f32 v169, v134, v135
	v_cvt_pk_bf16_f32 v170, v128, v129
	v_cvt_pk_bf16_f32 v171, v130, v131
	global_store_dwordx4 v[224:225], v[168:171], off offset:256 sc1
	s_cbranch_vccnz .LBB0_1880
	s_lshl_b64 s[42:43], s[56:57], 1
	s_add_u32 s42, s63, s42
	v_pk_mul_f32 v[170:171], v[184:185], v[134:135]
	v_pk_mul_f32 v[168:169], v[182:183], v[132:133]
	v_pk_mul_f32 v[216:217], v[192:193], v[130:131]
	s_addc_u32 s43, s64, s43
	v_pk_mul_f32 v[218:219], v[190:191], v[128:129]
	v_cvt_pk_bf16_f32 v168, v168, v169
	v_cvt_pk_bf16_f32 v169, v170, v171
	s_nop 0
	v_cvt_pk_bf16_f32 v170, v218, v219
	v_cvt_pk_bf16_f32 v171, v216, v217
	v_lshl_add_u64 v[216:217], v[226:227], 1, s[42:43]
	global_store_dwordx4 v[216:217], v[168:171], off offset:256 sc1

; __device__ __forceinline__ unsigned cvt_pk_bf16(float lo, float hi) { unsigned r; asm volatile("v_cvt_pk_bf16_f32 %0, %1, %2" : "=v"(r) : "v"(lo), "v"(hi)); return r; }
;     __device__ __forceinline__ void operator()(const f32x4 (&acc)[2][2][4][2], const Unit& u, int wr, int wc, int fr, int fq) const {
;     ...
;             for (int m = 0; m < 4; ++m) { const int rl = wr * 64 + fr + ai * HALF + m * 16; const size_t off = (size_t)rl * DM + col0; float sq = 0.f;
;                 bf16_t* hrow = h16 + (size_t)rowt * DM + off;
; #pragma unroll
;                 for (int bj = 0; bj < 2; ++bj) { f32x4 b0, b1;
;                     if (bb) { b0 = *(const f32x4*)(bb + off + bj * HALF); b1 = *(const f32x4*)(bb + off + bj * HALF + 4); }
;                     else { const u32x4 r = raw[m][bj];
;                         b0 = (f32x4){__uint_as_float(r.x << 16), __uint_as_float(r.x & 0xffff0000u), __uint_as_float(r.y << 16), __uint_as_float(r.y & 0xffff0000u)};
;                         b1 = (f32x4){__uint_as_float(r.z << 16), __uint_as_float(r.z & 0xffff0000u), __uint_as_float(r.w << 16), __uint_as_float(r.w & 0xffff0000u)}; }
;                     const f32x4 o0 = b0 + gv[bj][0] * acc[ai][bj][m][0], o1 = b1 + gv[bj][1] * acc[ai][bj][m][1];
;                     u32x4 w; w.x = cvt_pk_bf16(o0[0], o0[1]); w.y = cvt_pk_bf16(o0[2], o0[3]); w.z = cvt_pk_bf16(o1[0], o1[1]); w.w = cvt_pk_bf16(o1[2], o1[3]);
;                     *(u32x4*)(hrow + bj * HALF) = w;
;                     sq += ((o0[0] * o0[0] + o0[1] * o0[1]) + (o0[2] * o0[2] + o0[3] * o0[3])) + ((o1[0] * o1[0] + o1[1] * o1[1]) + (o1[2] * o1[2] + o1[3] * o1[3]));
;                     if (hb) { const f32x4 y0 = o0 * wv[bj][0], y1 = o1 * wv[bj][1]; u32x4 z; z.x = cvt_pk_bf16(y0[0], y0[1]); z.y = cvt_pk_bf16(y0[2], y0[3]); z.z = cvt_pk_bf16(y1[0], y1[1]); z.w = cvt_pk_bf16(y1[2], y1[3]);
;                         *(u32x4*)(hb + (size_t)rowt * DM + off + bj * HALF) = z; } }
.LBB0_1882:
	s_or_b64 exec, exec, s[58:59]
	s_waitcnt lgkmcnt(0)
	v_lshlrev_b64 v[128:129], 10, v[220:221]
	v_lshlrev_b32_e32 v132, 16, v164
	v_and_b32_e32 v133, 0xffff0000, v164
	v_lshlrev_b32_e32 v134, 16, v165
	v_and_b32_e32 v135, 0xffff0000, v165
	v_lshlrev_b32_e32 v136, 16, v166
	v_and_b32_e32 v137, 0xffff0000, v166
	v_lshlrev_b32_e32 v138, 16, v167
	v_and_b32_e32 v139, 0xffff0000, v167
	v_lshl_add_u64 v[128:129], v[128:129], 0, v[196:197]
	v_pk_fma_f32 v[126:127], v[126:127], v[70:71], v[134:135]
	v_pk_fma_f32 v[124:125], v[124:125], v[68:69], v[132:133]
	v_pk_fma_f32 v[122:123], v[122:123], v[78:79], v[138:139]
	v_pk_fma_f32 v[120:121], v[120:121], v[76:77], v[136:137]
	s_and_b64 vcc, exec, s[40:41]
	v_cvt_pk_bf16_f32 v132, v124, v125
	v_cvt_pk_bf16_f32 v133, v126, v127
	v_cvt_pk_bf16_f32 v134, v120, v121
	v_cvt_pk_bf16_f32 v135, v122, v123
	global_store_dwordx4 v[222:223], v[132:135], off sc1
	s_cbranch_vccnz .LBB0_1884
	s_lshl_b64 s[52:53], s[56:57], 1
	s_add_u32 s52, s63, s52
	v_pk_mul_f32 v[134:135], v[188:189], v[126:127]
	v_pk_mul_f32 v[132:133], v[186:187], v[124:125]
	v_pk_mul_f32 v[136:137], v[198:199], v[122:123]
	s_addc_u32 s53, s64, s53
	v_pk_mul_f32 v[138:139], v[194:195], v[120:121]
	v_cvt_pk_bf16_f32 v132, v132, v133
	v_cvt_pk_bf16_f32 v133, v134, v135
	s_nop 0
	v_cvt_pk_bf16_f32 v134, v138, v139
	v_cvt_pk_bf16_f32 v135, v136, v137
	v_lshl_add_u64 v[136:137], v[128:129], 1, s[52:53]
	global_store_dwordx4 v[136:137], v[132:135], off sc1
.LBB0_1884:
	s_nop 1
	v_lshlrev_b32_e32 v132, 16, v160
	v_and_b32_e32 v133, 0xffff0000, v160
	v_lshlrev_b32_e32 v134, 16, v161
	v_and_b32_e32 v135, 0xffff0000, v161
	v_lshlrev_b32_e32 v136, 16, v162
	v_and_b32_e32 v137, 0xffff0000, v162
	v_lshlrev_b32_e32 v138, 16, v163
	v_and_b32_e32 v139, 0xffff0000, v163
	v_pk_fma_f32 v[118:119], v[118:119], v[66:67], v[134:135]
	v_pk_fma_f32 v[116:117], v[116:117], v[64:65], v[132:133]
	v_pk_fma_f32 v[114:115], v[114:115], v[74:75], v[138:139]
	v_pk_fma_f32 v[112:113], v[112:113], v[72:73], v[136:137]
	s_and_b64 vcc, exec, s[40:41]
	v_cvt_pk_bf16_f32 v132, v116, v117
	v_cvt_pk_bf16_f32 v133, v118, v119
	v_cvt_pk_bf16_f32 v134, v112, v113
	v_cvt_pk_bf16_f32 v135, v114, v115
	global_store_dwordx4 v[222:223], v[132:135], off offset:256 sc1
	s_cbranch_vccnz .LBB0_1886
	s_lshl_b64 s[52:53], s[56:57], 1
	s_add_u32 s52, s63, s52
	s_addc_u32 s53, s64, s53
	v_pk_mul_f32 v[134:135], v[184:185], v[118:119]
	v_pk_mul_f32 v[132:133], v[182:183], v[116:117]
	v_lshl_add_u64 v[128:129], v[128:129], 1, s[52:53]
	v_pk_mul_f32 v[136:137], v[192:193], v[114:115]
	v_pk_mul_f32 v[138:139], v[190:191], v[112:113]
	v_cvt_pk_bf16_f32 v132, v132, v133
	v_cvt_pk_bf16_f32 v133, v134, v135
	s_nop 0
	v_cvt_pk_bf16_f32 v134, v138, v139
	v_cvt_pk_bf16_f32 v135, v136, v137
	global_store_dwordx4 v[128:129], v[132:135], off offset:256 sc1

; __device__ __forceinline__ unsigned cvt_pk_bf16(float lo, float hi) { unsigned r; asm volatile("v_cvt_pk_bf16_f32 %0, %1, %2" : "=v"(r) : "v"(lo), "v"(hi)); return r; }
;     __device__ __forceinline__ void operator()(const f32x4 (&acc)[2][2][4][2], const Unit& u, int wr, int wc, int fr, int fq) const {
;     ...
;             for (int m = 0; m < 4; ++m) { const int rl = wr * 64 + fr + ai * HALF + m * 16; const size_t off = (size_t)rl * DM + col0; float sq = 0.f;
;                 bf16_t* hrow = h16 + (size_t)rowt * DM + off;
; #pragma unroll
;                 for (int bj = 0; bj < 2; ++bj) { f32x4 b0, b1;
;                     if (bb) { b0 = *(const f32x4*)(bb + off + bj * HALF); b1 = *(const f32x4*)(bb + off + bj * HALF + 4); }
;                     else { const u32x4 r = raw[m][bj];
;                         b0 = (f32x4){__uint_as_float(r.x << 16), __uint_as_float(r.x & 0xffff0000u), __uint_as_float(r.y << 16), __uint_as_float(r.y & 0xffff0000u)};
;                         b1 = (f32x4){__uint_as_float(r.z << 16), __uint_as_float(r.z & 0xffff0000u), __uint_as_float(r.w << 16), __uint_as_float(r.w & 0xffff0000u)}; }
;                     const f32x4 o0 = b0 + gv[bj][0] * acc[ai][bj][m][0], o1 = b1 + gv[bj][1] * acc[ai][bj][m][1];
;                     u32x4 w; w.x = cvt_pk_bf16(o0[0], o0[1]); w.y = cvt_pk_bf16(o0[2], o0[3]); w.z = cvt_pk_bf16(o1[0], o1[1]); w.w = cvt_pk_bf16(o1[2], o1[3]);
;                     *(u32x4*)(hrow + bj * HALF) = w;
;                     sq += ((o0[0] * o0[0] + o0[1] * o0[1]) + (o0[2] * o0[2] + o0[3] * o0[3])) + ((o1[0] * o1[0] + o1[1] * o1[1]) + (o1[2] * o1[2] + o1[3] * o1[3]));
;                     if (hb) { const f32x4 y0 = o0 * wv[bj][0], y1 = o1 * wv[bj][1]; u32x4 z; z.x = cvt_pk_bf16(y0[0], y0[1]); z.y = cvt_pk_bf16(y0[2], y0[3]); z.z = cvt_pk_bf16(y1[0], y1[1]); z.w = cvt_pk_bf16(y1[2], y1[3]);
;                         *(u32x4*)(hb + (size_t)rowt * DM + off + bj * HALF) = z; } }
.LBB0_1888:
	s_or_b64 exec, exec, s[58:59]
	s_waitcnt lgkmcnt(0)
	v_lshlrev_b64 v[112:113], 10, v[208:209]
	v_lshlrev_b32_e32 v114, 16, v156
	v_and_b32_e32 v115, 0xffff0000, v156
	v_lshlrev_b32_e32 v116, 16, v157
	v_and_b32_e32 v117, 0xffff0000, v157
	v_lshlrev_b32_e32 v118, 16, v158
	v_and_b32_e32 v119, 0xffff0000, v158
	v_lshlrev_b32_e32 v120, 16, v159
	v_and_b32_e32 v121, 0xffff0000, v159
	v_lshl_add_u64 v[112:113], v[112:113], 0, v[196:197]
	v_pk_fma_f32 v[110:111], v[110:111], v[70:71], v[116:117]
	v_pk_fma_f32 v[108:109], v[108:109], v[68:69], v[114:115]
	v_pk_fma_f32 v[106:107], v[106:107], v[78:79], v[120:121]
	v_pk_fma_f32 v[104:105], v[104:105], v[76:77], v[118:119]
	s_and_b64 vcc, exec, s[40:41]
	v_cvt_pk_bf16_f32 v114, v108, v109
	v_cvt_pk_bf16_f32 v115, v110, v111
	v_cvt_pk_bf16_f32 v116, v104, v105
	v_cvt_pk_bf16_f32 v117, v106, v107
	global_store_dwordx4 v[210:211], v[114:117], off sc1
	s_cbranch_vccnz .LBB0_1890
	s_lshl_b64 s[52:53], s[56:57], 1
	s_add_u32 s52, s63, s52
	v_pk_mul_f32 v[116:117], v[188:189], v[110:111]
	v_pk_mul_f32 v[114:115], v[186:187], v[108:109]
	v_pk_mul_f32 v[118:119], v[198:199], v[106:107]
	s_addc_u32 s53, s64, s53
	v_pk_mul_f32 v[120:121], v[194:195], v[104:105]
	v_cvt_pk_bf16_f32 v114, v114, v115
	v_cvt_pk_bf16_f32 v115, v116, v117
	s_nop 0
	v_cvt_pk_bf16_f32 v116, v120, v121
	v_cvt_pk_bf16_f32 v117, v118, v119
	v_lshl_add_u64 v[118:119], v[112:113], 1, s[52:53]
	global_store_dwordx4 v[118:119], v[114:117], off sc1
.LBB0_1890:
	s_nop 1
	v_lshlrev_b32_e32 v114, 16, v152
	v_and_b32_e32 v115, 0xffff0000, v152
	v_lshlrev_b32_e32 v116, 16, v153
	v_and_b32_e32 v117, 0xffff0000, v153
	v_lshlrev_b32_e32 v118, 16, v154
	v_and_b32_e32 v119, 0xffff0000, v154
	v_lshlrev_b32_e32 v120, 16, v155
	v_and_b32_e32 v121, 0xffff0000, v155
	v_pk_fma_f32 v[102:103], v[102:103], v[66:67], v[116:117]
	v_pk_fma_f32 v[100:101], v[100:101], v[64:65], v[114:115]
	v_pk_fma_f32 v[98:99], v[98:99], v[74:75], v[120:121]
	v_pk_fma_f32 v[96:97], v[96:97], v[72:73], v[118:119]
	s_and_b64 vcc, exec, s[40:41]
	v_cvt_pk_bf16_f32 v114, v100, v101
	v_cvt_pk_bf16_f32 v115, v102, v103
	v_cvt_pk_bf16_f32 v116, v96, v97
	v_cvt_pk_bf16_f32 v117, v98, v99
	global_store_dwordx4 v[210:211], v[114:117], off offset:256 sc1
	s_cbranch_vccnz .LBB0_1892
	s_lshl_b64 s[52:53], s[56:57], 1
	s_add_u32 s52, s63, s52
	s_addc_u32 s53, s64, s53
	v_pk_mul_f32 v[116:117], v[184:185], v[102:103]
	v_pk_mul_f32 v[114:115], v[182:183], v[100:101]
	v_lshl_add_u64 v[112:113], v[112:113], 1, s[52:53]
	v_pk_mul_f32 v[118:119], v[192:193], v[98:99]
	v_pk_mul_f32 v[120:121], v[190:191], v[96:97]
	v_cvt_pk_bf16_f32 v114, v114, v115
	v_cvt_pk_bf16_f32 v115, v116, v117
	s_nop 0
	v_cvt_pk_bf16_f32 v116, v120, v121
	v_cvt_pk_bf16_f32 v117, v118, v119
	global_store_dwordx4 v[112:113], v[114:117], off offset:256 sc1

; __device__ __forceinline__ unsigned cvt_pk_bf16(float lo, float hi) { unsigned r; asm volatile("v_cvt_pk_bf16_f32 %0, %1, %2" : "=v"(r) : "v"(lo), "v"(hi)); return r; }
;     __device__ __forceinline__ void operator()(const f32x4 (&acc)[2][2][4][2], const Unit& u, int wr, int wc, int fr, int fq) const {
;     ...
;             for (int m = 0; m < 4; ++m) { const int rl = wr * 64 + fr + ai * HALF + m * 16; const size_t off = (size_t)rl * DM + col0; float sq = 0.f;
;                 bf16_t* hrow = h16 + (size_t)rowt * DM + off;
; #pragma unroll
;                 for (int bj = 0; bj < 2; ++bj) { f32x4 b0, b1;
;                     if (bb) { b0 = *(const f32x4*)(bb + off + bj * HALF); b1 = *(const f32x4*)(bb + off + bj * HALF + 4); }
;                     else { const u32x4 r = raw[m][bj];
;                         b0 = (f32x4){__uint_as_float(r.x << 16), __uint_as_float(r.x & 0xffff0000u), __uint_as_float(r.y << 16), __uint_as_float(r.y & 0xffff0000u)};
;                         b1 = (f32x4){__uint_as_float(r.z << 16), __uint_as_float(r.z & 0xffff0000u), __uint_as_float(r.w << 16), __uint_as_float(r.w & 0xffff0000u)}; }
;                     const f32x4 o0 = b0 + gv[bj][0] * acc[ai][bj][m][0], o1 = b1 + gv[bj][1] * acc[ai][bj][m][1];
;                     u32x4 w; w.x = cvt_pk_bf16(o0[0], o0[1]); w.y = cvt_pk_bf16(o0[2], o0[3]); w.z = cvt_pk_bf16(o1[0], o1[1]); w.w = cvt_pk_bf16(o1[2], o1[3]);
;                     *(u32x4*)(hrow + bj * HALF) = w;
;                     sq += ((o0[0] * o0[0] + o0[1] * o0[1]) + (o0[2] * o0[2] + o0[3] * o0[3])) + ((o1[0] * o1[0] + o1[1] * o1[1]) + (o1[2] * o1[2] + o1[3] * o1[3]));
;                     if (hb) { const f32x4 y0 = o0 * wv[bj][0], y1 = o1 * wv[bj][1]; u32x4 z; z.x = cvt_pk_bf16(y0[0], y0[1]); z.y = cvt_pk_bf16(y0[2], y0[3]); z.z = cvt_pk_bf16(y1[0], y1[1]); z.w = cvt_pk_bf16(y1[2], y1[3]);
;                         *(u32x4*)(hb + (size_t)rowt * DM + off + bj * HALF) = z; } }
.LBB0_1894:
	s_or_b64 exec, exec, s[58:59]
	s_waitcnt lgkmcnt(0)
	v_lshlrev_b64 v[96:97], 10, v[204:205]
	v_lshlrev_b32_e32 v98, 16, v148
	v_and_b32_e32 v99, 0xffff0000, v148
	v_lshlrev_b32_e32 v100, 16, v149
	v_and_b32_e32 v101, 0xffff0000, v149
	v_lshlrev_b32_e32 v102, 16, v150
	v_and_b32_e32 v103, 0xffff0000, v150
	v_lshlrev_b32_e32 v104, 16, v151
	v_and_b32_e32 v105, 0xffff0000, v151
	v_lshl_add_u64 v[96:97], v[96:97], 0, v[196:197]
	v_pk_fma_f32 v[94:95], v[94:95], v[70:71], v[100:101]
	v_pk_fma_f32 v[92:93], v[92:93], v[68:69], v[98:99]
	v_pk_fma_f32 v[90:91], v[90:91], v[78:79], v[104:105]
	v_pk_fma_f32 v[88:89], v[88:89], v[76:77], v[102:103]
	s_and_b64 vcc, exec, s[40:41]
	v_cvt_pk_bf16_f32 v98, v92, v93
	v_cvt_pk_bf16_f32 v99, v94, v95
	v_cvt_pk_bf16_f32 v100, v88, v89
	v_cvt_pk_bf16_f32 v101, v90, v91
	global_store_dwordx4 v[206:207], v[98:101], off sc1
	s_cbranch_vccnz .LBB0_1896
	s_lshl_b64 s[52:53], s[56:57], 1
	s_add_u32 s52, s63, s52
	v_pk_mul_f32 v[100:101], v[188:189], v[94:95]
	v_pk_mul_f32 v[98:99], v[186:187], v[92:93]
	v_pk_mul_f32 v[102:103], v[198:199], v[90:91]
	s_addc_u32 s53, s64, s53
	v_pk_mul_f32 v[104:105], v[194:195], v[88:89]
	v_cvt_pk_bf16_f32 v98, v98, v99
	v_cvt_pk_bf16_f32 v99, v100, v101
	s_nop 0
	v_cvt_pk_bf16_f32 v100, v104, v105
	v_cvt_pk_bf16_f32 v101, v102, v103
	v_lshl_add_u64 v[102:103], v[96:97], 1, s[52:53]
	global_store_dwordx4 v[102:103], v[98:101], off sc1
.LBB0_1896:
	s_nop 1
	v_lshlrev_b32_e32 v98, 16, v144
	v_and_b32_e32 v99, 0xffff0000, v144
	v_lshlrev_b32_e32 v100, 16, v145
	v_and_b32_e32 v101, 0xffff0000, v145
	v_lshlrev_b32_e32 v102, 16, v146
	v_and_b32_e32 v103, 0xffff0000, v146
	v_lshlrev_b32_e32 v104, 16, v147
	v_and_b32_e32 v105, 0xffff0000, v147
	v_pk_fma_f32 v[86:87], v[86:87], v[66:67], v[100:101]
	v_pk_fma_f32 v[84:85], v[84:85], v[64:65], v[98:99]
	v_pk_fma_f32 v[82:83], v[82:83], v[74:75], v[104:105]
	v_pk_fma_f32 v[80:81], v[80:81], v[72:73], v[102:103]
	s_and_b64 vcc, exec, s[40:41]
	v_cvt_pk_bf16_f32 v98, v84, v85
	v_cvt_pk_bf16_f32 v99, v86, v87
	v_cvt_pk_bf16_f32 v100, v80, v81
	v_cvt_pk_bf16_f32 v101, v82, v83
	global_store_dwordx4 v[206:207], v[98:101], off offset:256 sc1
	s_cbranch_vccnz .LBB0_1898
	s_lshl_b64 s[52:53], s[56:57], 1
	s_add_u32 s52, s63, s52
	s_addc_u32 s53, s64, s53
	v_pk_mul_f32 v[100:101], v[184:185], v[86:87]
	v_pk_mul_f32 v[98:99], v[182:183], v[84:85]
	v_lshl_add_u64 v[96:97], v[96:97], 1, s[52:53]
	v_pk_mul_f32 v[102:103], v[192:193], v[82:83]
	v_pk_mul_f32 v[104:105], v[190:191], v[80:81]
	v_cvt_pk_bf16_f32 v98, v98, v99
	v_cvt_pk_bf16_f32 v99, v100, v101
	s_nop 0
	v_cvt_pk_bf16_f32 v100, v104, v105
	v_cvt_pk_bf16_f32 v101, v102, v103
	global_store_dwordx4 v[96:97], v[98:101], off offset:256 sc1

; __device__ __forceinline__ unsigned cvt_pk_bf16(float lo, float hi) { unsigned r; asm volatile("v_cvt_pk_bf16_f32 %0, %1, %2" : "=v"(r) : "v"(lo), "v"(hi)); return r; }
;     __device__ __forceinline__ void operator()(const f32x4 (&acc)[2][2][4][2], const Unit& u, int wr, int wc, int fr, int fq) const {
;     ...
;             for (int m = 0; m < 4; ++m)
; #pragma unroll
;                 for (int bj = 0; bj < 2; ++bj) raw[m][bj] = *(const u32x4*)(h16 + (size_t)rowt * DM + (size_t)(wr * 64 + fr + ai * HALF + m * 16) * DM + col0 + bj * HALF);
; #pragma unroll
;             for (int m = 0; m < 4; ++m) { const int rl = wr * 64 + fr + ai * HALF + m * 16; const size_t off = (size_t)rl * DM + col0; float sq = 0.f;
;                 bf16_t* hrow = h16 + (size_t)rowt * DM + off;
; #pragma unroll
;                 for (int bj = 0; bj < 2; ++bj) { f32x4 b0, b1;
;                     if (bb) { b0 = *(const f32x4*)(bb + off + bj * HALF); b1 = *(const f32x4*)(bb + off + bj * HALF + 4); }
;                     else { const u32x4 r = raw[m][bj];
;                         b0 = (f32x4){__uint_as_float(r.x << 16), __uint_as_float(r.x & 0xffff0000u), __uint_as_float(r.y << 16), __uint_as_float(r.y & 0xffff0000u)};
;                         b1 = (f32x4){__uint_as_float(r.z << 16), __uint_as_float(r.z & 0xffff0000u), __uint_as_float(r.w << 16), __uint_as_float(r.w & 0xffff0000u)}; }
;                     const f32x4 o0 = b0 + gv[bj][0] * acc[ai][bj][m][0], o1 = b1 + gv[bj][1] * acc[ai][bj][m][1];
;                     u32x4 w; w.x = cvt_pk_bf16(o0[0], o0[1]); w.y = cvt_pk_bf16(o0[2], o0[3]); w.z = cvt_pk_bf16(o1[0], o1[1]); w.w = cvt_pk_bf16(o1[2], o1[3]);
;                     *(u32x4*)(hrow + bj * HALF) = w;
;                     sq += ((o0[0] * o0[0] + o0[1] * o0[1]) + (o0[2] * o0[2] + o0[3] * o0[3])) + ((o1[0] * o1[0] + o1[1] * o1[1]) + (o1[2] * o1[2] + o1[3] * o1[3]));
;                     if (hb) { const f32x4 y0 = o0 * wv[bj][0], y1 = o1 * wv[bj][1]; u32x4 z; z.x = cvt_pk_bf16(y0[0], y0[1]); z.y = cvt_pk_bf16(y0[2], y0[3]); z.z = cvt_pk_bf16(y1[0], y1[1]); z.w = cvt_pk_bf16(y1[2], y1[3]);
;                         *(u32x4*)(hb + (size_t)rowt * DM + off + bj * HALF) = z; } }
.LBB0_1900:
	s_or_b64 exec, exec, s[58:59]
	v_add_u32_e32 v120, 0x80, v200
	v_ashrrev_i32_e32 v121, 31, v120
	v_add_u32_e32 v116, 0x90, v200
	s_waitcnt lgkmcnt(0)
	v_lshlrev_b64 v[80:81], 11, v[120:121]
	v_ashrrev_i32_e32 v117, 31, v116
	v_add_u32_e32 v112, 0xa0, v200
	v_lshl_add_u64 v[122:123], v[202:203], 0, v[80:81]
	v_lshlrev_b64 v[80:81], 11, v[116:117]
	v_ashrrev_i32_e32 v113, 31, v112
	v_add_u32_e32 v108, 0xb0, v200
	v_lshl_add_u64 v[118:119], v[202:203], 0, v[80:81]
	v_lshlrev_b64 v[80:81], 11, v[112:113]
	v_ashrrev_i32_e32 v109, 31, v108
	global_load_dwordx4 v[104:107], v[122:123], off offset:256
	global_load_dwordx4 v[126:129], v[122:123], off
	v_lshl_add_u64 v[114:115], v[202:203], 0, v[80:81]
	v_lshlrev_b64 v[80:81], 11, v[108:109]
	v_lshl_add_u64 v[110:111], v[202:203], 0, v[80:81]
	global_load_dwordx4 v[100:103], v[118:119], off
	global_load_dwordx4 v[96:99], v[118:119], off offset:256
	global_load_dwordx4 v[92:95], v[114:115], off
	global_load_dwordx4 v[88:91], v[114:115], off offset:256
	global_load_dwordx4 v[84:87], v[110:111], off
	global_load_dwordx4 v[80:83], v[110:111], off offset:256
	v_lshlrev_b64 v[124:125], 10, v[120:121]
	v_lshl_add_u64 v[124:125], v[124:125], 0, v[196:197]
	s_and_b64 vcc, exec, s[40:41]
	s_waitcnt vmcnt(6)
	v_lshlrev_b32_e32 v132, 16, v126
	v_and_b32_e32 v133, 0xffff0000, v126
	v_lshlrev_b32_e32 v126, 16, v127
	v_and_b32_e32 v127, 0xffff0000, v127
	v_lshlrev_b32_e32 v134, 16, v128
	v_and_b32_e32 v135, 0xffff0000, v128
	v_lshlrev_b32_e32 v128, 16, v129
	v_and_b32_e32 v129, 0xffff0000, v129
	v_pk_fma_f32 v[62:63], v[62:63], v[70:71], v[126:127]
	v_pk_fma_f32 v[60:61], v[60:61], v[68:69], v[132:133]
	v_pk_fma_f32 v[58:59], v[58:59], v[78:79], v[128:129]
	v_pk_fma_f32 v[56:57], v[56:57], v[76:77], v[134:135]
	v_cvt_pk_bf16_f32 v126, v60, v61
	v_cvt_pk_bf16_f32 v127, v62, v63
	s_nop 0
	v_cvt_pk_bf16_f32 v128, v56, v57
	v_cvt_pk_bf16_f32 v129, v58, v59
	global_store_dwordx4 v[122:123], v[126:129], off sc1
	s_cbranch_vccnz .LBB0_1902
	s_lshl_b64 s[52:53], s[56:57], 1
	s_add_u32 s52, s63, s52
	v_pk_mul_f32 v[128:129], v[188:189], v[62:63]
	v_pk_mul_f32 v[126:127], v[186:187], v[60:61]
	v_pk_mul_f32 v[132:133], v[198:199], v[58:59]
	s_addc_u32 s53, s64, s53
	v_pk_mul_f32 v[134:135], v[194:195], v[56:57]
	v_cvt_pk_bf16_f32 v126, v126, v127
	v_cvt_pk_bf16_f32 v127, v128, v129
	s_nop 0
	v_cvt_pk_bf16_f32 v128, v134, v135
	v_cvt_pk_bf16_f32 v129, v132, v133
	v_lshl_add_u64 v[132:133], v[124:125], 1, s[52:53]
	global_store_dwordx4 v[132:133], v[126:129], off sc1
.LBB0_1902:
	s_nop 1
	v_lshlrev_b32_e32 v126, 16, v104
	v_and_b32_e32 v127, 0xffff0000, v104
	v_lshlrev_b32_e32 v104, 16, v105
	v_and_b32_e32 v105, 0xffff0000, v105
	v_lshlrev_b32_e32 v128, 16, v106
	v_and_b32_e32 v129, 0xffff0000, v106
	v_lshlrev_b32_e32 v106, 16, v107
	v_and_b32_e32 v107, 0xffff0000, v107
	v_pk_fma_f32 v[54:55], v[54:55], v[66:67], v[104:105]
	v_pk_fma_f32 v[52:53], v[52:53], v[64:65], v[126:127]
	v_pk_fma_f32 v[50:51], v[50:51], v[74:75], v[106:107]
	v_pk_fma_f32 v[48:49], v[48:49], v[72:73], v[128:129]
	s_and_b64 vcc, exec, s[40:41]
	v_cvt_pk_bf16_f32 v104, v52, v53
	v_cvt_pk_bf16_f32 v105, v54, v55
	v_cvt_pk_bf16_f32 v106, v48, v49
	v_cvt_pk_bf16_f32 v107, v50, v51
	global_store_dwordx4 v[122:123], v[104:107], off offset:256 sc1
	s_cbranch_vccnz .LBB0_1904
	s_lshl_b64 s[52:53], s[56:57], 1
	s_add_u32 s52, s63, s52
	v_pk_mul_f32 v[106:107], v[184:185], v[54:55]
	v_pk_mul_f32 v[104:105], v[182:183], v[52:53]
	v_pk_mul_f32 v[122:123], v[192:193], v[50:51]
	s_addc_u32 s53, s64, s53
	v_pk_mul_f32 v[126:127], v[190:191], v[48:49]
	v_cvt_pk_bf16_f32 v104, v104, v105
	v_cvt_pk_bf16_f32 v105, v106, v107
	s_nop 0
	v_cvt_pk_bf16_f32 v106, v126, v127
	v_cvt_pk_bf16_f32 v107, v122, v123
	v_lshl_add_u64 v[122:123], v[124:125], 1, s[52:53]
	global_store_dwordx4 v[122:123], v[104:107], off offset:256 sc1

; __device__ __forceinline__ unsigned cvt_pk_bf16(float lo, float hi) { unsigned r; asm volatile("v_cvt_pk_bf16_f32 %0, %1, %2" : "=v"(r) : "v"(lo), "v"(hi)); return r; }
;     __device__ __forceinline__ void operator()(const f32x4 (&acc)[2][2][4][2], const Unit& u, int wr, int wc, int fr, int fq) const {
;     ...
;             for (int m = 0; m < 4; ++m) { const int rl = wr * 64 + fr + ai * HALF + m * 16; const size_t off = (size_t)rl * DM + col0; float sq = 0.f;
;                 bf16_t* hrow = h16 + (size_t)rowt * DM + off;
; #pragma unroll
;                 for (int bj = 0; bj < 2; ++bj) { f32x4 b0, b1;
;                     if (bb) { b0 = *(const f32x4*)(bb + off + bj * HALF); b1 = *(const f32x4*)(bb + off + bj * HALF + 4); }
;                     else { const u32x4 r = raw[m][bj];
;                         b0 = (f32x4){__uint_as_float(r.x << 16), __uint_as_float(r.x & 0xffff0000u), __uint_as_float(r.y << 16), __uint_as_float(r.y & 0xffff0000u)};
;                         b1 = (f32x4){__uint_as_float(r.z << 16), __uint_as_float(r.z & 0xffff0000u), __uint_as_float(r.w << 16), __uint_as_float(r.w & 0xffff0000u)}; }
;                     const f32x4 o0 = b0 + gv[bj][0] * acc[ai][bj][m][0], o1 = b1 + gv[bj][1] * acc[ai][bj][m][1];
;                     u32x4 w; w.x = cvt_pk_bf16(o0[0], o0[1]); w.y = cvt_pk_bf16(o0[2], o0[3]); w.z = cvt_pk_bf16(o1[0], o1[1]); w.w = cvt_pk_bf16(o1[2], o1[3]);
;                     *(u32x4*)(hrow + bj * HALF) = w;
;                     sq += ((o0[0] * o0[0] + o0[1] * o0[1]) + (o0[2] * o0[2] + o0[3] * o0[3])) + ((o1[0] * o1[0] + o1[1] * o1[1]) + (o1[2] * o1[2] + o1[3] * o1[3]));
;                     if (hb) { const f32x4 y0 = o0 * wv[bj][0], y1 = o1 * wv[bj][1]; u32x4 z; z.x = cvt_pk_bf16(y0[0], y0[1]); z.y = cvt_pk_bf16(y0[2], y0[3]); z.z = cvt_pk_bf16(y1[0], y1[1]); z.w = cvt_pk_bf16(y1[2], y1[3]);
;                         *(u32x4*)(hb + (size_t)rowt * DM + off + bj * HALF) = z; } }
.LBB0_1906:
	s_or_b64 exec, exec, s[58:59]
	s_waitcnt lgkmcnt(0)
	v_lshlrev_b64 v[48:49], 10, v[116:117]
	s_waitcnt vmcnt(7)
	v_lshlrev_b32_e32 v50, 16, v100
	v_and_b32_e32 v51, 0xffff0000, v100
	v_lshlrev_b32_e32 v52, 16, v101
	v_and_b32_e32 v53, 0xffff0000, v101
	v_lshlrev_b32_e32 v54, 16, v102
	v_and_b32_e32 v55, 0xffff0000, v102
	v_lshlrev_b32_e32 v56, 16, v103
	v_and_b32_e32 v57, 0xffff0000, v103
	v_lshl_add_u64 v[48:49], v[48:49], 0, v[196:197]
	v_pk_fma_f32 v[46:47], v[46:47], v[70:71], v[52:53]
	v_pk_fma_f32 v[44:45], v[44:45], v[68:69], v[50:51]
	v_pk_fma_f32 v[42:43], v[42:43], v[78:79], v[56:57]
	v_pk_fma_f32 v[40:41], v[40:41], v[76:77], v[54:55]
	s_and_b64 vcc, exec, s[40:41]
	v_cvt_pk_bf16_f32 v50, v44, v45
	v_cvt_pk_bf16_f32 v51, v46, v47
	v_cvt_pk_bf16_f32 v52, v40, v41
	v_cvt_pk_bf16_f32 v53, v42, v43
	global_store_dwordx4 v[118:119], v[50:53], off sc1
	s_cbranch_vccnz .LBB0_1908
	s_lshl_b64 s[52:53], s[56:57], 1
	s_add_u32 s52, s63, s52
	v_pk_mul_f32 v[52:53], v[188:189], v[46:47]
	v_pk_mul_f32 v[50:51], v[186:187], v[44:45]
	v_pk_mul_f32 v[54:55], v[198:199], v[42:43]
	s_addc_u32 s53, s64, s53
	v_pk_mul_f32 v[56:57], v[194:195], v[40:41]
	v_cvt_pk_bf16_f32 v50, v50, v51
	v_cvt_pk_bf16_f32 v51, v52, v53
	s_nop 0
	v_cvt_pk_bf16_f32 v52, v56, v57
	v_cvt_pk_bf16_f32 v53, v54, v55
	v_lshl_add_u64 v[54:55], v[48:49], 1, s[52:53]
	global_store_dwordx4 v[54:55], v[50:53], off sc1
.LBB0_1908:
	s_waitcnt vmcnt(7)
	s_nop 0
	v_lshlrev_b32_e32 v50, 16, v96
	v_and_b32_e32 v51, 0xffff0000, v96
	v_lshlrev_b32_e32 v52, 16, v97
	v_and_b32_e32 v53, 0xffff0000, v97
	v_lshlrev_b32_e32 v54, 16, v98
	v_and_b32_e32 v55, 0xffff0000, v98
	v_lshlrev_b32_e32 v56, 16, v99
	v_and_b32_e32 v57, 0xffff0000, v99
	v_pk_fma_f32 v[38:39], v[38:39], v[66:67], v[52:53]
	v_pk_fma_f32 v[36:37], v[36:37], v[64:65], v[50:51]
	v_pk_fma_f32 v[34:35], v[34:35], v[74:75], v[56:57]
	v_pk_fma_f32 v[32:33], v[32:33], v[72:73], v[54:55]
	s_and_b64 vcc, exec, s[40:41]
	v_cvt_pk_bf16_f32 v50, v36, v37
	v_cvt_pk_bf16_f32 v51, v38, v39
	v_cvt_pk_bf16_f32 v52, v32, v33
	v_cvt_pk_bf16_f32 v53, v34, v35
	global_store_dwordx4 v[118:119], v[50:53], off offset:256 sc1
	s_cbranch_vccnz .LBB0_1910
	s_lshl_b64 s[52:53], s[56:57], 1
	s_add_u32 s52, s63, s52
	s_addc_u32 s53, s64, s53
	v_pk_mul_f32 v[52:53], v[184:185], v[38:39]
	v_pk_mul_f32 v[50:51], v[182:183], v[36:37]
	v_lshl_add_u64 v[48:49], v[48:49], 1, s[52:53]
	v_pk_mul_f32 v[54:55], v[192:193], v[34:35]
	v_pk_mul_f32 v[56:57], v[190:191], v[32:33]
	v_cvt_pk_bf16_f32 v50, v50, v51
	v_cvt_pk_bf16_f32 v51, v52, v53
	s_nop 0
	v_cvt_pk_bf16_f32 v52, v56, v57
	v_cvt_pk_bf16_f32 v53, v54, v55
	global_store_dwordx4 v[48:49], v[50:53], off offset:256 sc1

; __device__ __forceinline__ unsigned cvt_pk_bf16(float lo, float hi) { unsigned r; asm volatile("v_cvt_pk_bf16_f32 %0, %1, %2" : "=v"(r) : "v"(lo), "v"(hi)); return r; }
;     __device__ __forceinline__ void operator()(const f32x4 (&acc)[2][2][4][2], const Unit& u, int wr, int wc, int fr, int fq) const {
;     ...
;             for (int m = 0; m < 4; ++m) { const int rl = wr * 64 + fr + ai * HALF + m * 16; const size_t off = (size_t)rl * DM + col0; float sq = 0.f;
;                 bf16_t* hrow = h16 + (size_t)rowt * DM + off;
; #pragma unroll
;                 for (int bj = 0; bj < 2; ++bj) { f32x4 b0, b1;
;                     if (bb) { b0 = *(const f32x4*)(bb + off + bj * HALF); b1 = *(const f32x4*)(bb + off + bj * HALF + 4); }
;                     else { const u32x4 r = raw[m][bj];
;                         b0 = (f32x4){__uint_as_float(r.x << 16), __uint_as_float(r.x & 0xffff0000u), __uint_as_float(r.y << 16), __uint_as_float(r.y & 0xffff0000u)};
;                         b1 = (f32x4){__uint_as_float(r.z << 16), __uint_as_float(r.z & 0xffff0000u), __uint_as_float(r.w << 16), __uint_as_float(r.w & 0xffff0000u)}; }
;                     const f32x4 o0 = b0 + gv[bj][0] * acc[ai][bj][m][0], o1 = b1 + gv[bj][1] * acc[ai][bj][m][1];
;                     u32x4 w; w.x = cvt_pk_bf16(o0[0], o0[1]); w.y = cvt_pk_bf16(o0[2], o0[3]); w.z = cvt_pk_bf16(o1[0], o1[1]); w.w = cvt_pk_bf16(o1[2], o1[3]);
;                     *(u32x4*)(hrow + bj * HALF) = w;
;                     sq += ((o0[0] * o0[0] + o0[1] * o0[1]) + (o0[2] * o0[2] + o0[3] * o0[3])) + ((o1[0] * o1[0] + o1[1] * o1[1]) + (o1[2] * o1[2] + o1[3] * o1[3]));
;                     if (hb) { const f32x4 y0 = o0 * wv[bj][0], y1 = o1 * wv[bj][1]; u32x4 z; z.x = cvt_pk_bf16(y0[0], y0[1]); z.y = cvt_pk_bf16(y0[2], y0[3]); z.z = cvt_pk_bf16(y1[0], y1[1]); z.w = cvt_pk_bf16(y1[2], y1[3]);
;                         *(u32x4*)(hb + (size_t)rowt * DM + off + bj * HALF) = z; } }
.LBB0_1912:
	s_or_b64 exec, exec, s[58:59]
	s_waitcnt lgkmcnt(0)
	v_lshlrev_b64 v[32:33], 10, v[112:113]
	s_waitcnt vmcnt(7)
	v_lshlrev_b32_e32 v34, 16, v92
	v_and_b32_e32 v35, 0xffff0000, v92
	v_lshlrev_b32_e32 v36, 16, v93
	v_and_b32_e32 v37, 0xffff0000, v93
	v_lshlrev_b32_e32 v38, 16, v94
	v_and_b32_e32 v39, 0xffff0000, v94
	v_lshlrev_b32_e32 v40, 16, v95
	v_and_b32_e32 v41, 0xffff0000, v95
	v_lshl_add_u64 v[32:33], v[32:33], 0, v[196:197]
	v_pk_fma_f32 v[30:31], v[30:31], v[70:71], v[36:37]
	v_pk_fma_f32 v[28:29], v[28:29], v[68:69], v[34:35]
	v_pk_fma_f32 v[26:27], v[26:27], v[78:79], v[40:41]
	v_pk_fma_f32 v[24:25], v[24:25], v[76:77], v[38:39]
	s_and_b64 vcc, exec, s[40:41]
	v_cvt_pk_bf16_f32 v34, v28, v29
	v_cvt_pk_bf16_f32 v35, v30, v31
	v_cvt_pk_bf16_f32 v36, v24, v25
	v_cvt_pk_bf16_f32 v37, v26, v27
	global_store_dwordx4 v[114:115], v[34:37], off sc1
	s_cbranch_vccnz .LBB0_1914
	s_lshl_b64 s[52:53], s[56:57], 1
	s_add_u32 s52, s63, s52
	v_pk_mul_f32 v[36:37], v[188:189], v[30:31]
	v_pk_mul_f32 v[34:35], v[186:187], v[28:29]
	v_pk_mul_f32 v[38:39], v[198:199], v[26:27]
	s_addc_u32 s53, s64, s53
	v_pk_mul_f32 v[40:41], v[194:195], v[24:25]
	v_cvt_pk_bf16_f32 v34, v34, v35
	v_cvt_pk_bf16_f32 v35, v36, v37
	s_nop 0
	v_cvt_pk_bf16_f32 v36, v40, v41
	v_cvt_pk_bf16_f32 v37, v38, v39
	v_lshl_add_u64 v[38:39], v[32:33], 1, s[52:53]
	global_store_dwordx4 v[38:39], v[34:37], off sc1
.LBB0_1914:
	s_waitcnt vmcnt(7)
	s_nop 0
	v_lshlrev_b32_e32 v34, 16, v88
	v_and_b32_e32 v35, 0xffff0000, v88
	v_lshlrev_b32_e32 v36, 16, v89
	v_and_b32_e32 v37, 0xffff0000, v89
	v_lshlrev_b32_e32 v38, 16, v90
	v_and_b32_e32 v39, 0xffff0000, v90
	v_lshlrev_b32_e32 v40, 16, v91
	v_and_b32_e32 v41, 0xffff0000, v91
	v_pk_fma_f32 v[22:23], v[22:23], v[66:67], v[36:37]
	v_pk_fma_f32 v[20:21], v[20:21], v[64:65], v[34:35]
	v_pk_fma_f32 v[18:19], v[18:19], v[74:75], v[40:41]
	v_pk_fma_f32 v[16:17], v[16:17], v[72:73], v[38:39]
	s_and_b64 vcc, exec, s[40:41]
	v_cvt_pk_bf16_f32 v34, v20, v21
	v_cvt_pk_bf16_f32 v35, v22, v23
	v_cvt_pk_bf16_f32 v36, v16, v17
	v_cvt_pk_bf16_f32 v37, v18, v19
	global_store_dwordx4 v[114:115], v[34:37], off offset:256 sc1
	s_cbranch_vccnz .LBB0_1916
	s_lshl_b64 s[52:53], s[56:57], 1
	s_add_u32 s52, s63, s52
	s_addc_u32 s53, s64, s53
	v_pk_mul_f32 v[36:37], v[184:185], v[22:23]
	v_pk_mul_f32 v[34:35], v[182:183], v[20:21]
	v_lshl_add_u64 v[32:33], v[32:33], 1, s[52:53]
	v_pk_mul_f32 v[38:39], v[192:193], v[18:19]
	v_pk_mul_f32 v[40:41], v[190:191], v[16:17]
	v_cvt_pk_bf16_f32 v34, v34, v35
	v_cvt_pk_bf16_f32 v35, v36, v37
	s_nop 0
	v_cvt_pk_bf16_f32 v36, v40, v41
	v_cvt_pk_bf16_f32 v37, v38, v39
	global_store_dwordx4 v[32:33], v[34:37], off offset:256 sc1

; __device__ __forceinline__ unsigned cvt_pk_bf16(float lo, float hi) { unsigned r; asm volatile("v_cvt_pk_bf16_f32 %0, %1, %2" : "=v"(r) : "v"(lo), "v"(hi)); return r; }
;     __device__ __forceinline__ void operator()(const f32x4 (&acc)[2][2][4][2], const Unit& u, int wr, int wc, int fr, int fq) const {
;     ...
;             for (int m = 0; m < 4; ++m) { const int rl = wr * 64 + fr + ai * HALF + m * 16; const size_t off = (size_t)rl * DM + col0; float sq = 0.f;
;                 bf16_t* hrow = h16 + (size_t)rowt * DM + off;
; #pragma unroll
;                 for (int bj = 0; bj < 2; ++bj) { f32x4 b0, b1;
;                     if (bb) { b0 = *(const f32x4*)(bb + off + bj * HALF); b1 = *(const f32x4*)(bb + off + bj * HALF + 4); }
;                     else { const u32x4 r = raw[m][bj];
;                         b0 = (f32x4){__uint_as_float(r.x << 16), __uint_as_float(r.x & 0xffff0000u), __uint_as_float(r.y << 16), __uint_as_float(r.y & 0xffff0000u)};
;                         b1 = (f32x4){__uint_as_float(r.z << 16), __uint_as_float(r.z & 0xffff0000u), __uint_as_float(r.w << 16), __uint_as_float(r.w & 0xffff0000u)}; }
;                     const f32x4 o0 = b0 + gv[bj][0] * acc[ai][bj][m][0], o1 = b1 + gv[bj][1] * acc[ai][bj][m][1];
;                     u32x4 w; w.x = cvt_pk_bf16(o0[0], o0[1]); w.y = cvt_pk_bf16(o0[2], o0[3]); w.z = cvt_pk_bf16(o1[0], o1[1]); w.w = cvt_pk_bf16(o1[2], o1[3]);
;                     *(u32x4*)(hrow + bj * HALF) = w;
;                     sq += ((o0[0] * o0[0] + o0[1] * o0[1]) + (o0[2] * o0[2] + o0[3] * o0[3])) + ((o1[0] * o1[0] + o1[1] * o1[1]) + (o1[2] * o1[2] + o1[3] * o1[3]));
;                     if (hb) { const f32x4 y0 = o0 * wv[bj][0], y1 = o1 * wv[bj][1]; u32x4 z; z.x = cvt_pk_bf16(y0[0], y0[1]); z.y = cvt_pk_bf16(y0[2], y0[3]); z.z = cvt_pk_bf16(y1[0], y1[1]); z.w = cvt_pk_bf16(y1[2], y1[3]);
;                         *(u32x4*)(hb + (size_t)rowt * DM + off + bj * HALF) = z; } }
.LBB0_1918:
	s_or_b64 exec, exec, s[58:59]
	s_waitcnt lgkmcnt(0)
	v_lshlrev_b64 v[16:17], 10, v[108:109]
	s_waitcnt vmcnt(7)
	v_lshlrev_b32_e32 v18, 16, v84
	v_and_b32_e32 v19, 0xffff0000, v84
	v_lshlrev_b32_e32 v20, 16, v85
	v_and_b32_e32 v21, 0xffff0000, v85
	v_lshlrev_b32_e32 v22, 16, v86
	v_and_b32_e32 v23, 0xffff0000, v86
	v_lshlrev_b32_e32 v24, 16, v87
	v_and_b32_e32 v25, 0xffff0000, v87
	v_lshl_add_u64 v[16:17], v[16:17], 0, v[196:197]
	v_pk_fma_f32 v[14:15], v[14:15], v[70:71], v[20:21]
	v_pk_fma_f32 v[12:13], v[12:13], v[68:69], v[18:19]
	v_pk_fma_f32 v[10:11], v[10:11], v[78:79], v[24:25]
	v_pk_fma_f32 v[8:9], v[8:9], v[76:77], v[22:23]
	s_and_b64 vcc, exec, s[40:41]
	v_cvt_pk_bf16_f32 v18, v12, v13
	v_cvt_pk_bf16_f32 v19, v14, v15
	v_cvt_pk_bf16_f32 v20, v8, v9
	v_cvt_pk_bf16_f32 v21, v10, v11
	global_store_dwordx4 v[110:111], v[18:21], off sc1
	s_cbranch_vccnz .LBB0_1920
	s_lshl_b64 s[52:53], s[56:57], 1
	s_add_u32 s52, s63, s52
	v_pk_mul_f32 v[20:21], v[188:189], v[14:15]
	v_pk_mul_f32 v[18:19], v[186:187], v[12:13]
	v_pk_mul_f32 v[22:23], v[198:199], v[10:11]
	s_addc_u32 s53, s64, s53
	v_pk_mul_f32 v[24:25], v[194:195], v[8:9]
	v_cvt_pk_bf16_f32 v18, v18, v19
	v_cvt_pk_bf16_f32 v19, v20, v21
	s_nop 0
	v_cvt_pk_bf16_f32 v20, v24, v25
	v_cvt_pk_bf16_f32 v21, v22, v23
	v_lshl_add_u64 v[22:23], v[16:17], 1, s[52:53]
	global_store_dwordx4 v[22:23], v[18:21], off sc1
.LBB0_1920:
	s_waitcnt vmcnt(7)
	s_nop 0
	v_lshlrev_b32_e32 v18, 16, v80
	v_and_b32_e32 v19, 0xffff0000, v80
	v_lshlrev_b32_e32 v20, 16, v81
	v_and_b32_e32 v21, 0xffff0000, v81
	v_lshlrev_b32_e32 v22, 16, v82
	v_and_b32_e32 v23, 0xffff0000, v82
	v_lshlrev_b32_e32 v24, 16, v83
	v_and_b32_e32 v25, 0xffff0000, v83
	v_pk_fma_f32 v[6:7], v[6:7], v[66:67], v[20:21]
	v_pk_fma_f32 v[4:5], v[4:5], v[64:65], v[18:19]
	v_pk_fma_f32 v[2:3], v[2:3], v[74:75], v[24:25]
	v_pk_fma_f32 v[0:1], v[0:1], v[72:73], v[22:23]
	s_and_b64 vcc, exec, s[40:41]
	v_cvt_pk_bf16_f32 v18, v4, v5
	v_cvt_pk_bf16_f32 v19, v6, v7
	v_cvt_pk_bf16_f32 v20, v0, v1
	v_cvt_pk_bf16_f32 v21, v2, v3
	global_store_dwordx4 v[110:111], v[18:21], off offset:256 sc1
	s_cbranch_vccnz .LBB0_1922
	s_lshl_b64 s[40:41], s[56:57], 1
	s_add_u32 s40, s63, s40
	s_addc_u32 s41, s64, s41
	v_pk_mul_f32 v[20:21], v[184:185], v[6:7]
	v_pk_mul_f32 v[18:19], v[182:183], v[4:5]
	v_lshl_add_u64 v[16:17], v[16:17], 1, s[40:41]
	v_pk_mul_f32 v[22:23], v[192:193], v[2:3]
	v_pk_mul_f32 v[24:25], v[190:191], v[0:1]
	v_cvt_pk_bf16_f32 v18, v18, v19
	v_cvt_pk_bf16_f32 v19, v20, v21
	s_nop 0
	v_cvt_pk_bf16_f32 v20, v24, v25
	v_cvt_pk_bf16_f32 v21, v22, v23
	global_store_dwordx4 v[16:17], v[18:21], off offset:256 sc1

;     __device__ __forceinline__ void operator()(const f32x4 (&acc)[2][2][4][2], const Unit& u, int wr, int wc, int fr, int fq) const {
;     ...
;         const int rowt = u.pm * BM, b = rowt >= MLAT ? 2 : (rowt >> 13);
;         const float* gp = gate + b * 6144; const int col0 = u.pn * BM + wc * 32 + 8 * fq;
;         f32x4 gv[2][2], wv[2][2];
; #pragma unroll
;         for (int bj = 0; bj < 2; ++bj)
; #pragma unroll
;             for (int n = 0; n < 2; ++n) { gv[bj][n] = *(const f32x4*)(gp + col0 + bj * HALF + n * 4); if (cs) gv[bj][n] = gv[bj][n] * *(const f32x4*)(cs + col0 + bj * HALF + n * 4);
;                 if (hb) wv[bj][n] = *(const f32x4*)(wn_g + col0 + bj * HALF + n * 4) * (*(const f32x4*)(wn_sc + b * 6144 + col0 + bj * HALF + n * 4) + 1.0f); }
;         const float* bb = base_lat ? (rowt >= MLAT ? base_ctx + (size_t)(rowt - MLAT) * DM : base_lat + (size_t)rowt * DM) : nullptr;
; #pragma unroll
;         for (int ai = 0; ai < 2; ++ai) {
;             u32x4 raw[4][2];
; #pragma unroll
;             for (int m = 0; m < 4; ++m)
; #pragma unroll
;                 for (int bj = 0; bj < 2; ++bj) raw[m][bj] = *(const u32x4*)(h16 + (size_t)rowt * DM + (size_t)(wr * 64 + fr + ai * HALF + m * 16) * DM + col0 + bj * HALF);
; #pragma unroll
;             for (int m = 0; m < 4; ++m) { const int rl = wr * 64 + fr + ai * HALF + m * 16; const size_t off = (size_t)rl * DM + col0; float sq = 0.f;
;                 bf16_t* hrow = h16 + (size_t)rowt * DM + off;
; #pragma unroll
;                 for (int bj = 0; bj < 2; ++bj) { f32x4 b0, b1;
;                     if (bb) { b0 = *(const f32x4*)(bb + off + bj * HALF); b1 = *(const f32x4*)(bb + off + bj * HALF + 4); }
;                     else { const u32x4 r = raw[m][bj];
;                         b0 = (f32x4){__uint_as_float(r.x << 16), __uint_as_float(r.x & 0xffff0000u), __uint_as_float(r.y << 16), __uint_as_float(r.y & 0xffff0000u)};
;                         b1 = (f32x4){__uint_as_float(r.z << 16), __uint_as_float(r.z & 0xffff0000u), __uint_as_float(r.w << 16), __uint_as_float(r.w & 0xffff0000u)}; }
;                     const f32x4 o0 = b0 + gv[bj][0] * acc[ai][bj][m][0], o1 = b1 + gv[bj][1] * acc[ai][bj][m][1];
;                     u32x4 w; w.x = cvt_pk_bf16(o0[0], o0[1]); w.y = cvt_pk_bf16(o0[2], o0[3]); w.z = cvt_pk_bf16(o1[0], o1[1]); w.w = cvt_pk_bf16(o1[2], o1[3]);
.LBB0_1963:
	s_lshr_b32 s3, s40, 5
	s_mul_i32 s16, s3, 0x1800
	s_ashr_i32 s17, s16, 31
	s_lshl_b64 s[16:17], s[16:17], 2
	s_add_u32 s20, s76, s16
	s_addc_u32 s21, s77, s17
	s_lshl_b32 s3, s2, 8
	v_mov_b32_e32 v160, v229
	v_mov_b32_e32 v161, v230
	s_or_b32 s3, s3, s88
	s_add_u32 s16, s80, s16
	v_lshl_add_u32 v198, v161, 3, s3
	v_ashrrev_i32_e32 v199, 31, v198
	v_lshlrev_b64 v[88:89], 2, v[198:199]
	v_lshl_add_u64 v[152:153], s[20:21], 0, v[88:89]
	s_addc_u32 s17, s81, s17
	v_lshl_add_u64 v[154:155], s[12:13], 0, v[88:89]
	v_lshl_add_u64 v[156:157], s[16:17], 0, v[88:89]
	global_load_dwordx4 v[104:107], v[152:153], off offset:16
	global_load_dwordx4 v[108:111], v[152:153], off
	global_load_dwordx4 v[88:91], v[154:155], off offset:16
	global_load_dwordx4 v[92:95], v[154:155], off
	global_load_dwordx4 v[144:147], v[156:157], off offset:16
	global_load_dwordx4 v[148:151], v[156:157], off
	s_ashr_i32 s57, s56, 31
	s_lshl_b64 s[40:41], s[56:57], 11
	v_add_u32_e32 v200, s87, v160
	s_add_u32 s16, s73, s40
	s_addc_u32 s17, s75, s41
	v_ashrrev_i32_e32 v201, 31, v200
	v_add_u32_e32 v220, 16, v200
	v_lshl_add_u64 v[202:203], v[198:199], 1, s[16:17]
	v_ashrrev_i32_e32 v221, 31, v220
	v_add_u32_e32 v208, 32, v200
	v_ashrrev_i32_e32 v209, 31, v208
	v_add_u32_e32 v204, 48, v200
	v_ashrrev_i32_e32 v205, 31, v204
	v_lshlrev_b64 v[216:217], 10, v[200:201]
	v_cmp_eq_u32_e32 vcc, 0, v161
	v_lshl_add_u64 v[226:227], v[216:217], 0, v[198:199]
	s_add_u32 s58, s78, s40
	s_addc_u32 s59, s79, s41
	s_waitcnt vmcnt(0)
	v_pk_add_f32 v[150:151], v[150:151], 1.0 op_sel_hi:[1,0]
	v_pk_add_f32 v[148:149], v[148:149], 1.0 op_sel_hi:[1,0]
	v_pk_mul_f32 v[192:193], v[94:95], v[150:151]
	v_pk_mul_f32 v[196:197], v[92:93], v[148:149]
	v_pk_add_f32 v[92:93], v[146:147], 1.0 op_sel_hi:[1,0]
	v_pk_add_f32 v[94:95], v[144:145], 1.0 op_sel_hi:[1,0]
	v_pk_mul_f32 v[190:191], v[90:91], v[92:93]
	v_pk_mul_f32 v[194:195], v[88:89], v[94:95]
	global_load_dwordx4 v[88:91], v[152:153], off offset:528
	global_load_dwordx4 v[92:95], v[152:153], off offset:512
	global_load_dwordx4 v[144:147], v[154:155], off offset:528
	global_load_dwordx4 v[148:151], v[154:155], off offset:512
	s_nop 0
	global_load_dwordx4 v[152:155], v[156:157], off offset:528
	s_nop 0
	global_load_dwordx4 v[156:159], v[156:157], off offset:512
	s_waitcnt vmcnt(0)
	v_pk_add_f32 v[158:159], v[158:159], 1.0 op_sel_hi:[1,0]
	s_nop 0
	v_pk_mul_f32 v[188:189], v[150:151], v[158:159]
	v_pk_add_f32 v[150:151], v[152:153], 1.0 op_sel_hi:[1,0]
	v_pk_add_f32 v[156:157], v[156:157], 1.0 op_sel_hi:[1,0]
	v_pk_mul_f32 v[186:187], v[144:145], v[150:151]
	v_lshlrev_b64 v[144:145], 11, v[200:201]
	v_lshl_add_u64 v[224:225], v[202:203], 0, v[144:145]
	v_lshlrev_b64 v[144:145], 11, v[220:221]
	v_lshl_add_u64 v[222:223], v[202:203], 0, v[144:145]
	v_lshlrev_b64 v[144:145], 11, v[208:209]
	v_lshl_add_u64 v[210:211], v[202:203], 0, v[144:145]
	v_lshlrev_b64 v[144:145], 11, v[204:205]
	v_pk_mul_f32 v[182:183], v[148:149], v[156:157]
	v_pk_add_f32 v[148:149], v[154:155], 1.0 op_sel_hi:[1,0]
	v_lshl_add_u64 v[206:207], v[202:203], 0, v[144:145]
	v_pk_mul_f32 v[184:185], v[146:147], v[148:149]
	global_load_dwordx4 v[168:171], v[224:225], off offset:256
	global_load_dwordx4 v[164:167], v[222:223], off
	global_load_dwordx4 v[160:163], v[222:223], off offset:256
	global_load_dwordx4 v[156:159], v[210:211], off
	global_load_dwordx4 v[152:155], v[210:211], off offset:256
	global_load_dwordx4 v[148:151], v[206:207], off
	global_load_dwordx4 v[144:147], v[206:207], off offset:256
	global_load_dwordx4 v[216:219], v[224:225], off
	s_waitcnt vmcnt(0)
	v_lshlrev_b32_e32 v234, 16, v216
	v_and_b32_e32 v235, 0xffff0000, v216
	v_lshlrev_b32_e32 v216, 16, v217
	v_and_b32_e32 v217, 0xffff0000, v217
	v_lshlrev_b32_e32 v236, 16, v218
	v_and_b32_e32 v237, 0xffff0000, v218
	v_lshlrev_b32_e32 v218, 16, v219
	v_and_b32_e32 v219, 0xffff0000, v219
	v_pk_fma_f32 v[142:143], v[142:143], v[110:111], v[216:217]
	v_pk_fma_f32 v[140:141], v[140:141], v[108:109], v[234:235]
	v_pk_fma_f32 v[216:217], v[138:139], v[106:107], v[218:219]
	v_pk_fma_f32 v[218:219], v[136:137], v[104:105], v[236:237]
	v_cvt_pk_bf16_f32 v136, v140, v141
	v_cvt_pk_bf16_f32 v137, v142, v143
	s_nop 0
	v_cvt_pk_bf16_f32 v138, v218, v219
	v_cvt_pk_bf16_f32 v139, v216, v217
	global_store_dwordx4 v[224:225], v[136:139], off sc1
	s_nop 1
	v_mul_f32_e32 v136, v141, v141
	v_mul_f32_e32 v137, v143, v143
	v_fmac_f32_e32 v136, v140, v140
	v_fmac_f32_e32 v137, v142, v142
	v_add_f32_e32 v136, v136, v137
	v_mul_f32_e32 v137, v219, v219
	v_mul_f32_e32 v138, v217, v217
	v_fmac_f32_e32 v137, v218, v218
	v_fmac_f32_e32 v138, v216, v216
	v_add_f32_e32 v137, v137, v138
	v_add_f32_e32 v201, v136, v137
	v_pk_mul_f32 v[138:139], v[192:193], v[142:143]
	v_pk_mul_f32 v[136:137], v[196:197], v[140:141]
	v_pk_mul_f32 v[140:141], v[190:191], v[216:217]
	v_pk_mul_f32 v[142:143], v[194:195], v[218:219]
	v_cvt_pk_bf16_f32 v136, v136, v137
	v_cvt_pk_bf16_f32 v137, v138, v139
	s_nop 0
	v_cvt_pk_bf16_f32 v138, v142, v143
	v_cvt_pk_bf16_f32 v139, v140, v141
	v_lshl_add_u64 v[140:141], v[226:227], 1, s[58:59]
	global_store_dwordx4 v[140:141], v[136:139], off sc1
	v_lshlrev_b32_e32 v142, 16, v170
	v_and_b32_e32 v143, 0xffff0000, v170
	v_lshlrev_b32_e32 v136, 16, v168
	v_and_b32_e32 v137, 0xffff0000, v168
	v_lshlrev_b32_e32 v138, 16, v169
	v_and_b32_e32 v139, 0xffff0000, v169
	v_lshlrev_b32_e32 v168, 16, v171
	v_and_b32_e32 v169, 0xffff0000, v171
	v_pk_fma_f32 v[134:135], v[134:135], v[94:95], v[138:139]
	v_pk_fma_f32 v[132:133], v[132:133], v[92:93], v[136:137]
	v_pk_fma_f32 v[138:139], v[128:129], v[88:89], v[142:143]
	v_cvt_pk_bf16_f32 v128, v132, v133
; __device__ __forceinline__ unsigned cvt_pk_bf16(float lo, float hi) { unsigned r; asm volatile("v_cvt_pk_bf16_f32 %0, %1, %2" : "=v"(r) : "v"(lo), "v"(hi)); return r; }
;     __device__ __forceinline__ void operator()(const f32x4 (&acc)[2][2][4][2], const Unit& u, int wr, int wc, int fr, int fq) const {
;     ...
;                 for (int bj = 0; bj < 2; ++bj) { f32x4 b0, b1;
;                     if (bb) { b0 = *(const f32x4*)(bb + off + bj * HALF); b1 = *(const f32x4*)(bb + off + bj * HALF + 4); }
;                     else { const u32x4 r = raw[m][bj];
;                         b0 = (f32x4){__uint_as_float(r.x << 16), __uint_as_float(r.x & 0xffff0000u), __uint_as_float(r.y << 16), __uint_as_float(r.y & 0xffff0000u)};
;                         b1 = (f32x4){__uint_as_float(r.z << 16), __uint_as_float(r.z & 0xffff0000u), __uint_as_float(r.w << 16), __uint_as_float(r.w & 0xffff0000u)}; }
;                     const f32x4 o0 = b0 + gv[bj][0] * acc[ai][bj][m][0], o1 = b1 + gv[bj][1] * acc[ai][bj][m][1];
;                     u32x4 w; w.x = cvt_pk_bf16(o0[0], o0[1]); w.y = cvt_pk_bf16(o0[2], o0[3]); w.z = cvt_pk_bf16(o1[0], o1[1]); w.w = cvt_pk_bf16(o1[2], o1[3]);
;                     *(u32x4*)(hrow + bj * HALF) = w;
;                     sq += ((o0[0] * o0[0] + o0[1] * o0[1]) + (o0[2] * o0[2] + o0[3] * o0[3])) + ((o1[0] * o1[0] + o1[1] * o1[1]) + (o1[2] * o1[2] + o1[3] * o1[3]));
;                     if (hb) { const f32x4 y0 = o0 * wv[bj][0], y1 = o1 * wv[bj][1]; u32x4 z; z.x = cvt_pk_bf16(y0[0], y0[1]); z.y = cvt_pk_bf16(y0[2], y0[3]); z.z = cvt_pk_bf16(y1[0], y1[1]); z.w = cvt_pk_bf16(y1[2], y1[3]);
;                         *(u32x4*)(hb + (size_t)rowt * DM + off + bj * HALF) = z; } }
;                 if (ssq) { sq += __shfl_xor(sq, 16); sq += __shfl_xor(sq, 32); if (fq == 0) ssq[(size_t)(rowt + rl) * 16 + u.pn * 4 + wc] = sq; } }
	v_cvt_pk_bf16_f32 v129, v134, v135
	v_pk_fma_f32 v[136:137], v[130:131], v[90:91], v[168:169]
	v_cvt_pk_bf16_f32 v130, v138, v139
	s_nop 0
	v_cvt_pk_bf16_f32 v131, v136, v137
	global_store_dwordx4 v[224:225], v[128:131], off offset:256 sc1
	s_nop 1
	v_mul_f32_e32 v128, v133, v133
	v_mul_f32_e32 v129, v135, v135
	v_fmac_f32_e32 v128, v132, v132
	v_fmac_f32_e32 v129, v134, v134
	v_add_f32_e32 v128, v128, v129
	v_mul_f32_e32 v129, v139, v139
	v_mul_f32_e32 v130, v137, v137
	v_fmac_f32_e32 v129, v138, v138
	v_fmac_f32_e32 v130, v136, v136
	v_add_f32_e32 v129, v129, v130
	v_add_f32_e32 v128, v128, v129
	v_add_f32_e32 v142, v128, v201
	v_pk_mul_f32 v[128:129], v[182:183], v[132:133]
	v_pk_mul_f32 v[130:131], v[188:189], v[134:135]
	v_cvt_pk_bf16_f32 v128, v128, v129
	v_pk_mul_f32 v[132:133], v[184:185], v[136:137]
	v_cvt_pk_bf16_f32 v129, v130, v131
	v_pk_mul_f32 v[134:135], v[186:187], v[138:139]
	s_nop 0
	v_cvt_pk_bf16_f32 v130, v134, v135
	v_cvt_pk_bf16_f32 v131, v132, v133
	global_store_dwordx4 v[140:141], v[128:131], off offset:256 sc1
	s_nop 1
	v_and_b32_e32 v129, 64, v246
	v_xor_b32_e32 v128, 16, v246
	v_add_u32_e32 v129, 64, v129
	v_cmp_lt_i32_e64 s[40:41], v128, v129
	v_xor_b32_e32 v131, 32, v246
	s_nop 0
	v_cndmask_b32_e64 v128, v246, v128, s[40:41]
	v_lshlrev_b32_e32 v128, 2, v128
	ds_bpermute_b32 v130, v128, v142
	v_cmp_lt_i32_e64 s[40:41], v131, v129
	s_waitcnt lgkmcnt(0)
	v_add_f32_e32 v130, v142, v130
	v_cndmask_b32_e64 v129, v246, v131, s[40:41]
	v_lshlrev_b32_e32 v129, 2, v129
	ds_bpermute_b32 v131, v129, v130
	s_and_saveexec_b64 s[40:41], vcc
	s_cbranch_execz .LBB0_1965
	s_waitcnt lgkmcnt(0)
	v_add_f32_e32 v132, v130, v131
	v_add_u32_e32 v130, s56, v200
	v_ashrrev_i32_e32 v131, 31, v130
	s_lshl_b32 s16, s2, 2
	v_lshlrev_b64 v[130:131], 6, v[130:131]
	s_ashr_i32 s17, s16, 31
	v_lshl_add_u64 v[130:131], s[14:15], 0, v[130:131]
	v_lshl_add_u64 v[130:131], s[16:17], 2, v[130:131]
	s_lshl_b32 s8, s86, 2
	v_lshl_add_u64 v[130:131], v[130:131], 0, s[8:9]
	global_store_dword v[130:131], v132, off
.LBB0_1965:
	s_or_b64 exec, exec, s[40:41]
	v_lshlrev_b32_e32 v132, 16, v164
	v_and_b32_e32 v133, 0xffff0000, v164
	v_lshlrev_b32_e32 v134, 16, v165
	v_and_b32_e32 v135, 0xffff0000, v165
	v_lshlrev_b32_e32 v136, 16, v166
	v_and_b32_e32 v137, 0xffff0000, v166
	v_lshlrev_b32_e32 v138, 16, v167
	v_and_b32_e32 v139, 0xffff0000, v167
	v_pk_fma_f32 v[126:127], v[126:127], v[110:111], v[134:135]
	v_pk_fma_f32 v[124:125], v[124:125], v[108:109], v[132:133]
	v_pk_fma_f32 v[134:135], v[120:121], v[104:105], v[136:137]
	v_cvt_pk_bf16_f32 v120, v124, v125
	v_cvt_pk_bf16_f32 v121, v126, v127
	v_pk_fma_f32 v[132:133], v[122:123], v[106:107], v[138:139]
	v_cvt_pk_bf16_f32 v122, v134, v135
	s_waitcnt lgkmcnt(0)
	v_lshlrev_b64 v[130:131], 10, v[220:221]
	v_cvt_pk_bf16_f32 v123, v132, v133
	global_store_dwordx4 v[222:223], v[120:123], off sc1
	v_lshl_add_u64 v[130:131], v[130:131], 0, v[198:199]
	s_nop 0
	v_mul_f32_e32 v120, v125, v125
	v_mul_f32_e32 v121, v127, v127
	v_fmac_f32_e32 v120, v124, v124
	v_fmac_f32_e32 v121, v126, v126
	v_add_f32_e32 v120, v120, v121
	v_mul_f32_e32 v121, v135, v135
	v_mul_f32_e32 v122, v133, v133
	v_fmac_f32_e32 v121, v134, v134
	v_fmac_f32_e32 v122, v132, v132
	v_add_f32_e32 v121, v121, v122
	v_add_f32_e32 v136, v120, v121
	v_pk_mul_f32 v[122:123], v[192:193], v[126:127]
	v_pk_mul_f32 v[120:121], v[196:197], v[124:125]
	v_pk_mul_f32 v[124:125], v[190:191], v[132:133]
	v_pk_mul_f32 v[126:127], v[194:195], v[134:135]
	v_cvt_pk_bf16_f32 v120, v120, v121
	v_cvt_pk_bf16_f32 v121, v122, v123
	s_nop 0
	v_cvt_pk_bf16_f32 v122, v126, v127
	v_cvt_pk_bf16_f32 v123, v124, v125
	v_lshl_add_u64 v[124:125], v[130:131], 1, s[58:59]
	global_store_dwordx4 v[124:125], v[120:123], off sc1
	v_lshlrev_b32_e32 v126, 16, v162
	v_and_b32_e32 v127, 0xffff0000, v162
	v_lshlrev_b32_e32 v120, 16, v160
	v_and_b32_e32 v121, 0xffff0000, v160
	v_lshlrev_b32_e32 v122, 16, v161
	v_and_b32_e32 v123, 0xffff0000, v161
	v_lshlrev_b32_e32 v130, 16, v163
	v_and_b32_e32 v131, 0xffff0000, v163
	v_pk_fma_f32 v[118:119], v[118:119], v[94:95], v[122:123]
	v_pk_fma_f32 v[116:117], v[116:117], v[92:93], v[120:121]
	v_pk_fma_f32 v[122:123], v[112:113], v[88:89], v[126:127]
	v_cvt_pk_bf16_f32 v112, v116, v117
	v_cvt_pk_bf16_f32 v113, v118, v119
	v_pk_fma_f32 v[120:121], v[114:115], v[90:91], v[130:131]
	v_cvt_pk_bf16_f32 v114, v122, v123
	s_nop 0
	v_cvt_pk_bf16_f32 v115, v120, v121
	global_store_dwordx4 v[222:223], v[112:115], off offset:256 sc1
	s_nop 1
	v_mul_f32_e32 v112, v117, v117
	v_mul_f32_e32 v113, v119, v119
	v_fmac_f32_e32 v112, v116, v116
	v_fmac_f32_e32 v113, v118, v118
	v_add_f32_e32 v112, v112, v113
	v_mul_f32_e32 v113, v123, v123
	v_mul_f32_e32 v114, v121, v121
	v_fmac_f32_e32 v113, v122, v122
	v_fmac_f32_e32 v114, v120, v120
	v_add_f32_e32 v113, v113, v114
	v_add_f32_e32 v112, v112, v113
	v_add_f32_e32 v115, v136, v112
	ds_bpermute_b32 v126, v128, v115
	v_pk_mul_f32 v[112:113], v[182:183], v[116:117]
	v_pk_mul_f32 v[116:117], v[186:187], v[122:123]
	v_cvt_pk_bf16_f32 v114, v112, v113
	v_pk_mul_f32 v[118:119], v[188:189], v[118:119]
	s_waitcnt lgkmcnt(0)
	v_add_f32_e32 v112, v115, v126
	ds_bpermute_b32 v113, v129, v112
	v_pk_mul_f32 v[120:121], v[184:185], v[120:121]
	v_cvt_pk_bf16_f32 v115, v118, v119
	v_cvt_pk_bf16_f32 v116, v116, v117
	s_nop 0
	v_cvt_pk_bf16_f32 v117, v120, v121
	global_store_dwordx4 v[124:125], v[114:117], off offset:256 sc1
	s_and_saveexec_b64 s[40:41], vcc
	s_cbranch_execz .LBB0_1967
	s_waitcnt lgkmcnt(0)
	v_add_f32_e32 v114, v112, v113
	v_add_u32_e32 v112, s56, v220
	v_ashrrev_i32_e32 v113, 31, v112
	s_lshl_b32 s16, s2, 2
	v_lshlrev_b64 v[112:113], 6, v[112:113]
	s_ashr_i32 s17, s16, 31
	v_lshl_add_u64 v[112:113], s[14:15], 0, v[112:113]
	v_lshl_add_u64 v[112:113], s[16:17], 2, v[112:113]
	s_lshl_b32 s8, s86, 2
	v_lshl_add_u64 v[112:113], v[112:113], 0, s[8:9]
	global_store_dword v[112:113], v114, off
; __device__ __forceinline__ unsigned cvt_pk_bf16(float lo, float hi) { unsigned r; asm volatile("v_cvt_pk_bf16_f32 %0, %1, %2" : "=v"(r) : "v"(lo), "v"(hi)); return r; }
;     __device__ __forceinline__ void operator()(const f32x4 (&acc)[2][2][4][2], const Unit& u, int wr, int wc, int fr, int fq) const {
;     ...
;                 for (int bj = 0; bj < 2; ++bj) { f32x4 b0, b1;
;                     if (bb) { b0 = *(const f32x4*)(bb + off + bj * HALF); b1 = *(const f32x4*)(bb + off + bj * HALF + 4); }
;                     else { const u32x4 r = raw[m][bj];
;                         b0 = (f32x4){__uint_as_float(r.x << 16), __uint_as_float(r.x & 0xffff0000u), __uint_as_float(r.y << 16), __uint_as_float(r.y & 0xffff0000u)};
;                         b1 = (f32x4){__uint_as_float(r.z << 16), __uint_as_float(r.z & 0xffff0000u), __uint_as_float(r.w << 16), __uint_as_float(r.w & 0xffff0000u)}; }
;                     const f32x4 o0 = b0 + gv[bj][0] * acc[ai][bj][m][0], o1 = b1 + gv[bj][1] * acc[ai][bj][m][1];
;                     u32x4 w; w.x = cvt_pk_bf16(o0[0], o0[1]); w.y = cvt_pk_bf16(o0[2], o0[3]); w.z = cvt_pk_bf16(o1[0], o1[1]); w.w = cvt_pk_bf16(o1[2], o1[3]);
;                     *(u32x4*)(hrow + bj * HALF) = w;
;                     sq += ((o0[0] * o0[0] + o0[1] * o0[1]) + (o0[2] * o0[2] + o0[3] * o0[3])) + ((o1[0] * o1[0] + o1[1] * o1[1]) + (o1[2] * o1[2] + o1[3] * o1[3]));
;                     if (hb) { const f32x4 y0 = o0 * wv[bj][0], y1 = o1 * wv[bj][1]; u32x4 z; z.x = cvt_pk_bf16(y0[0], y0[1]); z.y = cvt_pk_bf16(y0[2], y0[3]); z.z = cvt_pk_bf16(y1[0], y1[1]); z.w = cvt_pk_bf16(y1[2], y1[3]);
;                         *(u32x4*)(hb + (size_t)rowt * DM + off + bj * HALF) = z; } }
;                 if (ssq) { sq += __shfl_xor(sq, 16); sq += __shfl_xor(sq, 32); if (fq == 0) ssq[(size_t)(rowt + rl) * 16 + u.pn * 4 + wc] = sq; } }
.LBB0_1967:
	s_or_b64 exec, exec, s[40:41]
	v_lshlrev_b32_e32 v114, 16, v156
	v_and_b32_e32 v115, 0xffff0000, v156
	v_lshlrev_b32_e32 v116, 16, v157
	v_and_b32_e32 v117, 0xffff0000, v157
	v_lshlrev_b32_e32 v118, 16, v158
	v_and_b32_e32 v119, 0xffff0000, v158
	v_lshlrev_b32_e32 v120, 16, v159
	v_and_b32_e32 v121, 0xffff0000, v159
	v_pk_fma_f32 v[102:103], v[102:103], v[110:111], v[116:117]
	v_pk_fma_f32 v[100:101], v[100:101], v[108:109], v[114:115]
	v_pk_fma_f32 v[116:117], v[96:97], v[104:105], v[118:119]
	v_cvt_pk_bf16_f32 v96, v100, v101
	v_cvt_pk_bf16_f32 v97, v102, v103
	v_pk_fma_f32 v[114:115], v[98:99], v[106:107], v[120:121]
	v_cvt_pk_bf16_f32 v98, v116, v117
	s_waitcnt lgkmcnt(0)
	v_lshlrev_b64 v[112:113], 10, v[208:209]
	v_cvt_pk_bf16_f32 v99, v114, v115
	global_store_dwordx4 v[210:211], v[96:99], off sc1
	v_lshl_add_u64 v[112:113], v[112:113], 0, v[198:199]
	s_nop 0
	v_mul_f32_e32 v96, v101, v101
	v_mul_f32_e32 v97, v103, v103
	v_fmac_f32_e32 v96, v100, v100
	v_fmac_f32_e32 v97, v102, v102
	v_add_f32_e32 v96, v96, v97
	v_mul_f32_e32 v97, v117, v117
	v_mul_f32_e32 v98, v115, v115
	v_fmac_f32_e32 v97, v116, v116
	v_fmac_f32_e32 v98, v114, v114
	v_add_f32_e32 v97, v97, v98
	v_add_f32_e32 v118, v96, v97
	v_pk_mul_f32 v[98:99], v[192:193], v[102:103]
	v_pk_mul_f32 v[96:97], v[196:197], v[100:101]
	v_pk_mul_f32 v[100:101], v[190:191], v[114:115]
	v_pk_mul_f32 v[102:103], v[194:195], v[116:117]
	v_cvt_pk_bf16_f32 v96, v96, v97
	v_cvt_pk_bf16_f32 v97, v98, v99
	s_nop 0
	v_cvt_pk_bf16_f32 v98, v102, v103
	v_cvt_pk_bf16_f32 v99, v100, v101
	v_lshl_add_u64 v[100:101], v[112:113], 1, s[58:59]
	global_store_dwordx4 v[100:101], v[96:99], off sc1
	v_lshlrev_b32_e32 v102, 16, v154
	v_and_b32_e32 v103, 0xffff0000, v154
	v_lshlrev_b32_e32 v96, 16, v152
	v_and_b32_e32 v97, 0xffff0000, v152
	v_lshlrev_b32_e32 v98, 16, v153
	v_and_b32_e32 v99, 0xffff0000, v153
	v_lshlrev_b32_e32 v112, 16, v155
	v_and_b32_e32 v113, 0xffff0000, v155
	v_pk_fma_f32 v[86:87], v[86:87], v[94:95], v[98:99]
	v_pk_fma_f32 v[84:85], v[84:85], v[92:93], v[96:97]
	v_pk_fma_f32 v[98:99], v[80:81], v[88:89], v[102:103]
	v_cvt_pk_bf16_f32 v80, v84, v85
	v_cvt_pk_bf16_f32 v81, v86, v87
	v_pk_fma_f32 v[96:97], v[82:83], v[90:91], v[112:113]
	v_cvt_pk_bf16_f32 v82, v98, v99
	s_nop 0
	v_cvt_pk_bf16_f32 v83, v96, v97
	global_store_dwordx4 v[210:211], v[80:83], off offset:256 sc1
	s_nop 1
	v_mul_f32_e32 v80, v85, v85
	v_mul_f32_e32 v81, v87, v87
	v_fmac_f32_e32 v80, v84, v84
	v_fmac_f32_e32 v81, v86, v86
	v_add_f32_e32 v80, v80, v81
	v_mul_f32_e32 v81, v99, v99
	v_mul_f32_e32 v82, v97, v97
	v_fmac_f32_e32 v81, v98, v98
	v_fmac_f32_e32 v82, v96, v96
	v_add_f32_e32 v81, v81, v82
	v_add_f32_e32 v80, v80, v81
	v_add_f32_e32 v83, v118, v80
	ds_bpermute_b32 v102, v128, v83
	v_pk_mul_f32 v[80:81], v[182:183], v[84:85]
	v_pk_mul_f32 v[84:85], v[186:187], v[98:99]
	v_cvt_pk_bf16_f32 v82, v80, v81
	v_pk_mul_f32 v[86:87], v[188:189], v[86:87]
	s_waitcnt lgkmcnt(0)
	v_add_f32_e32 v80, v83, v102
	ds_bpermute_b32 v81, v129, v80
	v_pk_mul_f32 v[96:97], v[184:185], v[96:97]
	v_cvt_pk_bf16_f32 v83, v86, v87
	v_cvt_pk_bf16_f32 v84, v84, v85
	s_nop 0
	v_cvt_pk_bf16_f32 v85, v96, v97
	global_store_dwordx4 v[100:101], v[82:85], off offset:256 sc1
	s_and_saveexec_b64 s[40:41], vcc
	s_cbranch_execz .LBB0_1969
	s_waitcnt lgkmcnt(0)
	v_add_f32_e32 v82, v80, v81
	v_add_u32_e32 v80, s56, v208
	v_ashrrev_i32_e32 v81, 31, v80
	s_lshl_b32 s16, s2, 2
	v_lshlrev_b64 v[80:81], 6, v[80:81]
	s_ashr_i32 s17, s16, 31
	v_lshl_add_u64 v[80:81], s[14:15], 0, v[80:81]
	v_lshl_add_u64 v[80:81], s[16:17], 2, v[80:81]
	s_lshl_b32 s8, s86, 2
	v_lshl_add_u64 v[80:81], v[80:81], 0, s[8:9]
	global_store_dword v[80:81], v82, off
.LBB0_1969:
	s_or_b64 exec, exec, s[40:41]
	v_lshlrev_b32_e32 v82, 16, v148
	v_and_b32_e32 v83, 0xffff0000, v148
	v_lshlrev_b32_e32 v84, 16, v149
	v_and_b32_e32 v85, 0xffff0000, v149
	v_lshlrev_b32_e32 v86, 16, v150
	v_and_b32_e32 v87, 0xffff0000, v150
	v_lshlrev_b32_e32 v96, 16, v151
	v_and_b32_e32 v97, 0xffff0000, v151
	v_pk_fma_f32 v[78:79], v[78:79], v[110:111], v[84:85]
	v_pk_fma_f32 v[76:77], v[76:77], v[108:109], v[82:83]
	v_pk_fma_f32 v[84:85], v[72:73], v[104:105], v[86:87]
	v_cvt_pk_bf16_f32 v72, v76, v77
	v_cvt_pk_bf16_f32 v73, v78, v79
	v_pk_fma_f32 v[82:83], v[74:75], v[106:107], v[96:97]
	v_cvt_pk_bf16_f32 v74, v84, v85
	s_waitcnt lgkmcnt(0)
	v_lshlrev_b64 v[80:81], 10, v[204:205]
	v_cvt_pk_bf16_f32 v75, v82, v83
	global_store_dwordx4 v[206:207], v[72:75], off sc1
	v_lshl_add_u64 v[80:81], v[80:81], 0, v[198:199]
	s_nop 0
	v_mul_f32_e32 v72, v77, v77
	v_mul_f32_e32 v73, v79, v79
	v_fmac_f32_e32 v72, v76, v76
	v_fmac_f32_e32 v73, v78, v78
	v_add_f32_e32 v72, v72, v73
	v_mul_f32_e32 v73, v85, v85
	v_mul_f32_e32 v74, v83, v83
	v_fmac_f32_e32 v73, v84, v84
	v_fmac_f32_e32 v74, v82, v82
	v_add_f32_e32 v73, v73, v74
	v_add_f32_e32 v86, v72, v73
	v_pk_mul_f32 v[74:75], v[192:193], v[78:79]
	v_pk_mul_f32 v[72:73], v[196:197], v[76:77]
	v_pk_mul_f32 v[76:77], v[190:191], v[82:83]
	v_pk_mul_f32 v[78:79], v[194:195], v[84:85]
	v_cvt_pk_bf16_f32 v72, v72, v73
	v_cvt_pk_bf16_f32 v73, v74, v75
	s_nop 0
	v_cvt_pk_bf16_f32 v74, v78, v79
	v_cvt_pk_bf16_f32 v75, v76, v77
	v_lshl_add_u64 v[76:77], v[80:81], 1, s[58:59]
	global_store_dwordx4 v[76:77], v[72:75], off sc1
	v_lshlrev_b32_e32 v78, 16, v146
	v_and_b32_e32 v79, 0xffff0000, v146
	v_lshlrev_b32_e32 v72, 16, v144
	v_and_b32_e32 v73, 0xffff0000, v144
	v_lshlrev_b32_e32 v74, 16, v145
	v_and_b32_e32 v75, 0xffff0000, v145
	v_lshlrev_b32_e32 v80, 16, v147
	v_and_b32_e32 v81, 0xffff0000, v147
	v_pk_fma_f32 v[70:71], v[70:71], v[94:95], v[74:75]
	v_pk_fma_f32 v[68:69], v[68:69], v[92:93], v[72:73]
	v_pk_fma_f32 v[74:75], v[64:65], v[88:89], v[78:79]
	v_cvt_pk_bf16_f32 v64, v68, v69
	v_cvt_pk_bf16_f32 v65, v70, v71
	v_pk_fma_f32 v[72:73], v[66:67], v[90:91], v[80:81]
	v_cvt_pk_bf16_f32 v66, v74, v75
	s_nop 0
	v_cvt_pk_bf16_f32 v67, v72, v73
	global_store_dwordx4 v[206:207], v[64:67], off offset:256 sc1
	s_nop 1
	v_mul_f32_e32 v64, v69, v69
	v_mul_f32_e32 v65, v71, v71
	v_fmac_f32_e32 v64, v68, v68
	v_fmac_f32_e32 v65, v70, v70
	v_add_f32_e32 v64, v64, v65
	v_mul_f32_e32 v65, v75, v75
	v_mul_f32_e32 v66, v73, v73
	v_fmac_f32_e32 v65, v74, v74
	v_fmac_f32_e32 v66, v72, v72
	v_add_f32_e32 v65, v65, v66
	v_add_f32_e32 v64, v64, v65
	v_add_f32_e32 v67, v86, v64
	ds_bpermute_b32 v78, v128, v67
	v_pk_mul_f32 v[64:65], v[182:183], v[68:69]
	v_pk_mul_f32 v[68:69], v[186:187], v[74:75]
	v_cvt_pk_bf16_f32 v66, v64, v65
	v_pk_mul_f32 v[70:71], v[188:189], v[70:71]
	s_waitcnt lgkmcnt(0)
	v_add_f32_e32 v64, v67, v78
	ds_bpermute_b32 v65, v129, v64
	v_pk_mul_f32 v[72:73], v[184:185], v[72:73]
	v_cvt_pk_bf16_f32 v67, v70, v71
	v_cvt_pk_bf16_f32 v68, v68, v69
	s_nop 0
	v_cvt_pk_bf16_f32 v69, v72, v73
	global_store_dwordx4 v[76:77], v[66:69], off offset:256 sc1
	s_and_saveexec_b64 s[40:41], vcc
	s_cbranch_execz .LBB0_1971
; __device__ __forceinline__ unsigned cvt_pk_bf16(float lo, float hi) { unsigned r; asm volatile("v_cvt_pk_bf16_f32 %0, %1, %2" : "=v"(r) : "v"(lo), "v"(hi)); return r; }
;     __device__ __forceinline__ void operator()(const f32x4 (&acc)[2][2][4][2], const Unit& u, int wr, int wc, int fr, int fq) const {
;     ...
;             for (int m = 0; m < 4; ++m)
; #pragma unroll
;                 for (int bj = 0; bj < 2; ++bj) raw[m][bj] = *(const u32x4*)(h16 + (size_t)rowt * DM + (size_t)(wr * 64 + fr + ai * HALF + m * 16) * DM + col0 + bj * HALF);
; #pragma unroll
;             for (int m = 0; m < 4; ++m) { const int rl = wr * 64 + fr + ai * HALF + m * 16; const size_t off = (size_t)rl * DM + col0; float sq = 0.f;
;                 bf16_t* hrow = h16 + (size_t)rowt * DM + off;
; #pragma unroll
;                 for (int bj = 0; bj < 2; ++bj) { f32x4 b0, b1;
;                     if (bb) { b0 = *(const f32x4*)(bb + off + bj * HALF); b1 = *(const f32x4*)(bb + off + bj * HALF + 4); }
;                     else { const u32x4 r = raw[m][bj];
;                         b0 = (f32x4){__uint_as_float(r.x << 16), __uint_as_float(r.x & 0xffff0000u), __uint_as_float(r.y << 16), __uint_as_float(r.y & 0xffff0000u)};
;                         b1 = (f32x4){__uint_as_float(r.z << 16), __uint_as_float(r.z & 0xffff0000u), __uint_as_float(r.w << 16), __uint_as_float(r.w & 0xffff0000u)}; }
;                     const f32x4 o0 = b0 + gv[bj][0] * acc[ai][bj][m][0], o1 = b1 + gv[bj][1] * acc[ai][bj][m][1];
;                     u32x4 w; w.x = cvt_pk_bf16(o0[0], o0[1]); w.y = cvt_pk_bf16(o0[2], o0[3]); w.z = cvt_pk_bf16(o1[0], o1[1]); w.w = cvt_pk_bf16(o1[2], o1[3]);
;                     *(u32x4*)(hrow + bj * HALF) = w;
;                     sq += ((o0[0] * o0[0] + o0[1] * o0[1]) + (o0[2] * o0[2] + o0[3] * o0[3])) + ((o1[0] * o1[0] + o1[1] * o1[1]) + (o1[2] * o1[2] + o1[3] * o1[3]));
;                     if (hb) { const f32x4 y0 = o0 * wv[bj][0], y1 = o1 * wv[bj][1]; u32x4 z; z.x = cvt_pk_bf16(y0[0], y0[1]); z.y = cvt_pk_bf16(y0[2], y0[3]); z.z = cvt_pk_bf16(y1[0], y1[1]); z.w = cvt_pk_bf16(y1[2], y1[3]);
;                         *(u32x4*)(hb + (size_t)rowt * DM + off + bj * HALF) = z; } }
;                 if (ssq) { sq += __shfl_xor(sq, 16); sq += __shfl_xor(sq, 32); if (fq == 0) ssq[(size_t)(rowt + rl) * 16 + u.pn * 4 + wc] = sq; } }
	s_waitcnt lgkmcnt(0)
	v_add_f32_e32 v66, v64, v65
	v_add_u32_e32 v64, s56, v204
	v_ashrrev_i32_e32 v65, 31, v64
	s_lshl_b32 s16, s2, 2
	v_lshlrev_b64 v[64:65], 6, v[64:65]
	s_ashr_i32 s17, s16, 31
	v_lshl_add_u64 v[64:65], s[14:15], 0, v[64:65]
	v_lshl_add_u64 v[64:65], s[16:17], 2, v[64:65]
	s_lshl_b32 s8, s86, 2
	v_lshl_add_u64 v[64:65], v[64:65], 0, s[8:9]
	global_store_dword v[64:65], v66, off
.LBB0_1971:
	s_or_b64 exec, exec, s[40:41]
	v_add_u32_e32 v120, 0x80, v200
	v_ashrrev_i32_e32 v121, 31, v120
	v_add_u32_e32 v116, 0x90, v200
	s_waitcnt lgkmcnt(0)
	v_lshlrev_b64 v[64:65], 11, v[120:121]
	v_ashrrev_i32_e32 v117, 31, v116
	v_add_u32_e32 v112, 0xa0, v200
	v_lshl_add_u64 v[122:123], v[202:203], 0, v[64:65]
	v_lshlrev_b64 v[64:65], 11, v[116:117]
	v_ashrrev_i32_e32 v113, 31, v112
	v_add_u32_e32 v100, 0xb0, v200
	v_lshl_add_u64 v[118:119], v[202:203], 0, v[64:65]
	v_lshlrev_b64 v[64:65], 11, v[112:113]
	v_ashrrev_i32_e32 v101, 31, v100
	v_lshl_add_u64 v[114:115], v[202:203], 0, v[64:65]
	v_lshlrev_b64 v[64:65], 11, v[100:101]
	v_lshl_add_u64 v[102:103], v[202:203], 0, v[64:65]
	global_load_dwordx4 v[96:99], v[122:123], off offset:256
	global_load_dwordx4 v[84:87], v[118:119], off
	global_load_dwordx4 v[80:83], v[118:119], off offset:256
	global_load_dwordx4 v[76:79], v[114:115], off
	global_load_dwordx4 v[72:75], v[114:115], off offset:256
	global_load_dwordx4 v[68:71], v[102:103], off
	global_load_dwordx4 v[64:67], v[102:103], off offset:256
	global_load_dwordx4 v[130:133], v[122:123], off
	v_lshlrev_b64 v[124:125], 10, v[120:121]
	v_lshl_add_u64 v[124:125], v[124:125], 0, v[198:199]
	s_waitcnt vmcnt(0)
	v_lshlrev_b32_e32 v126, 16, v130
	v_and_b32_e32 v127, 0xffff0000, v130
	v_lshlrev_b32_e32 v130, 16, v131
	v_and_b32_e32 v131, 0xffff0000, v131
	v_lshlrev_b32_e32 v134, 16, v132
	v_and_b32_e32 v135, 0xffff0000, v132
	v_lshlrev_b32_e32 v132, 16, v133
	v_and_b32_e32 v133, 0xffff0000, v133
	v_pk_fma_f32 v[130:131], v[62:63], v[110:111], v[130:131]
	v_pk_fma_f32 v[60:61], v[60:61], v[108:109], v[126:127]
	v_pk_fma_f32 v[126:127], v[58:59], v[106:107], v[132:133]
	v_pk_fma_f32 v[132:133], v[56:57], v[104:105], v[134:135]
	v_cvt_pk_bf16_f32 v56, v60, v61
	v_cvt_pk_bf16_f32 v57, v130, v131
	s_nop 0
	v_cvt_pk_bf16_f32 v58, v132, v133
	v_cvt_pk_bf16_f32 v59, v126, v127
	global_store_dwordx4 v[122:123], v[56:59], off sc1
	s_nop 1
	v_mul_f32_e32 v56, v61, v61
	v_mul_f32_e32 v57, v131, v131
	v_fmac_f32_e32 v56, v60, v60
	v_fmac_f32_e32 v57, v130, v130
	v_add_f32_e32 v56, v56, v57
	v_mul_f32_e32 v57, v133, v133
	v_mul_f32_e32 v58, v127, v127
	v_fmac_f32_e32 v57, v132, v132
	v_fmac_f32_e32 v58, v126, v126
	v_add_f32_e32 v57, v57, v58
	v_add_f32_e32 v62, v56, v57
	v_pk_mul_f32 v[58:59], v[192:193], v[130:131]
	v_pk_mul_f32 v[56:57], v[196:197], v[60:61]
	v_pk_mul_f32 v[60:61], v[190:191], v[126:127]
	v_pk_mul_f32 v[126:127], v[194:195], v[132:133]
	v_cvt_pk_bf16_f32 v56, v56, v57
	v_cvt_pk_bf16_f32 v57, v58, v59
	s_nop 0
	v_cvt_pk_bf16_f32 v58, v126, v127
	v_cvt_pk_bf16_f32 v59, v60, v61
	v_lshl_add_u64 v[60:61], v[124:125], 1, s[58:59]
	global_store_dwordx4 v[60:61], v[56:59], off sc1
	s_nop 1
	v_lshlrev_b32_e32 v56, 16, v96
	v_and_b32_e32 v57, 0xffff0000, v96
	v_lshlrev_b32_e32 v58, 16, v97
	v_and_b32_e32 v59, 0xffff0000, v97
	v_lshlrev_b32_e32 v96, 16, v98
	v_and_b32_e32 v97, 0xffff0000, v98
	v_lshlrev_b32_e32 v98, 16, v99
	v_and_b32_e32 v99, 0xffff0000, v99
	v_pk_fma_f32 v[54:55], v[54:55], v[94:95], v[58:59]
	v_pk_fma_f32 v[52:53], v[52:53], v[92:93], v[56:57]
	v_pk_fma_f32 v[58:59], v[48:49], v[88:89], v[96:97]
	v_cvt_pk_bf16_f32 v48, v52, v53
	v_cvt_pk_bf16_f32 v49, v54, v55
	v_pk_fma_f32 v[56:57], v[50:51], v[90:91], v[98:99]
	v_cvt_pk_bf16_f32 v50, v58, v59
	s_nop 0
	v_cvt_pk_bf16_f32 v51, v56, v57
	global_store_dwordx4 v[122:123], v[48:51], off offset:256 sc1
	s_nop 1
	v_mul_f32_e32 v48, v53, v53
	v_mul_f32_e32 v49, v55, v55
	v_fmac_f32_e32 v48, v52, v52
	v_fmac_f32_e32 v49, v54, v54
	v_add_f32_e32 v48, v48, v49
	v_mul_f32_e32 v49, v59, v59
	v_mul_f32_e32 v50, v57, v57
	v_fmac_f32_e32 v49, v58, v58
	v_fmac_f32_e32 v50, v56, v56
	v_add_f32_e32 v49, v49, v50
	v_add_f32_e32 v48, v48, v49
	v_add_f32_e32 v62, v48, v62
	v_pk_mul_f32 v[48:49], v[182:183], v[52:53]
	v_pk_mul_f32 v[50:51], v[188:189], v[54:55]
	v_cvt_pk_bf16_f32 v48, v48, v49
	v_pk_mul_f32 v[52:53], v[184:185], v[56:57]
	v_pk_mul_f32 v[54:55], v[186:187], v[58:59]
	v_cvt_pk_bf16_f32 v49, v50, v51
	s_nop 0
	v_cvt_pk_bf16_f32 v50, v54, v55
	v_cvt_pk_bf16_f32 v51, v52, v53
	global_store_dwordx4 v[60:61], v[48:51], off offset:256 sc1
	ds_bpermute_b32 v48, v128, v62
	s_waitcnt lgkmcnt(0)
	v_add_f32_e32 v48, v62, v48
	ds_bpermute_b32 v49, v129, v48
	s_and_saveexec_b64 s[40:41], vcc
	s_cbranch_execz .LBB0_1973
	s_waitcnt lgkmcnt(0)
	v_add_f32_e32 v50, v48, v49
	v_add_u32_e32 v48, s56, v120
	v_ashrrev_i32_e32 v49, 31, v48
	s_lshl_b32 s16, s2, 2
	v_lshlrev_b64 v[48:49], 6, v[48:49]
	s_ashr_i32 s17, s16, 31
	v_lshl_add_u64 v[48:49], s[14:15], 0, v[48:49]
	v_lshl_add_u64 v[48:49], s[16:17], 2, v[48:49]
	s_lshl_b32 s8, s86, 2
	v_lshl_add_u64 v[48:49], v[48:49], 0, s[8:9]
	global_store_dword v[48:49], v50, off
; __device__ __forceinline__ unsigned cvt_pk_bf16(float lo, float hi) { unsigned r; asm volatile("v_cvt_pk_bf16_f32 %0, %1, %2" : "=v"(r) : "v"(lo), "v"(hi)); return r; }
;     __device__ __forceinline__ void operator()(const f32x4 (&acc)[2][2][4][2], const Unit& u, int wr, int wc, int fr, int fq) const {
;     ...
;             for (int m = 0; m < 4; ++m) { const int rl = wr * 64 + fr + ai * HALF + m * 16; const size_t off = (size_t)rl * DM + col0; float sq = 0.f;
;                 bf16_t* hrow = h16 + (size_t)rowt * DM + off;
; #pragma unroll
;                 for (int bj = 0; bj < 2; ++bj) { f32x4 b0, b1;
;                     if (bb) { b0 = *(const f32x4*)(bb + off + bj * HALF); b1 = *(const f32x4*)(bb + off + bj * HALF + 4); }
;                     else { const u32x4 r = raw[m][bj];
;                         b0 = (f32x4){__uint_as_float(r.x << 16), __uint_as_float(r.x & 0xffff0000u), __uint_as_float(r.y << 16), __uint_as_float(r.y & 0xffff0000u)};
;                         b1 = (f32x4){__uint_as_float(r.z << 16), __uint_as_float(r.z & 0xffff0000u), __uint_as_float(r.w << 16), __uint_as_float(r.w & 0xffff0000u)}; }
;                     const f32x4 o0 = b0 + gv[bj][0] * acc[ai][bj][m][0], o1 = b1 + gv[bj][1] * acc[ai][bj][m][1];
;                     u32x4 w; w.x = cvt_pk_bf16(o0[0], o0[1]); w.y = cvt_pk_bf16(o0[2], o0[3]); w.z = cvt_pk_bf16(o1[0], o1[1]); w.w = cvt_pk_bf16(o1[2], o1[3]);
;                     *(u32x4*)(hrow + bj * HALF) = w;
;                     sq += ((o0[0] * o0[0] + o0[1] * o0[1]) + (o0[2] * o0[2] + o0[3] * o0[3])) + ((o1[0] * o1[0] + o1[1] * o1[1]) + (o1[2] * o1[2] + o1[3] * o1[3]));
;                     if (hb) { const f32x4 y0 = o0 * wv[bj][0], y1 = o1 * wv[bj][1]; u32x4 z; z.x = cvt_pk_bf16(y0[0], y0[1]); z.y = cvt_pk_bf16(y0[2], y0[3]); z.z = cvt_pk_bf16(y1[0], y1[1]); z.w = cvt_pk_bf16(y1[2], y1[3]);
;                         *(u32x4*)(hb + (size_t)rowt * DM + off + bj * HALF) = z; } }
;                 if (ssq) { sq += __shfl_xor(sq, 16); sq += __shfl_xor(sq, 32); if (fq == 0) ssq[(size_t)(rowt + rl) * 16 + u.pn * 4 + wc] = sq; } }
.LBB0_1973:
	s_or_b64 exec, exec, s[40:41]
	v_lshlrev_b32_e32 v50, 16, v84
	v_and_b32_e32 v51, 0xffff0000, v84
	v_lshlrev_b32_e32 v52, 16, v85
	v_and_b32_e32 v53, 0xffff0000, v85
	v_lshlrev_b32_e32 v54, 16, v86
	v_and_b32_e32 v55, 0xffff0000, v86
	v_lshlrev_b32_e32 v56, 16, v87
	v_and_b32_e32 v57, 0xffff0000, v87
	v_pk_fma_f32 v[46:47], v[46:47], v[110:111], v[52:53]
	v_pk_fma_f32 v[44:45], v[44:45], v[108:109], v[50:51]
	v_pk_fma_f32 v[52:53], v[40:41], v[104:105], v[54:55]
	v_cvt_pk_bf16_f32 v40, v44, v45
	v_cvt_pk_bf16_f32 v41, v46, v47
	v_pk_fma_f32 v[50:51], v[42:43], v[106:107], v[56:57]
	v_cvt_pk_bf16_f32 v42, v52, v53
	s_waitcnt lgkmcnt(0)
	v_lshlrev_b64 v[48:49], 10, v[116:117]
	v_cvt_pk_bf16_f32 v43, v50, v51
	global_store_dwordx4 v[118:119], v[40:43], off sc1
	v_lshl_add_u64 v[48:49], v[48:49], 0, v[198:199]
	s_nop 0
	v_mul_f32_e32 v40, v45, v45
	v_mul_f32_e32 v41, v47, v47
	v_fmac_f32_e32 v40, v44, v44
	v_fmac_f32_e32 v41, v46, v46
	v_add_f32_e32 v40, v40, v41
	v_mul_f32_e32 v41, v53, v53
	v_mul_f32_e32 v42, v51, v51
	v_fmac_f32_e32 v41, v52, v52
	v_fmac_f32_e32 v42, v50, v50
	v_add_f32_e32 v41, v41, v42
	v_add_f32_e32 v54, v40, v41
	v_pk_mul_f32 v[42:43], v[192:193], v[46:47]
	v_pk_mul_f32 v[40:41], v[196:197], v[44:45]
	v_pk_mul_f32 v[44:45], v[190:191], v[50:51]
	v_pk_mul_f32 v[46:47], v[194:195], v[52:53]
	v_cvt_pk_bf16_f32 v40, v40, v41
	v_cvt_pk_bf16_f32 v41, v42, v43
	s_nop 0
	v_cvt_pk_bf16_f32 v42, v46, v47
	v_cvt_pk_bf16_f32 v43, v44, v45
	v_lshl_add_u64 v[44:45], v[48:49], 1, s[58:59]
	global_store_dwordx4 v[44:45], v[40:43], off sc1
	v_lshlrev_b32_e32 v46, 16, v82
	v_and_b32_e32 v47, 0xffff0000, v82
	v_lshlrev_b32_e32 v40, 16, v80
	v_and_b32_e32 v41, 0xffff0000, v80
	v_lshlrev_b32_e32 v42, 16, v81
	v_and_b32_e32 v43, 0xffff0000, v81
	v_lshlrev_b32_e32 v48, 16, v83
	v_and_b32_e32 v49, 0xffff0000, v83
	v_pk_fma_f32 v[38:39], v[38:39], v[94:95], v[42:43]
	v_pk_fma_f32 v[36:37], v[36:37], v[92:93], v[40:41]
	v_pk_fma_f32 v[42:43], v[32:33], v[88:89], v[46:47]
	v_cvt_pk_bf16_f32 v32, v36, v37
	v_cvt_pk_bf16_f32 v33, v38, v39
	v_pk_fma_f32 v[40:41], v[34:35], v[90:91], v[48:49]
	v_cvt_pk_bf16_f32 v34, v42, v43
	s_nop 0
	v_cvt_pk_bf16_f32 v35, v40, v41
	global_store_dwordx4 v[118:119], v[32:35], off offset:256 sc1
	s_nop 1
	v_mul_f32_e32 v32, v37, v37
	v_mul_f32_e32 v33, v39, v39
	v_fmac_f32_e32 v32, v36, v36
	v_fmac_f32_e32 v33, v38, v38
	v_add_f32_e32 v32, v32, v33
	v_mul_f32_e32 v33, v43, v43
	v_mul_f32_e32 v34, v41, v41
	v_fmac_f32_e32 v33, v42, v42
	v_fmac_f32_e32 v34, v40, v40
	v_add_f32_e32 v33, v33, v34
	v_add_f32_e32 v32, v32, v33
	v_add_f32_e32 v35, v54, v32
	ds_bpermute_b32 v46, v128, v35
	v_pk_mul_f32 v[32:33], v[182:183], v[36:37]
	v_pk_mul_f32 v[36:37], v[186:187], v[42:43]
	v_cvt_pk_bf16_f32 v34, v32, v33
	v_pk_mul_f32 v[38:39], v[188:189], v[38:39]
	s_waitcnt lgkmcnt(0)
	v_add_f32_e32 v32, v35, v46
	ds_bpermute_b32 v33, v129, v32
	v_pk_mul_f32 v[40:41], v[184:185], v[40:41]
	v_cvt_pk_bf16_f32 v35, v38, v39
	v_cvt_pk_bf16_f32 v36, v36, v37
	s_nop 0
	v_cvt_pk_bf16_f32 v37, v40, v41
	global_store_dwordx4 v[44:45], v[34:37], off offset:256 sc1
	s_and_saveexec_b64 s[40:41], vcc
	s_cbranch_execz .LBB0_1975
	s_waitcnt lgkmcnt(0)
	v_add_f32_e32 v34, v32, v33
	v_add_u32_e32 v32, s56, v116
	v_ashrrev_i32_e32 v33, 31, v32
	s_lshl_b32 s16, s2, 2
	v_lshlrev_b64 v[32:33], 6, v[32:33]
	s_ashr_i32 s17, s16, 31
	v_lshl_add_u64 v[32:33], s[14:15], 0, v[32:33]
	v_lshl_add_u64 v[32:33], s[16:17], 2, v[32:33]
	s_lshl_b32 s8, s86, 2
	v_lshl_add_u64 v[32:33], v[32:33], 0, s[8:9]
	global_store_dword v[32:33], v34, off
; __device__ __forceinline__ unsigned cvt_pk_bf16(float lo, float hi) { unsigned r; asm volatile("v_cvt_pk_bf16_f32 %0, %1, %2" : "=v"(r) : "v"(lo), "v"(hi)); return r; }
;     __device__ __forceinline__ void operator()(const f32x4 (&acc)[2][2][4][2], const Unit& u, int wr, int wc, int fr, int fq) const {
;     ...
;             for (int m = 0; m < 4; ++m) { const int rl = wr * 64 + fr + ai * HALF + m * 16; const size_t off = (size_t)rl * DM + col0; float sq = 0.f;
;                 bf16_t* hrow = h16 + (size_t)rowt * DM + off;
; #pragma unroll
;                 for (int bj = 0; bj < 2; ++bj) { f32x4 b0, b1;
;                     if (bb) { b0 = *(const f32x4*)(bb + off + bj * HALF); b1 = *(const f32x4*)(bb + off + bj * HALF + 4); }
;                     else { const u32x4 r = raw[m][bj];
;                         b0 = (f32x4){__uint_as_float(r.x << 16), __uint_as_float(r.x & 0xffff0000u), __uint_as_float(r.y << 16), __uint_as_float(r.y & 0xffff0000u)};
;                         b1 = (f32x4){__uint_as_float(r.z << 16), __uint_as_float(r.z & 0xffff0000u), __uint_as_float(r.w << 16), __uint_as_float(r.w & 0xffff0000u)}; }
;                     const f32x4 o0 = b0 + gv[bj][0] * acc[ai][bj][m][0], o1 = b1 + gv[bj][1] * acc[ai][bj][m][1];
;                     u32x4 w; w.x = cvt_pk_bf16(o0[0], o0[1]); w.y = cvt_pk_bf16(o0[2], o0[3]); w.z = cvt_pk_bf16(o1[0], o1[1]); w.w = cvt_pk_bf16(o1[2], o1[3]);
;                     *(u32x4*)(hrow + bj * HALF) = w;
;                     sq += ((o0[0] * o0[0] + o0[1] * o0[1]) + (o0[2] * o0[2] + o0[3] * o0[3])) + ((o1[0] * o1[0] + o1[1] * o1[1]) + (o1[2] * o1[2] + o1[3] * o1[3]));
;                     if (hb) { const f32x4 y0 = o0 * wv[bj][0], y1 = o1 * wv[bj][1]; u32x4 z; z.x = cvt_pk_bf16(y0[0], y0[1]); z.y = cvt_pk_bf16(y0[2], y0[3]); z.z = cvt_pk_bf16(y1[0], y1[1]); z.w = cvt_pk_bf16(y1[2], y1[3]);
;                         *(u32x4*)(hb + (size_t)rowt * DM + off + bj * HALF) = z; } }
;                 if (ssq) { sq += __shfl_xor(sq, 16); sq += __shfl_xor(sq, 32); if (fq == 0) ssq[(size_t)(rowt + rl) * 16 + u.pn * 4 + wc] = sq; } }
.LBB0_1975:
	s_or_b64 exec, exec, s[40:41]
	v_lshlrev_b32_e32 v34, 16, v76
	v_and_b32_e32 v35, 0xffff0000, v76
	v_lshlrev_b32_e32 v36, 16, v77
	v_and_b32_e32 v37, 0xffff0000, v77
	v_lshlrev_b32_e32 v38, 16, v78
	v_and_b32_e32 v39, 0xffff0000, v78
	v_lshlrev_b32_e32 v40, 16, v79
	v_and_b32_e32 v41, 0xffff0000, v79
	v_pk_fma_f32 v[30:31], v[30:31], v[110:111], v[36:37]
	v_pk_fma_f32 v[28:29], v[28:29], v[108:109], v[34:35]
	v_pk_fma_f32 v[36:37], v[24:25], v[104:105], v[38:39]
	v_cvt_pk_bf16_f32 v24, v28, v29
	v_cvt_pk_bf16_f32 v25, v30, v31
	v_pk_fma_f32 v[34:35], v[26:27], v[106:107], v[40:41]
	v_cvt_pk_bf16_f32 v26, v36, v37
	s_waitcnt lgkmcnt(0)
	v_lshlrev_b64 v[32:33], 10, v[112:113]
	v_cvt_pk_bf16_f32 v27, v34, v35
	global_store_dwordx4 v[114:115], v[24:27], off sc1
	v_lshl_add_u64 v[32:33], v[32:33], 0, v[198:199]
	s_nop 0
	v_mul_f32_e32 v24, v29, v29
	v_mul_f32_e32 v25, v31, v31
	v_fmac_f32_e32 v24, v28, v28
	v_fmac_f32_e32 v25, v30, v30
	v_add_f32_e32 v24, v24, v25
	v_mul_f32_e32 v25, v37, v37
	v_mul_f32_e32 v26, v35, v35
	v_fmac_f32_e32 v25, v36, v36
	v_fmac_f32_e32 v26, v34, v34
	v_add_f32_e32 v25, v25, v26
	v_add_f32_e32 v38, v24, v25
	v_pk_mul_f32 v[26:27], v[192:193], v[30:31]
	v_pk_mul_f32 v[24:25], v[196:197], v[28:29]
	v_pk_mul_f32 v[28:29], v[190:191], v[34:35]
	v_pk_mul_f32 v[30:31], v[194:195], v[36:37]
	v_cvt_pk_bf16_f32 v24, v24, v25
	v_cvt_pk_bf16_f32 v25, v26, v27
	s_nop 0
	v_cvt_pk_bf16_f32 v26, v30, v31
	v_cvt_pk_bf16_f32 v27, v28, v29
	v_lshl_add_u64 v[28:29], v[32:33], 1, s[58:59]
	global_store_dwordx4 v[28:29], v[24:27], off sc1
	v_lshlrev_b32_e32 v30, 16, v74
	v_and_b32_e32 v31, 0xffff0000, v74
	v_lshlrev_b32_e32 v24, 16, v72
	v_and_b32_e32 v25, 0xffff0000, v72
	v_lshlrev_b32_e32 v26, 16, v73
	v_and_b32_e32 v27, 0xffff0000, v73
	v_lshlrev_b32_e32 v32, 16, v75
	v_and_b32_e32 v33, 0xffff0000, v75
	v_pk_fma_f32 v[22:23], v[22:23], v[94:95], v[26:27]
	v_pk_fma_f32 v[20:21], v[20:21], v[92:93], v[24:25]
	v_pk_fma_f32 v[26:27], v[16:17], v[88:89], v[30:31]
	v_cvt_pk_bf16_f32 v16, v20, v21
	v_cvt_pk_bf16_f32 v17, v22, v23
	v_pk_fma_f32 v[24:25], v[18:19], v[90:91], v[32:33]
	v_cvt_pk_bf16_f32 v18, v26, v27
	s_nop 0
	v_cvt_pk_bf16_f32 v19, v24, v25
	global_store_dwordx4 v[114:115], v[16:19], off offset:256 sc1
	s_nop 1
	v_mul_f32_e32 v16, v21, v21
	v_mul_f32_e32 v17, v23, v23
	v_fmac_f32_e32 v16, v20, v20
	v_fmac_f32_e32 v17, v22, v22
	v_add_f32_e32 v16, v16, v17
	v_mul_f32_e32 v17, v27, v27
	v_mul_f32_e32 v18, v25, v25
	v_fmac_f32_e32 v17, v26, v26
	v_fmac_f32_e32 v18, v24, v24
	v_add_f32_e32 v17, v17, v18
	v_add_f32_e32 v16, v16, v17
	v_add_f32_e32 v19, v38, v16
	ds_bpermute_b32 v30, v128, v19
	v_pk_mul_f32 v[16:17], v[182:183], v[20:21]
	v_pk_mul_f32 v[20:21], v[186:187], v[26:27]
	v_cvt_pk_bf16_f32 v18, v16, v17
	v_pk_mul_f32 v[22:23], v[188:189], v[22:23]
	s_waitcnt lgkmcnt(0)
	v_add_f32_e32 v16, v19, v30
	ds_bpermute_b32 v17, v129, v16
	v_pk_mul_f32 v[24:25], v[184:185], v[24:25]
	v_cvt_pk_bf16_f32 v19, v22, v23
	v_cvt_pk_bf16_f32 v20, v20, v21
	s_nop 0
	v_cvt_pk_bf16_f32 v21, v24, v25
	global_store_dwordx4 v[28:29], v[18:21], off offset:256 sc1
	s_and_saveexec_b64 s[40:41], vcc
	s_cbranch_execz .LBB0_1977
	s_waitcnt lgkmcnt(0)
	v_add_f32_e32 v18, v16, v17
	v_add_u32_e32 v16, s56, v112
	v_ashrrev_i32_e32 v17, 31, v16
	s_lshl_b32 s16, s2, 2
	v_lshlrev_b64 v[16:17], 6, v[16:17]
	s_ashr_i32 s17, s16, 31
	v_lshl_add_u64 v[16:17], s[14:15], 0, v[16:17]
	v_lshl_add_u64 v[16:17], s[16:17], 2, v[16:17]
	s_lshl_b32 s8, s86, 2
	v_lshl_add_u64 v[16:17], v[16:17], 0, s[8:9]
	global_store_dword v[16:17], v18, off
.LBB0_1977:
	s_or_b64 exec, exec, s[40:41]
	v_lshlrev_b32_e32 v18, 16, v68
	v_and_b32_e32 v19, 0xffff0000, v68
	v_lshlrev_b32_e32 v20, 16, v69
	v_and_b32_e32 v21, 0xffff0000, v69
	v_lshlrev_b32_e32 v22, 16, v70
	v_and_b32_e32 v23, 0xffff0000, v70
	v_lshlrev_b32_e32 v24, 16, v71
	v_and_b32_e32 v25, 0xffff0000, v71
	v_pk_fma_f32 v[14:15], v[14:15], v[110:111], v[20:21]
	v_pk_fma_f32 v[12:13], v[12:13], v[108:109], v[18:19]
	v_pk_fma_f32 v[20:21], v[8:9], v[104:105], v[22:23]
	v_cvt_pk_bf16_f32 v8, v12, v13
	v_cvt_pk_bf16_f32 v9, v14, v15
	v_pk_fma_f32 v[18:19], v[10:11], v[106:107], v[24:25]
	v_cvt_pk_bf16_f32 v10, v20, v21
	s_waitcnt lgkmcnt(0)
	v_lshlrev_b64 v[16:17], 10, v[100:101]
	v_cvt_pk_bf16_f32 v11, v18, v19
	global_store_dwordx4 v[102:103], v[8:11], off sc1
	v_lshl_add_u64 v[16:17], v[16:17], 0, v[198:199]
	s_nop 0
	v_mul_f32_e32 v8, v13, v13
	v_mul_f32_e32 v9, v15, v15
	v_fmac_f32_e32 v8, v12, v12
	v_fmac_f32_e32 v9, v14, v14
	v_add_f32_e32 v8, v8, v9
	v_mul_f32_e32 v9, v21, v21
	v_mul_f32_e32 v10, v19, v19
	v_fmac_f32_e32 v9, v20, v20
	v_fmac_f32_e32 v10, v18, v18
	v_add_f32_e32 v9, v9, v10
	v_add_f32_e32 v22, v8, v9
	v_pk_mul_f32 v[10:11], v[192:193], v[14:15]
	v_pk_mul_f32 v[8:9], v[196:197], v[12:13]
	v_pk_mul_f32 v[12:13], v[190:191], v[18:19]
	v_pk_mul_f32 v[14:15], v[194:195], v[20:21]
	v_cvt_pk_bf16_f32 v8, v8, v9
	v_cvt_pk_bf16_f32 v9, v10, v11
	s_nop 0
	v_cvt_pk_bf16_f32 v10, v14, v15
	v_cvt_pk_bf16_f32 v11, v12, v13
	v_lshl_add_u64 v[12:13], v[16:17], 1, s[58:59]
	global_store_dwordx4 v[12:13], v[8:11], off sc1
	v_lshlrev_b32_e32 v14, 16, v66
	v_and_b32_e32 v15, 0xffff0000, v66
	v_lshlrev_b32_e32 v8, 16, v64
	v_and_b32_e32 v9, 0xffff0000, v64
	v_lshlrev_b32_e32 v10, 16, v65
	v_and_b32_e32 v11, 0xffff0000, v65
	v_lshlrev_b32_e32 v16, 16, v67
	v_and_b32_e32 v17, 0xffff0000, v67
	v_pk_fma_f32 v[6:7], v[6:7], v[94:95], v[10:11]
	v_pk_fma_f32 v[4:5], v[4:5], v[92:93], v[8:9]
	v_pk_fma_f32 v[10:11], v[0:1], v[88:89], v[14:15]
	v_cvt_pk_bf16_f32 v0, v4, v5
	v_cvt_pk_bf16_f32 v1, v6, v7
	v_pk_fma_f32 v[8:9], v[2:3], v[90:91], v[16:17]
	v_cvt_pk_bf16_f32 v2, v10, v11
	s_nop 0
	v_cvt_pk_bf16_f32 v3, v8, v9
	global_store_dwordx4 v[102:103], v[0:3], off offset:256 sc1
	s_nop 1
	v_mul_f32_e32 v0, v5, v5
	v_mul_f32_e32 v1, v7, v7
	v_fmac_f32_e32 v0, v4, v4
	v_fmac_f32_e32 v1, v6, v6
	v_add_f32_e32 v0, v0, v1
	v_mul_f32_e32 v1, v11, v11
	v_mul_f32_e32 v2, v9, v9
	v_fmac_f32_e32 v1, v10, v10
	v_fmac_f32_e32 v2, v8, v8
	v_add_f32_e32 v1, v1, v2
	v_add_f32_e32 v0, v0, v1
	v_add_f32_e32 v3, v22, v0
	ds_bpermute_b32 v14, v128, v3
	v_pk_mul_f32 v[0:1], v[182:183], v[4:5]
	v_pk_mul_f32 v[4:5], v[186:187], v[10:11]
	v_cvt_pk_bf16_f32 v2, v0, v1
	v_pk_mul_f32 v[6:7], v[188:189], v[6:7]
	s_waitcnt lgkmcnt(0)
	v_add_f32_e32 v0, v3, v14
	ds_bpermute_b32 v1, v129, v0
	v_pk_mul_f32 v[8:9], v[184:185], v[8:9]
	v_cvt_pk_bf16_f32 v3, v6, v7
	v_cvt_pk_bf16_f32 v4, v4, v5
	s_nop 0
	v_cvt_pk_bf16_f32 v5, v8, v9
	global_store_dwordx4 v[12:13], v[2:5], off offset:256 sc1
	s_and_saveexec_b64 s[40:41], vcc
	s_cbranch_execz .LBB0_1979
	s_waitcnt lgkmcnt(0)
	v_add_f32_e32 v2, v0, v1
	v_add_u32_e32 v0, s56, v100
	v_ashrrev_i32_e32 v1, 31, v0
	s_lshl_b32 s2, s2, 2
	v_lshlrev_b64 v[0:1], 6, v[0:1]
	s_ashr_i32 s3, s2, 31
	v_lshl_add_u64 v[0:1], s[14:15], 0, v[0:1]
	v_lshl_add_u64 v[0:1], s[2:3], 2, v[0:1]
	s_lshl_b32 s8, s86, 2
	v_lshl_add_u64 v[0:1], v[0:1], 0, s[8:9]
	global_store_dword v[0:1], v2, off
